# v25 with agent-scope write-through (sc1) instead of system-scope (sc0 sc1) on all global stores
# speedup vs baseline: 1.0170x; 1.0030x over previous
; __device__ __forceinline__ void tr_item(const float* W, int K, int N, int nblk, bf16_t* WT, LAS float* scr, int item, int lane, bool qperm) {
;     ...
; #pragma unroll 8
;     for (int i = 0; i < 32; ++i) { const int kk = 2 * i + (lane >> 5); const float v = W[(size_t)(k0 + kk) * N + src]; scr[kk * 33 + (lane & 31)] = ok ? v : 0.f; }
.LBB0_18:
	s_lshl_b32 s76, s60, 1
	s_lshl_b32 s77, s61, 1
	v_or_b32_e32 v26, s77, v8
	s_add_i32 s78, s76, 4
	s_add_i32 s79, s77, 4
	s_add_i32 s80, s76, 8
	s_add_i32 s81, s77, 8
	s_add_i32 s82, s76, 12
	s_add_i32 s83, s77, 12
	s_add_i32 s84, s76, 16
	s_add_i32 s85, s77, 16
	s_add_i32 s86, s76, 20
	s_add_i32 s87, s77, 20
	s_add_i32 s88, s76, 24
	s_add_i32 s89, s77, 24
	s_add_i32 s90, s76, 28
	s_add_i32 s91, s77, 28
	v_or_b32_e32 v24, s76, v3
	v_ashrrev_i32_e32 v27, 31, v26
	v_or_b32_e32 v28, s78, v3
	v_or_b32_e32 v30, s79, v8
	v_or_b32_e32 v32, s80, v3
	v_or_b32_e32 v34, s81, v8
	v_or_b32_e32 v36, s82, v3
	v_or_b32_e32 v38, s83, v8
	v_or_b32_e32 v40, s84, v3
	v_or_b32_e32 v42, s85, v8
	v_or_b32_e32 v44, s86, v3
	v_or_b32_e32 v46, s87, v8
	v_or_b32_e32 v48, s88, v3
	v_or_b32_e32 v50, s89, v8
	v_or_b32_e32 v52, s90, v3
	v_or_b32_e32 v54, s91, v8
	v_ashrrev_i32_e32 v25, 31, v24
	v_lshlrev_b64 v[26:27], 12, v[26:27]
	v_ashrrev_i32_e32 v31, 31, v30
	v_ashrrev_i32_e32 v29, 31, v28
	v_ashrrev_i32_e32 v35, 31, v34
	v_ashrrev_i32_e32 v33, 31, v32
	v_ashrrev_i32_e32 v39, 31, v38
	v_ashrrev_i32_e32 v37, 31, v36
	v_ashrrev_i32_e32 v43, 31, v42
	v_ashrrev_i32_e32 v41, 31, v40
	v_ashrrev_i32_e32 v47, 31, v46
	v_ashrrev_i32_e32 v45, 31, v44
	v_ashrrev_i32_e32 v51, 31, v50
	v_ashrrev_i32_e32 v49, 31, v48
	v_ashrrev_i32_e32 v55, 31, v54
	v_ashrrev_i32_e32 v53, 31, v52
	v_lshlrev_b64 v[24:25], 12, v[24:25]
	v_lshl_add_u64 v[26:27], v[14:15], 0, v[26:27]
	v_lshlrev_b64 v[28:29], 12, v[28:29]
	v_lshlrev_b64 v[30:31], 12, v[30:31]
	v_lshlrev_b64 v[32:33], 12, v[32:33]
	v_lshlrev_b64 v[34:35], 12, v[34:35]
	v_lshlrev_b64 v[36:37], 12, v[36:37]
	v_lshlrev_b64 v[38:39], 12, v[38:39]
	v_lshlrev_b64 v[40:41], 12, v[40:41]
	v_lshlrev_b64 v[42:43], 12, v[42:43]
	v_lshlrev_b64 v[44:45], 12, v[44:45]
	v_lshlrev_b64 v[46:47], 12, v[46:47]
	v_lshlrev_b64 v[48:49], 12, v[48:49]
	v_lshlrev_b64 v[50:51], 12, v[50:51]
	v_lshlrev_b64 v[52:53], 12, v[52:53]
	v_lshlrev_b64 v[54:55], 12, v[54:55]
	v_lshl_add_u64 v[24:25], v[14:15], 0, v[24:25]
	v_lshl_add_u64 v[30:31], v[14:15], 0, v[30:31]
	v_lshl_add_u64 v[28:29], v[14:15], 0, v[28:29]
	v_lshl_add_u64 v[34:35], v[14:15], 0, v[34:35]
	v_lshl_add_u64 v[32:33], v[14:15], 0, v[32:33]
	v_lshl_add_u64 v[38:39], v[14:15], 0, v[38:39]
	v_lshl_add_u64 v[36:37], v[14:15], 0, v[36:37]
	v_lshl_add_u64 v[42:43], v[14:15], 0, v[42:43]
	v_lshl_add_u64 v[40:41], v[14:15], 0, v[40:41]
	v_lshl_add_u64 v[46:47], v[14:15], 0, v[46:47]
	v_lshl_add_u64 v[44:45], v[14:15], 0, v[44:45]
	v_lshl_add_u64 v[50:51], v[14:15], 0, v[50:51]
	v_lshl_add_u64 v[48:49], v[14:15], 0, v[48:49]
	v_lshl_add_u64 v[54:55], v[14:15], 0, v[54:55]
	v_lshl_add_u64 v[52:53], v[14:15], 0, v[52:53]
	global_load_dword v11, v[26:27], off
	global_load_dword v56, v[24:25], off
	global_load_dword v57, v[30:31], off
	global_load_dword v58, v[28:29], off
	global_load_dword v59, v[34:35], off
	global_load_dword v60, v[32:33], off
	global_load_dword v61, v[38:39], off
	global_load_dword v62, v[36:37], off
	global_load_dword v63, v[42:43], off
	global_load_dword v64, v[40:41], off
	global_load_dword v65, v[46:47], off
	global_load_dword v66, v[44:45], off
	global_load_dword v67, v[50:51], off
	global_load_dword v68, v[48:49], off
	global_load_dword v69, v[54:55], off
	global_load_dword v70, v[52:53], off
	v_or_b32_e32 v26, s76, v1
	v_or_b32_e32 v24, s77, v2
	s_add_i32 s61, s61, 16
	s_add_i32 s60, s60, 16
	s_add_i32 s75, s75, -16
	v_mad_u64_u32 v[24:25], s[76:77], v24, s66, v[4:5]
	v_mad_u64_u32 v[26:27], s[76:77], v26, s66, v[4:5]
	v_or_b32_e32 v25, s78, v1
	v_or_b32_e32 v27, s79, v2
	v_or_b32_e32 v34, s80, v1
	v_or_b32_e32 v32, s81, v2
	v_or_b32_e32 v38, s82, v1
	v_or_b32_e32 v36, s83, v2
	v_or_b32_e32 v42, s84, v1
	v_or_b32_e32 v40, s85, v2
	v_or_b32_e32 v46, s86, v1
	v_or_b32_e32 v44, s87, v2
	v_or_b32_e32 v50, s88, v1
	v_or_b32_e32 v48, s89, v2
	v_or_b32_e32 v54, s90, v1
	v_or_b32_e32 v52, s91, v2
	s_cmp_lg_u32 s75, 0
	v_mad_u64_u32 v[28:29], s[76:77], v27, s66, v[4:5]
	v_mad_u64_u32 v[30:31], s[76:77], v25, s66, v[4:5]
	v_mad_u64_u32 v[32:33], s[76:77], v32, s66, v[4:5]
	v_mad_u64_u32 v[34:35], s[76:77], v34, s66, v[4:5]
	v_mad_u64_u32 v[36:37], s[76:77], v36, s66, v[4:5]
	v_mad_u64_u32 v[38:39], s[76:77], v38, s66, v[4:5]
	v_mad_u64_u32 v[40:41], s[76:77], v40, s66, v[4:5]
	v_mad_u64_u32 v[42:43], s[76:77], v42, s66, v[4:5]
	v_mad_u64_u32 v[44:45], s[76:77], v44, s66, v[4:5]
	v_mad_u64_u32 v[46:47], s[76:77], v46, s66, v[4:5]
	v_mad_u64_u32 v[48:49], s[76:77], v48, s66, v[4:5]
	v_mad_u64_u32 v[50:51], s[76:77], v50, s66, v[4:5]
	v_mad_u64_u32 v[52:53], s[76:77], v52, s66, v[4:5]
	v_mad_u64_u32 v[54:55], s[76:77], v54, s66, v[4:5]
	s_waitcnt vmcnt(0)
	ds_write_b32 v24, v11
	ds_write_b32 v26, v56
	ds_write_b32 v28, v57
	ds_write_b32 v30, v58
	ds_write_b32 v32, v59
	ds_write_b32 v34, v60
	ds_write_b32 v36, v61
	ds_write_b32 v38, v62
	ds_write_b32 v40, v63
	ds_write_b32 v42, v64
	ds_write_b32 v44, v65
	ds_write_b32 v46, v66
	ds_write_b32 v48, v67
	ds_write_b32 v50, v68
	ds_write_b32 v52, v69
	ds_write_b32 v54, v70
	s_cbranch_scc1 .LBB0_18
; #define LAS __attribute__((address_space(3)))
; __device__ __forceinline__ unsigned cvtpk(float lo, float hi) { f32x2_t v = {lo, hi}; bf16x2_t b = __builtin_convertvector(v, bf16x2_t); return __builtin_bit_cast(unsigned, b); }
; __device__ __forceinline__ void tr_item(const float* W, int K, int N, int nblk, bf16_t* WT, LAS float* scr, int item, int lane, bool qperm) {
;     ...
;     asm volatile("s_waitcnt lgkmcnt(0)" ::: "memory");
;     const int c = lane & 7;
; #pragma unroll
;     for (int j = 0; j < 4; ++j) { const int n = (lane >> 3) + 8 * j; const LAS float* s = scr + (8 * c) * 33 + n;
;         u32x4 o; o.x = cvtpk(s[0 * 33], s[1 * 33]); o.y = cvtpk(s[2 * 33], s[3 * 33]); o.z = cvtpk(s[4 * 33], s[5 * 33]); o.w = cvtpk(s[6 * 33], s[7 * 33]);
;         *(u32x4*)(WT + (size_t)(n0 + n) * K + k0 + 8 * c) = o; }
;     asm volatile("s_waitcnt lgkmcnt(0)" ::: "memory");
	s_waitcnt lgkmcnt(0)
	ds_read2_b32 v[14:15], v19 offset0:33 offset1:41
	ds_read2_b32 v[24:25], v19 offset1:8
	ds_read2_b32 v[26:27], v19 offset0:66 offset1:74
	ds_read2_b32 v[28:29], v19 offset0:99 offset1:107
	ds_read2_b32 v[30:31], v19 offset0:132 offset1:140
	ds_read2_b32 v[32:33], v19 offset0:165 offset1:173
	ds_read2_b32 v[34:35], v19 offset0:198 offset1:206
	ds_read2_b32 v[36:37], v19 offset0:231 offset1:239
	v_lshl_add_u64 v[12:13], v[12:13], 1, s[4:5]
	v_mov_b32_e32 v11, v9
	v_lshl_add_u64 v[10:11], v[10:11], 1, v[12:13]
	v_lshlrev_b32_e32 v8, 1, v6
	v_or_b32_e32 v3, v16, v18
	v_lshl_add_u64 v[38:39], v[10:11], 0, v[8:9]
	v_lshlrev_b32_e32 v8, 11, v3
	s_waitcnt lgkmcnt(0)
	v_cvt_pk_bf16_f32 v10, v24, v14
	v_cvt_pk_bf16_f32 v11, v26, v28
	v_cvt_pk_bf16_f32 v12, v30, v32
	v_cvt_pk_bf16_f32 v13, v34, v36
	v_lshl_add_u64 v[40:41], v[38:39], 0, v[8:9]
	global_store_dwordx4 v[40:41], v[10:13], off sc1
	v_or_b32_e32 v3, v16, v20
	v_lshlrev_b32_e32 v8, 11, v3
	v_cvt_pk_bf16_f32 v10, v25, v15
	v_cvt_pk_bf16_f32 v11, v27, v29
	v_cvt_pk_bf16_f32 v12, v31, v33
	v_cvt_pk_bf16_f32 v13, v35, v37
	ds_read2_b32 v[24:25], v19 offset0:49 offset1:57
	ds_read2_b32 v[26:27], v19 offset0:16 offset1:24
	ds_read2_b32 v[28:29], v19 offset0:82 offset1:90
	ds_read2_b32 v[30:31], v19 offset0:115 offset1:123
	ds_read2_b32 v[32:33], v19 offset0:148 offset1:156
	ds_read2_b32 v[34:35], v19 offset0:181 offset1:189
	ds_read2_b32 v[36:37], v19 offset0:214 offset1:222
	ds_read2_b32 v[40:41], v19 offset0:247 offset1:255
	v_or_b32_e32 v3, v16, v21
	v_lshl_add_u64 v[14:15], v[38:39], 0, v[8:9]
	v_lshlrev_b32_e32 v8, 11, v3
	v_or_b32_e32 v3, v16, v22
	global_store_dwordx4 v[14:15], v[10:13], off sc1
	v_lshl_add_u64 v[14:15], v[38:39], 0, v[8:9]
	v_lshlrev_b32_e32 v8, 11, v3
	s_waitcnt lgkmcnt(6)
	v_cvt_pk_bf16_f32 v10, v26, v24
	s_waitcnt lgkmcnt(4)
	v_cvt_pk_bf16_f32 v11, v28, v30
	s_waitcnt lgkmcnt(2)
	v_cvt_pk_bf16_f32 v12, v32, v34
	s_waitcnt lgkmcnt(0)
	v_cvt_pk_bf16_f32 v13, v36, v40
	global_store_dwordx4 v[14:15], v[10:13], off sc1
	v_lshl_add_u64 v[14:15], v[38:39], 0, v[8:9]
	v_readlane_b32 s84, v254, 7
	v_cvt_pk_bf16_f32 v10, v27, v25
	v_cvt_pk_bf16_f32 v11, v29, v31
	v_cvt_pk_bf16_f32 v12, v33, v35
	v_cvt_pk_bf16_f32 v13, v37, v41
	global_store_dwordx4 v[14:15], v[10:13], off sc1
	s_waitcnt lgkmcnt(0)
	v_readlane_b32 s75, v254, 6
	v_readlane_b32 s85, v254, 8

; __device__ __forceinline__ void tr_item(const float* W, int K, int N, int nblk, bf16_t* WT, LAS float* scr, int item, int lane, bool qperm) {
;     ...
; #pragma unroll 8
;     for (int i = 0; i < 32; ++i) { const int kk = 2 * i + (lane >> 5); const float v = W[(size_t)(k0 + kk) * N + src]; scr[kk * 33 + (lane & 31)] = ok ? v : 0.f; }
.LBB0_22:
	s_lshl_b32 s76, s60, 1
	s_lshl_b32 s77, s61, 1
	v_or_b32_e32 v8, s77, v16
	s_add_i32 s78, s76, 4
	s_add_i32 s79, s77, 4
	v_mov_b32_e32 v29, v9
	s_add_i32 s81, s77, 8
	v_lshlrev_b64 v[42:43], 13, v[8:9]
	v_or_b32_e32 v28, s78, v3
	v_or_b32_e32 v8, s79, v16
	v_mov_b32_e32 v27, v9
	v_or_b32_e32 v26, s76, v3
	s_add_i32 s83, s77, 12
	v_lshlrev_b64 v[28:29], 13, v[28:29]
	v_lshlrev_b64 v[44:45], 13, v[8:9]
	v_or_b32_e32 v8, s81, v16
	s_add_i32 s80, s76, 8
	s_add_i32 s82, s76, 12
	s_add_i32 s85, s77, 16
	v_lshlrev_b64 v[26:27], 13, v[26:27]
	v_lshl_add_u64 v[42:43], v[14:15], 0, v[42:43]
	v_lshl_add_u64 v[28:29], v[14:15], 0, v[28:29]
	v_lshlrev_b64 v[46:47], 13, v[8:9]
	v_or_b32_e32 v8, s83, v16
	v_mov_b32_e32 v31, v9
	v_mov_b32_e32 v33, v9
	s_add_i32 s87, s77, 20
	v_or_b32_e32 v30, s80, v3
	v_or_b32_e32 v32, s82, v3
	v_lshl_add_u64 v[26:27], v[14:15], 0, v[26:27]
	v_lshl_add_u64 v[44:45], v[14:15], 0, v[44:45]
	global_load_dword v13, v[42:43], off
	global_load_dword v25, v[26:27], off
	global_load_dword v58, v[44:45], off
	global_load_dword v59, v[28:29], off
	v_lshlrev_b64 v[28:29], 13, v[8:9]
	v_or_b32_e32 v8, s85, v16
	s_add_i32 s84, s76, 16
	s_add_i32 s86, s76, 20
	s_add_i32 s89, s77, 24
	v_lshlrev_b64 v[30:31], 13, v[30:31]
	v_lshlrev_b64 v[32:33], 13, v[32:33]
	v_lshl_add_u64 v[26:27], v[14:15], 0, v[46:47]
	v_lshl_add_u64 v[28:29], v[14:15], 0, v[28:29]
	v_lshlrev_b64 v[42:43], 13, v[8:9]
	v_or_b32_e32 v8, s87, v16
	v_mov_b32_e32 v35, v9
	v_mov_b32_e32 v37, v9
	s_add_i32 s88, s76, 24
	s_add_i32 s90, s76, 28
	s_add_i32 s91, s77, 28
	v_or_b32_e32 v34, s84, v3
	v_or_b32_e32 v36, s86, v3
	v_lshl_add_u64 v[30:31], v[14:15], 0, v[30:31]
	v_lshl_add_u64 v[32:33], v[14:15], 0, v[32:33]
	global_load_dword v60, v[26:27], off
	global_load_dword v61, v[30:31], off
	global_load_dword v62, v[28:29], off
	global_load_dword v63, v[32:33], off
	v_lshlrev_b64 v[28:29], 13, v[8:9]
	v_or_b32_e32 v8, s89, v16
	v_mov_b32_e32 v39, v9
	v_mov_b32_e32 v41, v9
	v_or_b32_e32 v38, s88, v3
	v_or_b32_e32 v40, s90, v3
	v_lshlrev_b64 v[34:35], 13, v[34:35]
	v_lshlrev_b64 v[36:37], 13, v[36:37]
	v_lshl_add_u64 v[26:27], v[14:15], 0, v[42:43]
	v_lshl_add_u64 v[28:29], v[14:15], 0, v[28:29]
	v_lshlrev_b64 v[30:31], 13, v[8:9]
	v_or_b32_e32 v8, s91, v16
	v_lshlrev_b64 v[38:39], 13, v[38:39]
	v_lshlrev_b64 v[40:41], 13, v[40:41]
	v_lshl_add_u64 v[34:35], v[14:15], 0, v[34:35]
	v_lshl_add_u64 v[36:37], v[14:15], 0, v[36:37]
	global_load_dword v64, v[26:27], off
	global_load_dword v65, v[34:35], off
	global_load_dword v66, v[28:29], off
	global_load_dword v67, v[36:37], off
	v_lshl_add_u64 v[26:27], v[14:15], 0, v[30:31]
	v_lshlrev_b64 v[28:29], 13, v[8:9]
	v_lshl_add_u64 v[38:39], v[14:15], 0, v[38:39]
	v_lshl_add_u64 v[40:41], v[14:15], 0, v[40:41]
	v_lshl_add_u64 v[28:29], v[14:15], 0, v[28:29]
	global_load_dword v8, v[26:27], off
	global_load_dword v68, v[38:39], off
	global_load_dword v69, v[28:29], off
	global_load_dword v70, v[40:41], off
	v_or_b32_e32 v28, s76, v1
	v_or_b32_e32 v26, s77, v2
	s_add_i32 s61, s61, 16
	s_add_i32 s60, s60, 16
	s_add_i32 s75, s75, -16
	v_mad_u64_u32 v[26:27], s[76:77], v26, s66, v[4:5]
	v_mad_u64_u32 v[28:29], s[76:77], v28, s66, v[4:5]
	v_or_b32_e32 v27, s78, v1
	v_or_b32_e32 v29, s79, v2
	v_or_b32_e32 v36, s80, v1
	v_or_b32_e32 v34, s81, v2
	v_or_b32_e32 v40, s82, v1
	v_or_b32_e32 v38, s83, v2
	v_or_b32_e32 v44, s84, v1
	v_or_b32_e32 v42, s85, v2
	v_or_b32_e32 v48, s86, v1
	v_or_b32_e32 v46, s87, v2
	v_or_b32_e32 v52, s88, v1
	v_or_b32_e32 v50, s89, v2
	v_or_b32_e32 v56, s90, v1
	v_or_b32_e32 v54, s91, v2
	s_cmp_lg_u32 s75, 0
	v_mad_u64_u32 v[30:31], s[76:77], v29, s66, v[4:5]
	v_mad_u64_u32 v[32:33], s[76:77], v27, s66, v[4:5]
	v_mad_u64_u32 v[34:35], s[76:77], v34, s66, v[4:5]
	v_mad_u64_u32 v[36:37], s[76:77], v36, s66, v[4:5]
	v_mad_u64_u32 v[38:39], s[76:77], v38, s66, v[4:5]
	v_mad_u64_u32 v[40:41], s[76:77], v40, s66, v[4:5]
	v_mad_u64_u32 v[42:43], s[76:77], v42, s66, v[4:5]
	v_mad_u64_u32 v[44:45], s[76:77], v44, s66, v[4:5]
	v_mad_u64_u32 v[46:47], s[76:77], v46, s66, v[4:5]
	v_mad_u64_u32 v[48:49], s[76:77], v48, s66, v[4:5]
	v_mad_u64_u32 v[50:51], s[76:77], v50, s66, v[4:5]
	v_mad_u64_u32 v[52:53], s[76:77], v52, s66, v[4:5]
	v_mad_u64_u32 v[54:55], s[76:77], v54, s66, v[4:5]
	v_mad_u64_u32 v[56:57], s[76:77], v56, s66, v[4:5]
	s_waitcnt vmcnt(0)
	ds_write_b32 v26, v13
	ds_write_b32 v28, v25
	ds_write_b32 v30, v58
	ds_write_b32 v32, v59
	ds_write_b32 v34, v60
	ds_write_b32 v36, v61
	ds_write_b32 v38, v62
	ds_write_b32 v40, v63
	ds_write_b32 v42, v64
	ds_write_b32 v44, v65
	ds_write_b32 v46, v66
	ds_write_b32 v48, v67
	ds_write_b32 v50, v8
	ds_write_b32 v52, v68
	ds_write_b32 v54, v69
	ds_write_b32 v56, v70
	s_cbranch_scc1 .LBB0_22
; #define LAS __attribute__((address_space(3)))
; __device__ __forceinline__ unsigned cvtpk(float lo, float hi) { f32x2_t v = {lo, hi}; bf16x2_t b = __builtin_convertvector(v, bf16x2_t); return __builtin_bit_cast(unsigned, b); }
; __device__ __forceinline__ void tr_item(const float* W, int K, int N, int nblk, bf16_t* WT, LAS float* scr, int item, int lane, bool qperm) {
;     ...
;     asm volatile("s_waitcnt lgkmcnt(0)" ::: "memory");
;     const int c = lane & 7;
; #pragma unroll
;     for (int j = 0; j < 4; ++j) { const int n = (lane >> 3) + 8 * j; const LAS float* s = scr + (8 * c) * 33 + n;
;         u32x4 o; o.x = cvtpk(s[0 * 33], s[1 * 33]); o.y = cvtpk(s[2 * 33], s[3 * 33]); o.z = cvtpk(s[4 * 33], s[5 * 33]); o.w = cvtpk(s[6 * 33], s[7 * 33]);
;         *(u32x4*)(WT + (size_t)(n0 + n) * K + k0 + 8 * c) = o; }
;     asm volatile("s_waitcnt lgkmcnt(0)" ::: "memory");
	s_waitcnt lgkmcnt(0)
	ds_read2_b32 v[14:15], v19 offset0:33 offset1:41
	ds_read2_b32 v[26:27], v19 offset1:8
	ds_read2_b32 v[28:29], v19 offset0:66 offset1:74
	ds_read2_b32 v[30:31], v19 offset0:99 offset1:107
	ds_read2_b32 v[32:33], v19 offset0:132 offset1:140
	ds_read2_b32 v[34:35], v19 offset0:165 offset1:173
	ds_read2_b32 v[36:37], v19 offset0:198 offset1:206
	ds_read2_b32 v[38:39], v19 offset0:231 offset1:239
	v_lshlrev_b64 v[10:11], 20, v[10:11]
	v_lshl_add_u64 v[10:11], s[6:7], 0, v[10:11]
	v_mov_b32_e32 v13, v9
	v_lshl_add_u64 v[10:11], v[12:13], 1, v[10:11]
	v_lshlrev_b32_e32 v8, 1, v6
	v_or_b32_e32 v3, v24, v18
	v_lshl_add_u64 v[40:41], v[10:11], 0, v[8:9]
	v_lshlrev_b32_e32 v8, 9, v3
	s_waitcnt lgkmcnt(0)
	v_cvt_pk_bf16_f32 v10, v26, v14
	v_cvt_pk_bf16_f32 v11, v28, v30
	v_cvt_pk_bf16_f32 v12, v32, v34
	v_cvt_pk_bf16_f32 v13, v36, v38
	v_lshl_add_u64 v[42:43], v[40:41], 0, v[8:9]
	global_store_dwordx4 v[42:43], v[10:13], off sc1
	v_or_b32_e32 v3, v24, v20
	v_lshlrev_b32_e32 v8, 9, v3
	v_cvt_pk_bf16_f32 v10, v27, v15
	v_cvt_pk_bf16_f32 v11, v29, v31
	v_cvt_pk_bf16_f32 v12, v33, v35
	v_cvt_pk_bf16_f32 v13, v37, v39
	ds_read2_b32 v[26:27], v19 offset0:49 offset1:57
	ds_read2_b32 v[28:29], v19 offset0:16 offset1:24
	ds_read2_b32 v[30:31], v19 offset0:82 offset1:90
	ds_read2_b32 v[32:33], v19 offset0:115 offset1:123
	ds_read2_b32 v[34:35], v19 offset0:148 offset1:156
	ds_read2_b32 v[36:37], v19 offset0:181 offset1:189
	ds_read2_b32 v[38:39], v19 offset0:214 offset1:222
	ds_read2_b32 v[42:43], v19 offset0:247 offset1:255
	v_or_b32_e32 v3, v24, v21
	v_lshl_add_u64 v[14:15], v[40:41], 0, v[8:9]
	v_lshlrev_b32_e32 v8, 9, v3
	v_or_b32_e32 v3, v24, v22
	global_store_dwordx4 v[14:15], v[10:13], off sc1
	v_lshl_add_u64 v[14:15], v[40:41], 0, v[8:9]
	v_lshlrev_b32_e32 v8, 9, v3
	s_waitcnt lgkmcnt(6)
	v_cvt_pk_bf16_f32 v10, v28, v26
	s_waitcnt lgkmcnt(4)
	v_cvt_pk_bf16_f32 v11, v30, v32
	s_waitcnt lgkmcnt(2)
	v_cvt_pk_bf16_f32 v12, v34, v36
	s_waitcnt lgkmcnt(0)
	v_cvt_pk_bf16_f32 v13, v38, v42
	global_store_dwordx4 v[14:15], v[10:13], off sc1
	v_lshl_add_u64 v[14:15], v[40:41], 0, v[8:9]
	v_readlane_b32 s84, v254, 7
	v_cvt_pk_bf16_f32 v10, v29, v27
	v_cvt_pk_bf16_f32 v11, v31, v33
	v_cvt_pk_bf16_f32 v12, v35, v37
	v_cvt_pk_bf16_f32 v13, v39, v43
	global_store_dwordx4 v[14:15], v[10:13], off sc1
	s_waitcnt lgkmcnt(0)
	v_readlane_b32 s75, v254, 6
	v_readlane_b32 s85, v254, 8

; __device__ __forceinline__ int qperm_src(int n) { const int hh = n / 96, d = n - hh * 96; if (d < 64) return n; const int j = d - 64; return hh * 96 + 64 + ((j & 1) ? 16 + (j >> 1) : (j >> 1)); }
; __device__ __forceinline__ void tr_item(const float* W, int K, int N, int nblk, bf16_t* WT, LAS float* scr, int item, int lane, bool qperm) {
;     ...
;     const int nn = n0 + (lane & 31); const bool ok = nn < N; const int src = qperm ? qperm_src(ok ? nn : 0) : (ok ? nn : 0);
; #pragma unroll 8
;     for (int i = 0; i < 32; ++i) { const int kk = 2 * i + (lane >> 5); const float v = W[(size_t)(k0 + kk) * N + src]; scr[kk * 33 + (lane & 31)] = ok ? v : 0.f; }
.LBB0_29:
	s_lshl_b32 s61, s0, 1
	s_lshl_b32 s75, s1, 1
	v_or_b32_e32 v15, s61, v3
	v_or_b32_e32 v16, s75, v8
	s_add_i32 s78, s61, 4
	s_add_i32 s79, s75, 4
	s_add_i32 s80, s61, 8
	s_add_i32 s81, s75, 8
	s_add_i32 s82, s61, 12
	s_add_i32 s83, s75, 12
	s_add_i32 s84, s61, 16
	s_add_i32 s85, s75, 16
	s_add_i32 s86, s61, 20
	s_add_i32 s87, s75, 20
	s_add_i32 s88, s61, 24
	s_add_i32 s89, s75, 24
	s_add_i32 s90, s61, 28
	s_add_i32 s91, s75, 28
	v_mad_u64_u32 v[24:25], s[76:77], v16, s67, v[12:13]
	v_mad_u64_u32 v[26:27], s[76:77], v15, s67, v[12:13]
	v_or_b32_e32 v15, s78, v3
	v_or_b32_e32 v16, s79, v8
	v_or_b32_e32 v34, s80, v3
	v_or_b32_e32 v32, s81, v8
	v_or_b32_e32 v38, s82, v3
	v_or_b32_e32 v36, s83, v8
	v_or_b32_e32 v42, s84, v3
	v_or_b32_e32 v40, s85, v8
	v_or_b32_e32 v46, s86, v3
	v_or_b32_e32 v44, s87, v8
	v_or_b32_e32 v50, s88, v3
	v_or_b32_e32 v48, s89, v8
	v_or_b32_e32 v54, s90, v3
	v_or_b32_e32 v52, s91, v8
	v_mad_u64_u32 v[28:29], s[76:77], v16, s67, v[12:13]
	v_mad_u64_u32 v[30:31], s[76:77], v15, s67, v[12:13]
	v_mad_u64_u32 v[32:33], s[76:77], v32, s67, v[12:13]
	v_mad_u64_u32 v[34:35], s[76:77], v34, s67, v[12:13]
	v_mad_u64_u32 v[36:37], s[76:77], v36, s67, v[12:13]
	v_mad_u64_u32 v[38:39], s[76:77], v38, s67, v[12:13]
	v_mad_u64_u32 v[40:41], s[76:77], v40, s67, v[12:13]
	v_mad_u64_u32 v[42:43], s[76:77], v42, s67, v[12:13]
	v_mad_u64_u32 v[44:45], s[76:77], v44, s67, v[12:13]
	v_mad_u64_u32 v[46:47], s[76:77], v46, s67, v[12:13]
	v_mad_u64_u32 v[48:49], s[76:77], v48, s67, v[12:13]
	v_mad_u64_u32 v[50:51], s[76:77], v50, s67, v[12:13]
	v_mad_u64_u32 v[52:53], s[76:77], v52, s67, v[12:13]
	v_mad_u64_u32 v[54:55], s[76:77], v54, s67, v[12:13]
	global_load_dword v15, v[26:27], off
	global_load_dword v16, v[28:29], off
	global_load_dword v56, v[38:39], off
	global_load_dword v57, v[34:35], off
	global_load_dword v58, v[30:31], off
	global_load_dword v59, v[24:25], off
	global_load_dword v60, v[36:37], off
	global_load_dword v61, v[32:33], off
	global_load_dword v62, v[42:43], off
	global_load_dword v63, v[44:45], off
	global_load_dword v64, v[54:55], off
	global_load_dword v65, v[50:51], off
	global_load_dword v66, v[46:47], off
	global_load_dword v67, v[40:41], off
	global_load_dword v68, v[48:49], off
	global_load_dword v69, v[52:53], off
	v_or_b32_e32 v26, s61, v1
	v_or_b32_e32 v24, s75, v2
	v_mad_u64_u32 v[24:25], s[76:77], v24, s66, v[4:5]
	v_mad_u64_u32 v[26:27], s[76:77], v26, s66, v[4:5]
	s_add_i32 s1, s1, 16
	s_add_i32 s0, s0, 16
	s_add_i32 s60, s60, -16
	v_or_b32_e32 v25, s78, v1
	v_or_b32_e32 v27, s79, v2
	v_or_b32_e32 v34, s80, v1
	v_or_b32_e32 v32, s81, v2
	v_or_b32_e32 v38, s82, v1
	v_or_b32_e32 v36, s83, v2
	v_or_b32_e32 v42, s84, v1
	v_or_b32_e32 v40, s85, v2
	v_or_b32_e32 v46, s86, v1
	v_or_b32_e32 v44, s87, v2
	v_or_b32_e32 v50, s88, v1
	v_or_b32_e32 v48, s89, v2
	v_or_b32_e32 v54, s90, v1
	v_or_b32_e32 v52, s91, v2
	s_cmp_lg_u32 s60, 0
	v_mad_u64_u32 v[28:29], s[76:77], v27, s66, v[4:5]
	v_mad_u64_u32 v[30:31], s[76:77], v25, s66, v[4:5]
	v_mad_u64_u32 v[32:33], s[76:77], v32, s66, v[4:5]
	v_mad_u64_u32 v[34:35], s[76:77], v34, s66, v[4:5]
	v_mad_u64_u32 v[36:37], s[76:77], v36, s66, v[4:5]
	v_mad_u64_u32 v[38:39], s[76:77], v38, s66, v[4:5]
	v_mad_u64_u32 v[40:41], s[76:77], v40, s66, v[4:5]
	v_mad_u64_u32 v[42:43], s[76:77], v42, s66, v[4:5]
	v_mad_u64_u32 v[44:45], s[76:77], v44, s66, v[4:5]
	v_mad_u64_u32 v[46:47], s[76:77], v46, s66, v[4:5]
	v_mad_u64_u32 v[48:49], s[76:77], v48, s66, v[4:5]
	v_mad_u64_u32 v[50:51], s[76:77], v50, s66, v[4:5]
	v_mad_u64_u32 v[52:53], s[76:77], v52, s66, v[4:5]
	v_mad_u64_u32 v[54:55], s[76:77], v54, s66, v[4:5]
	s_waitcnt vmcnt(15)
	v_cndmask_b32_e32 v15, 0, v15, vcc
	s_waitcnt vmcnt(14)
	v_cndmask_b32_e32 v16, 0, v16, vcc
	s_waitcnt vmcnt(13)
	v_cndmask_b32_e32 v33, 0, v56, vcc
	s_waitcnt vmcnt(12)
	v_cndmask_b32_e32 v29, 0, v57, vcc
	s_waitcnt vmcnt(11)
	v_cndmask_b32_e32 v27, 0, v58, vcc
	s_waitcnt vmcnt(10)
	v_cndmask_b32_e32 v25, 0, v59, vcc
	s_waitcnt vmcnt(9)
	v_cndmask_b32_e32 v35, 0, v60, vcc
	s_waitcnt vmcnt(8)
	v_cndmask_b32_e32 v31, 0, v61, vcc
	s_waitcnt vmcnt(7)
	v_cndmask_b32_e32 v37, 0, v62, vcc
	s_waitcnt vmcnt(6)
	v_cndmask_b32_e32 v43, 0, v63, vcc
	s_waitcnt vmcnt(5)
	v_cndmask_b32_e32 v49, 0, v64, vcc
	s_waitcnt vmcnt(4)
	v_cndmask_b32_e32 v45, 0, v65, vcc
	s_waitcnt vmcnt(3)
	v_cndmask_b32_e32 v41, 0, v66, vcc
	s_waitcnt vmcnt(2)
	v_cndmask_b32_e32 v39, 0, v67, vcc
	s_waitcnt vmcnt(1)
	v_cndmask_b32_e32 v47, 0, v68, vcc
	s_waitcnt vmcnt(0)
	v_cndmask_b32_e32 v51, 0, v69, vcc
	ds_write_b32 v24, v25
	ds_write_b32 v26, v15
	ds_write_b32 v28, v16
	ds_write_b32 v30, v27
	ds_write_b32 v32, v31
	ds_write_b32 v34, v29
	ds_write_b32 v36, v35
	ds_write_b32 v38, v33
	ds_write_b32 v40, v39
	ds_write_b32 v42, v37
	ds_write_b32 v44, v43
	ds_write_b32 v46, v41
	ds_write_b32 v48, v47
	ds_write_b32 v50, v45
	ds_write_b32 v52, v51
	ds_write_b32 v54, v49
	s_cbranch_scc1 .LBB0_29
; #define LAS __attribute__((address_space(3)))
; __device__ __forceinline__ unsigned cvtpk(float lo, float hi) { f32x2_t v = {lo, hi}; bf16x2_t b = __builtin_convertvector(v, bf16x2_t); return __builtin_bit_cast(unsigned, b); }
; __device__ __forceinline__ void tr_item(const float* W, int K, int N, int nblk, bf16_t* WT, LAS float* scr, int item, int lane, bool qperm) {
;     ...
;     asm volatile("s_waitcnt lgkmcnt(0)" ::: "memory");
;     const int c = lane & 7;
; #pragma unroll
;     for (int j = 0; j < 4; ++j) { const int n = (lane >> 3) + 8 * j; const LAS float* s = scr + (8 * c) * 33 + n;
;         u32x4 o; o.x = cvtpk(s[0 * 33], s[1 * 33]); o.y = cvtpk(s[2 * 33], s[3 * 33]); o.z = cvtpk(s[4 * 33], s[5 * 33]); o.w = cvtpk(s[6 * 33], s[7 * 33]);
;         *(u32x4*)(WT + (size_t)(n0 + n) * K + k0 + 8 * c) = o; }
;     asm volatile("s_waitcnt lgkmcnt(0)" ::: "memory");
	s_waitcnt lgkmcnt(0)
	ds_read2_b32 v[24:25], v19 offset0:33 offset1:41
	ds_read2_b32 v[26:27], v19 offset1:8
	ds_read2_b32 v[28:29], v19 offset0:66 offset1:74
	ds_read2_b32 v[30:31], v19 offset0:99 offset1:107
	ds_read2_b32 v[32:33], v19 offset0:132 offset1:140
	ds_read2_b32 v[34:35], v19 offset0:165 offset1:173
	ds_read2_b32 v[36:37], v19 offset0:198 offset1:206
	ds_read2_b32 v[38:39], v19 offset0:231 offset1:239
	v_mul_hi_i32_i24_e32 v13, 0x120000, v10
	v_mul_i32_i24_e32 v12, 0x120000, v10
	v_lshl_add_u64 v[12:13], s[24:25], 0, v[12:13]
	v_lshlrev_b32_e32 v8, 1, v14
	v_lshl_add_u64 v[12:13], v[12:13], 0, v[8:9]
	v_lshlrev_b32_e32 v8, 1, v6
	v_lshl_add_u64 v[40:41], v[12:13], 0, v[8:9]
	v_or_b32_e32 v3, v11, v18
	s_waitcnt lgkmcnt(6)
	v_cvt_pk_bf16_f32 v12, v26, v24
	s_waitcnt lgkmcnt(4)
	v_cvt_pk_bf16_f32 v13, v28, v30
	s_waitcnt lgkmcnt(2)
	v_cvt_pk_bf16_f32 v14, v32, v34
	s_waitcnt lgkmcnt(0)
	v_cvt_pk_bf16_f32 v15, v36, v38
	v_mad_i64_i32 v[42:43], s[0:1], v3, s68, v[40:41]
	global_store_dwordx4 v[42:43], v[12:15], off sc1
	v_or_b32_e32 v3, v11, v20
	v_readlane_b32 s84, v254, 7
	v_cvt_pk_bf16_f32 v12, v27, v25
	v_cvt_pk_bf16_f32 v13, v29, v31
	v_cvt_pk_bf16_f32 v14, v33, v35
	v_cvt_pk_bf16_f32 v15, v37, v39
	ds_read2_b32 v[26:27], v19 offset0:49 offset1:57
	ds_read2_b32 v[28:29], v19 offset0:16 offset1:24
	ds_read2_b32 v[30:31], v19 offset0:82 offset1:90
	ds_read2_b32 v[32:33], v19 offset0:115 offset1:123
	ds_read2_b32 v[34:35], v19 offset0:148 offset1:156
	ds_read2_b32 v[36:37], v19 offset0:181 offset1:189
	ds_read2_b32 v[38:39], v19 offset0:214 offset1:222
	ds_read2_b32 v[42:43], v19 offset0:247 offset1:255
	v_mad_i64_i32 v[24:25], s[0:1], v3, s68, v[40:41]
	v_or_b32_e32 v3, v11, v21
	global_store_dwordx4 v[24:25], v[12:15], off sc1
	v_mad_i64_i32 v[24:25], s[0:1], v3, s68, v[40:41]
	s_waitcnt lgkmcnt(6)
	v_cvt_pk_bf16_f32 v12, v28, v26
	s_waitcnt lgkmcnt(4)
	v_cvt_pk_bf16_f32 v13, v30, v32
	s_waitcnt lgkmcnt(2)
	v_cvt_pk_bf16_f32 v14, v34, v36
	s_waitcnt lgkmcnt(0)
	v_cvt_pk_bf16_f32 v15, v38, v42
	v_or_b32_e32 v3, v11, v22
	global_store_dwordx4 v[24:25], v[12:15], off sc1
	v_mad_i64_i32 v[10:11], s[0:1], v3, s68, v[40:41]
	s_nop 0
	v_cvt_pk_bf16_f32 v12, v29, v27
	v_cvt_pk_bf16_f32 v13, v31, v33
	v_cvt_pk_bf16_f32 v14, v35, v37
	v_cvt_pk_bf16_f32 v15, v39, v43
	global_store_dwordx4 v[10:11], v[12:15], off sc1
	s_waitcnt lgkmcnt(0)
	v_readlane_b32 s75, v254, 6
	v_readlane_b32 s85, v254, 8

; __device__ __forceinline__ int qperm_src(int n) { const int hh = n / 96, d = n - hh * 96; if (d < 64) return n; const int j = d - 64; return hh * 96 + 64 + ((j & 1) ? 16 + (j >> 1) : (j >> 1)); }
; __device__ __forceinline__ void tr_item(const float* W, int K, int N, int nblk, bf16_t* WT, LAS float* scr, int item, int lane, bool qperm) {
;     ...
;     const int nn = n0 + (lane & 31); const bool ok = nn < N; const int src = qperm ? qperm_src(ok ? nn : 0) : (ok ? nn : 0);
; #pragma unroll 8
;     for (int i = 0; i < 32; ++i) { const int kk = 2 * i + (lane >> 5); const float v = W[(size_t)(k0 + kk) * N + src]; scr[kk * 33 + (lane & 31)] = ok ? v : 0.f; }
.LBB0_34:
	s_lshl_b32 s59, s39, 1
	s_lshl_b32 s60, s38, 1
	v_or_b32_e32 v15, s59, v3
	v_or_b32_e32 v16, s60, v8
	s_add_i32 s75, s59, 4
	s_add_i32 s78, s60, 4
	s_add_i32 s79, s59, 8
	s_add_i32 s80, s60, 8
	s_add_i32 s81, s59, 12
	s_add_i32 s82, s60, 12
	s_add_i32 s83, s59, 16
	s_add_i32 s84, s60, 16
	s_add_i32 s85, s59, 20
	s_add_i32 s86, s60, 20
	s_add_i32 s87, s59, 24
	s_add_i32 s88, s60, 24
	s_add_i32 s89, s59, 28
	s_add_i32 s90, s60, 28
	v_mad_u64_u32 v[24:25], s[76:77], v16, s69, v[12:13]
	v_mad_u64_u32 v[26:27], s[76:77], v15, s69, v[12:13]
	v_or_b32_e32 v15, s75, v3
	v_or_b32_e32 v16, s78, v8
	v_or_b32_e32 v34, s79, v3
	v_or_b32_e32 v32, s80, v8
	v_or_b32_e32 v38, s81, v3
	v_or_b32_e32 v36, s82, v8
	v_or_b32_e32 v42, s83, v3
	v_or_b32_e32 v40, s84, v8
	v_or_b32_e32 v46, s85, v3
	v_or_b32_e32 v44, s86, v8
	v_or_b32_e32 v50, s87, v3
	v_or_b32_e32 v48, s88, v8
	v_or_b32_e32 v54, s89, v3
	v_or_b32_e32 v52, s90, v8
	v_mad_u64_u32 v[28:29], s[76:77], v16, s69, v[12:13]
	v_mad_u64_u32 v[30:31], s[76:77], v15, s69, v[12:13]
	v_mad_u64_u32 v[32:33], s[76:77], v32, s69, v[12:13]
	v_mad_u64_u32 v[34:35], s[76:77], v34, s69, v[12:13]
	v_mad_u64_u32 v[36:37], s[76:77], v36, s69, v[12:13]
	v_mad_u64_u32 v[38:39], s[76:77], v38, s69, v[12:13]
	v_mad_u64_u32 v[40:41], s[76:77], v40, s69, v[12:13]
	v_mad_u64_u32 v[42:43], s[76:77], v42, s69, v[12:13]
	v_mad_u64_u32 v[44:45], s[76:77], v44, s69, v[12:13]
	v_mad_u64_u32 v[46:47], s[76:77], v46, s69, v[12:13]
	v_mad_u64_u32 v[48:49], s[76:77], v48, s69, v[12:13]
	v_mad_u64_u32 v[50:51], s[76:77], v50, s69, v[12:13]
	v_mad_u64_u32 v[52:53], s[76:77], v52, s69, v[12:13]
	v_mad_u64_u32 v[54:55], s[76:77], v54, s69, v[12:13]
	global_load_dword v15, v[26:27], off
	global_load_dword v16, v[28:29], off
	global_load_dword v56, v[38:39], off
	global_load_dword v57, v[34:35], off
	global_load_dword v58, v[30:31], off
	global_load_dword v59, v[24:25], off
	global_load_dword v60, v[36:37], off
	global_load_dword v61, v[32:33], off
	global_load_dword v62, v[42:43], off
	global_load_dword v63, v[44:45], off
	global_load_dword v64, v[54:55], off
	global_load_dword v65, v[50:51], off
	global_load_dword v66, v[46:47], off
	global_load_dword v67, v[40:41], off
	global_load_dword v68, v[48:49], off
	global_load_dword v69, v[52:53], off
	v_or_b32_e32 v26, s59, v1
	v_or_b32_e32 v24, s60, v2
	v_mad_u64_u32 v[24:25], s[60:61], v24, s66, v[4:5]
	v_mad_u64_u32 v[26:27], s[60:61], v26, s66, v[4:5]
	s_add_i32 s38, s38, 16
	s_add_i32 s39, s39, 16
	s_add_i32 s58, s58, -16
	v_or_b32_e32 v25, s75, v1
	v_or_b32_e32 v27, s78, v2
	v_or_b32_e32 v34, s79, v1
	v_or_b32_e32 v32, s80, v2
	v_or_b32_e32 v38, s81, v1
	v_or_b32_e32 v36, s82, v2
	v_or_b32_e32 v42, s83, v1
	v_or_b32_e32 v40, s84, v2
	v_or_b32_e32 v46, s85, v1
	v_or_b32_e32 v44, s86, v2
	v_or_b32_e32 v50, s87, v1
	v_or_b32_e32 v48, s88, v2
	v_or_b32_e32 v54, s89, v1
	v_or_b32_e32 v52, s90, v2
	s_cmp_lg_u32 s58, 0
	v_mad_u64_u32 v[28:29], s[60:61], v27, s66, v[4:5]
	v_mad_u64_u32 v[30:31], s[60:61], v25, s66, v[4:5]
	v_mad_u64_u32 v[32:33], s[60:61], v32, s66, v[4:5]
	v_mad_u64_u32 v[34:35], s[60:61], v34, s66, v[4:5]
	v_mad_u64_u32 v[36:37], s[60:61], v36, s66, v[4:5]
	v_mad_u64_u32 v[38:39], s[60:61], v38, s66, v[4:5]
	v_mad_u64_u32 v[40:41], s[60:61], v40, s66, v[4:5]
	v_mad_u64_u32 v[42:43], s[60:61], v42, s66, v[4:5]
	v_mad_u64_u32 v[44:45], s[60:61], v44, s66, v[4:5]
	v_mad_u64_u32 v[46:47], s[60:61], v46, s66, v[4:5]
	v_mad_u64_u32 v[48:49], s[60:61], v48, s66, v[4:5]
	v_mad_u64_u32 v[50:51], s[60:61], v50, s66, v[4:5]
	v_mad_u64_u32 v[52:53], s[60:61], v52, s66, v[4:5]
	v_mad_u64_u32 v[54:55], s[60:61], v54, s66, v[4:5]
	s_waitcnt vmcnt(15)
	v_cndmask_b32_e32 v15, 0, v15, vcc
	s_waitcnt vmcnt(14)
	v_cndmask_b32_e32 v16, 0, v16, vcc
	s_waitcnt vmcnt(13)
	v_cndmask_b32_e32 v33, 0, v56, vcc
	s_waitcnt vmcnt(12)
	v_cndmask_b32_e32 v29, 0, v57, vcc
	s_waitcnt vmcnt(11)
	v_cndmask_b32_e32 v27, 0, v58, vcc
	s_waitcnt vmcnt(10)
	v_cndmask_b32_e32 v25, 0, v59, vcc
	s_waitcnt vmcnt(9)
	v_cndmask_b32_e32 v35, 0, v60, vcc
	s_waitcnt vmcnt(8)
	v_cndmask_b32_e32 v31, 0, v61, vcc
	s_waitcnt vmcnt(7)
	v_cndmask_b32_e32 v37, 0, v62, vcc
	s_waitcnt vmcnt(6)
	v_cndmask_b32_e32 v43, 0, v63, vcc
	s_waitcnt vmcnt(5)
	v_cndmask_b32_e32 v49, 0, v64, vcc
	s_waitcnt vmcnt(4)
	v_cndmask_b32_e32 v45, 0, v65, vcc
	s_waitcnt vmcnt(3)
	v_cndmask_b32_e32 v41, 0, v66, vcc
	s_waitcnt vmcnt(2)
	v_cndmask_b32_e32 v39, 0, v67, vcc
	s_waitcnt vmcnt(1)
	v_cndmask_b32_e32 v47, 0, v68, vcc
	s_waitcnt vmcnt(0)
	v_cndmask_b32_e32 v51, 0, v69, vcc
	ds_write_b32 v24, v25
	ds_write_b32 v26, v15
	ds_write_b32 v28, v16
	ds_write_b32 v30, v27
	ds_write_b32 v32, v31
	ds_write_b32 v34, v29
	ds_write_b32 v36, v35
	ds_write_b32 v38, v33
	ds_write_b32 v40, v39
	ds_write_b32 v42, v37
	ds_write_b32 v44, v43
	ds_write_b32 v46, v41
	ds_write_b32 v48, v47
	ds_write_b32 v50, v45
	ds_write_b32 v52, v51
	ds_write_b32 v54, v49
	s_cbranch_scc1 .LBB0_34
; #define LAS __attribute__((address_space(3)))
; __device__ __forceinline__ unsigned cvtpk(float lo, float hi) { f32x2_t v = {lo, hi}; bf16x2_t b = __builtin_convertvector(v, bf16x2_t); return __builtin_bit_cast(unsigned, b); }
; __device__ __forceinline__ void tr_item(const float* W, int K, int N, int nblk, bf16_t* WT, LAS float* scr, int item, int lane, bool qperm) {
;     ...
;     asm volatile("s_waitcnt lgkmcnt(0)" ::: "memory");
;     const int c = lane & 7;
; #pragma unroll
;     for (int j = 0; j < 4; ++j) { const int n = (lane >> 3) + 8 * j; const LAS float* s = scr + (8 * c) * 33 + n;
;         u32x4 o; o.x = cvtpk(s[0 * 33], s[1 * 33]); o.y = cvtpk(s[2 * 33], s[3 * 33]); o.z = cvtpk(s[4 * 33], s[5 * 33]); o.w = cvtpk(s[6 * 33], s[7 * 33]);
;         *(u32x4*)(WT + (size_t)(n0 + n) * K + k0 + 8 * c) = o; }
;     asm volatile("s_waitcnt lgkmcnt(0)" ::: "memory");
	s_waitcnt lgkmcnt(0)
	ds_read2_b32 v[24:25], v19 offset0:33 offset1:41
	ds_read2_b32 v[26:27], v19 offset1:8
	ds_read2_b32 v[28:29], v19 offset0:66 offset1:74
	ds_read2_b32 v[30:31], v19 offset0:99 offset1:107
	ds_read2_b32 v[32:33], v19 offset0:132 offset1:140
	ds_read2_b32 v[34:35], v19 offset0:165 offset1:173
	ds_read2_b32 v[36:37], v19 offset0:198 offset1:206
	ds_read2_b32 v[38:39], v19 offset0:231 offset1:239
	v_mul_hi_i32_i24_e32 v13, 0x380000, v10
	v_mul_i32_i24_e32 v12, 0x380000, v10
	v_lshl_add_u64 v[12:13], s[26:27], 0, v[12:13]
	v_lshlrev_b32_e32 v8, 1, v14
	v_or_b32_e32 v42, v11, v18
	v_lshl_add_u64 v[12:13], v[12:13], 0, v[8:9]
	v_lshlrev_b32_e32 v8, 1, v6
	v_ashrrev_i32_e32 v43, 31, v42
	v_lshl_add_u64 v[40:41], v[12:13], 0, v[8:9]
	v_lshlrev_b64 v[42:43], 11, v[42:43]
	s_waitcnt lgkmcnt(6)
	v_cvt_pk_bf16_f32 v12, v26, v24
	s_waitcnt lgkmcnt(4)
	v_cvt_pk_bf16_f32 v13, v28, v30
	s_waitcnt lgkmcnt(2)
	v_cvt_pk_bf16_f32 v14, v32, v34
	s_waitcnt lgkmcnt(0)
	v_cvt_pk_bf16_f32 v15, v36, v38
	v_lshl_add_u64 v[42:43], v[40:41], 0, v[42:43]
	v_or_b32_e32 v24, v11, v20
	global_store_dwordx4 v[42:43], v[12:15], off sc1
	v_or_b32_e32 v10, v11, v22
	v_readlane_b32 s84, v254, 7
	v_cvt_pk_bf16_f32 v12, v27, v25
	v_ashrrev_i32_e32 v25, 31, v24
	v_cvt_pk_bf16_f32 v13, v29, v31
	v_cvt_pk_bf16_f32 v14, v33, v35
	v_cvt_pk_bf16_f32 v15, v37, v39
	v_lshlrev_b64 v[24:25], 11, v[24:25]
	ds_read2_b32 v[26:27], v19 offset0:49 offset1:57
	ds_read2_b32 v[28:29], v19 offset0:16 offset1:24
	ds_read2_b32 v[30:31], v19 offset0:82 offset1:90
	ds_read2_b32 v[32:33], v19 offset0:115 offset1:123
	ds_read2_b32 v[34:35], v19 offset0:148 offset1:156
	ds_read2_b32 v[36:37], v19 offset0:181 offset1:189
	ds_read2_b32 v[38:39], v19 offset0:214 offset1:222
	ds_read2_b32 v[42:43], v19 offset0:247 offset1:255
	v_lshl_add_u64 v[24:25], v[40:41], 0, v[24:25]
	global_store_dwordx4 v[24:25], v[12:15], off sc1
	v_or_b32_e32 v24, v11, v21
	v_ashrrev_i32_e32 v25, 31, v24
	v_lshlrev_b64 v[24:25], 11, v[24:25]
	v_ashrrev_i32_e32 v11, 31, v10
	s_waitcnt lgkmcnt(6)
	v_cvt_pk_bf16_f32 v12, v28, v26
	s_waitcnt lgkmcnt(4)
	v_cvt_pk_bf16_f32 v13, v30, v32
	s_waitcnt lgkmcnt(2)
	v_cvt_pk_bf16_f32 v14, v34, v36
	s_waitcnt lgkmcnt(0)
	v_cvt_pk_bf16_f32 v15, v38, v42
	v_lshl_add_u64 v[24:25], v[40:41], 0, v[24:25]
	v_lshlrev_b64 v[10:11], 11, v[10:11]
	global_store_dwordx4 v[24:25], v[12:15], off sc1
	v_lshl_add_u64 v[10:11], v[40:41], 0, v[10:11]
	v_readlane_b32 s75, v254, 6
	v_cvt_pk_bf16_f32 v12, v29, v27
	v_cvt_pk_bf16_f32 v13, v31, v33
	v_cvt_pk_bf16_f32 v14, v35, v37
	v_cvt_pk_bf16_f32 v15, v39, v43
	global_store_dwordx4 v[10:11], v[12:15], off sc1
	s_waitcnt lgkmcnt(0)
	v_readlane_b32 s85, v254, 8

; __device__ __forceinline__ int qperm_src(int n) { const int hh = n / 96, d = n - hh * 96; if (d < 64) return n; const int j = d - 64; return hh * 96 + 64 + ((j & 1) ? 16 + (j >> 1) : (j >> 1)); }
; __device__ __forceinline__ void tr_item(const float* W, int K, int N, int nblk, bf16_t* WT, LAS float* scr, int item, int lane, bool qperm) {
;     ...
;     const int nn = n0 + (lane & 31); const bool ok = nn < N; const int src = qperm ? qperm_src(ok ? nn : 0) : (ok ? nn : 0);
; #pragma unroll 8
;     for (int i = 0; i < 32; ++i) { const int kk = 2 * i + (lane >> 5); const float v = W[(size_t)(k0 + kk) * N + src]; scr[kk * 33 + (lane & 31)] = ok ? v : 0.f; }
.LBB0_39:
	s_lshl_b32 s39, s37, 1
	s_lshl_b32 s58, s36, 1
	v_mov_b32_e32 v25, v9
	v_or_b32_e32 v24, s39, v3
	v_or_b32_e32 v8, s58, v14
	s_add_i32 s61, s58, 4
	s_add_i32 s60, s39, 4
	s_add_i32 s75, s39, 8
	s_add_i32 s76, s58, 8
	v_lshlrev_b64 v[24:25], 12, v[24:25]
	v_lshlrev_b64 v[40:41], 12, v[8:9]
	v_or_b32_e32 v8, s61, v14
	v_mov_b32_e32 v27, v9
	v_mov_b32_e32 v29, v9
	s_add_i32 s77, s39, 12
	s_add_i32 s78, s58, 12
	s_add_i32 s79, s39, 16
	v_or_b32_e32 v26, s60, v3
	v_or_b32_e32 v28, s75, v3
	v_lshl_add_u64 v[24:25], v[10:11], 0, v[24:25]
	v_lshlrev_b64 v[42:43], 12, v[8:9]
	v_or_b32_e32 v8, s76, v14
	v_mov_b32_e32 v31, v9
	v_mov_b32_e32 v33, v9
	s_add_i32 s80, s58, 16
	s_add_i32 s81, s39, 20
	s_add_i32 s83, s39, 24
	s_add_i32 s85, s39, 28
	v_or_b32_e32 v30, s77, v3
	v_or_b32_e32 v32, s79, v3
	v_lshlrev_b64 v[26:27], 12, v[26:27]
	v_lshlrev_b64 v[28:29], 12, v[28:29]
	global_load_dword v56, v[24:25], off
	v_lshl_add_u64 v[24:25], v[10:11], 0, v[42:43]
	v_lshlrev_b64 v[42:43], 12, v[8:9]
	v_or_b32_e32 v8, s78, v14
	v_mov_b32_e32 v35, v9
	v_mov_b32_e32 v37, v9
	v_mov_b32_e32 v39, v9
	s_add_i32 s82, s58, 20
	v_or_b32_e32 v34, s81, v3
	v_or_b32_e32 v36, s83, v3
	v_or_b32_e32 v38, s85, v3
	v_lshlrev_b64 v[30:31], 12, v[30:31]
	v_lshlrev_b64 v[32:33], 12, v[32:33]
	v_lshl_add_u64 v[26:27], v[10:11], 0, v[26:27]
	v_lshl_add_u64 v[28:29], v[10:11], 0, v[28:29]
	v_lshlrev_b64 v[44:45], 12, v[8:9]
	v_or_b32_e32 v8, s80, v14
	s_add_i32 s84, s58, 24
	v_lshlrev_b64 v[34:35], 12, v[34:35]
	v_lshlrev_b64 v[36:37], 12, v[36:37]
	v_lshlrev_b64 v[38:39], 12, v[38:39]
	v_lshl_add_u64 v[30:31], v[10:11], 0, v[30:31]
	v_lshl_add_u64 v[32:33], v[10:11], 0, v[32:33]
	global_load_dword v57, v[26:27], off
	global_load_dword v58, v[28:29], off
	global_load_dword v59, v[30:31], off
	v_lshl_add_u64 v[26:27], v[10:11], 0, v[44:45]
	v_lshlrev_b64 v[28:29], 12, v[8:9]
	v_or_b32_e32 v8, s82, v14
	s_add_i32 s86, s58, 28
	v_lshl_add_u64 v[40:41], v[10:11], 0, v[40:41]
	v_lshl_add_u64 v[34:35], v[10:11], 0, v[34:35]
	v_lshl_add_u64 v[36:37], v[10:11], 0, v[36:37]
	v_lshl_add_u64 v[38:39], v[10:11], 0, v[38:39]
	v_lshl_add_u64 v[42:43], v[10:11], 0, v[42:43]
	global_load_dword v60, v[32:33], off
	global_load_dword v61, v[34:35], off
	global_load_dword v62, v[36:37], off
	global_load_dword v63, v[38:39], off
	global_load_dword v64, v[26:27], off
	global_load_dword v65, v[42:43], off
	global_load_dword v66, v[24:25], off
	global_load_dword v67, v[40:41], off
	v_lshlrev_b64 v[26:27], 12, v[8:9]
	v_or_b32_e32 v8, s84, v14
	v_lshl_add_u64 v[24:25], v[10:11], 0, v[28:29]
	v_lshlrev_b64 v[28:29], 12, v[8:9]
	v_or_b32_e32 v8, s86, v14
	v_lshlrev_b64 v[30:31], 12, v[8:9]
	v_lshl_add_u64 v[30:31], v[10:11], 0, v[30:31]
	v_lshl_add_u64 v[26:27], v[10:11], 0, v[26:27]
	v_lshl_add_u64 v[28:29], v[10:11], 0, v[28:29]
	global_load_dword v8, v[30:31], off
	global_load_dword v68, v[28:29], off
	global_load_dword v69, v[26:27], off
	global_load_dword v70, v[24:25], off
	v_or_b32_e32 v26, s39, v1
	v_or_b32_e32 v24, s58, v2
	v_mad_u64_u32 v[24:25], s[58:59], v24, s66, v[4:5]
	v_mad_u64_u32 v[26:27], s[58:59], v26, s66, v[4:5]
	v_or_b32_e32 v40, s80, v2
	v_or_b32_e32 v25, s60, v1
	v_or_b32_e32 v27, s61, v2
	v_or_b32_e32 v42, s79, v1
	v_or_b32_e32 v46, s81, v1
	v_or_b32_e32 v44, s82, v2
	v_mad_u64_u32 v[40:41], s[58:59], v40, s66, v[4:5]
	s_add_i32 s36, s36, 16
	s_add_i32 s37, s37, 16
	s_add_i32 s38, s38, -16
	v_or_b32_e32 v34, s75, v1
	v_or_b32_e32 v32, s76, v2
	v_or_b32_e32 v38, s77, v1
	v_or_b32_e32 v36, s78, v2
	v_mad_u64_u32 v[28:29], s[58:59], v27, s66, v[4:5]
	v_mad_u64_u32 v[30:31], s[58:59], v25, s66, v[4:5]
	v_mad_u64_u32 v[42:43], s[58:59], v42, s66, v[4:5]
	v_mad_u64_u32 v[44:45], s[58:59], v44, s66, v[4:5]
	v_mad_u64_u32 v[46:47], s[58:59], v46, s66, v[4:5]
	v_or_b32_e32 v50, s83, v1
	v_or_b32_e32 v48, s84, v2
	v_or_b32_e32 v54, s85, v1
	v_or_b32_e32 v52, s86, v2
	s_cmp_lg_u32 s38, 0
	v_mad_u64_u32 v[32:33], s[58:59], v32, s66, v[4:5]
	v_mad_u64_u32 v[34:35], s[58:59], v34, s66, v[4:5]
	v_mad_u64_u32 v[36:37], s[58:59], v36, s66, v[4:5]
	v_mad_u64_u32 v[38:39], s[58:59], v38, s66, v[4:5]
	s_waitcnt vmcnt(15)
	v_cndmask_b32_e32 v25, 0, v56, vcc
	v_mad_u64_u32 v[48:49], s[58:59], v48, s66, v[4:5]
	v_mad_u64_u32 v[50:51], s[58:59], v50, s66, v[4:5]
	v_mad_u64_u32 v[52:53], s[58:59], v52, s66, v[4:5]
	v_mad_u64_u32 v[54:55], s[58:59], v54, s66, v[4:5]
	s_waitcnt vmcnt(14)
	v_cndmask_b32_e32 v27, 0, v57, vcc
	s_waitcnt vmcnt(13)
	v_cndmask_b32_e32 v29, 0, v58, vcc
	s_waitcnt vmcnt(12)
	v_cndmask_b32_e32 v31, 0, v59, vcc
	s_waitcnt vmcnt(11)
	v_cndmask_b32_e32 v33, 0, v60, vcc
	s_waitcnt vmcnt(7)
	v_cndmask_b32_e32 v47, 0, v64, vcc
	s_waitcnt vmcnt(6)
	v_cndmask_b32_e32 v45, 0, v65, vcc
	s_waitcnt vmcnt(5)
	v_cndmask_b32_e32 v43, 0, v66, vcc
	s_waitcnt vmcnt(4)
	v_cndmask_b32_e32 v41, 0, v67, vcc
	ds_write_b32 v24, v41
	ds_write_b32 v26, v25
	ds_write_b32 v28, v43
	ds_write_b32 v30, v27
	ds_write_b32 v32, v45
	ds_write_b32 v34, v29
	ds_write_b32 v36, v47
	ds_write_b32 v38, v31
	v_cndmask_b32_e32 v35, 0, v61, vcc
	v_cndmask_b32_e32 v37, 0, v62, vcc
	v_cndmask_b32_e32 v39, 0, v63, vcc
	s_waitcnt vmcnt(3)
	v_cndmask_b32_e32 v8, 0, v8, vcc
	s_waitcnt vmcnt(2)
	v_cndmask_b32_e32 v26, 0, v68, vcc
	s_waitcnt vmcnt(1)
	v_cndmask_b32_e32 v25, 0, v69, vcc
	s_waitcnt vmcnt(0)
	v_cndmask_b32_e32 v24, 0, v70, vcc
	ds_write_b32 v40, v24
	ds_write_b32 v42, v33
	ds_write_b32 v44, v25
	ds_write_b32 v46, v35
	ds_write_b32 v48, v26
	ds_write_b32 v50, v37
	ds_write_b32 v52, v8
	ds_write_b32 v54, v39
	s_cbranch_scc1 .LBB0_39
; #define LAS __attribute__((address_space(3)))
; __device__ __forceinline__ unsigned cvtpk(float lo, float hi) { f32x2_t v = {lo, hi}; bf16x2_t b = __builtin_convertvector(v, bf16x2_t); return __builtin_bit_cast(unsigned, b); }
; __device__ __forceinline__ void tr_item(const float* W, int K, int N, int nblk, bf16_t* WT, LAS float* scr, int item, int lane, bool qperm) {
;     ...
;     asm volatile("s_waitcnt lgkmcnt(0)" ::: "memory");
;     const int c = lane & 7;
; #pragma unroll
;     for (int j = 0; j < 4; ++j) { const int n = (lane >> 3) + 8 * j; const LAS float* s = scr + (8 * c) * 33 + n;
;         u32x4 o; o.x = cvtpk(s[0 * 33], s[1 * 33]); o.y = cvtpk(s[2 * 33], s[3 * 33]); o.z = cvtpk(s[4 * 33], s[5 * 33]); o.w = cvtpk(s[6 * 33], s[7 * 33]);
;         *(u32x4*)(WT + (size_t)(n0 + n) * K + k0 + 8 * c) = o; }
;     asm volatile("s_waitcnt lgkmcnt(0)" ::: "memory");
	s_waitcnt lgkmcnt(0)
	ds_read2_b32 v[24:25], v19 offset0:33 offset1:41
	ds_read2_b32 v[26:27], v19 offset1:8
	ds_read2_b32 v[28:29], v19 offset0:66 offset1:74
	ds_read2_b32 v[30:31], v19 offset0:99 offset1:107
	ds_read2_b32 v[32:33], v19 offset0:132 offset1:140
	ds_read2_b32 v[34:35], v19 offset0:165 offset1:173
	ds_read2_b32 v[36:37], v19 offset0:198 offset1:206
	ds_read2_b32 v[38:39], v19 offset0:231 offset1:239
	v_lshl_add_u64 v[10:11], v[12:13], 1, s[28:29]
	v_lshlrev_b32_e32 v8, 1, v16
	v_or_b32_e32 v42, v15, v18
	v_lshl_add_u64 v[10:11], v[10:11], 0, v[8:9]
	v_lshlrev_b32_e32 v8, 1, v6
	v_ashrrev_i32_e32 v43, 31, v42
	v_lshl_add_u64 v[40:41], v[10:11], 0, v[8:9]
	v_lshlrev_b64 v[42:43], 11, v[42:43]
	s_waitcnt lgkmcnt(6)
	v_cvt_pk_bf16_f32 v10, v26, v24
	s_waitcnt lgkmcnt(4)
	v_cvt_pk_bf16_f32 v11, v28, v30
	s_waitcnt lgkmcnt(2)
	v_cvt_pk_bf16_f32 v12, v32, v34
	s_waitcnt lgkmcnt(0)
	v_cvt_pk_bf16_f32 v13, v36, v38
	v_lshl_add_u64 v[42:43], v[40:41], 0, v[42:43]
	v_or_b32_e32 v24, v15, v20
	global_store_dwordx4 v[42:43], v[10:13], off sc1
	v_or_b32_e32 v14, v15, v22
	v_readlane_b32 s84, v254, 7
	v_cvt_pk_bf16_f32 v10, v27, v25
	v_ashrrev_i32_e32 v25, 31, v24
	v_cvt_pk_bf16_f32 v11, v29, v31
	v_cvt_pk_bf16_f32 v12, v33, v35
	v_cvt_pk_bf16_f32 v13, v37, v39
	v_lshlrev_b64 v[24:25], 11, v[24:25]
	ds_read2_b32 v[26:27], v19 offset0:49 offset1:57
	ds_read2_b32 v[28:29], v19 offset0:16 offset1:24
	ds_read2_b32 v[30:31], v19 offset0:82 offset1:90
	ds_read2_b32 v[32:33], v19 offset0:115 offset1:123
	ds_read2_b32 v[34:35], v19 offset0:148 offset1:156
	ds_read2_b32 v[36:37], v19 offset0:181 offset1:189
	ds_read2_b32 v[38:39], v19 offset0:214 offset1:222
	ds_read2_b32 v[42:43], v19 offset0:247 offset1:255
	v_lshl_add_u64 v[24:25], v[40:41], 0, v[24:25]
	global_store_dwordx4 v[24:25], v[10:13], off sc1
	v_or_b32_e32 v24, v15, v21
	v_ashrrev_i32_e32 v25, 31, v24
	v_lshlrev_b64 v[24:25], 11, v[24:25]
	v_ashrrev_i32_e32 v15, 31, v14
	s_waitcnt lgkmcnt(6)
	v_cvt_pk_bf16_f32 v10, v28, v26
	s_waitcnt lgkmcnt(4)
	v_cvt_pk_bf16_f32 v11, v30, v32
	s_waitcnt lgkmcnt(2)
	v_cvt_pk_bf16_f32 v12, v34, v36
	s_waitcnt lgkmcnt(0)
	v_cvt_pk_bf16_f32 v13, v38, v42
	v_lshl_add_u64 v[24:25], v[40:41], 0, v[24:25]
	v_lshlrev_b64 v[14:15], 11, v[14:15]
	global_store_dwordx4 v[24:25], v[10:13], off sc1
	v_lshl_add_u64 v[14:15], v[40:41], 0, v[14:15]
	v_readlane_b32 s75, v254, 6
	v_cvt_pk_bf16_f32 v10, v29, v27
	v_cvt_pk_bf16_f32 v11, v31, v33
	v_cvt_pk_bf16_f32 v12, v35, v37
	v_cvt_pk_bf16_f32 v13, v39, v43
	global_store_dwordx4 v[14:15], v[10:13], off sc1
	s_waitcnt lgkmcnt(0)
	v_readlane_b32 s85, v254, 8

; __device__ __forceinline__ int qperm_src(int n) { const int hh = n / 96, d = n - hh * 96; if (d < 64) return n; const int j = d - 64; return hh * 96 + 64 + ((j & 1) ? 16 + (j >> 1) : (j >> 1)); }
; __device__ __forceinline__ void tr_item(const float* W, int K, int N, int nblk, bf16_t* WT, LAS float* scr, int item, int lane, bool qperm) {
;     ...
;     const int nn = n0 + (lane & 31); const bool ok = nn < N; const int src = qperm ? qperm_src(ok ? nn : 0) : (ok ? nn : 0);
; #pragma unroll 8
;     for (int i = 0; i < 32; ++i) { const int kk = 2 * i + (lane >> 5); const float v = W[(size_t)(k0 + kk) * N + src]; scr[kk * 33 + (lane & 31)] = ok ? v : 0.f; }
.LBB0_44:
	s_lshl_b32 s37, s35, 1
	s_lshl_b32 s38, s34, 1
	v_or_b32_e32 v13, s37, v3
	v_or_b32_e32 v16, s38, v8
	s_add_i32 s60, s37, 4
	s_add_i32 s61, s38, 4
	s_add_i32 s75, s37, 8
	s_add_i32 s76, s38, 8
	s_add_i32 s77, s37, 12
	s_add_i32 s78, s38, 12
	s_add_i32 s79, s37, 16
	s_add_i32 s80, s38, 16
	s_add_i32 s81, s37, 20
	s_add_i32 s82, s38, 20
	s_add_i32 s83, s37, 24
	s_add_i32 s84, s38, 24
	s_add_i32 s85, s37, 28
	s_add_i32 s86, s38, 28
	v_mad_i64_i32 v[24:25], s[58:59], v16, s72, v[14:15]
	v_mad_i64_i32 v[26:27], s[58:59], v13, s72, v[14:15]
	v_or_b32_e32 v13, s60, v3
	v_or_b32_e32 v16, s61, v8
	v_or_b32_e32 v34, s75, v3
	v_or_b32_e32 v32, s76, v8
	v_or_b32_e32 v38, s77, v3
	v_or_b32_e32 v36, s78, v8
	v_or_b32_e32 v42, s79, v3
	v_or_b32_e32 v40, s80, v8
	v_or_b32_e32 v46, s81, v3
	v_or_b32_e32 v44, s82, v8
	v_or_b32_e32 v50, s83, v3
	v_or_b32_e32 v48, s84, v8
	v_or_b32_e32 v54, s85, v3
	v_or_b32_e32 v52, s86, v8
	v_mad_i64_i32 v[28:29], s[58:59], v16, s72, v[14:15]
	v_mad_i64_i32 v[30:31], s[58:59], v13, s72, v[14:15]
	v_mad_i64_i32 v[32:33], s[58:59], v32, s72, v[14:15]
	v_mad_i64_i32 v[34:35], s[58:59], v34, s72, v[14:15]
	v_mad_i64_i32 v[36:37], s[58:59], v36, s72, v[14:15]
	v_mad_i64_i32 v[38:39], s[58:59], v38, s72, v[14:15]
	v_mad_i64_i32 v[40:41], s[58:59], v40, s72, v[14:15]
	v_mad_i64_i32 v[42:43], s[58:59], v42, s72, v[14:15]
	v_mad_i64_i32 v[44:45], s[58:59], v44, s72, v[14:15]
	v_mad_i64_i32 v[46:47], s[58:59], v46, s72, v[14:15]
	v_mad_i64_i32 v[48:49], s[58:59], v48, s72, v[14:15]
	v_mad_i64_i32 v[50:51], s[58:59], v50, s72, v[14:15]
	v_mad_i64_i32 v[52:53], s[58:59], v52, s72, v[14:15]
	v_mad_i64_i32 v[54:55], s[58:59], v54, s72, v[14:15]
	global_load_dword v13, v[26:27], off
	global_load_dword v16, v[28:29], off
	global_load_dword v56, v[30:31], off
	global_load_dword v57, v[36:37], off
	global_load_dword v58, v[32:33], off
	global_load_dword v59, v[24:25], off
	global_load_dword v60, v[34:35], off
	global_load_dword v61, v[38:39], off
	global_load_dword v62, v[42:43], off
	global_load_dword v63, v[44:45], off
	global_load_dword v64, v[46:47], off
	global_load_dword v65, v[52:53], off
	global_load_dword v66, v[48:49], off
	global_load_dword v67, v[40:41], off
	global_load_dword v68, v[50:51], off
	global_load_dword v69, v[54:55], off
	v_or_b32_e32 v26, s37, v1
	v_or_b32_e32 v24, s38, v2
	v_mad_u64_u32 v[24:25], s[38:39], v24, s66, v[4:5]
	v_mad_u64_u32 v[26:27], s[38:39], v26, s66, v[4:5]
	s_add_i32 s34, s34, 16
	s_add_i32 s35, s35, 16
	s_add_i32 s36, s36, -16
	v_or_b32_e32 v25, s60, v1
	v_or_b32_e32 v27, s61, v2
	v_or_b32_e32 v34, s75, v1
	v_or_b32_e32 v32, s76, v2
	v_or_b32_e32 v38, s77, v1
	v_or_b32_e32 v36, s78, v2
	v_or_b32_e32 v42, s79, v1
	v_or_b32_e32 v40, s80, v2
	v_or_b32_e32 v46, s81, v1
	v_or_b32_e32 v44, s82, v2
	v_or_b32_e32 v50, s83, v1
	v_or_b32_e32 v48, s84, v2
	v_or_b32_e32 v54, s85, v1
	v_or_b32_e32 v52, s86, v2
	s_cmp_lg_u32 s36, 0
	v_mad_u64_u32 v[28:29], s[38:39], v27, s66, v[4:5]
	v_mad_u64_u32 v[30:31], s[38:39], v25, s66, v[4:5]
	v_mad_u64_u32 v[32:33], s[38:39], v32, s66, v[4:5]
	v_mad_u64_u32 v[34:35], s[38:39], v34, s66, v[4:5]
	v_mad_u64_u32 v[36:37], s[38:39], v36, s66, v[4:5]
	v_mad_u64_u32 v[38:39], s[38:39], v38, s66, v[4:5]
	v_mad_u64_u32 v[40:41], s[38:39], v40, s66, v[4:5]
	v_mad_u64_u32 v[42:43], s[38:39], v42, s66, v[4:5]
	v_mad_u64_u32 v[44:45], s[38:39], v44, s66, v[4:5]
	v_mad_u64_u32 v[46:47], s[38:39], v46, s66, v[4:5]
	v_mad_u64_u32 v[48:49], s[38:39], v48, s66, v[4:5]
	v_mad_u64_u32 v[50:51], s[38:39], v50, s66, v[4:5]
	v_mad_u64_u32 v[52:53], s[38:39], v52, s66, v[4:5]
	v_mad_u64_u32 v[54:55], s[38:39], v54, s66, v[4:5]
	s_waitcnt vmcnt(15)
	v_cndmask_b32_e32 v13, 0, v13, vcc
	s_waitcnt vmcnt(14)
	v_cndmask_b32_e32 v16, 0, v16, vcc
	s_waitcnt vmcnt(13)
	v_cndmask_b32_e32 v27, 0, v56, vcc
	s_waitcnt vmcnt(12)
	v_cndmask_b32_e32 v35, 0, v57, vcc
	s_waitcnt vmcnt(11)
	v_cndmask_b32_e32 v31, 0, v58, vcc
	s_waitcnt vmcnt(10)
	v_cndmask_b32_e32 v25, 0, v59, vcc
	s_waitcnt vmcnt(9)
	v_cndmask_b32_e32 v29, 0, v60, vcc
	s_waitcnt vmcnt(8)
	v_cndmask_b32_e32 v33, 0, v61, vcc
	s_waitcnt vmcnt(7)
	v_cndmask_b32_e32 v37, 0, v62, vcc
	s_waitcnt vmcnt(6)
	v_cndmask_b32_e32 v43, 0, v63, vcc
	s_waitcnt vmcnt(5)
	v_cndmask_b32_e32 v41, 0, v64, vcc
	s_waitcnt vmcnt(4)
	v_cndmask_b32_e32 v51, 0, v65, vcc
	s_waitcnt vmcnt(3)
	v_cndmask_b32_e32 v47, 0, v66, vcc
	s_waitcnt vmcnt(2)
	v_cndmask_b32_e32 v39, 0, v67, vcc
	s_waitcnt vmcnt(1)
	v_cndmask_b32_e32 v45, 0, v68, vcc
	s_waitcnt vmcnt(0)
	v_cndmask_b32_e32 v49, 0, v69, vcc
	ds_write_b32 v24, v25
	ds_write_b32 v26, v13
	ds_write_b32 v28, v16
	ds_write_b32 v30, v27
	ds_write_b32 v32, v31
	ds_write_b32 v34, v29
	ds_write_b32 v36, v35
	ds_write_b32 v38, v33
	ds_write_b32 v40, v39
	ds_write_b32 v42, v37
	ds_write_b32 v44, v43
	ds_write_b32 v46, v41
	ds_write_b32 v48, v47
	ds_write_b32 v50, v45
	ds_write_b32 v52, v51
	ds_write_b32 v54, v49
	s_cbranch_scc1 .LBB0_44
; #define LAS __attribute__((address_space(3)))
; __device__ __forceinline__ unsigned cvtpk(float lo, float hi) { f32x2_t v = {lo, hi}; bf16x2_t b = __builtin_convertvector(v, bf16x2_t); return __builtin_bit_cast(unsigned, b); }
; __device__ __forceinline__ void tr_item(const float* W, int K, int N, int nblk, bf16_t* WT, LAS float* scr, int item, int lane, bool qperm) {
;     ...
;     asm volatile("s_waitcnt lgkmcnt(0)" ::: "memory");
;     const int c = lane & 7;
; #pragma unroll
;     for (int j = 0; j < 4; ++j) { const int n = (lane >> 3) + 8 * j; const LAS float* s = scr + (8 * c) * 33 + n;
;         u32x4 o; o.x = cvtpk(s[0 * 33], s[1 * 33]); o.y = cvtpk(s[2 * 33], s[3 * 33]); o.z = cvtpk(s[4 * 33], s[5 * 33]); o.w = cvtpk(s[6 * 33], s[7 * 33]);
;         *(u32x4*)(WT + (size_t)(n0 + n) * K + k0 + 8 * c) = o; }
;     asm volatile("s_waitcnt lgkmcnt(0)" ::: "memory");
; __device__ __forceinline__ void prologue(const Args& a, LAS unsigned char* lds) {
;     ...
;     for (int it = gw; it < 2 * IT; it += NGW) {
	s_waitcnt lgkmcnt(0)
	ds_read2_b32 v[24:25], v19 offset0:33 offset1:41
	ds_read2_b32 v[26:27], v19 offset1:8
	ds_read2_b32 v[28:29], v19 offset0:66 offset1:74
	ds_read2_b32 v[30:31], v19 offset0:99 offset1:107
	ds_read2_b32 v[32:33], v19 offset0:132 offset1:140
	ds_read2_b32 v[34:35], v19 offset0:165 offset1:173
	ds_read2_b32 v[36:37], v19 offset0:198 offset1:206
	ds_read2_b32 v[38:39], v19 offset0:231 offset1:239
	v_mov_b64_e32 v[14:15], s[42:43]
	v_mad_i64_i32 v[14:15], s[34:35], v10, s73, v[14:15]
	v_ashrrev_i32_e32 v13, 31, v12
	v_or_b32_e32 v42, v11, v18
	v_lshl_add_u64 v[12:13], v[12:13], 1, v[14:15]
	v_lshlrev_b32_e32 v8, 1, v6
	v_ashrrev_i32_e32 v43, 31, v42
	v_lshl_add_u64 v[40:41], v[12:13], 0, v[8:9]
	v_lshlrev_b64 v[42:43], 11, v[42:43]
	s_waitcnt lgkmcnt(6)
	v_cvt_pk_bf16_f32 v12, v26, v24
	s_waitcnt lgkmcnt(4)
	v_cvt_pk_bf16_f32 v13, v28, v30
	s_waitcnt lgkmcnt(2)
	v_cvt_pk_bf16_f32 v14, v32, v34
	s_waitcnt lgkmcnt(0)
	v_cvt_pk_bf16_f32 v15, v36, v38
	v_lshl_add_u64 v[42:43], v[40:41], 0, v[42:43]
	v_or_b32_e32 v24, v11, v20
	global_store_dwordx4 v[42:43], v[12:15], off sc1
	v_or_b32_e32 v10, v11, v22
	v_readlane_b32 s84, v254, 7
	v_cvt_pk_bf16_f32 v12, v27, v25
	v_ashrrev_i32_e32 v25, 31, v24
	v_cvt_pk_bf16_f32 v13, v29, v31
	v_cvt_pk_bf16_f32 v14, v33, v35
	v_cvt_pk_bf16_f32 v15, v37, v39
	v_lshlrev_b64 v[24:25], 11, v[24:25]
	ds_read2_b32 v[26:27], v19 offset0:49 offset1:57
	ds_read2_b32 v[28:29], v19 offset0:16 offset1:24
	ds_read2_b32 v[30:31], v19 offset0:82 offset1:90
	ds_read2_b32 v[32:33], v19 offset0:115 offset1:123
	ds_read2_b32 v[34:35], v19 offset0:148 offset1:156
	ds_read2_b32 v[36:37], v19 offset0:181 offset1:189
	ds_read2_b32 v[38:39], v19 offset0:214 offset1:222
	ds_read2_b32 v[42:43], v19 offset0:247 offset1:255
	v_lshl_add_u64 v[24:25], v[40:41], 0, v[24:25]
	global_store_dwordx4 v[24:25], v[12:15], off sc1
	v_or_b32_e32 v24, v11, v21
	v_ashrrev_i32_e32 v25, 31, v24
	v_lshlrev_b64 v[24:25], 11, v[24:25]
	v_ashrrev_i32_e32 v11, 31, v10
	s_waitcnt lgkmcnt(6)
	v_cvt_pk_bf16_f32 v12, v28, v26
	s_waitcnt lgkmcnt(4)
	v_cvt_pk_bf16_f32 v13, v30, v32
	s_waitcnt lgkmcnt(2)
	v_cvt_pk_bf16_f32 v14, v34, v36
	s_waitcnt lgkmcnt(0)
	v_cvt_pk_bf16_f32 v15, v38, v42
	v_lshl_add_u64 v[24:25], v[40:41], 0, v[24:25]
	v_lshlrev_b64 v[10:11], 11, v[10:11]
	global_store_dwordx4 v[24:25], v[12:15], off sc1
	v_lshl_add_u64 v[10:11], v[40:41], 0, v[10:11]
	v_readlane_b32 s75, v254, 6
	v_cvt_pk_bf16_f32 v12, v29, v27
	v_cvt_pk_bf16_f32 v13, v31, v33
	v_cvt_pk_bf16_f32 v14, v35, v37
	v_cvt_pk_bf16_f32 v15, v39, v43
	global_store_dwordx4 v[10:11], v[12:15], off sc1
	s_waitcnt lgkmcnt(0)
	v_readlane_b32 s85, v254, 8
	s_branch .LBB0_11

; __device__ __forceinline__ void prologue(const Args& a, LAS unsigned char* lds) {
;     ...
;         const int q = ((int)kq) & 3;
;         const double c = (q == 0) ? cn : (q == 1) ? -sn : (q == 2) ? -cn : sn;
;         const double s = (q == 0) ? sn : (q == 1) ? cn : (q == 2) ? -sn : -cn;
;         cs[pos * 32 + i] = (float)c; cs[pos * 32 + 16 + i] = (float)s;
.LBB0_49:
	s_or_b64 exec, exec, s[30:31]
	v_cmp_eq_u32_e64 s[4:5], 2, v30
	v_add_u32_e32 v1, s36, v1
	v_cvt_f32_f64_e32 v26, v[26:27]
	v_cndmask_b32_e64 v31, v24, v22, s[4:5]
	v_cndmask_b32_e64 v32, -v25, -v23, s[4:5]
	v_cmp_eq_u32_e64 s[4:5], 1, v30
	s_nop 1
	v_cndmask_b32_e64 v24, v31, v24, s[4:5]
	v_cndmask_b32_e64 v25, v32, v25, s[4:5]
	v_cndmask_b32_e64 v22, v24, v22, s[0:1]
	v_lshl_or_b32 v24, v29, 5, v28
	v_cndmask_b32_e64 v23, v25, v23, s[0:1]
	v_ashrrev_i32_e32 v25, 31, v24
	v_cmp_lt_i32_e64 s[0:1], s37, v1
	v_lshl_add_u64 v[24:25], v[24:25], 2, s[6:7]
	v_cvt_f32_f64_e32 v22, v[22:23]
	s_or_b64 s[14:15], s[0:1], s[14:15]
	global_store_dword v[24:25], v26, off sc1
	global_store_dword v[24:25], v22, off offset:64 sc1
	s_andn2_b64 exec, exec, s[14:15]
	s_cbranch_execz .LBB0_57

; #define GAS __attribute__((address_space(1)))
; __global__ void __launch_bounds__(512, 2) mega_fwd(Args a) {
;     ...
;         if (blockIdx.x == 0) { unsigned* bw = (unsigned*)(a.ws + W_BAR); for (int i = threadIdx.x; i < XCD_BAR_WORDS; i += 512) bw[i] = 0u; }
;         if (blockIdx.x == 0 && threadIdx.x == 0) { P* p = (P*)(a.ws + W_P); p->xp = (const GAS float*)a.xp; p->xs = (const GAS float*)a.xs; p->norm_g = (const GAS float*)a.norm_g; p->b_qn = (const GAS float*)a.b_qn; p->b_kvn = (const GAS float*)a.b_kvn; p->fin_g = (const GAS float*)a.fin_g; p->out = (GAS float*)a.out; }
.LBB0_61:
	s_mov_b32 s7, s6
	s_or_b64 s[0:1], s[6:7], s[2:3]
	v_cmp_le_u32_e32 vcc, s1, v1
	v_cmp_le_u32_e64 s[0:1], s0, v2
	s_waitcnt lgkmcnt(0)
	s_and_saveexec_b64 s[14:15], s[0:1]
	s_cbranch_execz .LBB0_63
	v_mov_b32_e32 v4, v6
	v_lshl_add_u64 v[8:9], v[4:5], 2, s[38:39]
	global_store_dword v[8:9], v5, off sc1
.LBB0_63:
	s_or_b64 exec, exec, s[14:15]
	s_and_saveexec_b64 s[0:1], vcc
	s_cbranch_execz .LBB0_60
	v_mov_b32_e32 v4, v7
	v_lshl_add_u64 v[8:9], v[4:5], 2, s[38:39]
	global_store_dword v[8:9], v5, off sc1
	s_branch .LBB0_60
.LBB0_65:
	s_or_b64 exec, exec, s[4:5]
	s_mov_b64 s[0:1], exec
	v_readlane_b32 s2, v254, 2
	v_readlane_b32 s3, v254, 3
	s_and_b64 s[2:3], s[0:1], s[2:3]
	s_mov_b64 exec, s[2:3]
	s_cbranch_execz .LBB0_67
	v_mov_b32_e32 v2, s8
	v_mov_b32_e32 v3, s9
	v_mov_b32_e32 v4, s10
	v_mov_b32_e32 v5, s11
	v_mov_b32_e32 v1, 0x3bc0000
	global_store_dwordx4 v1, v[2:5], s[42:43] sc1
	s_nop 1
	v_mov_b32_e32 v2, s12
	v_mov_b32_e32 v3, s13
	v_mov_b32_e32 v4, s20
	v_mov_b32_e32 v5, s21
	global_store_dwordx4 v1, v[2:5], s[42:43] offset:16 sc1
	s_nop 1
	v_mov_b32_e32 v2, s48
	v_mov_b32_e32 v3, s49
	v_mov_b32_e32 v4, s54
	v_mov_b32_e32 v5, s55
	global_store_dwordx4 v1, v[2:5], s[42:43] offset:32 sc1
	s_nop 1
	v_mov_b64_e32 v[2:3], s[40:41]
	global_store_dwordx2 v1, v[2:3], s[42:43] offset:48 sc1

; __device__ __forceinline__ void final_norm_phase(const _Float16* xh, float* out, const float* g, int rows) {
;     ...
;     for (int m0 = gw * 4; m0 < rows; m0 += NGW * 4) {
;         f32x4 v[4][4];
; #pragma unroll
;         for (int r = 0; r < 4; ++r) { const f16x4* xr = (const f16x4*)(xh + (size_t)(m0 + r) * DM) + lane;
; #pragma unroll
;             for (int j = 0; j < 4; ++j) v[r][j] = __builtin_convertvector(xr[64 * j], f32x4); }
; #pragma unroll
;         for (int r = 0; r < 4; ++r) { float s = 0.f;
; #pragma unroll
;             for (int j = 0; j < 4; ++j) s += (v[r][j].x * v[r][j].x + v[r][j].y * v[r][j].y) + (v[r][j].z * v[r][j].z + v[r][j].w * v[r][j].w);
.LBB0_184:
	v_add_co_u32_e32 v26, vcc, 0xfffff000, v24
	v_add_u32_e32 v20, s30, v20
	s_nop 0
	v_addc_co_u32_e32 v27, vcc, -1, v25, vcc
	global_load_dwordx2 v[16:17], v[26:27], off offset:-3584
	global_load_dwordx2 v[28:29], v[26:27], off offset:-2048
	global_load_dwordx2 v[34:35], v[24:25], off offset:-1536
	global_load_dwordx2 v[38:39], v[24:25], off offset:-1024
	global_load_dwordx2 v[46:47], v[24:25], off offset:-512
	global_load_dwordx2 v[92:93], v[24:25], off
	s_waitcnt vmcnt(5)
	v_cvt_f32_f16_e32 v82, v16
	v_cvt_f32_f16_sdwa v83, v16 dst_sel:DWORD dst_unused:UNUSED_PAD src0_sel:WORD_1
	v_cvt_f32_f16_e32 v84, v17
	v_cvt_f32_f16_sdwa v85, v17 dst_sel:DWORD dst_unused:UNUSED_PAD src0_sel:WORD_1
	global_load_dwordx2 v[16:17], v[26:27], off offset:-3072
	s_waitcnt vmcnt(5)
	v_cvt_f32_f16_sdwa v81, v28 dst_sel:DWORD dst_unused:UNUSED_PAD src0_sel:WORD_1
	v_cvt_f32_f16_e32 v80, v28
	s_waitcnt vmcnt(3)
	v_cvt_f32_f16_sdwa v37, v39 dst_sel:DWORD dst_unused:UNUSED_PAD src0_sel:WORD_1
	v_cvt_f32_f16_e32 v36, v39
	s_waitcnt vmcnt(2)
	v_cvt_f32_f16_sdwa v39, v46 dst_sel:DWORD dst_unused:UNUSED_PAD src0_sel:WORD_1
	v_cvt_f32_f16_sdwa v41, v47 dst_sel:DWORD dst_unused:UNUSED_PAD src0_sel:WORD_1
	v_cvt_f32_f16_e32 v40, v47
	v_pk_mul_f32 v[94:95], v[82:83], v[82:83]
	v_mul_f32_e32 v21, v80, v80
	s_waitcnt vmcnt(1)
	v_cvt_f32_f16_sdwa v47, v93 dst_sel:DWORD dst_unused:UNUSED_PAD src0_sel:WORD_1
	v_cvt_f32_f16_sdwa v49, v92 dst_sel:DWORD dst_unused:UNUSED_PAD src0_sel:WORD_1
	v_cvt_f32_f16_e32 v48, v92
	s_waitcnt vmcnt(0)
	v_cvt_f32_f16_e32 v74, v16
	v_cvt_f32_f16_sdwa v75, v16 dst_sel:DWORD dst_unused:UNUSED_PAD src0_sel:WORD_1
	v_cvt_f32_f16_e32 v78, v17
	v_cvt_f32_f16_sdwa v79, v17 dst_sel:DWORD dst_unused:UNUSED_PAD src0_sel:WORD_1
	global_load_dwordx2 v[16:17], v[26:27], off offset:-2560
	s_waitcnt vmcnt(0)
	v_cvt_f32_f16_e32 v18, v16
	v_cvt_f32_f16_sdwa v19, v16 dst_sel:DWORD dst_unused:UNUSED_PAD src0_sel:WORD_1
	v_cvt_f32_f16_e32 v76, v17
	v_cvt_f32_f16_sdwa v77, v17 dst_sel:DWORD dst_unused:UNUSED_PAD src0_sel:WORD_1
	v_cvt_f32_f16_sdwa v17, v29 dst_sel:DWORD dst_unused:UNUSED_PAD src0_sel:WORD_1
	v_cvt_f32_f16_e32 v16, v29
	global_load_dwordx2 v[28:29], v[26:27], off offset:-1536
	s_waitcnt vmcnt(0)
	v_cvt_f32_f16_e32 v60, v28
	v_cvt_f32_f16_sdwa v61, v28 dst_sel:DWORD dst_unused:UNUSED_PAD src0_sel:WORD_1
	v_cvt_f32_f16_e32 v68, v29
	v_cvt_f32_f16_sdwa v69, v29 dst_sel:DWORD dst_unused:UNUSED_PAD src0_sel:WORD_1
	global_load_dwordx2 v[28:29], v[26:27], off offset:-1024
	s_waitcnt vmcnt(0)
	v_cvt_f32_f16_e32 v58, v28
	global_load_dwordx2 v[26:27], v[26:27], off offset:-512
	v_cvt_f32_f16_sdwa v59, v28 dst_sel:DWORD dst_unused:UNUSED_PAD src0_sel:WORD_1
	v_cvt_f32_f16_e32 v66, v29
	v_cvt_f32_f16_sdwa v67, v29 dst_sel:DWORD dst_unused:UNUSED_PAD src0_sel:WORD_1
	v_cvt_f32_f16_sdwa v29, v35 dst_sel:DWORD dst_unused:UNUSED_PAD src0_sel:WORD_1
	v_cvt_f32_f16_e32 v28, v35
	v_cvt_f32_f16_sdwa v35, v38 dst_sel:DWORD dst_unused:UNUSED_PAD src0_sel:WORD_1
	s_waitcnt vmcnt(0)
	v_cvt_f32_f16_e32 v56, v26
	v_cvt_f32_f16_sdwa v57, v26 dst_sel:DWORD dst_unused:UNUSED_PAD src0_sel:WORD_1
	v_cvt_f32_f16_e32 v64, v27
	v_cvt_f32_f16_sdwa v65, v27 dst_sel:DWORD dst_unused:UNUSED_PAD src0_sel:WORD_1
	global_load_dwordx2 v[26:27], v[24:25], off offset:-4096
	s_waitcnt vmcnt(0)
	v_cvt_f32_f16_sdwa v55, v27 dst_sel:DWORD dst_unused:UNUSED_PAD src0_sel:WORD_1
	v_cvt_f32_f16_sdwa v63, v26 dst_sel:DWORD dst_unused:UNUSED_PAD src0_sel:WORD_1
	v_cvt_f32_f16_e32 v54, v27
	v_cvt_f32_f16_e32 v62, v26
	global_load_dwordx2 v[26:27], v[24:25], off offset:-3584
	s_waitcnt vmcnt(0)
	v_cvt_f32_f16_sdwa v71, v26 dst_sel:DWORD dst_unused:UNUSED_PAD src0_sel:WORD_1
	v_cvt_f32_f16_sdwa v73, v27 dst_sel:DWORD dst_unused:UNUSED_PAD src0_sel:WORD_1
	v_cvt_f32_f16_e32 v70, v26
	v_cvt_f32_f16_e32 v72, v27
	global_load_dwordx2 v[26:27], v[24:25], off offset:-3072
	s_waitcnt vmcnt(0)
	v_cvt_f32_f16_sdwa v31, v26 dst_sel:DWORD dst_unused:UNUSED_PAD src0_sel:WORD_1
	v_cvt_f32_f16_sdwa v33, v27 dst_sel:DWORD dst_unused:UNUSED_PAD src0_sel:WORD_1
	v_cvt_f32_f16_e32 v30, v26
	v_cvt_f32_f16_e32 v32, v27
	global_load_dwordx2 v[26:27], v[24:25], off offset:-2560
	s_waitcnt vmcnt(0)
	v_cvt_f32_f16_sdwa v43, v26 dst_sel:DWORD dst_unused:UNUSED_PAD src0_sel:WORD_1
	v_cvt_f32_f16_sdwa v45, v27 dst_sel:DWORD dst_unused:UNUSED_PAD src0_sel:WORD_1
	v_cvt_f32_f16_e32 v42, v26
	v_cvt_f32_f16_e32 v44, v27
	global_load_dwordx2 v[26:27], v[24:25], off offset:-2048
	v_lshl_add_u64 v[24:25], v[24:25], 0, s[68:69]
	s_waitcnt vmcnt(0)
	v_cvt_f32_f16_sdwa v51, v27 dst_sel:DWORD dst_unused:UNUSED_PAD src0_sel:WORD_1
	v_cvt_f32_f16_sdwa v53, v26 dst_sel:DWORD dst_unused:UNUSED_PAD src0_sel:WORD_1
	v_cvt_f32_f16_e32 v50, v27
	v_cvt_f32_f16_e32 v52, v26
	v_cvt_f32_f16_sdwa v27, v34 dst_sel:DWORD dst_unused:UNUSED_PAD src0_sel:WORD_1
	v_cvt_f32_f16_e32 v26, v34
	v_cvt_f32_f16_e32 v34, v38
	v_cvt_f32_f16_e32 v38, v46
	v_cvt_f32_f16_e32 v46, v93
	v_pk_mul_f32 v[92:93], v[84:85], v[84:85]
	s_nop 0
	v_pk_mov_b32 v[96:97], v[94:95], v[92:93] op_sel:[1,0]
	v_mov_b32_e32 v95, v93
	v_pk_add_f32 v[92:93], v[96:97], v[94:95]
	v_pk_mul_f32 v[94:95], v[78:79], v[78:79]
	v_pk_mul_f32 v[96:97], v[74:75], v[74:75]
	v_pk_add_f32 v[92:93], v[92:93], v[92:93] op_sel:[0,1] op_sel_hi:[1,0]
	v_pk_mov_b32 v[98:99], v[96:97], v[94:95] op_sel:[1,0]
	v_mov_b32_e32 v97, v95
	v_pk_add_f32 v[94:95], v[98:99], v[96:97]
	v_mul_f32_e32 v96, v81, v81
	v_pk_add_f32 v[94:95], v[94:95], v[94:95] op_sel:[0,1] op_sel_hi:[1,0]
	v_mov_b32_e32 v93, v21
	v_mov_b32_e32 v95, v96
	v_pk_add_f32 v[92:93], v[92:93], v[94:95]
	v_mul_f32_e32 v94, v19, v19
	v_mul_f32_e32 v97, v16, v16
	v_pk_fma_f32 v[94:95], v[18:19], v[18:19], v[94:95] op_sel_hi:[1,1,0]
	v_mul_f32_e32 v96, v77, v77
	v_mul_f32_e32 v98, v17, v17
	v_mov_b32_e32 v95, v97
	v_pk_fma_f32 v[96:97], v[76:77], v[76:77], v[96:97] op_sel_hi:[1,1,0]
	s_nop 0
	v_mov_b32_e32 v97, v98
	v_pk_add_f32 v[94:95], v[94:95], v[96:97]
	s_nop 0
	v_pk_add_f32 v[92:93], v[92:93], v[94:95]
	s_nop 0
	v_add_f32_e32 v21, v92, v93
	ds_bpermute_b32 v92, v86, v21
	s_waitcnt lgkmcnt(0)
; __device__ __forceinline__ void final_norm_phase(const _Float16* xh, float* out, const float* g, int rows) {
;     ...
;         for (int r = 0; r < 4; ++r) { float s = 0.f;
; #pragma unroll
;             for (int j = 0; j < 4; ++j) s += (v[r][j].x * v[r][j].x + v[r][j].y * v[r][j].y) + (v[r][j].z * v[r][j].z + v[r][j].w * v[r][j].w);
;             const float rstd = 1.0f / sqrtf(wave_sum(s) * (1.0f / DM) + RMS_EPS);
;             f32x4* orow = (f32x4*)(out + (size_t)(m0 + r) * DM) + lane;
; #pragma unroll
;             for (int j = 0; j < 4; ++j) orow[64 * j] = v[r][j] * rstd * gv[j]; }
	v_add_f32_e32 v21, v21, v92
	ds_bpermute_b32 v92, v87, v21
	s_waitcnt lgkmcnt(0)
	v_add_f32_e32 v21, v21, v92
	ds_bpermute_b32 v92, v88, v21
	s_waitcnt lgkmcnt(0)
	v_add_f32_e32 v21, v21, v92
	ds_bpermute_b32 v92, v89, v21
	s_waitcnt lgkmcnt(0)
	v_add_f32_e32 v21, v21, v92
	ds_bpermute_b32 v92, v90, v21
	s_waitcnt lgkmcnt(0)
	v_add_f32_e32 v21, v21, v92
	ds_bpermute_b32 v92, v91, v21
	s_waitcnt lgkmcnt(0)
	v_add_f32_e32 v21, v21, v92
	v_fmamk_f32 v21, v21, 0x3a800000, v195
	v_cmp_gt_f32_e32 vcc, s33, v21
	v_mul_f32_e32 v92, 0x4f800000, v21
	s_nop 0
	v_cndmask_b32_e32 v21, v21, v92, vcc
	v_sqrt_f32_e32 v92, v21
	s_nop 0
	v_add_u32_e32 v93, -1, v92
	v_fma_f32 v94, -v93, v92, v21
	v_cmp_ge_f32_e64 s[0:1], 0, v94
	v_add_u32_e32 v94, 1, v92
	s_nop 0
	v_cndmask_b32_e64 v93, v92, v93, s[0:1]
	v_fma_f32 v92, -v94, v92, v21
	v_cmp_lt_f32_e64 s[0:1], 0, v92
	s_nop 1
	v_cndmask_b32_e64 v92, v93, v94, s[0:1]
	v_mul_f32_e32 v93, 0x37800000, v92
	v_cndmask_b32_e32 v92, v92, v93, vcc
	v_cmp_class_f32_e32 vcc, v21, v197
	s_nop 1
	v_cndmask_b32_e32 v21, v92, v21, vcc
	v_div_scale_f32 v92, s[0:1], v21, v21, 1.0
	v_rcp_f32_e32 v93, v92
	s_movk_i32 s0, 0xd000
	v_fma_f32 v94, -v92, v93, 1.0
	v_fmac_f32_e32 v93, v94, v93
	v_div_scale_f32 v94, vcc, 1.0, v21, 1.0
	v_mul_f32_e32 v95, v94, v93
	v_fma_f32 v96, -v92, v95, v94
	v_fmac_f32_e32 v95, v96, v93
	v_fma_f32 v92, -v92, v95, v94
	v_div_fmas_f32 v92, v92, v93, v95
	v_div_fixup_f32 v92, v92, v21, 1.0
	v_pk_mul_f32 v[82:83], v[92:93], v[82:83] op_sel_hi:[0,1]
	v_pk_mul_f32 v[84:85], v[92:93], v[84:85] op_sel_hi:[0,1]
	v_add_co_u32_e32 v94, vcc, s0, v22
	v_pk_mul_f32 v[84:85], v[2:3], v[84:85]
	v_pk_mul_f32 v[82:83], v[0:1], v[82:83]
	v_addc_co_u32_e32 v95, vcc, -1, v23, vcc
	v_pk_mul_f32 v[74:75], v[92:93], v[74:75] op_sel_hi:[0,1]
	global_store_dwordx4 v[94:95], v[82:85], off offset:-3072 sc1
	v_pk_mul_f32 v[18:19], v[92:93], v[18:19] op_sel_hi:[0,1]
	v_pk_mul_f32 v[16:17], v[92:93], v[16:17] op_sel_hi:[0,1]
	v_pk_mul_f32 v[82:83], v[4:5], v[74:75]
	v_pk_mul_f32 v[74:75], v[92:93], v[76:77] op_sel_hi:[0,1]
	v_pk_mul_f32 v[76:77], v[10:11], v[74:75]
	v_pk_mul_f32 v[74:75], v[8:9], v[18:19]
	global_store_dwordx4 v[94:95], v[74:77], off offset:-1024 sc1
	s_movk_i32 s0, 0xe000
	v_pk_mul_f32 v[18:19], v[14:15], v[16:17]
	v_pk_mul_f32 v[74:75], v[92:93], v[80:81] op_sel_hi:[0,1]
	v_pk_mul_f32 v[16:17], v[12:13], v[74:75]
	v_add_co_u32_e32 v74, vcc, s0, v22
	v_pk_mul_f32 v[78:79], v[92:93], v[78:79] op_sel_hi:[0,1]
	s_nop 0
	v_addc_co_u32_e32 v75, vcc, -1, v23, vcc
	global_store_dwordx4 v[74:75], v[16:19], off offset:-4096 sc1
	v_pk_mul_f32 v[84:85], v[6:7], v[78:79]
	v_mul_f32_e32 v21, v62, v62
	v_pk_mul_f32 v[16:17], v[68:69], v[68:69]
	v_pk_mul_f32 v[18:19], v[60:61], v[60:61]
	global_store_dwordx4 v[94:95], v[82:85], off offset:-2048 sc1
	v_pk_mov_b32 v[76:77], v[18:19], v[16:17] op_sel:[1,0]
	v_mov_b32_e32 v19, v17
	v_pk_add_f32 v[16:17], v[76:77], v[18:19]
	v_pk_mul_f32 v[18:19], v[66:67], v[66:67]
	v_pk_mul_f32 v[76:77], v[58:59], v[58:59]
	v_pk_add_f32 v[16:17], v[16:17], v[16:17] op_sel:[0,1] op_sel_hi:[1,0]
	v_pk_mov_b32 v[78:79], v[76:77], v[18:19] op_sel:[1,0]
	v_mov_b32_e32 v77, v19
	v_pk_add_f32 v[18:19], v[78:79], v[76:77]
	v_mul_f32_e32 v76, v63, v63
	v_pk_add_f32 v[18:19], v[18:19], v[18:19] op_sel:[0,1] op_sel_hi:[1,0]
	v_mov_b32_e32 v17, v21
	v_mov_b32_e32 v19, v76
	v_pk_add_f32 v[16:17], v[16:17], v[18:19]
	v_mul_f32_e32 v18, v57, v57
	v_mul_f32_e32 v77, v54, v54
	v_pk_fma_f32 v[18:19], v[56:57], v[56:57], v[18:19] op_sel_hi:[1,1,0]
	v_mul_f32_e32 v76, v65, v65
	v_mul_f32_e32 v78, v55, v55
	v_mov_b32_e32 v19, v77
	v_pk_fma_f32 v[76:77], v[64:65], v[64:65], v[76:77] op_sel_hi:[1,1,0]
	s_nop 0
	v_mov_b32_e32 v77, v78
	v_pk_add_f32 v[18:19], v[18:19], v[76:77]
	s_nop 0
	v_pk_add_f32 v[16:17], v[16:17], v[18:19]
	s_nop 0
	v_add_f32_e32 v16, v16, v17
	ds_bpermute_b32 v17, v86, v16
	s_waitcnt lgkmcnt(0)
	v_add_f32_e32 v16, v16, v17
	ds_bpermute_b32 v17, v87, v16
	s_waitcnt lgkmcnt(0)
	v_add_f32_e32 v16, v16, v17
	ds_bpermute_b32 v17, v88, v16
	s_waitcnt lgkmcnt(0)
	v_add_f32_e32 v16, v16, v17
	ds_bpermute_b32 v17, v89, v16
	s_waitcnt lgkmcnt(0)
	v_add_f32_e32 v16, v16, v17
	ds_bpermute_b32 v17, v90, v16
	s_waitcnt lgkmcnt(0)
	v_add_f32_e32 v16, v16, v17
	ds_bpermute_b32 v17, v91, v16
	s_waitcnt lgkmcnt(0)
; __device__ __forceinline__ void final_norm_phase(const _Float16* xh, float* out, const float* g, int rows) {
;     ...
;         for (int r = 0; r < 4; ++r) { float s = 0.f;
; #pragma unroll
;             for (int j = 0; j < 4; ++j) s += (v[r][j].x * v[r][j].x + v[r][j].y * v[r][j].y) + (v[r][j].z * v[r][j].z + v[r][j].w * v[r][j].w);
;             const float rstd = 1.0f / sqrtf(wave_sum(s) * (1.0f / DM) + RMS_EPS);
;             f32x4* orow = (f32x4*)(out + (size_t)(m0 + r) * DM) + lane;
; #pragma unroll
;             for (int j = 0; j < 4; ++j) orow[64 * j] = v[r][j] * rstd * gv[j]; }
	v_add_f32_e32 v16, v16, v17
	v_fmamk_f32 v16, v16, 0x3a800000, v195
	v_cmp_gt_f32_e32 vcc, s33, v16
	v_mul_f32_e32 v17, 0x4f800000, v16
	s_nop 0
	v_cndmask_b32_e32 v16, v16, v17, vcc
	v_sqrt_f32_e32 v17, v16
	s_nop 0
	v_add_u32_e32 v18, -1, v17
	v_fma_f32 v19, -v18, v17, v16
	v_cmp_ge_f32_e64 s[0:1], 0, v19
	v_add_u32_e32 v19, 1, v17
	s_nop 0
	v_cndmask_b32_e64 v18, v17, v18, s[0:1]
	v_fma_f32 v17, -v19, v17, v16
	v_cmp_lt_f32_e64 s[0:1], 0, v17
	s_nop 1
	v_cndmask_b32_e64 v17, v18, v19, s[0:1]
	v_mul_f32_e32 v18, 0x37800000, v17
	v_cndmask_b32_e32 v17, v17, v18, vcc
	v_cmp_class_f32_e32 vcc, v16, v197
	s_nop 1
	v_cndmask_b32_e32 v16, v17, v16, vcc
	v_div_scale_f32 v17, s[0:1], v16, v16, 1.0
	v_rcp_f32_e32 v18, v17
	s_nop 0
	v_fma_f32 v19, -v17, v18, 1.0
	v_fmac_f32_e32 v18, v19, v18
	v_div_scale_f32 v19, vcc, 1.0, v16, 1.0
	v_mul_f32_e32 v21, v19, v18
	v_fma_f32 v76, -v17, v21, v19
	v_fmac_f32_e32 v21, v76, v18
	v_fma_f32 v17, -v17, v21, v19
	v_div_fmas_f32 v17, v17, v18, v21
	v_div_fixup_f32 v76, v17, v16, 1.0
	v_pk_mul_f32 v[16:17], v[76:77], v[60:61] op_sel_hi:[0,1]
	v_pk_mul_f32 v[18:19], v[76:77], v[68:69] op_sel_hi:[0,1]
	v_pk_mul_f32 v[18:19], v[2:3], v[18:19]
	v_pk_mul_f32 v[16:17], v[0:1], v[16:17]
	global_store_dwordx4 v[74:75], v[16:19], off offset:-3072 sc1
	v_mul_f32_e32 v21, v52, v52
	s_nop 0
	v_pk_mul_f32 v[16:17], v[76:77], v[58:59] op_sel_hi:[0,1]
	v_pk_mul_f32 v[18:19], v[76:77], v[66:67] op_sel_hi:[0,1]
	v_pk_mul_f32 v[18:19], v[6:7], v[18:19]
	v_pk_mul_f32 v[16:17], v[4:5], v[16:17]
	global_store_dwordx4 v[74:75], v[16:19], off offset:-2048 sc1
	s_nop 1
	v_pk_mul_f32 v[16:17], v[76:77], v[56:57] op_sel_hi:[0,1]
	v_pk_mul_f32 v[18:19], v[76:77], v[64:65] op_sel_hi:[0,1]
	v_pk_mul_f32 v[18:19], v[10:11], v[18:19]
	v_pk_mul_f32 v[16:17], v[8:9], v[16:17]
	global_store_dwordx4 v[74:75], v[16:19], off offset:-1024 sc1
	s_nop 1
	v_pk_mul_f32 v[16:17], v[76:77], v[62:63] op_sel_hi:[0,1]
	v_pk_mul_f32 v[18:19], v[76:77], v[54:55] op_sel_hi:[0,1]
	v_pk_mul_f32 v[18:19], v[14:15], v[18:19]
	v_pk_mul_f32 v[16:17], v[12:13], v[16:17]
	global_store_dwordx4 v[74:75], v[16:19], off sc1
	s_nop 1
	v_pk_mul_f32 v[16:17], v[72:73], v[72:73]
	v_pk_mul_f32 v[18:19], v[70:71], v[70:71]
	s_nop 0
	v_pk_mov_b32 v[54:55], v[18:19], v[16:17] op_sel:[1,0]
	v_mov_b32_e32 v19, v17
	v_pk_add_f32 v[16:17], v[54:55], v[18:19]
	v_pk_mul_f32 v[18:19], v[32:33], v[32:33]
	v_pk_mul_f32 v[54:55], v[30:31], v[30:31]
	v_pk_add_f32 v[16:17], v[16:17], v[16:17] op_sel:[0,1] op_sel_hi:[1,0]
	v_pk_mov_b32 v[56:57], v[54:55], v[18:19] op_sel:[1,0]
	v_mov_b32_e32 v55, v19
	v_pk_add_f32 v[18:19], v[56:57], v[54:55]
	v_mul_f32_e32 v54, v53, v53
	v_pk_add_f32 v[18:19], v[18:19], v[18:19] op_sel:[0,1] op_sel_hi:[1,0]
	v_mov_b32_e32 v17, v21
	v_mov_b32_e32 v19, v54
	v_pk_add_f32 v[16:17], v[16:17], v[18:19]
	v_mul_f32_e32 v18, v43, v43
	v_mul_f32_e32 v55, v50, v50
	v_pk_fma_f32 v[18:19], v[42:43], v[42:43], v[18:19] op_sel_hi:[1,1,0]
	v_mul_f32_e32 v54, v45, v45
	v_mul_f32_e32 v56, v51, v51
	v_mov_b32_e32 v19, v55
	v_pk_fma_f32 v[54:55], v[44:45], v[44:45], v[54:55] op_sel_hi:[1,1,0]
	s_nop 0
	v_mov_b32_e32 v55, v56
	v_pk_add_f32 v[18:19], v[18:19], v[54:55]
	s_nop 0
	v_pk_add_f32 v[16:17], v[16:17], v[18:19]
	s_nop 0
	v_add_f32_e32 v16, v16, v17
	ds_bpermute_b32 v17, v86, v16
	s_waitcnt lgkmcnt(0)
	v_add_f32_e32 v16, v16, v17
	ds_bpermute_b32 v17, v87, v16
	s_waitcnt lgkmcnt(0)
	v_add_f32_e32 v16, v16, v17
	ds_bpermute_b32 v17, v88, v16
	s_waitcnt lgkmcnt(0)
	v_add_f32_e32 v16, v16, v17
	ds_bpermute_b32 v17, v89, v16
	s_waitcnt lgkmcnt(0)
	v_add_f32_e32 v16, v16, v17
	ds_bpermute_b32 v17, v90, v16
	s_waitcnt lgkmcnt(0)
	v_add_f32_e32 v16, v16, v17
	ds_bpermute_b32 v17, v91, v16
	s_waitcnt lgkmcnt(0)
; __device__ __forceinline__ void final_norm_phase(const _Float16* xh, float* out, const float* g, int rows) {
;     ...
;         for (int r = 0; r < 4; ++r) { float s = 0.f;
; #pragma unroll
;             for (int j = 0; j < 4; ++j) s += (v[r][j].x * v[r][j].x + v[r][j].y * v[r][j].y) + (v[r][j].z * v[r][j].z + v[r][j].w * v[r][j].w);
;             const float rstd = 1.0f / sqrtf(wave_sum(s) * (1.0f / DM) + RMS_EPS);
;             f32x4* orow = (f32x4*)(out + (size_t)(m0 + r) * DM) + lane;
; #pragma unroll
;             for (int j = 0; j < 4; ++j) orow[64 * j] = v[r][j] * rstd * gv[j]; }
	v_add_f32_e32 v16, v16, v17
	v_fmamk_f32 v16, v16, 0x3a800000, v195
	v_cmp_gt_f32_e32 vcc, s33, v16
	v_mul_f32_e32 v17, 0x4f800000, v16
	s_nop 0
	v_cndmask_b32_e32 v16, v16, v17, vcc
	v_sqrt_f32_e32 v17, v16
	s_nop 0
	v_add_u32_e32 v18, -1, v17
	v_fma_f32 v19, -v18, v17, v16
	v_cmp_ge_f32_e64 s[0:1], 0, v19
	v_add_u32_e32 v19, 1, v17
	s_nop 0
	v_cndmask_b32_e64 v18, v17, v18, s[0:1]
	v_fma_f32 v17, -v19, v17, v16
	v_cmp_lt_f32_e64 s[0:1], 0, v17
	s_nop 1
	v_cndmask_b32_e64 v17, v18, v19, s[0:1]
	v_mul_f32_e32 v18, 0x37800000, v17
	v_cndmask_b32_e32 v17, v17, v18, vcc
	v_cmp_class_f32_e32 vcc, v16, v197
	s_nop 1
	v_cndmask_b32_e32 v16, v17, v16, vcc
	v_div_scale_f32 v17, s[0:1], v16, v16, 1.0
	v_rcp_f32_e32 v18, v17
	s_movk_i32 s0, 0xf000
	v_fma_f32 v19, -v17, v18, 1.0
	v_fmac_f32_e32 v18, v19, v18
	v_div_scale_f32 v19, vcc, 1.0, v16, 1.0
	v_mul_f32_e32 v21, v19, v18
	v_fma_f32 v54, -v17, v21, v19
	v_fmac_f32_e32 v21, v54, v18
	v_fma_f32 v17, -v17, v21, v19
	v_div_fmas_f32 v17, v17, v18, v21
	v_div_fixup_f32 v16, v17, v16, 1.0
	v_pk_mul_f32 v[18:19], v[16:17], v[70:71] op_sel_hi:[0,1]
	v_pk_mul_f32 v[54:55], v[16:17], v[72:73] op_sel_hi:[0,1]
	v_pk_mul_f32 v[56:57], v[2:3], v[54:55]
	v_pk_mul_f32 v[54:55], v[0:1], v[18:19]
	v_add_co_u32_e32 v18, vcc, s0, v22
	v_pk_mul_f32 v[30:31], v[16:17], v[30:31] op_sel_hi:[0,1]
	v_pk_mul_f32 v[32:33], v[16:17], v[32:33] op_sel_hi:[0,1]
	v_addc_co_u32_e32 v19, vcc, -1, v23, vcc
	v_pk_mul_f32 v[32:33], v[6:7], v[32:33]
	v_pk_mul_f32 v[30:31], v[4:5], v[30:31]
	global_store_dwordx4 v[18:19], v[30:33], off offset:-2048 sc1
	global_store_dwordx4 v[18:19], v[54:57], off offset:-3072 sc1
	v_mul_f32_e32 v21, v48, v48
	v_pk_mul_f32 v[30:31], v[16:17], v[42:43] op_sel_hi:[0,1]
	v_pk_mul_f32 v[32:33], v[16:17], v[44:45] op_sel_hi:[0,1]
	v_pk_mul_f32 v[32:33], v[10:11], v[32:33]
	v_pk_mul_f32 v[30:31], v[8:9], v[30:31]
	global_store_dwordx4 v[18:19], v[30:33], off offset:-1024 sc1
	s_nop 1
	v_pk_mul_f32 v[30:31], v[16:17], v[52:53] op_sel_hi:[0,1]
	v_pk_mul_f32 v[16:17], v[16:17], v[50:51] op_sel_hi:[0,1]
	v_pk_mul_f32 v[18:19], v[14:15], v[16:17]
	v_pk_mul_f32 v[16:17], v[12:13], v[30:31]
	global_store_dwordx4 v[22:23], v[16:19], off offset:-4096 sc1
	s_nop 1
	v_pk_mul_f32 v[16:17], v[28:29], v[28:29]
	v_pk_mul_f32 v[18:19], v[26:27], v[26:27]
	s_nop 0
	v_pk_mov_b32 v[30:31], v[18:19], v[16:17] op_sel:[1,0]
	v_mov_b32_e32 v19, v17
	v_pk_add_f32 v[16:17], v[30:31], v[18:19]
	v_pk_mul_f32 v[18:19], v[36:37], v[36:37]
	v_pk_mul_f32 v[30:31], v[34:35], v[34:35]
	v_pk_add_f32 v[16:17], v[16:17], v[16:17] op_sel:[0,1] op_sel_hi:[1,0]
	v_pk_mov_b32 v[32:33], v[30:31], v[18:19] op_sel:[1,0]
	v_mov_b32_e32 v31, v19
	v_pk_add_f32 v[18:19], v[32:33], v[30:31]
	v_mul_f32_e32 v30, v49, v49
	v_pk_add_f32 v[18:19], v[18:19], v[18:19] op_sel:[0,1] op_sel_hi:[1,0]
	v_mov_b32_e32 v17, v21
	v_mov_b32_e32 v19, v30
	v_pk_add_f32 v[16:17], v[16:17], v[18:19]
	v_mul_f32_e32 v18, v39, v39
	v_mul_f32_e32 v31, v46, v46
	v_pk_fma_f32 v[18:19], v[38:39], v[38:39], v[18:19] op_sel_hi:[1,1,0]
	v_mul_f32_e32 v30, v41, v41
	v_mul_f32_e32 v32, v47, v47
	v_mov_b32_e32 v19, v31
	v_pk_fma_f32 v[30:31], v[40:41], v[40:41], v[30:31] op_sel_hi:[1,1,0]
	s_nop 0
	v_mov_b32_e32 v31, v32
	v_pk_add_f32 v[18:19], v[18:19], v[30:31]
	s_nop 0
	v_pk_add_f32 v[16:17], v[16:17], v[18:19]
	s_nop 0
	v_add_f32_e32 v16, v16, v17
	ds_bpermute_b32 v17, v86, v16
	s_waitcnt lgkmcnt(0)
	v_add_f32_e32 v16, v16, v17
	ds_bpermute_b32 v17, v87, v16
	s_waitcnt lgkmcnt(0)
	v_add_f32_e32 v16, v16, v17
	ds_bpermute_b32 v17, v88, v16
	s_waitcnt lgkmcnt(0)
	v_add_f32_e32 v16, v16, v17
	ds_bpermute_b32 v17, v89, v16
	s_waitcnt lgkmcnt(0)
	v_add_f32_e32 v16, v16, v17
	ds_bpermute_b32 v17, v90, v16
	s_waitcnt lgkmcnt(0)
	v_add_f32_e32 v16, v16, v17
	ds_bpermute_b32 v17, v91, v16
	s_waitcnt lgkmcnt(0)
	v_add_f32_e32 v16, v16, v17
	v_fmamk_f32 v16, v16, 0x3a800000, v195
	v_cmp_gt_f32_e32 vcc, s33, v16
	v_mul_f32_e32 v17, 0x4f800000, v16
	s_nop 0
	v_cndmask_b32_e32 v16, v16, v17, vcc
	v_sqrt_f32_e32 v17, v16
	s_nop 0
	v_add_u32_e32 v18, -1, v17
	v_fma_f32 v19, -v18, v17, v16
	v_cmp_ge_f32_e64 s[0:1], 0, v19
	v_add_u32_e32 v19, 1, v17
	s_nop 0
	v_cndmask_b32_e64 v18, v17, v18, s[0:1]
	v_fma_f32 v17, -v19, v17, v16
	v_cmp_lt_f32_e64 s[0:1], 0, v17
	s_nop 1
	v_cndmask_b32_e64 v17, v18, v19, s[0:1]
	v_mul_f32_e32 v18, 0x37800000, v17
	v_cndmask_b32_e32 v17, v17, v18, vcc
	v_cmp_class_f32_e32 vcc, v16, v197
	s_nop 1
	v_cndmask_b32_e32 v16, v17, v16, vcc
	v_div_scale_f32 v17, s[0:1], v16, v16, 1.0
	v_rcp_f32_e32 v18, v17
	s_nop 0
	v_fma_f32 v19, -v17, v18, 1.0
	v_fmac_f32_e32 v18, v19, v18
	v_div_scale_f32 v19, vcc, 1.0, v16, 1.0
	v_mul_f32_e32 v21, v19, v18
	v_fma_f32 v30, -v17, v21, v19
	v_fmac_f32_e32 v21, v30, v18
	v_fma_f32 v17, -v17, v21, v19
	v_div_fmas_f32 v17, v17, v18, v21
	v_div_fixup_f32 v30, v17, v16, 1.0
	v_pk_mul_f32 v[16:17], v[30:31], v[26:27] op_sel_hi:[0,1]
	v_pk_mul_f32 v[18:19], v[30:31], v[28:29] op_sel_hi:[0,1]
	v_pk_mul_f32 v[18:19], v[2:3], v[18:19]
	v_pk_mul_f32 v[16:17], v[0:1], v[16:17]
	global_store_dwordx4 v[22:23], v[16:19], off offset:-3072 sc1
	v_cmp_le_i32_e32 vcc, s62, v20
	s_or_b64 s[6:7], vcc, s[6:7]
	v_pk_mul_f32 v[16:17], v[30:31], v[34:35] op_sel_hi:[0,1]
	v_pk_mul_f32 v[18:19], v[30:31], v[36:37] op_sel_hi:[0,1]
	v_pk_mul_f32 v[18:19], v[6:7], v[18:19]
	v_pk_mul_f32 v[16:17], v[4:5], v[16:17]
	global_store_dwordx4 v[22:23], v[16:19], off offset:-2048 sc1
	s_nop 1
	v_pk_mul_f32 v[16:17], v[30:31], v[38:39] op_sel_hi:[0,1]
	v_pk_mul_f32 v[18:19], v[30:31], v[40:41] op_sel_hi:[0,1]
	v_pk_mul_f32 v[18:19], v[10:11], v[18:19]
	v_pk_mul_f32 v[16:17], v[8:9], v[16:17]
	global_store_dwordx4 v[22:23], v[16:19], off offset:-1024 sc1
	s_nop 1
	v_pk_mul_f32 v[16:17], v[30:31], v[48:49] op_sel_hi:[0,1]
	v_pk_mul_f32 v[18:19], v[30:31], v[46:47] op_sel_hi:[0,1]
	v_pk_mul_f32 v[18:19], v[14:15], v[18:19]
	v_pk_mul_f32 v[16:17], v[12:13], v[16:17]
	global_store_dwordx4 v[22:23], v[16:19], off sc1
	v_lshl_add_u64 v[22:23], v[22:23], 0, s[70:71]
	s_andn2_b64 exec, exec, s[6:7]
	s_cbranch_execnz .LBB0_184

; __device__ __forceinline__ void mla_attn_phase(LAS unsigned char* lds, const bf16_t* q, const bf16_t* kv, const bf16_t* krope, const bf16_t* projb, bf16_t* y, int unit0, int G, int nu) {
;     ...
;     MLA_EXP(n0, n1);
;     MLA_PV(lds + sl_c + MLA_KB);
;     __syncthreads();
.LBB0_200:
	v_exp_f32_e32 v48, v48
	v_exp_f32_e32 v65, v32
	v_exp_f32_e32 v32, v49
	v_exp_f32_e32 v49, v33
	v_exp_f32_e32 v33, v50
	v_exp_f32_e32 v50, v34
	v_exp_f32_e32 v34, v51
	v_exp_f32_e32 v51, v35
	v_exp_f32_e32 v35, v52
	v_exp_f32_e32 v52, v36
	v_exp_f32_e32 v36, v53
	v_exp_f32_e32 v53, v37
	v_exp_f32_e32 v37, v54
	v_exp_f32_e32 v54, v38
	v_exp_f32_e32 v38, v55
	v_exp_f32_e32 v39, v39
	v_exp_f32_e32 v55, v56
	v_exp_f32_e32 v56, v40
	v_exp_f32_e32 v40, v57
	v_exp_f32_e32 v57, v41
	s_ashr_i32 s6, s2, 8
	s_ashr_i32 s7, s6, 31
	s_waitcnt vmcnt(2)
	ds_write_b128 v185, v[152:155]
	s_waitcnt vmcnt(1)
	ds_write_b128 v201, v[156:159]
	s_waitcnt vmcnt(0)
	ds_write_b128 v214, v[160:163]
	v_add_f32_e32 v66, v65, v48
	v_add_f32_e32 v68, v50, v33
	v_add_f32_e32 v69, v51, v34
	v_add_f32_e32 v71, v53, v36
	v_cvt_pk_bf16_f32 v33, v33, v34
	v_cvt_pk_bf16_f32 v34, v35, v36
	v_cvt_pk_bf16_f32 v36, v65, v49
	v_add_u32_e32 v65, 0x16000, v233
	s_lshl_b64 s[6:7], s[6:7], 12
	v_add_f32_e32 v67, v49, v32
	v_add_f32_e32 v70, v52, v35
	v_add_f32_e32 v72, v54, v37
	v_add_f32_e32 v73, v39, v38
	v_add_f32_e32 v74, v56, v55
	v_add_f32_e32 v75, v57, v40
	v_cvt_pk_bf16_f32 v32, v48, v32
	v_cvt_pk_bf16_f32 v35, v37, v38
	v_cvt_pk_bf16_f32 v37, v50, v51
	v_cvt_pk_bf16_f32 v38, v52, v53
	v_cvt_pk_bf16_f32 v39, v54, v39
	v_cvt_pk_bf16_f32 v40, v55, v40
	ds_read_b64_tr_b16 v[48:49], v65
	ds_read_b64_tr_b16 v[50:51], v65 offset:1536
	ds_read_b64_tr_b16 v[54:55], v65 offset:1600
	ds_read_b64_tr_b16 v[52:53], v65 offset:64
	s_add_i32 s3, s2, s56
	v_readlane_b32 s16, v254, 47
	v_exp_f32_e32 v41, v58
	v_exp_f32_e32 v58, v42
	v_exp_f32_e32 v42, v59
	v_exp_f32_e32 v59, v43
	v_exp_f32_e32 v43, v60
	v_exp_f32_e32 v60, v44
	v_exp_f32_e32 v44, v61
	v_exp_f32_e32 v61, v45
	s_cmp_lt_i32 s3, s16
	s_cselect_b32 s12, s3, s2
	s_ashr_i32 s8, s12, 8
	v_exp_f32_e32 v45, v62
	v_exp_f32_e32 v62, v46
	v_exp_f32_e32 v46, v63
	v_exp_f32_e32 v47, v47
	s_ashr_i32 s9, s8, 31
	v_add_f32_e32 v76, v58, v41
	v_add_f32_e32 v77, v59, v42
	v_add_f32_e32 v79, v61, v44
	v_cvt_pk_bf16_f32 v41, v41, v42
	v_cvt_pk_bf16_f32 v42, v43, v44
	v_cvt_pk_bf16_f32 v44, v56, v57
	v_add_f32_e32 v56, 0, v66
	s_waitcnt lgkmcnt(0)
	v_mfma_f32_32x32x16_bf16 v[16:31], v[32:35], v[52:55], v[16:31]
	s_lshl_b64 s[10:11], s[8:9], 12
	s_lshl_b32 s8, s12, 8
	v_add_f32_e32 v56, v67, v56
	s_and_b32 s8, s8, 0xf00
	v_add_f32_e32 v56, v68, v56
	s_bfe_u32 s15, s12, 0x40004
	s_or_b32 s12, s10, s8
	v_mfma_f32_32x32x16_bf16 v[0:15], v[32:35], v[48:51], v[0:15]
	s_lshl_b32 s8, s2, 8
	v_add_f32_e32 v78, v60, v43
	v_add_f32_e32 v80, v62, v45
	v_add_f32_e32 v81, v47, v46
	v_cvt_pk_bf16_f32 v43, v45, v46
	v_cvt_pk_bf16_f32 v45, v58, v59
	v_cvt_pk_bf16_f32 v46, v60, v61
	v_add_f32_e32 v60, v69, v56
	ds_read_b64_tr_b16 v[52:53], v65 offset:3072
	ds_read_b64_tr_b16 v[54:55], v65 offset:4608
	ds_read_b64_tr_b16 v[58:59], v65 offset:4672
	ds_read_b64_tr_b16 v[56:57], v65 offset:3136
	s_lshl_b32 s14, s15, 8
	s_and_b32 s8, s8, 0xf00
	s_add_u32 s8, s8, s0
	s_addc_u32 s13, 0, s1
	s_add_u32 s9, s8, s6
	s_addc_u32 s8, s13, s7
	s_mov_b32 s13, s11
	v_add_f32_e32 v60, v70, v60
	s_waitcnt lgkmcnt(0)
	v_mfma_f32_32x32x16_bf16 v[16:31], v[40:43], v[56:59], v[16:31]
	v_lshl_add_u64 v[32:33], s[12:13], 0, v[186:187]
	v_readlane_b32 s12, v254, 17
	v_add_f32_e32 v60, v71, v60
	s_lshl_b32 s2, s2, 3
	v_readlane_b32 s13, v254, 18
	v_add_f32_e32 v60, v72, v60
	s_and_b32 s6, s2, 0x780
	v_mfma_f32_32x32x16_bf16 v[0:15], v[40:43], v[52:55], v[0:15]
	v_mov_b64_e32 v[34:35], s[12:13]
	s_movk_i32 s2, 0xc00
	v_cvt_pk_bf16_f32 v47, v62, v47
	v_add_f32_e32 v66, v73, v60
	ds_read_b64_tr_b16 v[56:57], v65 offset:6144
	ds_read_b64_tr_b16 v[58:59], v65 offset:7680
	ds_read_b64_tr_b16 v[62:63], v65 offset:7744
	ds_read_b64_tr_b16 v[60:61], v65 offset:6208
	v_mad_u64_u32 v[34:35], s[12:13], v32, s2, v[34:35]
	v_mov_b32_e32 v32, v35
	v_add_f32_e32 v66, v74, v66
	v_mad_u64_u32 v[32:33], s[12:13], v33, s2, v[32:33]
	v_add_f32_e32 v66, v75, v66
	v_mov_b32_e32 v35, v32
	s_mul_i32 s76, s15, 0xc0
	v_add_f32_e32 v66, v76, v66
	v_lshl_add_u64 v[32:33], v[34:35], 0, s[76:77]
	v_mov_b32_e32 v201, v179
	v_add_f32_e32 v70, v77, v66
	s_waitcnt lgkmcnt(0)
	v_mfma_f32_32x32x16_bf16 v[16:31], v[36:39], v[60:63], v[16:31]
	v_lshl_add_u64 v[32:33], v[32:33], 0, v[200:201]
	ds_read_b64_tr_b16 v[60:61], v65 offset:9216
	ds_read_b64_tr_b16 v[62:63], v65 offset:10752
	ds_read_b64_tr_b16 v[68:69], v65 offset:10816
	ds_read_b64_tr_b16 v[66:67], v65 offset:9280
	v_add_f32_e32 v65, v78, v70
	s_waitcnt lgkmcnt(0)
	s_barrier
; #define LAS __attribute__((address_space(3)))
; __device__ __forceinline__ int crow(int r, int hi) { return (r & 3) + 8 * (r >> 2) + 4 * hi; }
; __device__ __forceinline__ void mla_attn_phase(LAS unsigned char* lds, const bf16_t* q, const bf16_t* kv, const bf16_t* krope, const bf16_t* projb, bf16_t* y, int unit0, int G, int nu) {
;     ...
;     const int unit_n = unit + G; const bool more = unit_n < nu;
;     { const int uf_ = more ? unit_n : unit; MLA_FETCH(uf_); }
;     lsum += __shfl_xor(lsum, 32);
;     const float inv = 1.0f / lsum;
;     LAS float* stg = (LAS float*)(lds + w * 8704);
; #pragma unroll
;     for (int rr = 0; rr < 16; ++rr) { const int qi = crow(rr, hi); const float a = __shfl(inv, qi); stg[qi * 68 + r32] = o0[rr] * a; stg[qi * 68 + 32 + r32] = o1[rr] * a; }
	global_load_dwordx4 v[148:151], v[32:33], off
	global_load_dwordx4 v[144:147], v[32:33], off offset:32
	global_load_dwordx4 v[140:143], v[32:33], off offset:64
	global_load_dwordx4 v[136:139], v[32:33], off offset:96
	global_load_dwordx4 v[132:135], v[32:33], off offset:128
	global_load_dwordx4 v[128:131], v[32:33], off offset:160
	v_mfma_f32_32x32x16_bf16 v[0:15], v[36:39], v[56:59], v[0:15]
	v_lshl_add_u64 v[32:33], s[10:11], 0, v[182:183]
	v_readlane_b32 s12, v254, 19
	v_add_f32_e32 v65, v79, v65
	v_lshlrev_b64 v[32:33], 12, v[32:33]
	v_readlane_b32 s13, v254, 20
	v_add_f32_e32 v65, v80, v65
	s_mov_b32 s15, s77
	v_lshl_add_u64 v[32:33], s[12:13], 0, v[32:33]
	v_add_f32_e32 v65, v81, v65
	v_lshl_add_u64 v[32:33], v[32:33], 0, s[14:15]
	v_mov_b32_e32 v203, v179
	v_lshl_add_u64 v[206:207], v[32:33], 0, v[202:203]
	v_add_f32_e32 v56, v64, v65
	v_add_co_u32_e32 v40, vcc, s83, v206
	ds_bpermute_b32 v57, v216, v56
	s_nop 0
	v_addc_co_u32_e32 v41, vcc, 0, v207, vcc
	s_mov_b32 s2, 0x40000
	v_mfma_f32_32x32x16_bf16 v[16:31], v[44:47], v[66:69], v[16:31]
	v_mov_b32_e32 v33, s11
	v_or_b32_e32 v32, s10, v184
	v_lshlrev_b64 v[32:33], 6, v[32:33]
	v_lshl_add_u64 v[208:209], v[188:189], 0, v[32:33]
	s_waitcnt lgkmcnt(0)
	v_add_f32_e32 v58, v56, v57
	v_div_scale_f32 v59, s[10:11], v58, v58, 1.0
	v_mfma_f32_32x32x16_bf16 v[0:15], v[44:47], v[60:63], v[0:15]
	v_add_co_u32_e32 v44, vcc, s2, v206
	s_mov_b32 s2, 0x60000
	s_nop 0
	v_addc_co_u32_e32 v45, vcc, 0, v207, vcc
	v_add_co_u32_e32 v48, vcc, s2, v206
	s_movk_i32 s2, 0x2000
	s_nop 0
	v_addc_co_u32_e32 v49, vcc, 0, v207, vcc
	v_add_co_u32_e32 v60, vcc, s2, v208
	s_mov_b32 s2, 0x80000
	s_nop 0
	v_addc_co_u32_e32 v61, vcc, 0, v209, vcc
	v_rcp_f32_e32 v62, v59
	v_add_co_u32_e32 v52, vcc, s2, v206
	s_mov_b32 s2, 0xa0000
	s_nop 0
	v_addc_co_u32_e32 v53, vcc, 0, v207, vcc
	v_add_co_u32_e32 v56, vcc, s2, v206
	v_fma_f32 v63, -v59, v62, 1.0
	s_nop 0
	v_addc_co_u32_e32 v57, vcc, 0, v207, vcc
	v_fmac_f32_e32 v62, v63, v62
	v_div_scale_f32 v63, vcc, 1.0, v58, 1.0
	v_mul_f32_e32 v64, v63, v62
	v_fma_f32 v65, -v59, v64, v63
	v_fmac_f32_e32 v64, v65, v62
	v_fma_f32 v59, -v59, v64, v63
	v_div_fmas_f32 v59, v59, v62, v64
	v_div_fixup_f32 v68, v59, v58, 1.0
	ds_bpermute_b32 v69, v217, v68
	ds_bpermute_b32 v70, v236, v68
	global_load_dwordx4 v[32:35], v[206:207], off
	global_load_dwordx4 v[36:39], v[208:209], off
	s_nop 0
	global_load_dwordx4 v[40:43], v[40:41], off
	s_nop 0
	global_load_dwordx4 v[44:47], v[44:45], off
	s_waitcnt lgkmcnt(1)
	v_mul_f32_e32 v0, v0, v69
	v_mul_f32_e32 v16, v16, v69
	global_load_dwordx4 v[48:51], v[48:49], off
	s_nop 0
	global_load_dwordx4 v[52:55], v[52:53], off
	s_nop 0
	global_load_dwordx4 v[56:59], v[56:57], off
	s_nop 0
	global_load_dwordx4 v[64:67], v[60:61], off offset:-4096
	s_nop 0
	global_load_dwordx4 v[60:63], v[60:61], off
	ds_write2_b32 v235, v0, v16 offset1:32
	ds_bpermute_b32 v0, v219, v68
	s_waitcnt lgkmcnt(2)
	v_mul_f32_e32 v1, v1, v70
	v_mul_f32_e32 v16, v17, v70
	ds_write2_b32 v237, v1, v16 offset1:32
	ds_bpermute_b32 v1, v220, v68
	s_waitcnt lgkmcnt(2)
	v_mul_f32_e32 v2, v2, v0
	v_mul_f32_e32 v0, v18, v0
	v_add_u32_e32 v16, 0x110, v237
	ds_write2_b32 v16, v2, v0 offset1:32
	ds_bpermute_b32 v0, v221, v68
	s_waitcnt lgkmcnt(2)
	v_mul_f32_e32 v2, v3, v1
	v_mul_f32_e32 v1, v19, v1
	v_add_u32_e32 v3, 0x220, v237
	ds_write2_b32 v3, v2, v1 offset1:32
	ds_bpermute_b32 v1, v222, v68
	s_waitcnt lgkmcnt(2)
	v_mul_f32_e32 v2, v4, v0
	v_mul_f32_e32 v0, v20, v0
	v_add_u32_e32 v3, 0x770, v237
	ds_write2_b32 v3, v2, v0 offset1:32
	ds_bpermute_b32 v0, v223, v68
	s_waitcnt lgkmcnt(2)
	v_mul_f32_e32 v2, v5, v1
	v_mul_f32_e32 v1, v21, v1
	v_add_u32_e32 v3, 0x880, v237
	ds_write2_b32 v3, v2, v1 offset1:32
	ds_bpermute_b32 v1, v224, v68
	s_waitcnt lgkmcnt(2)
	v_mul_f32_e32 v2, v6, v0
	v_mul_f32_e32 v0, v22, v0
	v_add_u32_e32 v3, 0x990, v237
	ds_write2_b32 v3, v2, v0 offset1:32
	ds_bpermute_b32 v0, v225, v68
	s_waitcnt lgkmcnt(2)
	v_mul_f32_e32 v2, v7, v1
	v_mul_f32_e32 v1, v23, v1
	v_add_u32_e32 v3, 0xaa0, v237
	ds_write2_b32 v3, v2, v1 offset1:32
	ds_bpermute_b32 v1, v226, v68
	s_waitcnt lgkmcnt(2)
	v_mul_f32_e32 v2, v8, v0
	v_mul_f32_e32 v0, v24, v0
	v_add_u32_e32 v3, 0xff0, v237
	ds_write2_b32 v3, v2, v0 offset1:32
	ds_bpermute_b32 v0, v227, v68
	s_waitcnt lgkmcnt(2)
	v_mul_f32_e32 v2, v9, v1
	v_mul_f32_e32 v1, v25, v1
	v_add_u32_e32 v3, 0x1100, v237
	ds_write2_b32 v3, v2, v1 offset1:32
	ds_bpermute_b32 v1, v228, v68
	s_waitcnt lgkmcnt(2)
	v_mul_f32_e32 v2, v10, v0
	v_mul_f32_e32 v0, v26, v0
	v_add_u32_e32 v3, 0x1210, v237
	ds_write2_b32 v3, v2, v0 offset1:32
	ds_bpermute_b32 v0, v229, v68
	s_waitcnt lgkmcnt(2)
	v_mul_f32_e32 v2, v11, v1
	v_mul_f32_e32 v1, v27, v1
	v_add_u32_e32 v3, 0x1320, v237
	ds_write2_b32 v3, v2, v1 offset1:32
	ds_bpermute_b32 v1, v230, v68
	s_waitcnt lgkmcnt(2)
	v_mul_f32_e32 v2, v12, v0
	v_mul_f32_e32 v0, v28, v0
	ds_write2_b32 v211, v2, v0 offset1:32
	ds_bpermute_b32 v0, v231, v68
	ds_bpermute_b32 v3, v232, v68
	s_waitcnt lgkmcnt(3)
	v_mul_f32_e32 v2, v13, v1
	v_mul_f32_e32 v1, v29, v1
	ds_write2_b32 v251, v2, v1 offset1:32
	s_waitcnt lgkmcnt(2)
	v_mul_f32_e32 v1, v14, v0
	v_mul_f32_e32 v0, v30, v0
	ds_write2_b32 v244, v1, v0 offset1:32
	s_waitcnt lgkmcnt(2)
	v_mul_f32_e32 v0, v15, v3
	v_mul_f32_e32 v1, v31, v3
	v_or_b32_e32 v16, s9, v190
	v_mov_b64_e32 v[2:3], s[54:55]
	s_movk_i32 s2, 0xe00
	ds_write2_b32 v245, v0, v1 offset1:32
	v_mad_u64_u32 v[0:1], s[10:11], v16, s2, v[2:3]
	v_mov_b32_e32 v28, 0xe00
	s_mov_b32 s7, s77
	v_mad_i32_i24 v1, s8, v28, v1
	v_lshl_add_u64 v[0:1], v[0:1], 0, s[6:7]
	v_mov_b32_e32 v205, v179
	s_waitcnt lgkmcnt(0)
; #define LAS __attribute__((address_space(3)))
; __device__ __forceinline__ unsigned cvtpk(float lo, float hi) { f32x2_t v = {lo, hi}; bf16x2_t b = __builtin_convertvector(v, bf16x2_t); return __builtin_bit_cast(unsigned, b); }
; __device__ __forceinline__ float silu_f(float x) { return x / (1.0f + __expf(-x)); }
; __device__ __forceinline__ void mla_attn_phase(LAS unsigned char* lds, const bf16_t* q, const bf16_t* kv, const bf16_t* krope, const bf16_t* projb, bf16_t* y, int unit0, int G, int nu) {
;     ...
; #pragma unroll
;     for (int i = 0; i < 4; ++i) { const int row = i * 8 + (lane >> 3), c8 = lane & 7; const size_t tok = row0 + qb * 256 + w * 32 + row;
;         const f32x4 x0 = *(const LAS f32x4*)(stg + row * 68 + c8 * 8), x1 = *(const LAS f32x4*)(stg + row * 68 + c8 * 8 + 4);
;         const u32x4 g = *(const u32x4*)(projb + tok * B_INP + 672 + h * 64 + c8 * 8);
;         u32x4 yo; yo.x = cvtpk(x0[0] * silu_f(bf_lo(g.x)), x0[1] * silu_f(bf_hi(g.x))); yo.y = cvtpk(x0[2] * silu_f(bf_lo(g.y)), x0[3] * silu_f(bf_hi(g.y)));
;         yo.z = cvtpk(x1[0] * silu_f(bf_lo(g.z)), x1[1] * silu_f(bf_hi(g.z))); yo.w = cvtpk(x1[2] * silu_f(bf_lo(g.w)), x1[3] * silu_f(bf_hi(g.w)));
;         *(u32x4*)(y + tok * DM + h * 64 + c8 * 8) = yo; }
	v_lshl_add_u64 v[0:1], v[0:1], 0, v[204:205]
	v_or_b32_e32 v102, s9, v194
	v_mad_u64_u32 v[100:101], s[10:11], v102, s2, v[2:3]
	v_mad_i32_i24 v101, s8, v28, v101
	v_lshl_add_u64 v[100:101], v[100:101], 0, s[6:7]
	v_lshl_add_u64 v[100:101], v[100:101], 0, v[204:205]
	v_or_b32_e32 v106, s9, v196
	v_mad_u64_u32 v[104:105], s[10:11], v106, s2, v[2:3]
	v_mad_i32_i24 v105, s8, v28, v105
	v_lshl_add_u64 v[104:105], v[104:105], 0, s[6:7]
	v_lshl_add_u64 v[104:105], v[104:105], 0, v[204:205]
	v_or_b32_e32 v110, s9, v198
	v_mad_u64_u32 v[108:109], s[10:11], v110, s2, v[2:3]
	v_mad_i32_i24 v109, s8, v28, v109
	v_lshl_add_u64 v[108:109], v[108:109], 0, s[6:7]
	v_lshl_add_u64 v[108:109], v[108:109], 0, v[204:205]
	global_load_dwordx4 v[84:87], v[0:1], off offset:1344
	global_load_dwordx4 v[88:91], v[100:101], off offset:1344
	global_load_dwordx4 v[92:95], v[104:105], off offset:1344
	global_load_dwordx4 v[96:99], v[108:109], off offset:1344
	v_mov_b32_e32 v17, s8
	s_cmp_ge_i32 s3, s16
	s_waitcnt vmcnt(3)
	v_mov_b32_e32 v4, v84
	v_mov_b32_e32 v5, v85
	v_mov_b32_e32 v6, v86
	v_mov_b32_e32 v7, v87
	v_lshlrev_b32_e32 v22, 16, v4
	v_and_b32_e32 v4, 0xffff0000, v4
	v_mul_f32_e32 v0, 0xbfb8aa3b, v22
	v_exp_f32_e32 v8, v0
	v_mul_f32_e32 v0, 0xbfb8aa3b, v4
	v_exp_f32_e32 v9, v0
	v_and_b32_e32 v26, 0xffff0000, v5
	v_lshl_add_u64 v[0:1], v[192:193], 0, s[6:7]
	v_pk_add_f32 v[18:19], v[8:9], 1.0 op_sel_hi:[1,0]
	s_nop 0
	v_div_scale_f32 v20, s[10:11], v19, v19, v4
	v_rcp_f32_e32 v21, v20
	ds_read_b128 v[8:11], v250
	ds_read_b128 v[12:15], v250 offset:16
	v_fma_f32 v23, -v20, v21, 1.0
	v_fmac_f32_e32 v21, v23, v21
	v_div_scale_f32 v23, vcc, v4, v19, v4
	v_mul_f32_e32 v24, v23, v21
	v_fma_f32 v25, -v20, v24, v23
	v_fmac_f32_e32 v24, v25, v21
	v_fma_f32 v20, -v20, v24, v23
	v_div_scale_f32 v23, s[10:11], v18, v18, v22
	v_rcp_f32_e32 v25, v23
	v_div_fmas_f32 v20, v20, v21, v24
	v_div_fixup_f32 v19, v20, v19, v4
	v_div_scale_f32 v20, vcc, v22, v18, v22
	v_fma_f32 v4, -v23, v25, 1.0
	v_fmac_f32_e32 v25, v4, v25
	v_mul_f32_e32 v21, v20, v25
	v_fma_f32 v4, -v23, v21, v20
	v_lshlrev_b32_e32 v24, 16, v5
	v_fmac_f32_e32 v21, v4, v25
	v_mul_f32_e32 v4, 0xbfb8aa3b, v24
	v_mul_f32_e32 v5, 0xbfb8aa3b, v26
	v_exp_f32_e32 v4, v4
	v_exp_f32_e32 v5, v5
	v_fma_f32 v20, -v23, v21, v20
	v_div_fmas_f32 v23, v20, v25, v21
	v_div_fixup_f32 v18, v23, v18, v22
	v_pk_add_f32 v[20:21], v[4:5], 1.0 op_sel_hi:[1,0]
	s_waitcnt lgkmcnt(1)
	v_pk_mul_f32 v[4:5], v[8:9], v[18:19]
	v_div_scale_f32 v25, s[10:11], v21, v21, v26
	v_rcp_f32_e32 v27, v25
	v_cvt_pk_bf16_f32 v4, v4, v5
	v_div_scale_f32 v22, s[10:11], v20, v20, v24
	v_fma_f32 v5, -v25, v27, 1.0
	v_fmac_f32_e32 v27, v5, v27
	v_div_scale_f32 v5, vcc, v26, v21, v26
	v_mul_f32_e32 v8, v5, v27
	v_fma_f32 v9, -v25, v8, v5
	v_rcp_f32_e32 v23, v22
	v_fmac_f32_e32 v8, v9, v27
	v_fma_f32 v5, -v25, v8, v5
	v_div_fmas_f32 v5, v5, v27, v8
	v_div_fixup_f32 v9, v5, v21, v26
	v_fma_f32 v5, -v22, v23, 1.0
	v_fmac_f32_e32 v23, v5, v23
	v_div_scale_f32 v5, vcc, v24, v20, v24
	v_mul_f32_e32 v8, v5, v23
	v_fma_f32 v18, -v22, v8, v5
	v_lshlrev_b32_e32 v21, 16, v6
	v_and_b32_e32 v6, 0xffff0000, v6
	v_fmac_f32_e32 v8, v18, v23
	v_mul_f32_e32 v18, 0xbfb8aa3b, v21
	v_mul_f32_e32 v19, 0xbfb8aa3b, v6
	v_exp_f32_e32 v18, v18
	v_exp_f32_e32 v19, v19
	v_fma_f32 v5, -v22, v8, v5
	v_div_fmas_f32 v5, v5, v23, v8
	v_div_fixup_f32 v8, v5, v20, v24
	v_pk_add_f32 v[18:19], v[18:19], 1.0 op_sel_hi:[1,0]
	v_pk_mul_f32 v[8:9], v[10:11], v[8:9]
	v_div_scale_f32 v22, s[10:11], v19, v19, v6
	v_rcp_f32_e32 v23, v22
	v_cvt_pk_bf16_f32 v5, v8, v9
	v_lshlrev_b32_e32 v20, 16, v7
	v_fma_f32 v8, -v22, v23, 1.0
	v_fmac_f32_e32 v23, v8, v23
	v_div_scale_f32 v8, vcc, v6, v19, v6
	v_mul_f32_e32 v9, v8, v23
	v_fma_f32 v10, -v22, v9, v8
	v_fmac_f32_e32 v9, v10, v23
	v_div_scale_f32 v10, s[10:11], v18, v18, v21
	v_rcp_f32_e32 v11, v10
	v_fma_f32 v8, -v22, v9, v8
	v_div_fmas_f32 v8, v8, v23, v9
	v_div_fixup_f32 v9, v8, v19, v6
	v_fma_f32 v6, -v10, v11, 1.0
	v_fmac_f32_e32 v11, v6, v11
	v_div_scale_f32 v8, vcc, v21, v18, v21
	v_mul_f32_e32 v19, v8, v11
	v_fma_f32 v6, -v10, v19, v8
	v_and_b32_e32 v22, 0xffff0000, v7
	v_fmac_f32_e32 v19, v6, v11
	v_mul_f32_e32 v6, 0xbfb8aa3b, v20
	v_mul_f32_e32 v7, 0xbfb8aa3b, v22
	v_exp_f32_e32 v6, v6
	v_exp_f32_e32 v7, v7
	v_fma_f32 v8, -v10, v19, v8
	v_div_fmas_f32 v8, v8, v11, v19
	v_div_fixup_f32 v8, v8, v18, v21
	v_pk_add_f32 v[10:11], v[6:7], 1.0 op_sel_hi:[1,0]
	s_waitcnt lgkmcnt(0)
	v_pk_mul_f32 v[6:7], v[12:13], v[8:9]
	v_div_scale_f32 v19, s[10:11], v11, v11, v22
	v_rcp_f32_e32 v23, v19
	v_cvt_pk_bf16_f32 v6, v6, v7
	v_div_scale_f32 v12, s[10:11], v10, v10, v20
	v_fma_f32 v7, -v19, v23, 1.0
	v_fmac_f32_e32 v23, v7, v23
	v_div_scale_f32 v7, vcc, v22, v11, v22
	v_mul_f32_e32 v8, v7, v23
	v_fma_f32 v9, -v19, v8, v7
	v_rcp_f32_e32 v13, v12
	v_fmac_f32_e32 v8, v9, v23
	v_fma_f32 v7, -v19, v8, v7
	v_div_fmas_f32 v7, v7, v23, v8
	v_div_fixup_f32 v9, v7, v11, v22
	v_fma_f32 v7, -v12, v13, 1.0
	v_fmac_f32_e32 v13, v7, v13
	v_div_scale_f32 v7, vcc, v20, v10, v20
	v_mul_f32_e32 v8, v7, v13
	v_fma_f32 v11, -v12, v8, v7
	v_fmac_f32_e32 v8, v11, v13
	v_fma_f32 v7, -v12, v8, v7
	v_div_fmas_f32 v7, v7, v13, v8
	v_div_fixup_f32 v8, v7, v10, v20
	v_pk_mul_f32 v[8:9], v[14:15], v[8:9]
	s_nop 0
	v_cvt_pk_bf16_f32 v7, v8, v9
	v_lshlrev_b64 v[8:9], 11, v[16:17]
	v_lshl_add_u64 v[8:9], v[0:1], 0, v[8:9]
	v_or_b32_e32 v16, s9, v194
	global_store_dwordx4 v[8:9], v[4:7], off sc1
	s_nop 1
	v_mad_u64_u32 v[4:5], s[10:11], v16, s2, v[2:3]
	v_mad_i32_i24 v5, s8, v28, v5
	v_lshl_add_u64 v[4:5], v[4:5], 0, s[6:7]
	v_lshl_add_u64 v[4:5], v[4:5], 0, v[204:205]
	s_waitcnt vmcnt(3)
; #define LAS __attribute__((address_space(3)))
; __device__ __forceinline__ unsigned cvtpk(float lo, float hi) { f32x2_t v = {lo, hi}; bf16x2_t b = __builtin_convertvector(v, bf16x2_t); return __builtin_bit_cast(unsigned, b); }
; __device__ __forceinline__ float silu_f(float x) { return x / (1.0f + __expf(-x)); }
; __device__ __forceinline__ void mla_attn_phase(LAS unsigned char* lds, const bf16_t* q, const bf16_t* kv, const bf16_t* krope, const bf16_t* projb, bf16_t* y, int unit0, int G, int nu) {
;     ...
; #pragma unroll
;     for (int i = 0; i < 4; ++i) { const int row = i * 8 + (lane >> 3), c8 = lane & 7; const size_t tok = row0 + qb * 256 + w * 32 + row;
;         const f32x4 x0 = *(const LAS f32x4*)(stg + row * 68 + c8 * 8), x1 = *(const LAS f32x4*)(stg + row * 68 + c8 * 8 + 4);
;         const u32x4 g = *(const u32x4*)(projb + tok * B_INP + 672 + h * 64 + c8 * 8);
;         u32x4 yo; yo.x = cvtpk(x0[0] * silu_f(bf_lo(g.x)), x0[1] * silu_f(bf_hi(g.x))); yo.y = cvtpk(x0[2] * silu_f(bf_lo(g.y)), x0[3] * silu_f(bf_hi(g.y)));
;         yo.z = cvtpk(x1[0] * silu_f(bf_lo(g.z)), x1[1] * silu_f(bf_hi(g.z))); yo.w = cvtpk(x1[2] * silu_f(bf_lo(g.w)), x1[3] * silu_f(bf_hi(g.w)));
;         *(u32x4*)(y + tok * DM + h * 64 + c8 * 8) = yo; }
	v_mov_b32_e32 v4, v88
	v_mov_b32_e32 v5, v89
	v_mov_b32_e32 v6, v90
	v_mov_b32_e32 v7, v91
	v_lshlrev_b32_e32 v22, 16, v4
	v_and_b32_e32 v4, 0xffff0000, v4
	v_mul_f32_e32 v8, 0xbfb8aa3b, v22
	v_mul_f32_e32 v9, 0xbfb8aa3b, v4
	v_exp_f32_e32 v8, v8
	v_exp_f32_e32 v9, v9
	v_and_b32_e32 v26, 0xffff0000, v5
	v_pk_add_f32 v[18:19], v[8:9], 1.0 op_sel_hi:[1,0]
	s_nop 0
	v_div_scale_f32 v20, s[10:11], v19, v19, v4
	v_rcp_f32_e32 v21, v20
	ds_read_b128 v[8:11], v250 offset:2176
	ds_read_b128 v[12:15], v250 offset:2192
	v_fma_f32 v23, -v20, v21, 1.0
	v_fmac_f32_e32 v21, v23, v21
	v_div_scale_f32 v23, vcc, v4, v19, v4
	v_mul_f32_e32 v24, v23, v21
	v_fma_f32 v25, -v20, v24, v23
	v_fmac_f32_e32 v24, v25, v21
	v_fma_f32 v20, -v20, v24, v23
	v_div_scale_f32 v23, s[10:11], v18, v18, v22
	v_rcp_f32_e32 v25, v23
	v_div_fmas_f32 v20, v20, v21, v24
	v_div_fixup_f32 v19, v20, v19, v4
	v_div_scale_f32 v20, vcc, v22, v18, v22
	v_fma_f32 v4, -v23, v25, 1.0
	v_fmac_f32_e32 v25, v4, v25
	v_mul_f32_e32 v21, v20, v25
	v_fma_f32 v4, -v23, v21, v20
	v_lshlrev_b32_e32 v24, 16, v5
	v_fmac_f32_e32 v21, v4, v25
	v_mul_f32_e32 v4, 0xbfb8aa3b, v24
	v_mul_f32_e32 v5, 0xbfb8aa3b, v26
	v_exp_f32_e32 v4, v4
	v_exp_f32_e32 v5, v5
	v_fma_f32 v20, -v23, v21, v20
	v_div_fmas_f32 v23, v20, v25, v21
	v_div_fixup_f32 v18, v23, v18, v22
	v_pk_add_f32 v[20:21], v[4:5], 1.0 op_sel_hi:[1,0]
	s_waitcnt lgkmcnt(1)
	v_pk_mul_f32 v[4:5], v[8:9], v[18:19]
	v_div_scale_f32 v25, s[10:11], v21, v21, v26
	v_rcp_f32_e32 v27, v25
	v_cvt_pk_bf16_f32 v4, v4, v5
	v_div_scale_f32 v22, s[10:11], v20, v20, v24
	v_fma_f32 v5, -v25, v27, 1.0
	v_fmac_f32_e32 v27, v5, v27
	v_div_scale_f32 v5, vcc, v26, v21, v26
	v_mul_f32_e32 v8, v5, v27
	v_fma_f32 v9, -v25, v8, v5
	v_rcp_f32_e32 v23, v22
	v_fmac_f32_e32 v8, v9, v27
	v_fma_f32 v5, -v25, v8, v5
	v_div_fmas_f32 v5, v5, v27, v8
	v_div_fixup_f32 v9, v5, v21, v26
	v_fma_f32 v5, -v22, v23, 1.0
	v_fmac_f32_e32 v23, v5, v23
	v_div_scale_f32 v5, vcc, v24, v20, v24
	v_mul_f32_e32 v8, v5, v23
	v_fma_f32 v18, -v22, v8, v5
	v_lshlrev_b32_e32 v21, 16, v6
	v_and_b32_e32 v6, 0xffff0000, v6
	v_fmac_f32_e32 v8, v18, v23
	v_mul_f32_e32 v18, 0xbfb8aa3b, v21
	v_mul_f32_e32 v19, 0xbfb8aa3b, v6
	v_exp_f32_e32 v18, v18
	v_exp_f32_e32 v19, v19
	v_fma_f32 v5, -v22, v8, v5
	v_div_fmas_f32 v5, v5, v23, v8
	v_div_fixup_f32 v8, v5, v20, v24
	v_pk_add_f32 v[18:19], v[18:19], 1.0 op_sel_hi:[1,0]
	v_pk_mul_f32 v[8:9], v[10:11], v[8:9]
	v_div_scale_f32 v22, s[10:11], v19, v19, v6
	v_rcp_f32_e32 v23, v22
	v_cvt_pk_bf16_f32 v5, v8, v9
	v_lshlrev_b32_e32 v20, 16, v7
	v_fma_f32 v8, -v22, v23, 1.0
	v_fmac_f32_e32 v23, v8, v23
	v_div_scale_f32 v8, vcc, v6, v19, v6
	v_mul_f32_e32 v9, v8, v23
	v_fma_f32 v10, -v22, v9, v8
	v_fmac_f32_e32 v9, v10, v23
	v_div_scale_f32 v10, s[10:11], v18, v18, v21
	v_rcp_f32_e32 v11, v10
	v_fma_f32 v8, -v22, v9, v8
	v_div_fmas_f32 v8, v8, v23, v9
	v_div_fixup_f32 v9, v8, v19, v6
	v_fma_f32 v6, -v10, v11, 1.0
	v_fmac_f32_e32 v11, v6, v11
	v_div_scale_f32 v8, vcc, v21, v18, v21
	v_mul_f32_e32 v19, v8, v11
	v_fma_f32 v6, -v10, v19, v8
	v_and_b32_e32 v22, 0xffff0000, v7
	v_fmac_f32_e32 v19, v6, v11
	v_mul_f32_e32 v6, 0xbfb8aa3b, v20
	v_mul_f32_e32 v7, 0xbfb8aa3b, v22
	v_exp_f32_e32 v6, v6
	v_exp_f32_e32 v7, v7
	v_fma_f32 v8, -v10, v19, v8
	v_div_fmas_f32 v8, v8, v11, v19
	v_div_fixup_f32 v8, v8, v18, v21
	v_pk_add_f32 v[10:11], v[6:7], 1.0 op_sel_hi:[1,0]
	s_waitcnt lgkmcnt(0)
	v_pk_mul_f32 v[6:7], v[12:13], v[8:9]
	v_div_scale_f32 v19, s[10:11], v11, v11, v22
	v_rcp_f32_e32 v23, v19
	v_cvt_pk_bf16_f32 v6, v6, v7
	v_div_scale_f32 v12, s[10:11], v10, v10, v20
	v_fma_f32 v7, -v19, v23, 1.0
	v_fmac_f32_e32 v23, v7, v23
	v_div_scale_f32 v7, vcc, v22, v11, v22
	v_mul_f32_e32 v8, v7, v23
	v_fma_f32 v9, -v19, v8, v7
	v_rcp_f32_e32 v13, v12
	v_fmac_f32_e32 v8, v9, v23
	v_fma_f32 v7, -v19, v8, v7
	v_div_fmas_f32 v7, v7, v23, v8
	v_div_fixup_f32 v9, v7, v11, v22
	v_fma_f32 v7, -v12, v13, 1.0
	v_fmac_f32_e32 v13, v7, v13
	v_div_scale_f32 v7, vcc, v20, v10, v20
	v_mul_f32_e32 v8, v7, v13
	v_fma_f32 v11, -v12, v8, v7
	v_fmac_f32_e32 v8, v11, v13
	v_fma_f32 v7, -v12, v8, v7
	v_div_fmas_f32 v7, v7, v13, v8
	v_div_fixup_f32 v8, v7, v10, v20
	v_pk_mul_f32 v[8:9], v[14:15], v[8:9]
	s_nop 0
	v_cvt_pk_bf16_f32 v7, v8, v9
	v_lshlrev_b64 v[8:9], 11, v[16:17]
	v_lshl_add_u64 v[8:9], v[0:1], 0, v[8:9]
	v_or_b32_e32 v16, s9, v196
	global_store_dwordx4 v[8:9], v[4:7], off sc1
	s_nop 1
	v_mad_u64_u32 v[4:5], s[10:11], v16, s2, v[2:3]
	v_mad_i32_i24 v5, s8, v28, v5
	v_lshl_add_u64 v[4:5], v[4:5], 0, s[6:7]
	v_lshl_add_u64 v[4:5], v[4:5], 0, v[204:205]
	s_waitcnt vmcnt(3)
	v_mov_b32_e32 v4, v92
	v_mov_b32_e32 v5, v93
	v_mov_b32_e32 v6, v94
	v_mov_b32_e32 v7, v95
	v_lshlrev_b32_e32 v22, 16, v4
	v_and_b32_e32 v4, 0xffff0000, v4
	v_mul_f32_e32 v8, 0xbfb8aa3b, v22
	v_mul_f32_e32 v9, 0xbfb8aa3b, v4
	v_exp_f32_e32 v8, v8
	v_exp_f32_e32 v9, v9
	v_and_b32_e32 v26, 0xffff0000, v5
	v_pk_add_f32 v[18:19], v[8:9], 1.0 op_sel_hi:[1,0]
	s_nop 0
	v_div_scale_f32 v20, s[10:11], v19, v19, v4
	v_rcp_f32_e32 v21, v20
	ds_read_b128 v[8:11], v250 offset:4352
	ds_read_b128 v[12:15], v250 offset:4368
	v_fma_f32 v23, -v20, v21, 1.0
	v_fmac_f32_e32 v21, v23, v21
	v_div_scale_f32 v23, vcc, v4, v19, v4
	v_mul_f32_e32 v24, v23, v21
	v_fma_f32 v25, -v20, v24, v23
	v_fmac_f32_e32 v24, v25, v21
	v_fma_f32 v20, -v20, v24, v23
	v_div_scale_f32 v23, s[10:11], v18, v18, v22
	v_rcp_f32_e32 v25, v23
	v_div_fmas_f32 v20, v20, v21, v24
	v_div_fixup_f32 v19, v20, v19, v4
	v_div_scale_f32 v20, vcc, v22, v18, v22
	v_fma_f32 v4, -v23, v25, 1.0
	v_fmac_f32_e32 v25, v4, v25
	v_mul_f32_e32 v21, v20, v25
	v_fma_f32 v4, -v23, v21, v20
	v_lshlrev_b32_e32 v24, 16, v5
	v_fmac_f32_e32 v21, v4, v25
	v_mul_f32_e32 v4, 0xbfb8aa3b, v24
	v_mul_f32_e32 v5, 0xbfb8aa3b, v26
	v_exp_f32_e32 v4, v4
	v_exp_f32_e32 v5, v5
	v_fma_f32 v20, -v23, v21, v20
	v_div_fmas_f32 v23, v20, v25, v21
	v_div_fixup_f32 v18, v23, v18, v22
	v_pk_add_f32 v[20:21], v[4:5], 1.0 op_sel_hi:[1,0]
	s_waitcnt lgkmcnt(1)
; #define LAS __attribute__((address_space(3)))
; __device__ __forceinline__ unsigned cvtpk(float lo, float hi) { f32x2_t v = {lo, hi}; bf16x2_t b = __builtin_convertvector(v, bf16x2_t); return __builtin_bit_cast(unsigned, b); }
; __device__ __forceinline__ float silu_f(float x) { return x / (1.0f + __expf(-x)); }
; __device__ __forceinline__ void mla_attn_phase(LAS unsigned char* lds, const bf16_t* q, const bf16_t* kv, const bf16_t* krope, const bf16_t* projb, bf16_t* y, int unit0, int G, int nu) {
;     ...
; #pragma unroll
;     for (int i = 0; i < 4; ++i) { const int row = i * 8 + (lane >> 3), c8 = lane & 7; const size_t tok = row0 + qb * 256 + w * 32 + row;
;         const f32x4 x0 = *(const LAS f32x4*)(stg + row * 68 + c8 * 8), x1 = *(const LAS f32x4*)(stg + row * 68 + c8 * 8 + 4);
;         const u32x4 g = *(const u32x4*)(projb + tok * B_INP + 672 + h * 64 + c8 * 8);
;         u32x4 yo; yo.x = cvtpk(x0[0] * silu_f(bf_lo(g.x)), x0[1] * silu_f(bf_hi(g.x))); yo.y = cvtpk(x0[2] * silu_f(bf_lo(g.y)), x0[3] * silu_f(bf_hi(g.y)));
;         yo.z = cvtpk(x1[0] * silu_f(bf_lo(g.z)), x1[1] * silu_f(bf_hi(g.z))); yo.w = cvtpk(x1[2] * silu_f(bf_lo(g.w)), x1[3] * silu_f(bf_hi(g.w)));
;         *(u32x4*)(y + tok * DM + h * 64 + c8 * 8) = yo; }
	v_pk_mul_f32 v[4:5], v[8:9], v[18:19]
	v_div_scale_f32 v25, s[10:11], v21, v21, v26
	v_rcp_f32_e32 v27, v25
	v_cvt_pk_bf16_f32 v4, v4, v5
	v_div_scale_f32 v22, s[10:11], v20, v20, v24
	v_fma_f32 v5, -v25, v27, 1.0
	v_fmac_f32_e32 v27, v5, v27
	v_div_scale_f32 v5, vcc, v26, v21, v26
	v_mul_f32_e32 v8, v5, v27
	v_fma_f32 v9, -v25, v8, v5
	v_rcp_f32_e32 v23, v22
	v_fmac_f32_e32 v8, v9, v27
	v_fma_f32 v5, -v25, v8, v5
	v_div_fmas_f32 v5, v5, v27, v8
	v_div_fixup_f32 v9, v5, v21, v26
	v_fma_f32 v5, -v22, v23, 1.0
	v_fmac_f32_e32 v23, v5, v23
	v_div_scale_f32 v5, vcc, v24, v20, v24
	v_mul_f32_e32 v8, v5, v23
	v_fma_f32 v18, -v22, v8, v5
	v_lshlrev_b32_e32 v21, 16, v6
	v_and_b32_e32 v6, 0xffff0000, v6
	v_fmac_f32_e32 v8, v18, v23
	v_mul_f32_e32 v18, 0xbfb8aa3b, v21
	v_mul_f32_e32 v19, 0xbfb8aa3b, v6
	v_exp_f32_e32 v18, v18
	v_exp_f32_e32 v19, v19
	v_fma_f32 v5, -v22, v8, v5
	v_div_fmas_f32 v5, v5, v23, v8
	v_div_fixup_f32 v8, v5, v20, v24
	v_pk_add_f32 v[18:19], v[18:19], 1.0 op_sel_hi:[1,0]
	v_pk_mul_f32 v[8:9], v[10:11], v[8:9]
	v_div_scale_f32 v22, s[10:11], v19, v19, v6
	v_rcp_f32_e32 v23, v22
	v_cvt_pk_bf16_f32 v5, v8, v9
	v_lshlrev_b32_e32 v20, 16, v7
	v_fma_f32 v8, -v22, v23, 1.0
	v_fmac_f32_e32 v23, v8, v23
	v_div_scale_f32 v8, vcc, v6, v19, v6
	v_mul_f32_e32 v9, v8, v23
	v_fma_f32 v10, -v22, v9, v8
	v_fmac_f32_e32 v9, v10, v23
	v_div_scale_f32 v10, s[10:11], v18, v18, v21
	v_rcp_f32_e32 v11, v10
	v_fma_f32 v8, -v22, v9, v8
	v_div_fmas_f32 v8, v8, v23, v9
	v_div_fixup_f32 v9, v8, v19, v6
	v_fma_f32 v6, -v10, v11, 1.0
	v_fmac_f32_e32 v11, v6, v11
	v_div_scale_f32 v8, vcc, v21, v18, v21
	v_mul_f32_e32 v19, v8, v11
	v_fma_f32 v6, -v10, v19, v8
	v_and_b32_e32 v22, 0xffff0000, v7
	v_fmac_f32_e32 v19, v6, v11
	v_mul_f32_e32 v6, 0xbfb8aa3b, v20
	v_mul_f32_e32 v7, 0xbfb8aa3b, v22
	v_exp_f32_e32 v6, v6
	v_exp_f32_e32 v7, v7
	v_fma_f32 v8, -v10, v19, v8
	v_div_fmas_f32 v8, v8, v11, v19
	v_div_fixup_f32 v8, v8, v18, v21
	v_pk_add_f32 v[10:11], v[6:7], 1.0 op_sel_hi:[1,0]
	s_waitcnt lgkmcnt(0)
	v_pk_mul_f32 v[6:7], v[12:13], v[8:9]
	v_div_scale_f32 v19, s[10:11], v11, v11, v22
	v_rcp_f32_e32 v23, v19
	v_cvt_pk_bf16_f32 v6, v6, v7
	v_div_scale_f32 v12, s[10:11], v10, v10, v20
	v_fma_f32 v7, -v19, v23, 1.0
	v_fmac_f32_e32 v23, v7, v23
	v_div_scale_f32 v7, vcc, v22, v11, v22
	v_mul_f32_e32 v8, v7, v23
	v_fma_f32 v9, -v19, v8, v7
	v_rcp_f32_e32 v13, v12
	v_fmac_f32_e32 v8, v9, v23
	v_fma_f32 v7, -v19, v8, v7
	v_div_fmas_f32 v7, v7, v23, v8
	v_div_fixup_f32 v9, v7, v11, v22
	v_fma_f32 v7, -v12, v13, 1.0
	v_fmac_f32_e32 v13, v7, v13
	v_div_scale_f32 v7, vcc, v20, v10, v20
	v_mul_f32_e32 v8, v7, v13
	v_fma_f32 v11, -v12, v8, v7
	v_fmac_f32_e32 v8, v11, v13
	v_fma_f32 v7, -v12, v8, v7
	v_div_fmas_f32 v7, v7, v13, v8
	v_div_fixup_f32 v8, v7, v10, v20
	v_pk_mul_f32 v[8:9], v[14:15], v[8:9]
	v_or_b32_e32 v14, s9, v198
	v_mad_u64_u32 v[2:3], s[10:11], v14, s2, v[2:3]
	v_cvt_pk_bf16_f32 v7, v8, v9
	v_lshlrev_b64 v[8:9], 11, v[16:17]
	v_mad_i32_i24 v3, s8, v28, v3
	v_lshl_add_u64 v[8:9], v[0:1], 0, v[8:9]
	v_lshl_add_u64 v[2:3], v[2:3], 0, s[6:7]
	global_store_dwordx4 v[8:9], v[4:7], off sc1
	v_lshl_add_u64 v[2:3], v[2:3], 0, v[204:205]
	v_mov_b32_e32 v15, s8
	s_mov_b32 s2, s3
	s_waitcnt vmcnt(3)
; #define LAS __attribute__((address_space(3)))
; __device__ __forceinline__ unsigned cvtpk(float lo, float hi) { f32x2_t v = {lo, hi}; bf16x2_t b = __builtin_convertvector(v, bf16x2_t); return __builtin_bit_cast(unsigned, b); }
; __device__ __forceinline__ float silu_f(float x) { return x / (1.0f + __expf(-x)); }
; __device__ __forceinline__ void mla_attn_phase(LAS unsigned char* lds, const bf16_t* q, const bf16_t* kv, const bf16_t* krope, const bf16_t* projb, bf16_t* y, int unit0, int G, int nu) {
;     ...
; #pragma unroll
;     for (int i = 0; i < 4; ++i) { const int row = i * 8 + (lane >> 3), c8 = lane & 7; const size_t tok = row0 + qb * 256 + w * 32 + row;
;         const f32x4 x0 = *(const LAS f32x4*)(stg + row * 68 + c8 * 8), x1 = *(const LAS f32x4*)(stg + row * 68 + c8 * 8 + 4);
;         const u32x4 g = *(const u32x4*)(projb + tok * B_INP + 672 + h * 64 + c8 * 8);
;         u32x4 yo; yo.x = cvtpk(x0[0] * silu_f(bf_lo(g.x)), x0[1] * silu_f(bf_hi(g.x))); yo.y = cvtpk(x0[2] * silu_f(bf_lo(g.y)), x0[3] * silu_f(bf_hi(g.y)));
;         yo.z = cvtpk(x1[0] * silu_f(bf_lo(g.z)), x1[1] * silu_f(bf_hi(g.z))); yo.w = cvtpk(x1[2] * silu_f(bf_lo(g.w)), x1[3] * silu_f(bf_hi(g.w)));
;         *(u32x4*)(y + tok * DM + h * 64 + c8 * 8) = yo; }
;     __syncthreads();
;     if (!more) break;
	v_mov_b32_e32 v2, v96
	v_mov_b32_e32 v3, v97
	v_mov_b32_e32 v4, v98
	v_mov_b32_e32 v5, v99
	v_lshlrev_b32_e32 v20, 16, v2
	v_and_b32_e32 v2, 0xffff0000, v2
	v_mul_f32_e32 v6, 0xbfb8aa3b, v20
	v_mul_f32_e32 v7, 0xbfb8aa3b, v2
	v_exp_f32_e32 v6, v6
	v_exp_f32_e32 v7, v7
	v_and_b32_e32 v24, 0xffff0000, v3
	v_pk_add_f32 v[16:17], v[6:7], 1.0 op_sel_hi:[1,0]
	s_nop 0
	v_div_scale_f32 v18, s[6:7], v17, v17, v2
	v_rcp_f32_e32 v19, v18
	ds_read_b128 v[6:9], v250 offset:6528
	ds_read_b128 v[10:13], v250 offset:6544
	v_fma_f32 v21, -v18, v19, 1.0
	v_fmac_f32_e32 v19, v21, v19
	v_div_scale_f32 v21, vcc, v2, v17, v2
	v_mul_f32_e32 v22, v21, v19
	v_fma_f32 v23, -v18, v22, v21
	v_fmac_f32_e32 v22, v23, v19
	v_fma_f32 v18, -v18, v22, v21
	v_div_scale_f32 v21, s[6:7], v16, v16, v20
	v_rcp_f32_e32 v23, v21
	v_div_fmas_f32 v18, v18, v19, v22
	v_div_fixup_f32 v17, v18, v17, v2
	v_div_scale_f32 v18, vcc, v20, v16, v20
	v_fma_f32 v2, -v21, v23, 1.0
	v_fmac_f32_e32 v23, v2, v23
	v_mul_f32_e32 v19, v18, v23
	v_fma_f32 v2, -v21, v19, v18
	v_lshlrev_b32_e32 v22, 16, v3
	v_fmac_f32_e32 v19, v2, v23
	v_mul_f32_e32 v2, 0xbfb8aa3b, v22
	v_mul_f32_e32 v3, 0xbfb8aa3b, v24
	v_exp_f32_e32 v2, v2
	v_exp_f32_e32 v3, v3
	v_fma_f32 v18, -v21, v19, v18
	v_div_fmas_f32 v21, v18, v23, v19
	v_div_fixup_f32 v16, v21, v16, v20
	v_pk_add_f32 v[18:19], v[2:3], 1.0 op_sel_hi:[1,0]
	s_waitcnt lgkmcnt(1)
	v_pk_mul_f32 v[2:3], v[6:7], v[16:17]
	v_div_scale_f32 v23, s[6:7], v19, v19, v24
	v_rcp_f32_e32 v25, v23
	v_cvt_pk_bf16_f32 v2, v2, v3
	v_div_scale_f32 v20, s[6:7], v18, v18, v22
	v_fma_f32 v3, -v23, v25, 1.0
	v_fmac_f32_e32 v25, v3, v25
	v_div_scale_f32 v3, vcc, v24, v19, v24
	v_mul_f32_e32 v6, v3, v25
	v_fma_f32 v7, -v23, v6, v3
	v_rcp_f32_e32 v21, v20
	v_fmac_f32_e32 v6, v7, v25
	v_fma_f32 v3, -v23, v6, v3
	v_div_fmas_f32 v3, v3, v25, v6
	v_div_fixup_f32 v7, v3, v19, v24
	v_fma_f32 v3, -v20, v21, 1.0
	v_fmac_f32_e32 v21, v3, v21
	v_div_scale_f32 v3, vcc, v22, v18, v22
	v_mul_f32_e32 v6, v3, v21
	v_fma_f32 v16, -v20, v6, v3
	v_lshlrev_b32_e32 v19, 16, v4
	v_and_b32_e32 v4, 0xffff0000, v4
	v_fmac_f32_e32 v6, v16, v21
	v_mul_f32_e32 v16, 0xbfb8aa3b, v19
	v_mul_f32_e32 v17, 0xbfb8aa3b, v4
	v_exp_f32_e32 v16, v16
	v_exp_f32_e32 v17, v17
	v_fma_f32 v3, -v20, v6, v3
	v_div_fmas_f32 v3, v3, v21, v6
	v_div_fixup_f32 v6, v3, v18, v22
	v_pk_add_f32 v[16:17], v[16:17], 1.0 op_sel_hi:[1,0]
	v_pk_mul_f32 v[6:7], v[8:9], v[6:7]
	v_div_scale_f32 v20, s[6:7], v17, v17, v4
	v_rcp_f32_e32 v21, v20
	v_cvt_pk_bf16_f32 v3, v6, v7
	v_lshlrev_b32_e32 v18, 16, v5
	v_fma_f32 v6, -v20, v21, 1.0
	v_fmac_f32_e32 v21, v6, v21
	v_div_scale_f32 v6, vcc, v4, v17, v4
	v_mul_f32_e32 v7, v6, v21
	v_fma_f32 v8, -v20, v7, v6
	v_fmac_f32_e32 v7, v8, v21
	v_div_scale_f32 v8, s[6:7], v16, v16, v19
	v_rcp_f32_e32 v9, v8
	v_fma_f32 v6, -v20, v7, v6
	v_div_fmas_f32 v6, v6, v21, v7
	v_div_fixup_f32 v7, v6, v17, v4
	v_fma_f32 v4, -v8, v9, 1.0
	v_fmac_f32_e32 v9, v4, v9
	v_div_scale_f32 v6, vcc, v19, v16, v19
	v_mul_f32_e32 v17, v6, v9
	v_fma_f32 v4, -v8, v17, v6
	v_and_b32_e32 v20, 0xffff0000, v5
	v_fmac_f32_e32 v17, v4, v9
	v_mul_f32_e32 v4, 0xbfb8aa3b, v18
	v_mul_f32_e32 v5, 0xbfb8aa3b, v20
	v_exp_f32_e32 v4, v4
	v_exp_f32_e32 v5, v5
	v_fma_f32 v6, -v8, v17, v6
	v_div_fmas_f32 v6, v6, v9, v17
	v_div_fixup_f32 v6, v6, v16, v19
	v_pk_add_f32 v[8:9], v[4:5], 1.0 op_sel_hi:[1,0]
	s_waitcnt lgkmcnt(0)
	v_pk_mul_f32 v[4:5], v[10:11], v[6:7]
	v_div_scale_f32 v17, s[6:7], v9, v9, v20
	v_rcp_f32_e32 v21, v17
	v_cvt_pk_bf16_f32 v4, v4, v5
	v_div_scale_f32 v10, s[6:7], v8, v8, v18
	v_fma_f32 v5, -v17, v21, 1.0
	v_fmac_f32_e32 v21, v5, v21
	v_div_scale_f32 v5, vcc, v20, v9, v20
	v_mul_f32_e32 v6, v5, v21
	v_fma_f32 v7, -v17, v6, v5
	v_rcp_f32_e32 v11, v10
	v_fmac_f32_e32 v6, v7, v21
	v_fma_f32 v5, -v17, v6, v5
	v_div_fmas_f32 v5, v5, v21, v6
	v_div_fixup_f32 v7, v5, v9, v20
	v_fma_f32 v5, -v10, v11, 1.0
	v_fmac_f32_e32 v11, v5, v11
	v_div_scale_f32 v5, vcc, v18, v8, v18
	v_mul_f32_e32 v6, v5, v11
	v_fma_f32 v9, -v10, v6, v5
	v_fmac_f32_e32 v6, v9, v11
	v_fma_f32 v5, -v10, v6, v5
	v_div_fmas_f32 v5, v5, v11, v6
	v_div_fixup_f32 v6, v5, v8, v18
	v_pk_mul_f32 v[6:7], v[12:13], v[6:7]
	s_nop 0
	v_cvt_pk_bf16_f32 v5, v6, v7
	v_lshlrev_b64 v[6:7], 11, v[14:15]
	v_lshl_add_u64 v[0:1], v[0:1], 0, v[6:7]
	global_store_dwordx4 v[0:1], v[2:5], off sc1
	s_barrier
	s_cbranch_scc1 .LBB0_211

; __device__ __forceinline__ unsigned cvtpk(float lo, float hi) { f32x2_t v = {lo, hi}; bf16x2_t b = __builtin_convertvector(v, bf16x2_t); return __builtin_bit_cast(unsigned, b); }
; __device__ __forceinline__ void mla_prep_phase(const bf16_t* projb, const float* gq, const float* gkv, const float* cs, bf16_t* cqn, bf16_t* ckvn, bf16_t* krope, int rows) {
;     ...
;             u32x4 oa; oa.x = cvtpk(xa[0] * ra * gA0[0], xa[1] * ra * gA0[1]); oa.y = cvtpk(xa[2] * ra * gA0[2], xa[3] * ra * gA0[3]);
;             oa.z = cvtpk(xa[4] * ra * gA1[0], xa[5] * ra * gA1[1]); oa.w = cvtpk(xa[6] * ra * gA1[2], xa[7] * ra * gA1[3]);
;             if (aq) *(u32x4*)(cqn + (size_t)m * 384 + 8 * lane) = oa; else *(u32x4*)(ckvn + (size_t)m * 256 + 8 * (lane - 48)) = oa;
;             if (lane < 16) { u32x4 ob; ob.x = cvtpk(xb[0] * rkv * gB0[0], xb[1] * rkv * gB0[1]); ob.y = cvtpk(xb[2] * rkv * gB0[2], xb[3] * rkv * gB0[3]);
;                 ob.z = cvtpk(xb[4] * rkv * gB1[0], xb[5] * rkv * gB1[1]); ob.w = cvtpk(xb[6] * rkv * gB1[2], xb[7] * rkv * gB1[3]);
;                 *(u32x4*)(ckvn + (size_t)m * 256 + 8 * (16 + lane)) = ob;
;                 const float x1 = bf1(r1[r]), x2 = bf1(r2[r]);
;                 *(unsigned*)(krope + (size_t)m * 32 + 2 * lane) = cvtpk(x1 * cc[r] - x2 * sn[r], x1 * sn[r] + x2 * cc[r]); } }
.LBB0_220:
	v_pk_mul_f32 v[42:43], v[88:89], v[84:85] op_sel_hi:[0,1]
	v_pk_mul_f32 v[42:43], v[0:1], v[42:43]
	s_nop 0
	v_cvt_pk_bf16_f32 v84, v42, v43
	v_pk_mul_f32 v[42:43], v[88:89], v[82:83] op_sel_hi:[0,1]
	v_pk_mul_f32 v[42:43], v[2:3], v[42:43]
	s_nop 0
	v_cvt_pk_bf16_f32 v85, v42, v43
	v_pk_mul_f32 v[42:43], v[88:89], v[80:81] op_sel_hi:[0,1]
	v_pk_mul_f32 v[42:43], v[4:5], v[42:43]
	s_nop 0
	v_cvt_pk_bf16_f32 v86, v42, v43
	v_pk_mul_f32 v[42:43], v[88:89], v[78:79] op_sel_hi:[0,1]
	v_pk_mul_f32 v[42:43], v[6:7], v[42:43]
	s_nop 0
	v_cvt_pk_bf16_f32 v87, v42, v43
	s_waitcnt vmcnt(20)
	v_lshlrev_b32_e32 v43, 16, v77
	v_lshlrev_b32_e32 v42, 16, v75
	s_waitcnt vmcnt(18)
	v_pk_mul_f32 v[76:77], v[76:77], v[42:43] op_sel:[0,1] op_sel_hi:[0,0]
	v_pk_fma_f32 v[78:79], v[74:75], v[42:43], v[76:77] neg_lo:[0,0,1] neg_hi:[0,0,1]
	v_pk_fma_f32 v[42:43], v[74:75], v[42:43], v[76:77] op_sel_hi:[0,1,1]
	v_cvt_pk_bf16_f32 v42, v78, v43
	global_store_dwordx4 v[44:45], v[84:87], off offset:-512 sc1
	global_store_dword v[40:41], v42, off offset:-128 sc1

; __device__ __forceinline__ unsigned cvtpk(float lo, float hi) { f32x2_t v = {lo, hi}; bf16x2_t b = __builtin_convertvector(v, bf16x2_t); return __builtin_bit_cast(unsigned, b); }
; __device__ __forceinline__ void mla_prep_phase(const bf16_t* projb, const float* gq, const float* gkv, const float* cs, bf16_t* cqn, bf16_t* ckvn, bf16_t* krope, int rows) {
;     ...
;             u32x4 oa; oa.x = cvtpk(xa[0] * ra * gA0[0], xa[1] * ra * gA0[1]); oa.y = cvtpk(xa[2] * ra * gA0[2], xa[3] * ra * gA0[3]);
;             oa.z = cvtpk(xa[4] * ra * gA1[0], xa[5] * ra * gA1[1]); oa.w = cvtpk(xa[6] * ra * gA1[2], xa[7] * ra * gA1[3]);
;             if (aq) *(u32x4*)(cqn + (size_t)m * 384 + 8 * lane) = oa; else *(u32x4*)(ckvn + (size_t)m * 256 + 8 * (lane - 48)) = oa;
;             if (lane < 16) { u32x4 ob; ob.x = cvtpk(xb[0] * rkv * gB0[0], xb[1] * rkv * gB0[1]); ob.y = cvtpk(xb[2] * rkv * gB0[2], xb[3] * rkv * gB0[3]);
;                 ob.z = cvtpk(xb[4] * rkv * gB1[0], xb[5] * rkv * gB1[1]); ob.w = cvtpk(xb[6] * rkv * gB1[2], xb[7] * rkv * gB1[3]);
;                 *(u32x4*)(ckvn + (size_t)m * 256 + 8 * (16 + lane)) = ob;
;                 const float x1 = bf1(r1[r]), x2 = bf1(r2[r]);
;                 *(unsigned*)(krope + (size_t)m * 32 + 2 * lane) = cvtpk(x1 * cc[r] - x2 * sn[r], x1 * sn[r] + x2 * cc[r]); } }
.LBB0_224:
	v_pk_mul_f32 v[32:33], v[84:85], v[42:43] op_sel_hi:[0,1]
	v_pk_mul_f32 v[34:35], v[84:85], v[36:37] op_sel_hi:[0,1]
	v_pk_mul_f32 v[32:33], v[0:1], v[32:33]
	v_pk_mul_f32 v[34:35], v[2:3], v[34:35]
	v_cvt_pk_bf16_f32 v32, v32, v33
	v_cvt_pk_bf16_f32 v33, v34, v35
	v_pk_mul_f32 v[34:35], v[84:85], v[74:75] op_sel_hi:[0,1]
	v_pk_mul_f32 v[36:37], v[84:85], v[38:39] op_sel_hi:[0,1]
	v_pk_mul_f32 v[34:35], v[4:5], v[34:35]
	v_pk_mul_f32 v[36:37], v[6:7], v[36:37]
	v_cvt_pk_bf16_f32 v34, v34, v35
	v_cvt_pk_bf16_f32 v35, v36, v37
	global_store_dwordx4 v[44:45], v[32:35], off sc1
	s_waitcnt vmcnt(15)
	s_nop 0
	v_lshlrev_b32_e32 v33, 16, v95
	v_lshlrev_b32_e32 v32, 16, v71
	s_waitcnt vmcnt(13)
	v_pk_mul_f32 v[34:35], v[72:73], v[32:33] op_sel:[0,1] op_sel_hi:[0,0]
	v_pk_fma_f32 v[36:37], v[70:71], v[32:33], v[34:35] neg_lo:[0,0,1] neg_hi:[0,0,1]
	v_pk_fma_f32 v[32:33], v[70:71], v[32:33], v[34:35] op_sel_hi:[0,1,1]
	v_cvt_pk_bf16_f32 v32, v36, v33
	global_store_dword v[40:41], v32, off offset:-64 sc1

; __device__ __forceinline__ unsigned cvtpk(float lo, float hi) { f32x2_t v = {lo, hi}; bf16x2_t b = __builtin_convertvector(v, bf16x2_t); return __builtin_bit_cast(unsigned, b); }
; __device__ __forceinline__ void mla_prep_phase(const bf16_t* projb, const float* gq, const float* gkv, const float* cs, bf16_t* cqn, bf16_t* ckvn, bf16_t* krope, int rows) {
;     ...
;             u32x4 oa; oa.x = cvtpk(xa[0] * ra * gA0[0], xa[1] * ra * gA0[1]); oa.y = cvtpk(xa[2] * ra * gA0[2], xa[3] * ra * gA0[3]);
;             oa.z = cvtpk(xa[4] * ra * gA1[0], xa[5] * ra * gA1[1]); oa.w = cvtpk(xa[6] * ra * gA1[2], xa[7] * ra * gA1[3]);
;             if (aq) *(u32x4*)(cqn + (size_t)m * 384 + 8 * lane) = oa; else *(u32x4*)(ckvn + (size_t)m * 256 + 8 * (lane - 48)) = oa;
;             if (lane < 16) { u32x4 ob; ob.x = cvtpk(xb[0] * rkv * gB0[0], xb[1] * rkv * gB0[1]); ob.y = cvtpk(xb[2] * rkv * gB0[2], xb[3] * rkv * gB0[3]);
;                 ob.z = cvtpk(xb[4] * rkv * gB1[0], xb[5] * rkv * gB1[1]); ob.w = cvtpk(xb[6] * rkv * gB1[2], xb[7] * rkv * gB1[3]);
;                 *(u32x4*)(ckvn + (size_t)m * 256 + 8 * (16 + lane)) = ob;
;                 const float x1 = bf1(r1[r]), x2 = bf1(r2[r]);
;                 *(unsigned*)(krope + (size_t)m * 32 + 2 * lane) = cvtpk(x1 * cc[r] - x2 * sn[r], x1 * sn[r] + x2 * cc[r]); } }
.LBB0_228:
	v_pk_mul_f32 v[24:25], v[72:73], v[32:33] op_sel_hi:[0,1]
	v_pk_mul_f32 v[26:27], v[72:73], v[28:29] op_sel_hi:[0,1]
	v_pk_mul_f32 v[24:25], v[0:1], v[24:25]
	v_pk_mul_f32 v[26:27], v[2:3], v[26:27]
	v_cvt_pk_bf16_f32 v24, v24, v25
	v_cvt_pk_bf16_f32 v25, v26, v27
	v_pk_mul_f32 v[26:27], v[72:73], v[34:35] op_sel_hi:[0,1]
	v_pk_mul_f32 v[28:29], v[72:73], v[30:31] op_sel_hi:[0,1]
	v_pk_mul_f32 v[26:27], v[4:5], v[26:27]
	v_pk_mul_f32 v[28:29], v[6:7], v[28:29]
	v_cvt_pk_bf16_f32 v26, v26, v27
	v_cvt_pk_bf16_f32 v27, v28, v29
	global_store_dwordx4 v[44:45], v[24:27], off offset:512 sc1
	s_waitcnt vmcnt(9)
	s_nop 0
	v_lshlrev_b32_e32 v25, 16, v94
	v_lshlrev_b32_e32 v24, 16, v93
	s_waitcnt vmcnt(7)
	v_pk_mul_f32 v[26:27], v[68:69], v[24:25] op_sel:[0,1] op_sel_hi:[0,0]
	v_pk_fma_f32 v[28:29], v[66:67], v[24:25], v[26:27] neg_lo:[0,0,1] neg_hi:[0,0,1]
	v_pk_fma_f32 v[24:25], v[66:67], v[24:25], v[26:27] op_sel_hi:[0,1,1]
	v_cvt_pk_bf16_f32 v24, v28, v25
	global_store_dword v[40:41], v24, off sc1

; __device__ __forceinline__ unsigned cvtpk(float lo, float hi) { f32x2_t v = {lo, hi}; bf16x2_t b = __builtin_convertvector(v, bf16x2_t); return __builtin_bit_cast(unsigned, b); }
; __device__ __forceinline__ void mla_prep_phase(const bf16_t* projb, const float* gq, const float* gkv, const float* cs, bf16_t* cqn, bf16_t* ckvn, bf16_t* krope, int rows) {
;     ...
;             u32x4 oa; oa.x = cvtpk(xa[0] * ra * gA0[0], xa[1] * ra * gA0[1]); oa.y = cvtpk(xa[2] * ra * gA0[2], xa[3] * ra * gA0[3]);
;             oa.z = cvtpk(xa[4] * ra * gA1[0], xa[5] * ra * gA1[1]); oa.w = cvtpk(xa[6] * ra * gA1[2], xa[7] * ra * gA1[3]);
;             if (aq) *(u32x4*)(cqn + (size_t)m * 384 + 8 * lane) = oa; else *(u32x4*)(ckvn + (size_t)m * 256 + 8 * (lane - 48)) = oa;
;             if (lane < 16) { u32x4 ob; ob.x = cvtpk(xb[0] * rkv * gB0[0], xb[1] * rkv * gB0[1]); ob.y = cvtpk(xb[2] * rkv * gB0[2], xb[3] * rkv * gB0[3]);
;                 ob.z = cvtpk(xb[4] * rkv * gB1[0], xb[5] * rkv * gB1[1]); ob.w = cvtpk(xb[6] * rkv * gB1[2], xb[7] * rkv * gB1[3]);
;                 *(u32x4*)(ckvn + (size_t)m * 256 + 8 * (16 + lane)) = ob;
;                 const float x1 = bf1(r1[r]), x2 = bf1(r2[r]);
;                 *(unsigned*)(krope + (size_t)m * 32 + 2 * lane) = cvtpk(x1 * cc[r] - x2 * sn[r], x1 * sn[r] + x2 * cc[r]); } }
.LBB0_232:
	global_store_dwordx4 v[44:45], v[40:43], off offset:-1536 sc1
	s_or_saveexec_b64 s[0:1], s[0:1]
	v_lshl_add_u64 v[46:47], s[42:43], 0, v[58:59]
	s_xor_b64 exec, exec, s[0:1]
	s_cbranch_execz .LBB0_219
.LBB0_233:
	global_store_dwordx4 v[46:47], v[40:43], off offset:-1536 sc1
	s_or_b64 exec, exec, s[0:1]
	s_nop 0
	v_lshl_add_u64 v[40:41], s[42:43], 0, v[60:61]
	s_and_saveexec_b64 s[0:1], s[8:9]
	s_cbranch_execnz .LBB0_220
	s_branch .LBB0_221
.LBB0_234:
	global_store_dwordx4 v[44:45], v[32:35], off offset:-1024 sc1
	s_andn2_saveexec_b64 s[0:1], s[0:1]
	s_cbranch_execz .LBB0_223
.LBB0_235:
	global_store_dwordx4 v[46:47], v[32:35], off offset:-768 sc1
	s_or_b64 exec, exec, s[0:1]
	s_and_saveexec_b64 s[0:1], s[8:9]
	s_cbranch_execnz .LBB0_224
	s_branch .LBB0_225
.LBB0_236:
	global_store_dwordx4 v[44:45], v[24:27], off offset:-512 sc1
	s_andn2_saveexec_b64 s[0:1], s[0:1]
	s_cbranch_execz .LBB0_227
.LBB0_237:
	global_store_dwordx4 v[46:47], v[24:27], off sc1
	s_or_b64 exec, exec, s[0:1]
	s_and_saveexec_b64 s[0:1], s[8:9]
	s_cbranch_execnz .LBB0_228
	s_branch .LBB0_229
.LBB0_238:
	global_store_dwordx4 v[44:45], v[16:19], off sc1
	s_andn2_saveexec_b64 s[0:1], s[0:1]
	s_cbranch_execz .LBB0_231
.LBB0_239:
	global_store_dwordx4 v[46:47], v[16:19], off offset:768 sc1
	s_or_b64 exec, exec, s[0:1]
	s_and_saveexec_b64 s[0:1], s[8:9]
	s_cbranch_execz .LBB0_216
.LBB0_240:
	v_pk_mul_f32 v[16:17], v[36:37], v[24:25] op_sel_hi:[0,1]
	v_pk_mul_f32 v[18:19], v[36:37], v[20:21] op_sel_hi:[0,1]
	v_pk_mul_f32 v[16:17], v[0:1], v[16:17]
	v_pk_mul_f32 v[18:19], v[2:3], v[18:19]
	v_cvt_pk_bf16_f32 v16, v16, v17
	v_cvt_pk_bf16_f32 v17, v18, v19
	v_pk_mul_f32 v[18:19], v[36:37], v[26:27] op_sel_hi:[0,1]
	v_pk_mul_f32 v[20:21], v[36:37], v[22:23] op_sel_hi:[0,1]
	v_pk_mul_f32 v[18:19], v[4:5], v[18:19]
	v_pk_mul_f32 v[20:21], v[6:7], v[20:21]
	v_cvt_pk_bf16_f32 v18, v18, v19
	v_cvt_pk_bf16_f32 v19, v20, v21
	global_store_dwordx4 v[44:45], v[16:19], off offset:1024 sc1
	s_waitcnt vmcnt(3)
	s_nop 0
	v_lshlrev_b32_e32 v17, 16, v92
	v_lshlrev_b32_e32 v16, 16, v49
	s_waitcnt vmcnt(1)
	v_pk_mul_f32 v[18:19], v[64:65], v[16:17] op_sel:[0,1] op_sel_hi:[0,0]
	v_pk_fma_f32 v[20:21], v[62:63], v[16:17], v[18:19] neg_lo:[0,0,1] neg_hi:[0,0,1]
	v_pk_fma_f32 v[16:17], v[62:63], v[16:17], v[18:19] op_sel_hi:[0,1,1]
	v_cvt_pk_bf16_f32 v16, v20, v17
	global_store_dword v[40:41], v16, off offset:64 sc1
	s_branch .LBB0_216

; __device__ __forceinline__ void dil_attn_unit(LAS unsigned char* lds, bf16_t* proj, float* lse, int unit, int Tc, bf16_t* ybuf) {
;     ...
;         const int tok0 = s * SEQ + U0 + 32 * w;
; #pragma unroll
;         for (int half = 0; half < 2; ++half) {
;             u32x4 o1[4], o2[4], gt[4]; float l1[4], l2[4];
; #pragma unroll
;             for (int i = 0; i < 4; ++i) { const int row = (half * 4 + i) * 4 + (lane >> 4), d8 = (lane & 15) * 8; const int tok = tok0 + row, t_ = tok & (SEQ - 1), s4_ = tok & ~(SEQ - 1);
;                 l1[i] = lse[(size_t)tok * 24 + 8 + h]; l2[i] = lse[(size_t)tok * 24 + 16 + h];
;                 o1[i] = *(const u32x4*)(proj + ((size_t)(24 + h) * Tc + s4_ + ((t_ & 3) << 10) + (t_ >> 2)) * 128 + d8);
;                 o2[i] = *(const u32x4*)(proj + ((size_t)(48 + h) * Tc + s4_ + ((t_ & 15) << 8) + (t_ >> 4)) * 128 + d8);
;                 gt[i] = *(const u32x4*)(proj + (size_t)9216 * Tc + (size_t)tok * 1024 + h * 128 + d8); }
; #pragma unroll
;             for (int i = 0; i < 4; ++i) { const int row = (half * 4 + i) * 4 + (lane >> 4), d8 = (lane & 15) * 8; const int tok = tok0 + row;
;                 const float l0 = lsr[row]; const float mxl = fmaxf(l0, fmaxf(l1[i], l2[i]));
;                 float w0 = __builtin_amdgcn_exp2f(l0 - mxl), w1 = __builtin_amdgcn_exp2f(l1[i] - mxl), w2 = __builtin_amdgcn_exp2f(l2[i] - mxl);
;                 const float iw = 1.0f / (w0 + w1 + w2); w0 *= iw; w1 *= iw; w2 *= iw;
.LBB0_248:
	s_or_b64 exec, exec, s[0:1]
	s_lshl_b32 s0, s92, 12
	s_or_b32 s1, s34, 24
	s_add_i32 s41, s41, s0
	s_mul_hi_i32 s5, s1, s62
	s_and_b32 s0, s41, 0xfffff000
	s_mul_i32 s6, s1, s62
	v_mov_b32_e32 v1, s5
	s_or_b32 s5, s34, 48
	s_ashr_i32 s1, s0, 31
	v_lshl_or_b32 v0, v75, 10, s6
	s_mul_hi_i32 s6, s5, s62
	s_mul_i32 s5, s5, s62
	v_lshl_add_u64 v[58:59], v[0:1], 0, s[0:1]
	s_add_u32 s0, s5, s0
	s_addc_u32 s1, s6, s1
	s_lshl_b32 s5, s34, 8
	v_readlane_b32 s6, v254, 57
	s_add_u32 s6, s6, s5
	v_readlane_b32 s7, v254, 59
	s_addc_u32 s7, s7, 0
	v_or_b32_e32 v0, s41, v75
	v_lshl_add_u64 v[56:57], s[6:7], 0, v[178:179]
	s_add_u32 s6, s64, s5
	s_addc_u32 s7, s65, 0
	v_lshl_add_u64 v[52:53], s[6:7], 0, v[178:179]
	v_readlane_b32 s6, v254, 11
	v_readlane_b32 s7, v254, 12
	s_lshl_b32 s76, s34, 2
	s_waitcnt lgkmcnt(0)
	v_mov_b32_e32 v1, 0xfe3
	v_mov_b64_e32 v[60:61], s[6:7]
	v_mad_i64_i32 v[2:3], s[6:7], v0, s66, v[60:61]
	v_lshl_add_u64 v[2:3], v[2:3], 0, s[76:77]
	global_load_dword v48, v[2:3], off offset:32
	global_load_dword v49, v[2:3], off offset:64
	v_bitop3_b32 v4, s41, v1, v75 bitop3:0xc8
	v_lshrrev_b32_e32 v2, 2, v4
	v_ashrrev_i32_e32 v1, 31, v0
	v_or_b32_e32 v2, v58, v2
	v_mov_b32_e32 v3, v59
	v_lshl_add_u64 v[54:55], s[54:55], 0, v[178:179]
	v_lshlrev_b64 v[2:3], 8, v[2:3]
	v_lshlrev_b64 v[64:65], 11, v[0:1]
	v_lshl_add_u64 v[2:3], v[54:55], 0, v[2:3]
	v_lshl_add_u64 v[0:1], v[56:57], 0, v[64:65]
	global_load_dwordx4 v[36:39], v[2:3], off
	global_load_dwordx4 v[44:47], v[0:1], off
	v_lshl_or_b32 v78, v75, 8, s0
	v_lshrrev_b32_e32 v2, 4, v4
	v_or_b32_e32 v62, v78, v2
	v_mov_b32_e32 v63, s1
	v_lshlrev_b64 v[2:3], 8, v[62:63]
	v_lshl_add_u64 v[2:3], v[54:55], 0, v[2:3]
	global_load_dwordx4 v[40:43], v[2:3], off
	v_or_b32_e32 v4, 4, v75
	v_or_b32_e32 v0, s41, v4
	v_mov_b32_e32 v1, 0xfe7
	v_mad_i64_i32 v[2:3], s[6:7], v0, s66, v[60:61]
	v_bitop3_b32 v5, s41, v1, v4 bitop3:0xc8
	v_lshl_add_u64 v[2:3], v[2:3], 0, s[76:77]
	global_load_dword v85, v[2:3], off offset:32
	global_load_dword v84, v[2:3], off offset:64
	v_lshrrev_b32_e32 v2, 2, v5
	v_ashrrev_i32_e32 v1, 31, v0
	v_or_b32_e32 v2, v58, v2
	v_mov_b32_e32 v3, v59
	v_lshlrev_b64 v[2:3], 8, v[2:3]
	v_lshlrev_b64 v[70:71], 11, v[0:1]
	v_lshl_add_u64 v[2:3], v[54:55], 0, v[2:3]
	v_lshl_add_u64 v[0:1], v[56:57], 0, v[70:71]
	global_load_dwordx4 v[24:27], v[2:3], off
	global_load_dwordx4 v[32:35], v[0:1], off
	v_lshlrev_b32_e32 v2, 8, v4
	v_lshrrev_b32_e32 v3, 4, v5
	v_or3_b32 v62, v3, v2, s0
	v_lshlrev_b64 v[2:3], 8, v[62:63]
	v_or_b32_e32 v4, 8, v75
	v_lshl_add_u64 v[2:3], v[54:55], 0, v[2:3]
	v_or_b32_e32 v0, s41, v4
	global_load_dwordx4 v[28:31], v[2:3], off
	v_mov_b32_e32 v1, 0xfeb
	v_mad_i64_i32 v[2:3], s[6:7], v0, s66, v[60:61]
	v_bitop3_b32 v5, s41, v1, v4 bitop3:0xc8
	v_lshl_add_u64 v[2:3], v[2:3], 0, s[76:77]
	global_load_dword v83, v[2:3], off offset:32
	global_load_dword v82, v[2:3], off offset:64
	v_lshrrev_b32_e32 v2, 2, v5
	v_ashrrev_i32_e32 v1, 31, v0
	v_or_b32_e32 v2, v58, v2
	v_mov_b32_e32 v3, v59
	v_lshlrev_b64 v[2:3], 8, v[2:3]
	v_lshlrev_b64 v[68:69], 11, v[0:1]
	v_lshl_add_u64 v[2:3], v[54:55], 0, v[2:3]
	v_lshl_add_u64 v[0:1], v[56:57], 0, v[68:69]
	global_load_dwordx4 v[12:15], v[2:3], off
	global_load_dwordx4 v[20:23], v[0:1], off
	v_lshlrev_b32_e32 v2, 8, v4
	v_lshrrev_b32_e32 v3, 4, v5
	v_or_b32_e32 v4, 12, v75
	v_or3_b32 v62, v3, v2, s0
	v_or_b32_e32 v8, s41, v4
	v_mov_b32_e32 v0, 0xfef
	v_lshlrev_b64 v[2:3], 8, v[62:63]
	v_bitop3_b32 v5, s41, v0, v4 bitop3:0xc8
	v_mad_i64_i32 v[0:1], s[6:7], v8, s66, v[60:61]
	v_lshl_add_u32 v50, v75, 2, s4
	v_lshl_add_u64 v[2:3], v[54:55], 0, v[2:3]
	v_lshl_add_u64 v[0:1], v[0:1], 0, s[76:77]
	v_add_u32_e32 v76, 0x4000, v50
	global_load_dwordx4 v[16:19], v[2:3], off
	global_load_dword v80, v[0:1], off offset:32
	global_load_dword v79, v[0:1], off offset:64
	ds_read2_b32 v[72:73], v76 offset0:128 offset1:132
	v_lshrrev_b32_e32 v0, 2, v5
	v_lshlrev_b32_e32 v4, 8, v4
	v_lshrrev_b32_e32 v5, 4, v5
	v_or3_b32 v62, v5, v4, s0
	s_waitcnt vmcnt(15) lgkmcnt(0)
	v_max3_f32 v50, v72, v48, v49
	v_sub_f32_e32 v51, v72, v50
	v_sub_f32_e32 v48, v48, v50
	v_exp_f32_e32 v51, v51
	v_exp_f32_e32 v48, v48
	v_sub_f32_e32 v49, v49, v50
	v_exp_f32_e32 v49, v49
	v_lshl_add_u32 v77, v88, 5, s4
	v_add_f32_e32 v50, v51, v48
	v_lshlrev_b64 v[4:5], 8, v[62:63]
	v_add_f32_e32 v50, v49, v50
	v_div_scale_f32 v62, s[4:5], v50, v50, 1.0
	v_rcp_f32_e32 v72, v62
	s_waitcnt vmcnt(13)
	v_lshlrev_b32_e32 v94, 16, v44
	v_and_b32_e32 v44, 0xffff0000, v44
	v_ashrrev_i32_e32 v9, 31, v8
	v_fma_f32 v74, -v62, v72, 1.0
	v_fmac_f32_e32 v72, v74, v72
	v_div_scale_f32 v74, vcc, 1.0, v50, 1.0
	v_mul_f32_e32 v81, v74, v72
	v_fma_f32 v86, -v62, v81, v74
	v_fmac_f32_e32 v81, v86, v72
	v_or_b32_e32 v0, v58, v0
	v_mov_b32_e32 v1, v59
	v_fma_f32 v62, -v62, v81, v74
	v_mul_f32_e32 v90, 0xbfb8aa3b, v94
	v_lshlrev_b32_e32 v92, 16, v36
	v_and_b32_e32 v93, 0xffff0000, v36
	v_mul_f32_e32 v36, 0xbfb8aa3b, v44
	v_lshlrev_b64 v[0:1], 8, v[0:1]
	v_lshlrev_b64 v[66:67], 11, v[8:9]
	v_div_fmas_f32 v62, v62, v72, v81
	s_movk_i32 s6, 0x210
	v_exp_f32_e32 v90, v90
	v_exp_f32_e32 v91, v36
	v_lshl_add_u64 v[0:1], v[54:55], 0, v[0:1]
	v_lshl_add_u64 v[4:5], v[54:55], 0, v[4:5]
	v_lshl_add_u64 v[8:9], v[56:57], 0, v[66:67]
	v_div_fixup_f32 v50, v62, v50, 1.0
	v_mad_u32_u24 v81, v75, s6, v77
	global_load_dwordx4 v[0:3], v[0:1], off
	v_mul_f32_e32 v72, v51, v50
	global_load_dwordx4 v[4:7], v[4:5], off
	v_mul_f32_e32 v74, v48, v50
	global_load_dwordx4 v[8:11], v[8:9], off
	v_mul_f32_e32 v62, v49, v50
	ds_read_b128 v[86:89], v81
	ds_read_b128 v[48:51], v81 offset:16
	v_pk_add_f32 v[90:91], v[90:91], 1.0 op_sel_hi:[1,0]
	v_pk_mul_f32 v[92:93], v[74:75], v[92:93] op_sel_hi:[0,1]
	v_div_scale_f32 v36, s[4:5], v91, v91, v44
	s_waitcnt lgkmcnt(1)
; #define LAS __attribute__((address_space(3)))
; __device__ __forceinline__ unsigned cvtpk(float lo, float hi) { f32x2_t v = {lo, hi}; bf16x2_t b = __builtin_convertvector(v, bf16x2_t); return __builtin_bit_cast(unsigned, b); }
; __device__ __forceinline__ float silu_f(float x) { return x / (1.0f + __expf(-x)); }
; __device__ __forceinline__ void dil_attn_unit(LAS unsigned char* lds, bf16_t* proj, float* lse, int unit, int Tc, bf16_t* ybuf) {
;     ...
;             for (int i = 0; i < 4; ++i) { const int row = (half * 4 + i) * 4 + (lane >> 4), d8 = (lane & 15) * 8; const int tok = tok0 + row;
;                 const float l0 = lsr[row]; const float mxl = fmaxf(l0, fmaxf(l1[i], l2[i]));
;                 float w0 = __builtin_amdgcn_exp2f(l0 - mxl), w1 = __builtin_amdgcn_exp2f(l1[i] - mxl), w2 = __builtin_amdgcn_exp2f(l2[i] - mxl);
;                 const float iw = 1.0f / (w0 + w1 + w2); w0 *= iw; w1 *= iw; w2 *= iw;
;                 const f32x4 x0 = *(const LAS f32x4*)(stf + row * 132 + d8), x1 = *(const LAS f32x4*)(stf + row * 132 + d8 + 4);
;                 u32x4 yo;
;                 yo.x = cvtpk((w0 * x0[0] + w1 * bf_lo(o1[i].x) + w2 * bf_lo(o2[i].x)) * silu_f(bf_lo(gt[i].x)), (w0 * x0[1] + w1 * bf_hi(o1[i].x) + w2 * bf_hi(o2[i].x)) * silu_f(bf_hi(gt[i].x)));
;                 yo.y = cvtpk((w0 * x0[2] + w1 * bf_lo(o1[i].y) + w2 * bf_lo(o2[i].y)) * silu_f(bf_lo(gt[i].y)), (w0 * x0[3] + w1 * bf_hi(o1[i].y) + w2 * bf_hi(o2[i].y)) * silu_f(bf_hi(gt[i].y)));
;                 yo.z = cvtpk((w0 * x1[0] + w1 * bf_lo(o1[i].z) + w2 * bf_lo(o2[i].z)) * silu_f(bf_lo(gt[i].z)), (w0 * x1[1] + w1 * bf_hi(o1[i].z) + w2 * bf_hi(o2[i].z)) * silu_f(bf_hi(gt[i].z)));
;                 yo.w = cvtpk((w0 * x1[2] + w1 * bf_lo(o1[i].w) + w2 * bf_lo(o2[i].w)) * silu_f(bf_lo(gt[i].w)), (w0 * x1[3] + w1 * bf_hi(o1[i].w) + w2 * bf_hi(o2[i].w)) * silu_f(bf_hi(gt[i].w)));
;                 *(u32x4*)(ybuf + (size_t)tok * DM + h * 128 + d8) = yo; }
	v_pk_fma_f32 v[86:87], v[86:87], v[72:73], v[92:93] op_sel_hi:[1,0,1]
	s_waitcnt vmcnt(15)
	v_lshlrev_b32_e32 v92, 16, v40
	v_and_b32_e32 v93, 0xffff0000, v40
	v_rcp_f32_e32 v40, v36
	v_pk_fma_f32 v[86:87], v[62:63], v[92:93], v[86:87] op_sel_hi:[0,1,1]
	v_fma_f32 v92, -v36, v40, 1.0
	v_fmac_f32_e32 v40, v92, v40
	v_div_scale_f32 v92, vcc, v44, v91, v44
	v_mul_f32_e32 v93, v92, v40
	v_fma_f32 v95, -v36, v93, v92
	v_fmac_f32_e32 v93, v95, v40
	v_fma_f32 v36, -v36, v93, v92
	v_div_fmas_f32 v36, v36, v40, v93
	v_div_fixup_f32 v91, v36, v91, v44
	v_div_scale_f32 v36, s[4:5], v90, v90, v94
	v_rcp_f32_e32 v40, v36
	s_nop 0
	v_fma_f32 v44, -v36, v40, 1.0
	v_fmac_f32_e32 v40, v44, v40
	v_div_scale_f32 v44, vcc, v94, v90, v94
	v_mul_f32_e32 v92, v44, v40
	v_fma_f32 v93, -v36, v92, v44
	v_fmac_f32_e32 v92, v93, v40
	v_fma_f32 v36, -v36, v92, v44
	v_div_fmas_f32 v36, v36, v40, v92
	v_div_fixup_f32 v90, v36, v90, v94
	v_pk_mul_f32 v[86:87], v[90:91], v[86:87]
	v_lshlrev_b32_e32 v90, 16, v45
	v_and_b32_e32 v91, 0xffff0000, v45
	v_mul_f32_e32 v40, 0xbfb8aa3b, v90
	v_lshlrev_b32_e32 v44, 16, v37
	v_and_b32_e32 v45, 0xffff0000, v37
	v_mul_f32_e32 v37, 0xbfb8aa3b, v91
	v_cvt_pk_bf16_f32 v36, v86, v87
	v_exp_f32_e32 v40, v40
	v_lshlrev_b32_e32 v86, 16, v41
	v_and_b32_e32 v87, 0xffff0000, v41
	v_exp_f32_e32 v41, v37
	v_pk_mul_f32 v[44:45], v[74:75], v[44:45] op_sel_hi:[0,1]
	v_pk_fma_f32 v[44:45], v[88:89], v[72:73], v[44:45] op_sel_hi:[1,0,1]
	v_pk_add_f32 v[40:41], v[40:41], 1.0 op_sel_hi:[1,0]
	s_nop 0
	v_div_scale_f32 v37, s[4:5], v41, v41, v91
	v_pk_fma_f32 v[44:45], v[62:63], v[86:87], v[44:45] op_sel_hi:[0,1,1]
	v_rcp_f32_e32 v86, v37
	s_nop 0
	v_fma_f32 v87, -v37, v86, 1.0
	v_fmac_f32_e32 v86, v87, v86
	v_div_scale_f32 v87, vcc, v91, v41, v91
	v_mul_f32_e32 v88, v87, v86
	v_fma_f32 v89, -v37, v88, v87
	v_fmac_f32_e32 v88, v89, v86
	v_fma_f32 v37, -v37, v88, v87
	v_div_fmas_f32 v37, v37, v86, v88
	v_div_fixup_f32 v41, v37, v41, v91
	v_div_scale_f32 v37, s[4:5], v40, v40, v90
	v_rcp_f32_e32 v86, v37
	s_nop 0
	v_fma_f32 v87, -v37, v86, 1.0
	v_fmac_f32_e32 v86, v87, v86
	v_div_scale_f32 v87, vcc, v90, v40, v90
	v_mul_f32_e32 v88, v87, v86
	v_fma_f32 v89, -v37, v88, v87
	v_fmac_f32_e32 v88, v89, v86
	v_fma_f32 v37, -v37, v88, v87
	v_div_fmas_f32 v37, v37, v86, v88
	v_div_fixup_f32 v40, v37, v40, v90
	v_pk_mul_f32 v[40:41], v[40:41], v[44:45]
	v_lshlrev_b32_e32 v86, 16, v46
	v_and_b32_e32 v46, 0xffff0000, v46
	v_cvt_pk_bf16_f32 v37, v40, v41
	v_mul_f32_e32 v40, 0xbfb8aa3b, v86
	v_lshlrev_b32_e32 v44, 16, v38
	v_and_b32_e32 v45, 0xffff0000, v38
	v_mul_f32_e32 v38, 0xbfb8aa3b, v46
	v_exp_f32_e32 v40, v40
	v_exp_f32_e32 v41, v38
	v_pk_mul_f32 v[44:45], v[74:75], v[44:45] op_sel_hi:[0,1]
	s_waitcnt lgkmcnt(0)
	v_pk_fma_f32 v[44:45], v[48:49], v[72:73], v[44:45] op_sel_hi:[1,0,1]
	v_lshlrev_b32_e32 v48, 16, v42
	v_pk_add_f32 v[40:41], v[40:41], 1.0 op_sel_hi:[1,0]
	v_and_b32_e32 v49, 0xffff0000, v42
	v_div_scale_f32 v38, s[4:5], v41, v41, v46
	v_rcp_f32_e32 v42, v38
	v_pk_fma_f32 v[44:45], v[62:63], v[48:49], v[44:45] op_sel_hi:[0,1,1]
	v_fma_f32 v48, -v38, v42, 1.0
	v_fmac_f32_e32 v42, v48, v42
	v_div_scale_f32 v48, vcc, v46, v41, v46
	v_mul_f32_e32 v49, v48, v42
	v_fma_f32 v87, -v38, v49, v48
	v_fmac_f32_e32 v49, v87, v42
	v_fma_f32 v38, -v38, v49, v48
	v_div_fmas_f32 v38, v38, v42, v49
	v_div_fixup_f32 v41, v38, v41, v46
	v_div_scale_f32 v38, s[4:5], v40, v40, v86
	v_rcp_f32_e32 v42, v38
	s_nop 0
	v_fma_f32 v46, -v38, v42, 1.0
	v_fmac_f32_e32 v42, v46, v42
	v_div_scale_f32 v46, vcc, v86, v40, v86
	v_mul_f32_e32 v48, v46, v42
	v_fma_f32 v49, -v38, v48, v46
	v_fmac_f32_e32 v48, v49, v42
	v_fma_f32 v38, -v38, v48, v46
	v_div_fmas_f32 v38, v38, v42, v48
	v_div_fixup_f32 v40, v38, v40, v86
	v_pk_mul_f32 v[40:41], v[40:41], v[44:45]
	v_lshlrev_b32_e32 v46, 16, v47
	v_and_b32_e32 v47, 0xffff0000, v47
	v_cvt_pk_bf16_f32 v38, v40, v41
	v_mul_f32_e32 v40, 0xbfb8aa3b, v46
	v_lshlrev_b32_e32 v44, 16, v39
	v_and_b32_e32 v45, 0xffff0000, v39
	v_mul_f32_e32 v39, 0xbfb8aa3b, v47
	v_exp_f32_e32 v40, v40
	v_exp_f32_e32 v41, v39
	v_pk_mul_f32 v[44:45], v[74:75], v[44:45] op_sel_hi:[0,1]
	v_pk_fma_f32 v[44:45], v[50:51], v[72:73], v[44:45] op_sel_hi:[1,0,1]
	v_lshlrev_b32_e32 v42, 16, v43
	v_pk_add_f32 v[40:41], v[40:41], 1.0 op_sel_hi:[1,0]
	v_and_b32_e32 v43, 0xffff0000, v43
	v_div_scale_f32 v39, s[4:5], v41, v41, v47
	v_pk_fma_f32 v[42:43], v[62:63], v[42:43], v[44:45] op_sel_hi:[0,1,1]
	v_rcp_f32_e32 v44, v39
	s_nop 0
	v_fma_f32 v45, -v39, v44, 1.0
	v_fmac_f32_e32 v44, v45, v44
	v_div_scale_f32 v45, vcc, v47, v41, v47
	v_mul_f32_e32 v48, v45, v44
	v_fma_f32 v49, -v39, v48, v45
	v_fmac_f32_e32 v48, v49, v44
	v_fma_f32 v39, -v39, v48, v45
	v_div_fmas_f32 v39, v39, v44, v48
	v_div_fixup_f32 v41, v39, v41, v47
	v_div_scale_f32 v39, s[4:5], v40, v40, v46
	v_rcp_f32_e32 v44, v39
	s_nop 0
	v_fma_f32 v45, -v39, v44, 1.0
	v_fmac_f32_e32 v44, v45, v44
	v_div_scale_f32 v45, vcc, v46, v40, v46
	v_mul_f32_e32 v47, v45, v44
	v_fma_f32 v48, -v39, v47, v45
	v_fmac_f32_e32 v47, v48, v44
	v_fma_f32 v39, -v39, v47, v45
	v_div_fmas_f32 v39, v39, v44, v47
	v_div_fixup_f32 v40, v39, v40, v46
	v_pk_mul_f32 v[40:41], v[40:41], v[42:43]
	s_nop 0
	v_cvt_pk_bf16_f32 v39, v40, v41
	v_lshl_add_u64 v[40:41], v[52:53], 0, v[64:65]
	global_store_dwordx4 v[40:41], v[36:39], off sc1
	ds_read2_b32 v[40:41], v76 offset0:136 offset1:140
	ds_read2_b32 v[64:65], v76 offset0:144 offset1:148
	s_waitcnt vmcnt(14)
	v_max3_f32 v36, v73, v85, v84
	v_sub_f32_e32 v37, v73, v36
	v_sub_f32_e32 v38, v85, v36
	v_exp_f32_e32 v37, v37
	v_exp_f32_e32 v38, v38
	v_sub_f32_e32 v36, v84, v36
	v_exp_f32_e32 v36, v36
	s_waitcnt vmcnt(13)
; #define LAS __attribute__((address_space(3)))
; __device__ __forceinline__ unsigned cvtpk(float lo, float hi) { f32x2_t v = {lo, hi}; bf16x2_t b = __builtin_convertvector(v, bf16x2_t); return __builtin_bit_cast(unsigned, b); }
; __device__ __forceinline__ float silu_f(float x) { return x / (1.0f + __expf(-x)); }
; __device__ __forceinline__ void dil_attn_unit(LAS unsigned char* lds, bf16_t* proj, float* lse, int unit, int Tc, bf16_t* ybuf) {
;     ...
;             for (int i = 0; i < 4; ++i) { const int row = (half * 4 + i) * 4 + (lane >> 4), d8 = (lane & 15) * 8; const int tok = tok0 + row;
;                 const float l0 = lsr[row]; const float mxl = fmaxf(l0, fmaxf(l1[i], l2[i]));
;                 float w0 = __builtin_amdgcn_exp2f(l0 - mxl), w1 = __builtin_amdgcn_exp2f(l1[i] - mxl), w2 = __builtin_amdgcn_exp2f(l2[i] - mxl);
;                 const float iw = 1.0f / (w0 + w1 + w2); w0 *= iw; w1 *= iw; w2 *= iw;
;                 const f32x4 x0 = *(const LAS f32x4*)(stf + row * 132 + d8), x1 = *(const LAS f32x4*)(stf + row * 132 + d8 + 4);
;                 u32x4 yo;
;                 yo.x = cvtpk((w0 * x0[0] + w1 * bf_lo(o1[i].x) + w2 * bf_lo(o2[i].x)) * silu_f(bf_lo(gt[i].x)), (w0 * x0[1] + w1 * bf_hi(o1[i].x) + w2 * bf_hi(o2[i].x)) * silu_f(bf_hi(gt[i].x)));
;                 yo.y = cvtpk((w0 * x0[2] + w1 * bf_lo(o1[i].y) + w2 * bf_lo(o2[i].y)) * silu_f(bf_lo(gt[i].y)), (w0 * x0[3] + w1 * bf_hi(o1[i].y) + w2 * bf_hi(o2[i].y)) * silu_f(bf_hi(gt[i].y)));
;                 yo.z = cvtpk((w0 * x1[0] + w1 * bf_lo(o1[i].z) + w2 * bf_lo(o2[i].z)) * silu_f(bf_lo(gt[i].z)), (w0 * x1[1] + w1 * bf_hi(o1[i].z) + w2 * bf_hi(o2[i].z)) * silu_f(bf_hi(gt[i].z)));
;                 yo.w = cvtpk((w0 * x1[2] + w1 * bf_lo(o1[i].w) + w2 * bf_lo(o2[i].w)) * silu_f(bf_lo(gt[i].w)), (w0 * x1[3] + w1 * bf_hi(o1[i].w) + w2 * bf_hi(o2[i].w)) * silu_f(bf_hi(gt[i].w)));
;                 *(u32x4*)(ybuf + (size_t)tok * DM + h * 128 + d8) = yo; }
	v_lshlrev_b32_e32 v84, 16, v24
	v_add_f32_e32 v39, v37, v38
	v_and_b32_e32 v85, 0xffff0000, v24
	v_add_f32_e32 v39, v36, v39
	v_div_scale_f32 v42, s[4:5], v39, v39, 1.0
	v_rcp_f32_e32 v43, v42
	s_nop 0
	v_fma_f32 v44, -v42, v43, 1.0
	v_fmac_f32_e32 v43, v44, v43
	v_div_scale_f32 v44, vcc, 1.0, v39, 1.0
	v_mul_f32_e32 v45, v44, v43
	v_fma_f32 v46, -v42, v45, v44
	v_fmac_f32_e32 v45, v46, v43
	v_fma_f32 v42, -v42, v45, v44
	v_div_fmas_f32 v42, v42, v43, v45
	s_waitcnt vmcnt(12)
	v_lshlrev_b32_e32 v43, 16, v32
	v_and_b32_e32 v32, 0xffff0000, v32
	v_mul_f32_e32 v45, 0xbfb8aa3b, v43
	v_mul_f32_e32 v24, 0xbfb8aa3b, v32
	v_exp_f32_e32 v72, v45
	v_exp_f32_e32 v73, v24
	v_div_fixup_f32 v39, v42, v39, 1.0
	v_mul_f32_e32 v44, v37, v39
	v_mul_f32_e32 v46, v38, v39
	v_mul_f32_e32 v42, v36, v39
	ds_read_b128 v[48:51], v81 offset:2112
	ds_read_b128 v[36:39], v81 offset:2128
	v_pk_add_f32 v[72:73], v[72:73], 1.0 op_sel_hi:[1,0]
	v_pk_mul_f32 v[84:85], v[46:47], v[84:85] op_sel_hi:[0,1]
	v_div_scale_f32 v24, s[4:5], v73, v73, v32
	s_waitcnt lgkmcnt(1)
	v_pk_fma_f32 v[48:49], v[48:49], v[44:45], v[84:85] op_sel_hi:[1,0,1]
	s_waitcnt vmcnt(11)
	v_lshlrev_b32_e32 v84, 16, v28
	v_and_b32_e32 v85, 0xffff0000, v28
	v_rcp_f32_e32 v28, v24
	v_pk_fma_f32 v[48:49], v[42:43], v[84:85], v[48:49] op_sel_hi:[0,1,1]
	v_fma_f32 v45, -v24, v28, 1.0
	v_fmac_f32_e32 v28, v45, v28
	v_div_scale_f32 v45, vcc, v32, v73, v32
	v_mul_f32_e32 v47, v45, v28
	v_fma_f32 v62, -v24, v47, v45
	v_fmac_f32_e32 v47, v62, v28
	v_fma_f32 v24, -v24, v47, v45
	v_div_fmas_f32 v24, v24, v28, v47
	v_div_fixup_f32 v73, v24, v73, v32
	v_div_scale_f32 v24, s[4:5], v72, v72, v43
	v_rcp_f32_e32 v28, v24
	s_nop 0
	v_fma_f32 v32, -v24, v28, 1.0
	v_fmac_f32_e32 v28, v32, v28
	v_div_scale_f32 v32, vcc, v43, v72, v43
	v_mul_f32_e32 v45, v32, v28
	v_fma_f32 v47, -v24, v45, v32
	v_fmac_f32_e32 v45, v47, v28
	v_fma_f32 v24, -v24, v45, v32
	v_div_fmas_f32 v24, v24, v28, v45
	v_div_fixup_f32 v72, v24, v72, v43
	v_lshlrev_b32_e32 v43, 16, v33
	v_and_b32_e32 v45, 0xffff0000, v33
	v_pk_mul_f32 v[48:49], v[72:73], v[48:49]
	v_mul_f32_e32 v28, 0xbfb8aa3b, v43
	v_lshlrev_b32_e32 v32, 16, v25
	v_and_b32_e32 v33, 0xffff0000, v25
	v_mul_f32_e32 v25, 0xbfb8aa3b, v45
	v_cvt_pk_bf16_f32 v24, v48, v49
	v_exp_f32_e32 v28, v28
	v_lshlrev_b32_e32 v48, 16, v29
	v_and_b32_e32 v49, 0xffff0000, v29
	v_exp_f32_e32 v29, v25
	v_pk_mul_f32 v[32:33], v[46:47], v[32:33] op_sel_hi:[0,1]
	v_pk_fma_f32 v[32:33], v[50:51], v[44:45], v[32:33] op_sel_hi:[1,0,1]
	v_pk_add_f32 v[28:29], v[28:29], 1.0 op_sel_hi:[1,0]
	s_nop 0
	v_div_scale_f32 v25, s[4:5], v29, v29, v45
	v_rcp_f32_e32 v47, v25
	v_pk_fma_f32 v[32:33], v[42:43], v[48:49], v[32:33] op_sel_hi:[0,1,1]
	v_fma_f32 v48, -v25, v47, 1.0
	v_fmac_f32_e32 v47, v48, v47
	v_div_scale_f32 v48, vcc, v45, v29, v45
	v_mul_f32_e32 v49, v48, v47
	v_fma_f32 v50, -v25, v49, v48
	v_fmac_f32_e32 v49, v50, v47
	v_fma_f32 v25, -v25, v49, v48
	v_div_fmas_f32 v25, v25, v47, v49
	v_div_fixup_f32 v29, v25, v29, v45
	v_div_scale_f32 v25, s[4:5], v28, v28, v43
	v_rcp_f32_e32 v45, v25
	s_nop 0
	v_fma_f32 v47, -v25, v45, 1.0
	v_fmac_f32_e32 v45, v47, v45
	v_div_scale_f32 v47, vcc, v43, v28, v43
	v_mul_f32_e32 v48, v47, v45
	v_fma_f32 v49, -v25, v48, v47
	v_fmac_f32_e32 v48, v49, v45
	v_fma_f32 v25, -v25, v48, v47
	v_div_fmas_f32 v25, v25, v45, v48
	v_div_fixup_f32 v28, v25, v28, v43
	v_pk_mul_f32 v[28:29], v[28:29], v[32:33]
	v_lshlrev_b32_e32 v43, 16, v34
	v_and_b32_e32 v34, 0xffff0000, v34
	v_cvt_pk_bf16_f32 v25, v28, v29
	v_mul_f32_e32 v28, 0xbfb8aa3b, v43
	v_lshlrev_b32_e32 v32, 16, v26
	v_and_b32_e32 v33, 0xffff0000, v26
	v_mul_f32_e32 v26, 0xbfb8aa3b, v34
	v_exp_f32_e32 v28, v28
	v_exp_f32_e32 v29, v26
	v_pk_mul_f32 v[32:33], v[46:47], v[32:33] op_sel_hi:[0,1]
	s_waitcnt lgkmcnt(0)
	v_pk_fma_f32 v[32:33], v[36:37], v[44:45], v[32:33] op_sel_hi:[1,0,1]
	v_lshlrev_b32_e32 v36, 16, v30
	v_pk_add_f32 v[28:29], v[28:29], 1.0 op_sel_hi:[1,0]
	v_and_b32_e32 v37, 0xffff0000, v30
	v_div_scale_f32 v26, s[4:5], v29, v29, v34
	v_rcp_f32_e32 v30, v26
	v_pk_fma_f32 v[32:33], v[42:43], v[36:37], v[32:33] op_sel_hi:[0,1,1]
	v_or_b32_e32 v48, 16, v75
	v_fma_f32 v36, -v26, v30, 1.0
	v_fmac_f32_e32 v30, v36, v30
	v_div_scale_f32 v36, vcc, v34, v29, v34
	v_mul_f32_e32 v37, v36, v30
	v_fma_f32 v45, -v26, v37, v36
	v_fmac_f32_e32 v37, v45, v30
	v_fma_f32 v26, -v26, v37, v36
	v_div_fmas_f32 v26, v26, v30, v37
	v_div_fixup_f32 v29, v26, v29, v34
	v_div_scale_f32 v26, s[4:5], v28, v28, v43
	v_rcp_f32_e32 v30, v26
	s_nop 0
	v_fma_f32 v34, -v26, v30, 1.0
	v_fmac_f32_e32 v30, v34, v30
	v_div_scale_f32 v34, vcc, v43, v28, v43
	v_mul_f32_e32 v36, v34, v30
	v_fma_f32 v37, -v26, v36, v34
	v_fmac_f32_e32 v36, v37, v30
	v_fma_f32 v26, -v26, v36, v34
	v_div_fmas_f32 v26, v26, v30, v36
	v_div_fixup_f32 v28, v26, v28, v43
	v_pk_mul_f32 v[28:29], v[28:29], v[32:33]
	v_lshlrev_b32_e32 v34, 16, v35
	v_and_b32_e32 v35, 0xffff0000, v35
	v_cvt_pk_bf16_f32 v26, v28, v29
	v_mul_f32_e32 v28, 0xbfb8aa3b, v34
	v_lshlrev_b32_e32 v32, 16, v27
	v_and_b32_e32 v33, 0xffff0000, v27
	v_mul_f32_e32 v27, 0xbfb8aa3b, v35
	v_exp_f32_e32 v28, v28
	v_exp_f32_e32 v29, v27
	v_pk_mul_f32 v[32:33], v[46:47], v[32:33] op_sel_hi:[0,1]
	v_pk_fma_f32 v[32:33], v[38:39], v[44:45], v[32:33] op_sel_hi:[1,0,1]
	v_lshlrev_b32_e32 v30, 16, v31
	v_pk_add_f32 v[28:29], v[28:29], 1.0 op_sel_hi:[1,0]
	v_and_b32_e32 v31, 0xffff0000, v31
	v_div_scale_f32 v27, s[4:5], v29, v29, v35
	v_pk_fma_f32 v[30:31], v[42:43], v[30:31], v[32:33] op_sel_hi:[0,1,1]
	v_rcp_f32_e32 v32, v27
	s_waitcnt vmcnt(8)
; #define LAS __attribute__((address_space(3)))
; __device__ __forceinline__ unsigned cvtpk(float lo, float hi) { f32x2_t v = {lo, hi}; bf16x2_t b = __builtin_convertvector(v, bf16x2_t); return __builtin_bit_cast(unsigned, b); }
; __device__ __forceinline__ float silu_f(float x) { return x / (1.0f + __expf(-x)); }
; __device__ __forceinline__ void dil_attn_unit(LAS unsigned char* lds, bf16_t* proj, float* lse, int unit, int Tc, bf16_t* ybuf) {
;     ...
;             for (int i = 0; i < 4; ++i) { const int row = (half * 4 + i) * 4 + (lane >> 4), d8 = (lane & 15) * 8; const int tok = tok0 + row;
;                 const float l0 = lsr[row]; const float mxl = fmaxf(l0, fmaxf(l1[i], l2[i]));
;                 float w0 = __builtin_amdgcn_exp2f(l0 - mxl), w1 = __builtin_amdgcn_exp2f(l1[i] - mxl), w2 = __builtin_amdgcn_exp2f(l2[i] - mxl);
;                 const float iw = 1.0f / (w0 + w1 + w2); w0 *= iw; w1 *= iw; w2 *= iw;
;                 const f32x4 x0 = *(const LAS f32x4*)(stf + row * 132 + d8), x1 = *(const LAS f32x4*)(stf + row * 132 + d8 + 4);
;                 u32x4 yo;
;                 yo.x = cvtpk((w0 * x0[0] + w1 * bf_lo(o1[i].x) + w2 * bf_lo(o2[i].x)) * silu_f(bf_lo(gt[i].x)), (w0 * x0[1] + w1 * bf_hi(o1[i].x) + w2 * bf_hi(o2[i].x)) * silu_f(bf_hi(gt[i].x)));
;                 yo.y = cvtpk((w0 * x0[2] + w1 * bf_lo(o1[i].y) + w2 * bf_lo(o2[i].y)) * silu_f(bf_lo(gt[i].y)), (w0 * x0[3] + w1 * bf_hi(o1[i].y) + w2 * bf_hi(o2[i].y)) * silu_f(bf_hi(gt[i].y)));
;                 yo.z = cvtpk((w0 * x1[0] + w1 * bf_lo(o1[i].z) + w2 * bf_lo(o2[i].z)) * silu_f(bf_lo(gt[i].z)), (w0 * x1[1] + w1 * bf_hi(o1[i].z) + w2 * bf_hi(o2[i].z)) * silu_f(bf_hi(gt[i].z)));
;                 yo.w = cvtpk((w0 * x1[2] + w1 * bf_lo(o1[i].w) + w2 * bf_lo(o2[i].w)) * silu_f(bf_lo(gt[i].w)), (w0 * x1[3] + w1 * bf_hi(o1[i].w) + w2 * bf_hi(o2[i].w)) * silu_f(bf_hi(gt[i].w)));
;                 *(u32x4*)(ybuf + (size_t)tok * DM + h * 128 + d8) = yo; }
	v_lshlrev_b32_e32 v42, 16, v12
	v_and_b32_e32 v43, 0xffff0000, v12
	v_fma_f32 v33, -v27, v32, 1.0
	v_fmac_f32_e32 v32, v33, v32
	v_div_scale_f32 v33, vcc, v35, v29, v35
	v_mul_f32_e32 v36, v33, v32
	v_fma_f32 v37, -v27, v36, v33
	v_fmac_f32_e32 v36, v37, v32
	v_fma_f32 v27, -v27, v36, v33
	v_div_fmas_f32 v27, v27, v32, v36
	v_div_fixup_f32 v29, v27, v29, v35
	v_div_scale_f32 v27, s[4:5], v28, v28, v34
	v_rcp_f32_e32 v32, v27
	s_nop 0
	v_fma_f32 v33, -v27, v32, 1.0
	v_fmac_f32_e32 v32, v33, v32
	v_div_scale_f32 v33, vcc, v34, v28, v34
	v_mul_f32_e32 v35, v33, v32
	v_fma_f32 v36, -v27, v35, v33
	v_fmac_f32_e32 v35, v36, v32
	v_fma_f32 v27, -v27, v35, v33
	v_div_fmas_f32 v27, v27, v32, v35
	v_div_fixup_f32 v28, v27, v28, v34
	v_pk_mul_f32 v[28:29], v[28:29], v[30:31]
	s_nop 0
	v_cvt_pk_bf16_f32 v27, v28, v29
	v_lshl_add_u64 v[28:29], v[52:53], 0, v[70:71]
	global_store_dwordx4 v[28:29], v[24:27], off sc1
	s_nop 1
	v_max3_f32 v24, v40, v83, v82
	v_sub_f32_e32 v25, v40, v24
	v_sub_f32_e32 v26, v83, v24
	v_exp_f32_e32 v25, v25
	v_exp_f32_e32 v26, v26
	v_sub_f32_e32 v24, v82, v24
	v_exp_f32_e32 v24, v24
	v_add_f32_e32 v27, v25, v26
	v_add_f32_e32 v27, v24, v27
	v_div_scale_f32 v28, s[4:5], v27, v27, 1.0
	v_rcp_f32_e32 v29, v28
	s_nop 0
	v_fma_f32 v30, -v28, v29, 1.0
	v_fmac_f32_e32 v29, v30, v29
	v_div_scale_f32 v30, vcc, 1.0, v27, 1.0
	v_mul_f32_e32 v31, v30, v29
	v_fma_f32 v32, -v28, v31, v30
	v_fmac_f32_e32 v31, v32, v29
	v_fma_f32 v28, -v28, v31, v30
	v_div_fmas_f32 v28, v28, v29, v31
	s_waitcnt vmcnt(8)
	v_lshlrev_b32_e32 v29, 16, v20
	v_and_b32_e32 v20, 0xffff0000, v20
	v_mul_f32_e32 v31, 0xbfb8aa3b, v29
	v_mul_f32_e32 v12, 0xbfb8aa3b, v20
	v_exp_f32_e32 v38, v31
	v_exp_f32_e32 v39, v12
	v_div_fixup_f32 v27, v28, v27, 1.0
	v_mul_f32_e32 v30, v25, v27
	v_mul_f32_e32 v32, v26, v27
	v_mul_f32_e32 v28, v24, v27
	ds_read_b128 v[34:37], v81 offset:4224
	ds_read_b128 v[24:27], v81 offset:4240
	v_pk_add_f32 v[38:39], v[38:39], 1.0 op_sel_hi:[1,0]
	v_pk_mul_f32 v[42:43], v[32:33], v[42:43] op_sel_hi:[0,1]
	v_div_scale_f32 v12, s[4:5], v39, v39, v20
	s_waitcnt lgkmcnt(1)
	v_pk_fma_f32 v[34:35], v[34:35], v[30:31], v[42:43] op_sel_hi:[1,0,1]
	s_waitcnt vmcnt(7)
	v_lshlrev_b32_e32 v42, 16, v16
	v_and_b32_e32 v43, 0xffff0000, v16
	v_rcp_f32_e32 v16, v12
	v_pk_fma_f32 v[34:35], v[28:29], v[42:43], v[34:35] op_sel_hi:[0,1,1]
	v_fma_f32 v31, -v12, v16, 1.0
	v_fmac_f32_e32 v16, v31, v16
	v_div_scale_f32 v31, vcc, v20, v39, v20
	v_mul_f32_e32 v33, v31, v16
	v_fma_f32 v40, -v12, v33, v31
	v_fmac_f32_e32 v33, v40, v16
	v_fma_f32 v12, -v12, v33, v31
	v_div_fmas_f32 v12, v12, v16, v33
	v_div_fixup_f32 v39, v12, v39, v20
	v_div_scale_f32 v12, s[4:5], v38, v38, v29
	v_rcp_f32_e32 v16, v12
	s_nop 0
	v_fma_f32 v20, -v12, v16, 1.0
	v_fmac_f32_e32 v16, v20, v16
	v_div_scale_f32 v20, vcc, v29, v38, v29
	v_mul_f32_e32 v31, v20, v16
	v_fma_f32 v33, -v12, v31, v20
	v_fmac_f32_e32 v31, v33, v16
	v_fma_f32 v12, -v12, v31, v20
	v_div_fmas_f32 v12, v12, v16, v31
	v_div_fixup_f32 v38, v12, v38, v29
	v_lshlrev_b32_e32 v29, 16, v21
	v_and_b32_e32 v31, 0xffff0000, v21
	v_pk_mul_f32 v[34:35], v[38:39], v[34:35]
	v_mul_f32_e32 v16, 0xbfb8aa3b, v29
	v_lshlrev_b32_e32 v20, 16, v13
	v_and_b32_e32 v21, 0xffff0000, v13
	v_mul_f32_e32 v13, 0xbfb8aa3b, v31
	v_cvt_pk_bf16_f32 v12, v34, v35
	v_exp_f32_e32 v16, v16
	v_lshlrev_b32_e32 v34, 16, v17
	v_and_b32_e32 v35, 0xffff0000, v17
	v_exp_f32_e32 v17, v13
	v_pk_mul_f32 v[20:21], v[32:33], v[20:21] op_sel_hi:[0,1]
	v_pk_fma_f32 v[20:21], v[36:37], v[30:31], v[20:21] op_sel_hi:[1,0,1]
	v_pk_add_f32 v[16:17], v[16:17], 1.0 op_sel_hi:[1,0]
	s_nop 0
	v_div_scale_f32 v13, s[4:5], v17, v17, v31
	v_rcp_f32_e32 v33, v13
	v_pk_fma_f32 v[20:21], v[28:29], v[34:35], v[20:21] op_sel_hi:[0,1,1]
	v_fma_f32 v34, -v13, v33, 1.0
	v_fmac_f32_e32 v33, v34, v33
	v_div_scale_f32 v34, vcc, v31, v17, v31
	v_mul_f32_e32 v35, v34, v33
	v_fma_f32 v36, -v13, v35, v34
	v_fmac_f32_e32 v35, v36, v33
	v_fma_f32 v13, -v13, v35, v34
	v_div_fmas_f32 v13, v13, v33, v35
	v_div_fixup_f32 v17, v13, v17, v31
	v_div_scale_f32 v13, s[4:5], v16, v16, v29
	v_rcp_f32_e32 v31, v13
	s_nop 0
	v_fma_f32 v33, -v13, v31, 1.0
	v_fmac_f32_e32 v31, v33, v31
	v_div_scale_f32 v33, vcc, v29, v16, v29
	v_mul_f32_e32 v34, v33, v31
	v_fma_f32 v35, -v13, v34, v33
	v_fmac_f32_e32 v34, v35, v31
	v_fma_f32 v13, -v13, v34, v33
	v_div_fmas_f32 v13, v13, v31, v34
	v_div_fixup_f32 v16, v13, v16, v29
	v_pk_mul_f32 v[16:17], v[16:17], v[20:21]
	v_lshlrev_b32_e32 v29, 16, v22
	v_and_b32_e32 v22, 0xffff0000, v22
	v_cvt_pk_bf16_f32 v13, v16, v17
	v_mul_f32_e32 v16, 0xbfb8aa3b, v29
	v_lshlrev_b32_e32 v20, 16, v14
	v_and_b32_e32 v21, 0xffff0000, v14
	v_mul_f32_e32 v14, 0xbfb8aa3b, v22
	v_exp_f32_e32 v16, v16
	v_exp_f32_e32 v17, v14
	v_pk_mul_f32 v[20:21], v[32:33], v[20:21] op_sel_hi:[0,1]
	s_waitcnt lgkmcnt(0)
; #define LAS __attribute__((address_space(3)))
; __device__ __forceinline__ unsigned cvtpk(float lo, float hi) { f32x2_t v = {lo, hi}; bf16x2_t b = __builtin_convertvector(v, bf16x2_t); return __builtin_bit_cast(unsigned, b); }
; __device__ __forceinline__ float silu_f(float x) { return x / (1.0f + __expf(-x)); }
; __device__ __forceinline__ void dil_attn_unit(LAS unsigned char* lds, bf16_t* proj, float* lse, int unit, int Tc, bf16_t* ybuf) {
;     ...
;             for (int i = 0; i < 4; ++i) { const int row = (half * 4 + i) * 4 + (lane >> 4), d8 = (lane & 15) * 8; const int tok = tok0 + row;
;                 const float l0 = lsr[row]; const float mxl = fmaxf(l0, fmaxf(l1[i], l2[i]));
;                 float w0 = __builtin_amdgcn_exp2f(l0 - mxl), w1 = __builtin_amdgcn_exp2f(l1[i] - mxl), w2 = __builtin_amdgcn_exp2f(l2[i] - mxl);
;                 const float iw = 1.0f / (w0 + w1 + w2); w0 *= iw; w1 *= iw; w2 *= iw;
;                 const f32x4 x0 = *(const LAS f32x4*)(stf + row * 132 + d8), x1 = *(const LAS f32x4*)(stf + row * 132 + d8 + 4);
;                 u32x4 yo;
;                 yo.x = cvtpk((w0 * x0[0] + w1 * bf_lo(o1[i].x) + w2 * bf_lo(o2[i].x)) * silu_f(bf_lo(gt[i].x)), (w0 * x0[1] + w1 * bf_hi(o1[i].x) + w2 * bf_hi(o2[i].x)) * silu_f(bf_hi(gt[i].x)));
;                 yo.y = cvtpk((w0 * x0[2] + w1 * bf_lo(o1[i].y) + w2 * bf_lo(o2[i].y)) * silu_f(bf_lo(gt[i].y)), (w0 * x0[3] + w1 * bf_hi(o1[i].y) + w2 * bf_hi(o2[i].y)) * silu_f(bf_hi(gt[i].y)));
;                 yo.z = cvtpk((w0 * x1[0] + w1 * bf_lo(o1[i].z) + w2 * bf_lo(o2[i].z)) * silu_f(bf_lo(gt[i].z)), (w0 * x1[1] + w1 * bf_hi(o1[i].z) + w2 * bf_hi(o2[i].z)) * silu_f(bf_hi(gt[i].z)));
;                 yo.w = cvtpk((w0 * x1[2] + w1 * bf_lo(o1[i].w) + w2 * bf_lo(o2[i].w)) * silu_f(bf_lo(gt[i].w)), (w0 * x1[3] + w1 * bf_hi(o1[i].w) + w2 * bf_hi(o2[i].w)) * silu_f(bf_hi(gt[i].w)));
;                 *(u32x4*)(ybuf + (size_t)tok * DM + h * 128 + d8) = yo; }
	v_pk_fma_f32 v[20:21], v[24:25], v[30:31], v[20:21] op_sel_hi:[1,0,1]
	v_lshlrev_b32_e32 v24, 16, v18
	v_pk_add_f32 v[16:17], v[16:17], 1.0 op_sel_hi:[1,0]
	v_and_b32_e32 v25, 0xffff0000, v18
	v_div_scale_f32 v14, s[4:5], v17, v17, v22
	v_rcp_f32_e32 v18, v14
	v_pk_fma_f32 v[20:21], v[28:29], v[24:25], v[20:21] op_sel_hi:[0,1,1]
	v_fma_f32 v24, -v14, v18, 1.0
	v_fmac_f32_e32 v18, v24, v18
	v_div_scale_f32 v24, vcc, v22, v17, v22
	v_mul_f32_e32 v25, v24, v18
	v_fma_f32 v31, -v14, v25, v24
	v_fmac_f32_e32 v25, v31, v18
	v_fma_f32 v14, -v14, v25, v24
	v_div_fmas_f32 v14, v14, v18, v25
	v_div_fixup_f32 v17, v14, v17, v22
	v_div_scale_f32 v14, s[4:5], v16, v16, v29
	v_rcp_f32_e32 v18, v14
	s_nop 0
	v_fma_f32 v22, -v14, v18, 1.0
	v_fmac_f32_e32 v18, v22, v18
	v_div_scale_f32 v22, vcc, v29, v16, v29
	v_mul_f32_e32 v24, v22, v18
	v_fma_f32 v25, -v14, v24, v22
	v_fmac_f32_e32 v24, v25, v18
	v_fma_f32 v14, -v14, v24, v22
	v_div_fmas_f32 v14, v14, v18, v24
	v_div_fixup_f32 v16, v14, v16, v29
	v_pk_mul_f32 v[16:17], v[16:17], v[20:21]
	v_lshlrev_b32_e32 v22, 16, v23
	v_and_b32_e32 v23, 0xffff0000, v23
	v_cvt_pk_bf16_f32 v14, v16, v17
	v_mul_f32_e32 v16, 0xbfb8aa3b, v22
	v_lshlrev_b32_e32 v20, 16, v15
	v_and_b32_e32 v21, 0xffff0000, v15
	v_mul_f32_e32 v15, 0xbfb8aa3b, v23
	v_exp_f32_e32 v16, v16
	v_exp_f32_e32 v17, v15
	v_pk_mul_f32 v[20:21], v[32:33], v[20:21] op_sel_hi:[0,1]
	v_pk_fma_f32 v[20:21], v[26:27], v[30:31], v[20:21] op_sel_hi:[1,0,1]
	v_lshlrev_b32_e32 v18, 16, v19
	v_pk_add_f32 v[16:17], v[16:17], 1.0 op_sel_hi:[1,0]
	v_and_b32_e32 v19, 0xffff0000, v19
	v_div_scale_f32 v15, s[4:5], v17, v17, v23
	v_pk_fma_f32 v[18:19], v[28:29], v[18:19], v[20:21] op_sel_hi:[0,1,1]
	v_rcp_f32_e32 v20, v15
	s_waitcnt vmcnt(4)
	v_lshlrev_b32_e32 v28, 16, v0
	v_and_b32_e32 v29, 0xffff0000, v0
	v_fma_f32 v21, -v15, v20, 1.0
	v_fmac_f32_e32 v20, v21, v20
	v_div_scale_f32 v21, vcc, v23, v17, v23
	v_mul_f32_e32 v24, v21, v20
	v_fma_f32 v25, -v15, v24, v21
	v_fmac_f32_e32 v24, v25, v20
	v_fma_f32 v15, -v15, v24, v21
	v_div_fmas_f32 v15, v15, v20, v24
	v_div_fixup_f32 v17, v15, v17, v23
	v_div_scale_f32 v15, s[4:5], v16, v16, v22
	v_rcp_f32_e32 v20, v15
	s_nop 0
	v_fma_f32 v21, -v15, v20, 1.0
	v_fmac_f32_e32 v20, v21, v20
	v_div_scale_f32 v21, vcc, v22, v16, v22
	v_mul_f32_e32 v23, v21, v20
	v_fma_f32 v24, -v15, v23, v21
	v_fmac_f32_e32 v23, v24, v20
	v_fma_f32 v15, -v15, v23, v21
	v_div_fmas_f32 v15, v15, v20, v23
	v_div_fixup_f32 v16, v15, v16, v22
	v_pk_mul_f32 v[16:17], v[16:17], v[18:19]
	s_nop 0
	v_cvt_pk_bf16_f32 v15, v16, v17
	v_lshl_add_u64 v[16:17], v[52:53], 0, v[68:69]
	global_store_dwordx4 v[16:17], v[12:15], off sc1
	s_nop 1
	v_max3_f32 v12, v41, v80, v79
	v_sub_f32_e32 v13, v41, v12
	v_sub_f32_e32 v14, v80, v12
	v_exp_f32_e32 v13, v13
	v_exp_f32_e32 v14, v14
	v_sub_f32_e32 v12, v79, v12
	v_exp_f32_e32 v12, v12
	v_add_f32_e32 v15, v13, v14
	v_add_f32_e32 v15, v12, v15
	v_div_scale_f32 v16, s[4:5], v15, v15, 1.0
	v_rcp_f32_e32 v17, v16
	s_nop 0
	v_fma_f32 v18, -v16, v17, 1.0
	v_fmac_f32_e32 v17, v18, v17
	v_div_scale_f32 v18, vcc, 1.0, v15, 1.0
	v_mul_f32_e32 v19, v18, v17
	v_fma_f32 v20, -v16, v19, v18
	v_fmac_f32_e32 v19, v20, v17
	v_fma_f32 v16, -v16, v19, v18
	v_div_fmas_f32 v16, v16, v17, v19
	s_waitcnt vmcnt(3)
	v_lshlrev_b32_e32 v17, 16, v8
	v_and_b32_e32 v8, 0xffff0000, v8
	v_mul_f32_e32 v19, 0xbfb8aa3b, v17
	v_mul_f32_e32 v0, 0xbfb8aa3b, v8
	v_exp_f32_e32 v26, v19
	v_exp_f32_e32 v27, v0
	v_div_fixup_f32 v15, v16, v15, 1.0
	v_mul_f32_e32 v18, v13, v15
	v_mul_f32_e32 v20, v14, v15
	v_mul_f32_e32 v16, v12, v15
	ds_read_b128 v[22:25], v81 offset:6336
	ds_read_b128 v[12:15], v81 offset:6352
	v_pk_add_f32 v[26:27], v[26:27], 1.0 op_sel_hi:[1,0]
	v_pk_mul_f32 v[28:29], v[20:21], v[28:29] op_sel_hi:[0,1]
	v_div_scale_f32 v0, s[4:5], v27, v27, v8
	s_waitcnt lgkmcnt(1)
	v_pk_fma_f32 v[22:23], v[22:23], v[18:19], v[28:29] op_sel_hi:[1,0,1]
	v_lshlrev_b32_e32 v28, 16, v4
	v_and_b32_e32 v29, 0xffff0000, v4
	v_rcp_f32_e32 v4, v0
	v_pk_fma_f32 v[22:23], v[16:17], v[28:29], v[22:23] op_sel_hi:[0,1,1]
	v_fma_f32 v19, -v0, v4, 1.0
	v_fmac_f32_e32 v4, v19, v4
	v_div_scale_f32 v19, vcc, v8, v27, v8
	v_mul_f32_e32 v21, v19, v4
	v_fma_f32 v28, -v0, v21, v19
	v_fmac_f32_e32 v21, v28, v4
	v_fma_f32 v0, -v0, v21, v19
	v_div_fmas_f32 v0, v0, v4, v21
	v_div_fixup_f32 v27, v0, v27, v8
	v_div_scale_f32 v0, s[4:5], v26, v26, v17
	v_rcp_f32_e32 v4, v0
	s_nop 0
	v_fma_f32 v8, -v0, v4, 1.0
	v_fmac_f32_e32 v4, v8, v4
	v_div_scale_f32 v8, vcc, v17, v26, v17
	v_mul_f32_e32 v19, v8, v4
	v_fma_f32 v21, -v0, v19, v8
	v_fmac_f32_e32 v19, v21, v4
	v_fma_f32 v0, -v0, v19, v8
	v_div_fmas_f32 v0, v0, v4, v19
	v_div_fixup_f32 v26, v0, v26, v17
	v_lshlrev_b32_e32 v17, 16, v9
	v_and_b32_e32 v19, 0xffff0000, v9
	v_pk_mul_f32 v[22:23], v[26:27], v[22:23]
	v_mul_f32_e32 v4, 0xbfb8aa3b, v17
	v_lshlrev_b32_e32 v8, 16, v1
	v_and_b32_e32 v9, 0xffff0000, v1
	v_mul_f32_e32 v1, 0xbfb8aa3b, v19
	v_cvt_pk_bf16_f32 v0, v22, v23
	v_exp_f32_e32 v4, v4
	v_lshlrev_b32_e32 v22, 16, v5
	v_and_b32_e32 v23, 0xffff0000, v5
	v_exp_f32_e32 v5, v1
	v_pk_mul_f32 v[8:9], v[20:21], v[8:9] op_sel_hi:[0,1]
	v_pk_fma_f32 v[8:9], v[24:25], v[18:19], v[8:9] op_sel_hi:[1,0,1]
	v_pk_add_f32 v[4:5], v[4:5], 1.0 op_sel_hi:[1,0]
	s_nop 0
	v_div_scale_f32 v1, s[4:5], v5, v5, v19
	v_rcp_f32_e32 v21, v1
	v_pk_fma_f32 v[8:9], v[16:17], v[22:23], v[8:9] op_sel_hi:[0,1,1]
	v_fma_f32 v22, -v1, v21, 1.0
	v_fmac_f32_e32 v21, v22, v21
	v_div_scale_f32 v22, vcc, v19, v5, v19
	v_mul_f32_e32 v23, v22, v21
	v_fma_f32 v24, -v1, v23, v22
	v_fmac_f32_e32 v23, v24, v21
	v_fma_f32 v1, -v1, v23, v22
	v_div_fmas_f32 v1, v1, v21, v23
	v_div_fixup_f32 v5, v1, v5, v19
	v_div_scale_f32 v1, s[4:5], v4, v4, v17
	v_rcp_f32_e32 v19, v1
	s_nop 0
	v_fma_f32 v21, -v1, v19, 1.0
	v_fmac_f32_e32 v19, v21, v19
	v_div_scale_f32 v21, vcc, v17, v4, v17
	v_mul_f32_e32 v22, v21, v19
	v_fma_f32 v23, -v1, v22, v21
	v_fmac_f32_e32 v22, v23, v19
	v_fma_f32 v1, -v1, v22, v21
	v_div_fmas_f32 v1, v1, v19, v22
	v_div_fixup_f32 v4, v1, v4, v17
	v_pk_mul_f32 v[4:5], v[4:5], v[8:9]
	v_lshlrev_b32_e32 v17, 16, v10
	v_and_b32_e32 v10, 0xffff0000, v10
	v_cvt_pk_bf16_f32 v1, v4, v5
	v_mul_f32_e32 v4, 0xbfb8aa3b, v17
	v_lshlrev_b32_e32 v8, 16, v2
	v_and_b32_e32 v9, 0xffff0000, v2
	v_mul_f32_e32 v2, 0xbfb8aa3b, v10
	v_exp_f32_e32 v4, v4
	v_exp_f32_e32 v5, v2
	v_pk_mul_f32 v[8:9], v[20:21], v[8:9] op_sel_hi:[0,1]
	s_waitcnt lgkmcnt(0)
; #define LAS __attribute__((address_space(3)))
; __device__ __forceinline__ void dil_attn_unit(LAS unsigned char* lds, bf16_t* proj, float* lse, int unit, int Tc, bf16_t* ybuf) {
;     ...
;             for (int i = 0; i < 4; ++i) { const int row = (half * 4 + i) * 4 + (lane >> 4), d8 = (lane & 15) * 8; const int tok = tok0 + row, t_ = tok & (SEQ - 1), s4_ = tok & ~(SEQ - 1);
;                 l1[i] = lse[(size_t)tok * 24 + 8 + h]; l2[i] = lse[(size_t)tok * 24 + 16 + h];
;                 o1[i] = *(const u32x4*)(proj + ((size_t)(24 + h) * Tc + s4_ + ((t_ & 3) << 10) + (t_ >> 2)) * 128 + d8);
;                 o2[i] = *(const u32x4*)(proj + ((size_t)(48 + h) * Tc + s4_ + ((t_ & 15) << 8) + (t_ >> 4)) * 128 + d8);
;                 gt[i] = *(const u32x4*)(proj + (size_t)9216 * Tc + (size_t)tok * 1024 + h * 128 + d8); }
;     ...
;             for (int i = 0; i < 4; ++i) { const int row = (half * 4 + i) * 4 + (lane >> 4), d8 = (lane & 15) * 8; const int tok = tok0 + row;
;                 const float l0 = lsr[row]; const float mxl = fmaxf(l0, fmaxf(l1[i], l2[i]));
;                 float w0 = __builtin_amdgcn_exp2f(l0 - mxl), w1 = __builtin_amdgcn_exp2f(l1[i] - mxl), w2 = __builtin_amdgcn_exp2f(l2[i] - mxl);
;                 const float iw = 1.0f / (w0 + w1 + w2); w0 *= iw; w1 *= iw; w2 *= iw;
;                 const f32x4 x0 = *(const LAS f32x4*)(stf + row * 132 + d8), x1 = *(const LAS f32x4*)(stf + row * 132 + d8 + 4);
;                 u32x4 yo;
;                 yo.x = cvtpk((w0 * x0[0] + w1 * bf_lo(o1[i].x) + w2 * bf_lo(o2[i].x)) * silu_f(bf_lo(gt[i].x)), (w0 * x0[1] + w1 * bf_hi(o1[i].x) + w2 * bf_hi(o2[i].x)) * silu_f(bf_hi(gt[i].x)));
;                 yo.y = cvtpk((w0 * x0[2] + w1 * bf_lo(o1[i].y) + w2 * bf_lo(o2[i].y)) * silu_f(bf_lo(gt[i].y)), (w0 * x0[3] + w1 * bf_hi(o1[i].y) + w2 * bf_hi(o2[i].y)) * silu_f(bf_hi(gt[i].y)));
;                 yo.z = cvtpk((w0 * x1[0] + w1 * bf_lo(o1[i].z) + w2 * bf_lo(o2[i].z)) * silu_f(bf_lo(gt[i].z)), (w0 * x1[1] + w1 * bf_hi(o1[i].z) + w2 * bf_hi(o2[i].z)) * silu_f(bf_hi(gt[i].z)));
;                 yo.w = cvtpk((w0 * x1[2] + w1 * bf_lo(o1[i].w) + w2 * bf_lo(o2[i].w)) * silu_f(bf_lo(gt[i].w)), (w0 * x1[3] + w1 * bf_hi(o1[i].w) + w2 * bf_hi(o2[i].w)) * silu_f(bf_hi(gt[i].w)));
;                 *(u32x4*)(ybuf + (size_t)tok * DM + h * 128 + d8) = yo; }
	v_pk_fma_f32 v[8:9], v[12:13], v[18:19], v[8:9] op_sel_hi:[1,0,1]
	v_lshlrev_b32_e32 v12, 16, v6
	v_pk_add_f32 v[4:5], v[4:5], 1.0 op_sel_hi:[1,0]
	v_and_b32_e32 v13, 0xffff0000, v6
	v_div_scale_f32 v2, s[4:5], v5, v5, v10
	v_rcp_f32_e32 v6, v2
	v_pk_fma_f32 v[8:9], v[16:17], v[12:13], v[8:9] op_sel_hi:[0,1,1]
	v_fma_f32 v12, -v2, v6, 1.0
	v_fmac_f32_e32 v6, v12, v6
	v_div_scale_f32 v12, vcc, v10, v5, v10
	v_mul_f32_e32 v13, v12, v6
	v_fma_f32 v19, -v2, v13, v12
	v_fmac_f32_e32 v13, v19, v6
	v_fma_f32 v2, -v2, v13, v12
	v_div_fmas_f32 v2, v2, v6, v13
	v_div_fixup_f32 v5, v2, v5, v10
	v_div_scale_f32 v2, s[4:5], v4, v4, v17
	v_rcp_f32_e32 v6, v2
	s_nop 0
	v_fma_f32 v10, -v2, v6, 1.0
	v_fmac_f32_e32 v6, v10, v6
	v_div_scale_f32 v10, vcc, v17, v4, v17
	v_mul_f32_e32 v12, v10, v6
	v_fma_f32 v13, -v2, v12, v10
	v_fmac_f32_e32 v12, v13, v6
	v_fma_f32 v2, -v2, v12, v10
	v_div_fmas_f32 v2, v2, v6, v12
	v_div_fixup_f32 v4, v2, v4, v17
	v_pk_mul_f32 v[4:5], v[4:5], v[8:9]
	v_lshlrev_b32_e32 v10, 16, v11
	v_and_b32_e32 v11, 0xffff0000, v11
	v_cvt_pk_bf16_f32 v2, v4, v5
	v_mul_f32_e32 v4, 0xbfb8aa3b, v10
	v_lshlrev_b32_e32 v8, 16, v3
	v_and_b32_e32 v9, 0xffff0000, v3
	v_mul_f32_e32 v3, 0xbfb8aa3b, v11
	v_exp_f32_e32 v4, v4
	v_exp_f32_e32 v5, v3
	v_pk_mul_f32 v[8:9], v[20:21], v[8:9] op_sel_hi:[0,1]
	v_pk_fma_f32 v[8:9], v[14:15], v[18:19], v[8:9] op_sel_hi:[1,0,1]
	v_lshlrev_b32_e32 v6, 16, v7
	v_pk_add_f32 v[4:5], v[4:5], 1.0 op_sel_hi:[1,0]
	v_and_b32_e32 v7, 0xffff0000, v7
	v_div_scale_f32 v3, s[4:5], v5, v5, v11
	v_pk_fma_f32 v[6:7], v[16:17], v[6:7], v[8:9] op_sel_hi:[0,1,1]
	v_rcp_f32_e32 v8, v3
	s_nop 0
	v_fma_f32 v9, -v3, v8, 1.0
	v_fmac_f32_e32 v8, v9, v8
	v_div_scale_f32 v9, vcc, v11, v5, v11
	v_mul_f32_e32 v12, v9, v8
	v_fma_f32 v13, -v3, v12, v9
	v_fmac_f32_e32 v12, v13, v8
	v_fma_f32 v3, -v3, v12, v9
	v_div_fmas_f32 v3, v3, v8, v12
	v_div_fixup_f32 v5, v3, v5, v11
	v_div_scale_f32 v3, s[4:5], v4, v4, v10
	v_rcp_f32_e32 v8, v3
	s_nop 0
	v_fma_f32 v9, -v3, v8, 1.0
	v_fmac_f32_e32 v8, v9, v8
	v_div_scale_f32 v9, vcc, v10, v4, v10
	v_mul_f32_e32 v11, v9, v8
	v_fma_f32 v12, -v3, v11, v9
	v_fmac_f32_e32 v11, v12, v8
	v_fma_f32 v3, -v3, v11, v9
	v_div_fmas_f32 v3, v3, v8, v11
	v_div_fixup_f32 v4, v3, v4, v10
	v_pk_mul_f32 v[4:5], v[4:5], v[6:7]
	s_nop 0
	v_cvt_pk_bf16_f32 v3, v4, v5
	v_lshl_add_u64 v[4:5], v[52:53], 0, v[66:67]
	global_store_dwordx4 v[4:5], v[0:3], off sc1
	s_nop 1
	v_or_b32_e32 v0, s41, v48
	v_mov_b32_e32 v1, 0xff3
	v_mad_i64_i32 v[2:3], s[4:5], v0, s66, v[60:61]
	v_bitop3_b32 v4, s41, v1, v48 bitop3:0xc8
	v_lshl_add_u64 v[2:3], v[2:3], 0, s[76:77]
	global_load_dword v49, v[2:3], off offset:32
	global_load_dword v50, v[2:3], off offset:64
	v_lshrrev_b32_e32 v2, 2, v4
	v_or_b32_e32 v2, v58, v2
	v_mov_b32_e32 v3, v59
	v_lshlrev_b64 v[2:3], 8, v[2:3]
	v_lshl_add_u64 v[2:3], v[54:55], 0, v[2:3]
	global_load_dwordx4 v[36:39], v[2:3], off
	v_bfe_u32 v2, v0, 4, 8
	v_ashrrev_i32_e32 v1, 31, v0
	v_or_b32_e32 v62, v78, v2
	v_lshlrev_b64 v[2:3], 8, v[62:63]
	v_lshlrev_b64 v[70:71], 11, v[0:1]
	v_lshl_add_u64 v[2:3], v[54:55], 0, v[2:3]
	v_lshl_add_u64 v[0:1], v[56:57], 0, v[70:71]
	v_or_b32_e32 v4, 20, v75
	global_load_dwordx4 v[40:43], v[2:3], off
	global_load_dwordx4 v[44:47], v[0:1], off
	v_or_b32_e32 v0, s41, v4
	v_mov_b32_e32 v1, 0xff7
	v_mad_i64_i32 v[2:3], s[4:5], v0, s66, v[60:61]
	v_bitop3_b32 v5, s41, v1, v4 bitop3:0xc8
	v_lshl_add_u64 v[2:3], v[2:3], 0, s[76:77]
	global_load_dword v79, v[2:3], off offset:32
	global_load_dword v78, v[2:3], off offset:64
	v_lshrrev_b32_e32 v2, 2, v5
	v_or_b32_e32 v2, v58, v2
	v_mov_b32_e32 v3, v59
	v_lshlrev_b64 v[2:3], 8, v[2:3]
	v_lshl_add_u64 v[2:3], v[54:55], 0, v[2:3]
	global_load_dwordx4 v[24:27], v[2:3], off
	v_lshlrev_b32_e32 v2, 8, v4
	v_and_b32_e32 v2, 0x700, v2
	v_bfe_u32 v3, v0, 4, 8
	v_ashrrev_i32_e32 v1, 31, v0
	v_or3_b32 v62, v3, v2, s0
	v_lshlrev_b64 v[2:3], 8, v[62:63]
	v_lshlrev_b64 v[68:69], 11, v[0:1]
	v_lshl_add_u64 v[2:3], v[54:55], 0, v[2:3]
	v_lshl_add_u64 v[0:1], v[56:57], 0, v[68:69]
	v_or_b32_e32 v4, 24, v75
	global_load_dwordx4 v[28:31], v[2:3], off
	global_load_dwordx4 v[32:35], v[0:1], off
	v_or_b32_e32 v0, s41, v4
	v_mov_b32_e32 v1, 0xffb
	v_mad_i64_i32 v[2:3], s[4:5], v0, s66, v[60:61]
	v_bitop3_b32 v5, s41, v1, v4 bitop3:0xc8
	v_lshl_add_u64 v[2:3], v[2:3], 0, s[76:77]
	global_load_dword v74, v[2:3], off offset:32
	global_load_dword v73, v[2:3], off offset:64
	v_lshrrev_b32_e32 v2, 2, v5
	v_or_b32_e32 v2, v58, v2
	v_mov_b32_e32 v3, v59
	v_lshlrev_b64 v[2:3], 8, v[2:3]
	v_lshl_add_u64 v[2:3], v[54:55], 0, v[2:3]
	global_load_dwordx4 v[12:15], v[2:3], off
	v_lshlrev_b32_e32 v2, 8, v4
	v_and_b32_e32 v2, 0xb00, v2
	v_bfe_u32 v3, v0, 4, 8
	v_ashrrev_i32_e32 v1, 31, v0
	v_or3_b32 v62, v3, v2, s0
	v_lshlrev_b64 v[2:3], 8, v[62:63]
	v_lshlrev_b64 v[66:67], 11, v[0:1]
	v_or_b32_e32 v4, 28, v75
	v_lshl_add_u64 v[2:3], v[54:55], 0, v[2:3]
	v_lshl_add_u64 v[0:1], v[56:57], 0, v[66:67]
	v_or_b32_e32 v8, s41, v4
	global_load_dwordx4 v[16:19], v[2:3], off
	global_load_dwordx4 v[20:23], v[0:1], off
	v_mad_i64_i32 v[0:1], s[4:5], v8, s66, v[60:61]
	v_lshl_add_u64 v[0:1], v[0:1], 0, s[76:77]
	global_load_dword v72, v[0:1], off offset:32
	global_load_dword v61, v[0:1], off offset:64
	v_lshlrev_b32_e32 v4, 8, v4
	v_bfe_u32 v0, v8, 2, 10
	v_and_b32_e32 v4, 0xf00, v4
	v_bfe_u32 v5, v8, 4, 8
	v_or_b32_e32 v58, v58, v0
	v_or3_b32 v62, v5, v4, s0
	v_ashrrev_i32_e32 v9, 31, v8
	v_lshlrev_b64 v[0:1], 8, v[58:59]
	v_lshlrev_b64 v[4:5], 8, v[62:63]
	v_lshl_add_u64 v[0:1], v[54:55], 0, v[0:1]
	v_lshl_add_u64 v[4:5], v[54:55], 0, v[4:5]
	v_lshlrev_b64 v[54:55], 11, v[8:9]
	s_waitcnt vmcnt(15)
; #define LAS __attribute__((address_space(3)))
; __device__ __forceinline__ unsigned cvtpk(float lo, float hi) { f32x2_t v = {lo, hi}; bf16x2_t b = __builtin_convertvector(v, bf16x2_t); return __builtin_bit_cast(unsigned, b); }
; __device__ __forceinline__ float silu_f(float x) { return x / (1.0f + __expf(-x)); }
; __device__ __forceinline__ void dil_attn_unit(LAS unsigned char* lds, bf16_t* proj, float* lse, int unit, int Tc, bf16_t* ybuf) {
;     ...
;             for (int i = 0; i < 4; ++i) { const int row = (half * 4 + i) * 4 + (lane >> 4), d8 = (lane & 15) * 8; const int tok = tok0 + row;
;                 const float l0 = lsr[row]; const float mxl = fmaxf(l0, fmaxf(l1[i], l2[i]));
;                 float w0 = __builtin_amdgcn_exp2f(l0 - mxl), w1 = __builtin_amdgcn_exp2f(l1[i] - mxl), w2 = __builtin_amdgcn_exp2f(l2[i] - mxl);
;                 const float iw = 1.0f / (w0 + w1 + w2); w0 *= iw; w1 *= iw; w2 *= iw;
;                 const f32x4 x0 = *(const LAS f32x4*)(stf + row * 132 + d8), x1 = *(const LAS f32x4*)(stf + row * 132 + d8 + 4);
;                 u32x4 yo;
;                 yo.x = cvtpk((w0 * x0[0] + w1 * bf_lo(o1[i].x) + w2 * bf_lo(o2[i].x)) * silu_f(bf_lo(gt[i].x)), (w0 * x0[1] + w1 * bf_hi(o1[i].x) + w2 * bf_hi(o2[i].x)) * silu_f(bf_hi(gt[i].x)));
;                 yo.y = cvtpk((w0 * x0[2] + w1 * bf_lo(o1[i].y) + w2 * bf_lo(o2[i].y)) * silu_f(bf_lo(gt[i].y)), (w0 * x0[3] + w1 * bf_hi(o1[i].y) + w2 * bf_hi(o2[i].y)) * silu_f(bf_hi(gt[i].y)));
;                 yo.z = cvtpk((w0 * x1[0] + w1 * bf_lo(o1[i].z) + w2 * bf_lo(o2[i].z)) * silu_f(bf_lo(gt[i].z)), (w0 * x1[1] + w1 * bf_hi(o1[i].z) + w2 * bf_hi(o2[i].z)) * silu_f(bf_hi(gt[i].z)));
;                 yo.w = cvtpk((w0 * x1[2] + w1 * bf_lo(o1[i].w) + w2 * bf_lo(o2[i].w)) * silu_f(bf_lo(gt[i].w)), (w0 * x1[3] + w1 * bf_hi(o1[i].w) + w2 * bf_hi(o2[i].w)) * silu_f(bf_hi(gt[i].w)));
;                 *(u32x4*)(ybuf + (size_t)tok * DM + h * 128 + d8) = yo; }
	v_max3_f32 v51, v64, v49, v50
	v_lshl_add_u64 v[8:9], v[56:57], 0, v[54:55]
	v_sub_f32_e32 v56, v64, v51
	v_sub_f32_e32 v49, v49, v51
	v_exp_f32_e32 v56, v56
	v_exp_f32_e32 v49, v49
	v_sub_f32_e32 v50, v50, v51
	v_exp_f32_e32 v50, v50
	s_waitcnt vmcnt(14)
	v_lshlrev_b32_e32 v84, 16, v36
	v_add_f32_e32 v51, v56, v49
	v_and_b32_e32 v85, 0xffff0000, v36
	v_add_f32_e32 v51, v50, v51
	v_div_scale_f32 v57, s[0:1], v51, v51, 1.0
	v_rcp_f32_e32 v58, v57
	global_load_dwordx4 v[0:3], v[0:1], off
	v_fma_f32 v59, -v57, v58, 1.0
	v_fmac_f32_e32 v58, v59, v58
	v_div_scale_f32 v59, vcc, 1.0, v51, 1.0
	v_mul_f32_e32 v60, v59, v58
	v_fma_f32 v62, -v57, v60, v59
	v_fmac_f32_e32 v60, v62, v58
	v_fma_f32 v57, -v57, v60, v59
	s_waitcnt vmcnt(13)
	v_lshlrev_b32_e32 v59, 16, v44
	v_and_b32_e32 v44, 0xffff0000, v44
	v_mul_f32_e32 v62, 0xbfb8aa3b, v59
	v_mul_f32_e32 v36, 0xbfb8aa3b, v44
	v_div_fmas_f32 v57, v57, v58, v60
	v_exp_f32_e32 v62, v62
	v_exp_f32_e32 v63, v36
	v_div_fixup_f32 v51, v57, v51, 1.0
	v_mad_u32_u24 v57, v48, s6, v77
	global_load_dwordx4 v[4:7], v[4:5], off
	v_mul_f32_e32 v58, v56, v51
	global_load_dwordx4 v[8:11], v[8:9], off
	v_mul_f32_e32 v60, v49, v51
	v_mul_f32_e32 v56, v50, v51
	ds_read_b128 v[80:83], v57
	ds_read_b128 v[48:51], v57 offset:16
	v_pk_add_f32 v[62:63], v[62:63], 1.0 op_sel_hi:[1,0]
	s_waitcnt vmcnt(3)
	v_pk_mul_f32 v[84:85], v[60:61], v[84:85] op_sel_hi:[0,1]
	v_div_scale_f32 v36, s[0:1], v63, v63, v44
	s_waitcnt lgkmcnt(1)
	v_pk_fma_f32 v[80:81], v[80:81], v[58:59], v[84:85] op_sel_hi:[1,0,1]
	v_lshlrev_b32_e32 v84, 16, v40
	v_and_b32_e32 v85, 0xffff0000, v40
	v_rcp_f32_e32 v40, v36
	v_pk_fma_f32 v[80:81], v[56:57], v[84:85], v[80:81] op_sel_hi:[0,1,1]
	v_fma_f32 v64, -v36, v40, 1.0
	v_fmac_f32_e32 v40, v64, v40
	v_div_scale_f32 v64, vcc, v44, v63, v44
	v_mul_f32_e32 v75, v64, v40
	v_fma_f32 v77, -v36, v75, v64
	v_fmac_f32_e32 v75, v77, v40
	v_fma_f32 v36, -v36, v75, v64
	v_div_fmas_f32 v36, v36, v40, v75
	v_div_fixup_f32 v63, v36, v63, v44
	v_div_scale_f32 v36, s[0:1], v62, v62, v59
	v_rcp_f32_e32 v40, v36
	s_nop 0
	v_fma_f32 v44, -v36, v40, 1.0
	v_fmac_f32_e32 v40, v44, v40
	v_div_scale_f32 v44, vcc, v59, v62, v59
	v_mul_f32_e32 v64, v44, v40
	v_fma_f32 v75, -v36, v64, v44
	v_fmac_f32_e32 v64, v75, v40
	v_fma_f32 v36, -v36, v64, v44
	v_div_fmas_f32 v36, v36, v40, v64
	v_div_fixup_f32 v62, v36, v62, v59
	v_lshlrev_b32_e32 v59, 16, v45
	v_and_b32_e32 v64, 0xffff0000, v45
	v_pk_mul_f32 v[62:63], v[62:63], v[80:81]
	v_mul_f32_e32 v40, 0xbfb8aa3b, v59
	v_lshlrev_b32_e32 v44, 16, v37
	v_and_b32_e32 v45, 0xffff0000, v37
	v_mul_f32_e32 v37, 0xbfb8aa3b, v64
	v_cvt_pk_bf16_f32 v36, v62, v63
	v_exp_f32_e32 v40, v40
	v_lshlrev_b32_e32 v62, 16, v41
	v_and_b32_e32 v63, 0xffff0000, v41
	v_exp_f32_e32 v41, v37
	v_pk_mul_f32 v[44:45], v[60:61], v[44:45] op_sel_hi:[0,1]
	v_pk_fma_f32 v[44:45], v[82:83], v[58:59], v[44:45] op_sel_hi:[1,0,1]
	v_pk_add_f32 v[40:41], v[40:41], 1.0 op_sel_hi:[1,0]
	s_nop 0
	v_div_scale_f32 v37, s[0:1], v41, v41, v64
	v_pk_fma_f32 v[44:45], v[56:57], v[62:63], v[44:45] op_sel_hi:[0,1,1]
	v_rcp_f32_e32 v62, v37
	s_nop 0
	v_fma_f32 v63, -v37, v62, 1.0
	v_fmac_f32_e32 v62, v63, v62
	v_div_scale_f32 v63, vcc, v64, v41, v64
	v_mul_f32_e32 v75, v63, v62
	v_fma_f32 v77, -v37, v75, v63
	v_fmac_f32_e32 v75, v77, v62
	v_fma_f32 v37, -v37, v75, v63
	v_div_fmas_f32 v37, v37, v62, v75
	v_div_fixup_f32 v41, v37, v41, v64
	v_div_scale_f32 v37, s[0:1], v40, v40, v59
	v_rcp_f32_e32 v62, v37
	s_nop 0
	v_fma_f32 v63, -v37, v62, 1.0
	v_fmac_f32_e32 v62, v63, v62
	v_div_scale_f32 v63, vcc, v59, v40, v59
	v_mul_f32_e32 v64, v63, v62
	v_fma_f32 v75, -v37, v64, v63
	v_fmac_f32_e32 v64, v75, v62
	v_fma_f32 v37, -v37, v64, v63
	v_div_fmas_f32 v37, v37, v62, v64
	v_div_fixup_f32 v40, v37, v40, v59
	v_pk_mul_f32 v[40:41], v[40:41], v[44:45]
	v_lshlrev_b32_e32 v59, 16, v46
	v_and_b32_e32 v46, 0xffff0000, v46
	v_cvt_pk_bf16_f32 v37, v40, v41
	v_mul_f32_e32 v40, 0xbfb8aa3b, v59
	v_lshlrev_b32_e32 v44, 16, v38
	v_and_b32_e32 v45, 0xffff0000, v38
	v_mul_f32_e32 v38, 0xbfb8aa3b, v46
	v_exp_f32_e32 v40, v40
	v_exp_f32_e32 v41, v38
	v_pk_mul_f32 v[44:45], v[60:61], v[44:45] op_sel_hi:[0,1]
	s_waitcnt lgkmcnt(0)
	v_pk_fma_f32 v[44:45], v[48:49], v[58:59], v[44:45] op_sel_hi:[1,0,1]
	v_lshlrev_b32_e32 v48, 16, v42
	v_pk_add_f32 v[40:41], v[40:41], 1.0 op_sel_hi:[1,0]
	v_and_b32_e32 v49, 0xffff0000, v42
	v_div_scale_f32 v38, s[0:1], v41, v41, v46
	v_rcp_f32_e32 v42, v38
	v_pk_fma_f32 v[44:45], v[56:57], v[48:49], v[44:45] op_sel_hi:[0,1,1]
	v_and_b32_e32 v63, 0xffff0000, v24
	v_fma_f32 v48, -v38, v42, 1.0
	v_fmac_f32_e32 v42, v48, v42
	v_div_scale_f32 v48, vcc, v46, v41, v46
	v_mul_f32_e32 v49, v48, v42
	v_fma_f32 v62, -v38, v49, v48
	v_fmac_f32_e32 v49, v62, v42
	v_fma_f32 v38, -v38, v49, v48
	v_div_fmas_f32 v38, v38, v42, v49
	v_div_fixup_f32 v41, v38, v41, v46
	v_div_scale_f32 v38, s[0:1], v40, v40, v59
	v_rcp_f32_e32 v42, v38
	v_lshlrev_b32_e32 v62, 16, v24
	v_fma_f32 v46, -v38, v42, 1.0
	v_fmac_f32_e32 v42, v46, v42
	v_div_scale_f32 v46, vcc, v59, v40, v59
	v_mul_f32_e32 v48, v46, v42
	v_fma_f32 v49, -v38, v48, v46
	v_fmac_f32_e32 v48, v49, v42
	v_fma_f32 v38, -v38, v48, v46
	v_div_fmas_f32 v38, v38, v42, v48
	v_div_fixup_f32 v40, v38, v40, v59
	v_pk_mul_f32 v[40:41], v[40:41], v[44:45]
	v_lshlrev_b32_e32 v46, 16, v47
	v_and_b32_e32 v47, 0xffff0000, v47
	v_cvt_pk_bf16_f32 v38, v40, v41
	v_mul_f32_e32 v40, 0xbfb8aa3b, v46
	v_lshlrev_b32_e32 v44, 16, v39
	v_and_b32_e32 v45, 0xffff0000, v39
	v_mul_f32_e32 v39, 0xbfb8aa3b, v47
	v_exp_f32_e32 v40, v40
	v_exp_f32_e32 v41, v39
	v_pk_mul_f32 v[44:45], v[60:61], v[44:45] op_sel_hi:[0,1]
; #define LAS __attribute__((address_space(3)))
; __device__ __forceinline__ unsigned cvtpk(float lo, float hi) { f32x2_t v = {lo, hi}; bf16x2_t b = __builtin_convertvector(v, bf16x2_t); return __builtin_bit_cast(unsigned, b); }
; __device__ __forceinline__ float silu_f(float x) { return x / (1.0f + __expf(-x)); }
; __device__ __forceinline__ void dil_attn_unit(LAS unsigned char* lds, bf16_t* proj, float* lse, int unit, int Tc, bf16_t* ybuf) {
;     ...
;             for (int i = 0; i < 4; ++i) { const int row = (half * 4 + i) * 4 + (lane >> 4), d8 = (lane & 15) * 8; const int tok = tok0 + row;
;                 const float l0 = lsr[row]; const float mxl = fmaxf(l0, fmaxf(l1[i], l2[i]));
;                 float w0 = __builtin_amdgcn_exp2f(l0 - mxl), w1 = __builtin_amdgcn_exp2f(l1[i] - mxl), w2 = __builtin_amdgcn_exp2f(l2[i] - mxl);
;                 const float iw = 1.0f / (w0 + w1 + w2); w0 *= iw; w1 *= iw; w2 *= iw;
;                 const f32x4 x0 = *(const LAS f32x4*)(stf + row * 132 + d8), x1 = *(const LAS f32x4*)(stf + row * 132 + d8 + 4);
;                 u32x4 yo;
;                 yo.x = cvtpk((w0 * x0[0] + w1 * bf_lo(o1[i].x) + w2 * bf_lo(o2[i].x)) * silu_f(bf_lo(gt[i].x)), (w0 * x0[1] + w1 * bf_hi(o1[i].x) + w2 * bf_hi(o2[i].x)) * silu_f(bf_hi(gt[i].x)));
;                 yo.y = cvtpk((w0 * x0[2] + w1 * bf_lo(o1[i].y) + w2 * bf_lo(o2[i].y)) * silu_f(bf_lo(gt[i].y)), (w0 * x0[3] + w1 * bf_hi(o1[i].y) + w2 * bf_hi(o2[i].y)) * silu_f(bf_hi(gt[i].y)));
;                 yo.z = cvtpk((w0 * x1[0] + w1 * bf_lo(o1[i].z) + w2 * bf_lo(o2[i].z)) * silu_f(bf_lo(gt[i].z)), (w0 * x1[1] + w1 * bf_hi(o1[i].z) + w2 * bf_hi(o2[i].z)) * silu_f(bf_hi(gt[i].z)));
;                 yo.w = cvtpk((w0 * x1[2] + w1 * bf_lo(o1[i].w) + w2 * bf_lo(o2[i].w)) * silu_f(bf_lo(gt[i].w)), (w0 * x1[3] + w1 * bf_hi(o1[i].w) + w2 * bf_hi(o2[i].w)) * silu_f(bf_hi(gt[i].w)));
;                 *(u32x4*)(ybuf + (size_t)tok * DM + h * 128 + d8) = yo; }
	v_pk_fma_f32 v[44:45], v[50:51], v[58:59], v[44:45] op_sel_hi:[1,0,1]
	v_lshlrev_b32_e32 v42, 16, v43
	v_pk_add_f32 v[40:41], v[40:41], 1.0 op_sel_hi:[1,0]
	v_and_b32_e32 v43, 0xffff0000, v43
	v_div_scale_f32 v39, s[0:1], v41, v41, v47
	v_pk_fma_f32 v[42:43], v[56:57], v[42:43], v[44:45] op_sel_hi:[0,1,1]
	v_rcp_f32_e32 v44, v39
	s_nop 0
	v_fma_f32 v45, -v39, v44, 1.0
	v_fmac_f32_e32 v44, v45, v44
	v_div_scale_f32 v45, vcc, v47, v41, v47
	v_mul_f32_e32 v48, v45, v44
	v_fma_f32 v49, -v39, v48, v45
	v_fmac_f32_e32 v48, v49, v44
	v_fma_f32 v39, -v39, v48, v45
	v_div_fmas_f32 v39, v39, v44, v48
	v_div_fixup_f32 v41, v39, v41, v47
	v_div_scale_f32 v39, s[0:1], v40, v40, v46
	v_rcp_f32_e32 v44, v39
	s_nop 0
	v_fma_f32 v45, -v39, v44, 1.0
	v_fmac_f32_e32 v44, v45, v44
	v_div_scale_f32 v45, vcc, v46, v40, v46
	v_mul_f32_e32 v47, v45, v44
	v_fma_f32 v48, -v39, v47, v45
	v_fmac_f32_e32 v47, v48, v44
	v_fma_f32 v39, -v39, v47, v45
	v_div_fmas_f32 v39, v39, v44, v47
	v_div_fixup_f32 v40, v39, v40, v46
	v_pk_mul_f32 v[40:41], v[40:41], v[42:43]
	s_nop 0
	v_cvt_pk_bf16_f32 v39, v40, v41
	v_lshl_add_u64 v[40:41], v[52:53], 0, v[70:71]
	global_store_dwordx4 v[40:41], v[36:39], off sc1
	ds_read2_b32 v[40:41], v76 offset0:152 offset1:156
	s_nop 0
	v_max3_f32 v36, v65, v79, v78
	v_sub_f32_e32 v37, v65, v36
	v_sub_f32_e32 v38, v79, v36
	v_exp_f32_e32 v37, v37
	v_exp_f32_e32 v38, v38
	v_sub_f32_e32 v36, v78, v36
	v_exp_f32_e32 v36, v36
	v_add_f32_e32 v39, v37, v38
	v_add_f32_e32 v39, v36, v39
	v_div_scale_f32 v42, s[0:1], v39, v39, 1.0
	v_rcp_f32_e32 v43, v42
	s_nop 0
	v_fma_f32 v44, -v42, v43, 1.0
	v_fmac_f32_e32 v43, v44, v43
	v_div_scale_f32 v44, vcc, 1.0, v39, 1.0
	v_mul_f32_e32 v45, v44, v43
	v_fma_f32 v46, -v42, v45, v44
	v_fmac_f32_e32 v45, v46, v43
	v_fma_f32 v42, -v42, v45, v44
	v_div_fmas_f32 v42, v42, v43, v45
	v_lshlrev_b32_e32 v43, 16, v32
	v_and_b32_e32 v32, 0xffff0000, v32
	v_mul_f32_e32 v45, 0xbfb8aa3b, v43
	v_mul_f32_e32 v24, 0xbfb8aa3b, v32
	v_exp_f32_e32 v58, v45
	v_exp_f32_e32 v59, v24
	v_div_fixup_f32 v39, v42, v39, 1.0
	v_mul_f32_e32 v44, v37, v39
	v_mul_f32_e32 v46, v38, v39
	v_mul_f32_e32 v42, v36, v39
	ds_read_b128 v[48:51], v57 offset:2112
	ds_read_b128 v[36:39], v57 offset:2128
	v_pk_add_f32 v[58:59], v[58:59], 1.0 op_sel_hi:[1,0]
	v_pk_mul_f32 v[62:63], v[46:47], v[62:63] op_sel_hi:[0,1]
	v_div_scale_f32 v24, s[0:1], v59, v59, v32
	s_waitcnt lgkmcnt(1)
	v_pk_fma_f32 v[48:49], v[48:49], v[44:45], v[62:63] op_sel_hi:[1,0,1]
	v_lshlrev_b32_e32 v62, 16, v28
	v_and_b32_e32 v63, 0xffff0000, v28
	v_rcp_f32_e32 v28, v24
	v_pk_fma_f32 v[48:49], v[42:43], v[62:63], v[48:49] op_sel_hi:[0,1,1]
	v_fma_f32 v45, -v24, v28, 1.0
	v_fmac_f32_e32 v28, v45, v28
	v_div_scale_f32 v45, vcc, v32, v59, v32
	v_mul_f32_e32 v47, v45, v28
	v_fma_f32 v56, -v24, v47, v45
	v_fmac_f32_e32 v47, v56, v28
	v_fma_f32 v24, -v24, v47, v45
	v_div_fmas_f32 v24, v24, v28, v47
	v_div_fixup_f32 v59, v24, v59, v32
	v_div_scale_f32 v24, s[0:1], v58, v58, v43
	v_rcp_f32_e32 v28, v24
	s_nop 0
	v_fma_f32 v32, -v24, v28, 1.0
	v_fmac_f32_e32 v28, v32, v28
	v_div_scale_f32 v32, vcc, v43, v58, v43
	v_mul_f32_e32 v45, v32, v28
	v_fma_f32 v47, -v24, v45, v32
	v_fmac_f32_e32 v45, v47, v28
	v_fma_f32 v24, -v24, v45, v32
	v_div_fmas_f32 v24, v24, v28, v45
	v_div_fixup_f32 v58, v24, v58, v43
	v_lshlrev_b32_e32 v43, 16, v33
	v_and_b32_e32 v45, 0xffff0000, v33
	v_pk_mul_f32 v[48:49], v[58:59], v[48:49]
	v_mul_f32_e32 v28, 0xbfb8aa3b, v43
	v_lshlrev_b32_e32 v32, 16, v25
	v_and_b32_e32 v33, 0xffff0000, v25
	v_mul_f32_e32 v25, 0xbfb8aa3b, v45
	v_cvt_pk_bf16_f32 v24, v48, v49
	v_exp_f32_e32 v28, v28
	v_lshlrev_b32_e32 v48, 16, v29
	v_and_b32_e32 v49, 0xffff0000, v29
	v_exp_f32_e32 v29, v25
	v_pk_mul_f32 v[32:33], v[46:47], v[32:33] op_sel_hi:[0,1]
	v_pk_fma_f32 v[32:33], v[50:51], v[44:45], v[32:33] op_sel_hi:[1,0,1]
	v_pk_add_f32 v[28:29], v[28:29], 1.0 op_sel_hi:[1,0]
	s_nop 0
	v_div_scale_f32 v25, s[0:1], v29, v29, v45
	v_rcp_f32_e32 v47, v25
	v_pk_fma_f32 v[32:33], v[42:43], v[48:49], v[32:33] op_sel_hi:[0,1,1]
	v_fma_f32 v48, -v25, v47, 1.0
	v_fmac_f32_e32 v47, v48, v47
	v_div_scale_f32 v48, vcc, v45, v29, v45
	v_mul_f32_e32 v49, v48, v47
	v_fma_f32 v50, -v25, v49, v48
	v_fmac_f32_e32 v49, v50, v47
	v_fma_f32 v25, -v25, v49, v48
	v_div_fmas_f32 v25, v25, v47, v49
	v_div_fixup_f32 v29, v25, v29, v45
	v_div_scale_f32 v25, s[0:1], v28, v28, v43
	v_rcp_f32_e32 v45, v25
	s_nop 0
	v_fma_f32 v47, -v25, v45, 1.0
	v_fmac_f32_e32 v45, v47, v45
	v_div_scale_f32 v47, vcc, v43, v28, v43
	v_mul_f32_e32 v48, v47, v45
	v_fma_f32 v49, -v25, v48, v47
	v_fmac_f32_e32 v48, v49, v45
	v_fma_f32 v25, -v25, v48, v47
	v_div_fmas_f32 v25, v25, v45, v48
	v_div_fixup_f32 v28, v25, v28, v43
	v_pk_mul_f32 v[28:29], v[28:29], v[32:33]
	v_lshlrev_b32_e32 v43, 16, v34
	v_and_b32_e32 v34, 0xffff0000, v34
	v_cvt_pk_bf16_f32 v25, v28, v29
	v_mul_f32_e32 v28, 0xbfb8aa3b, v43
	v_lshlrev_b32_e32 v32, 16, v26
	v_and_b32_e32 v33, 0xffff0000, v26
	v_mul_f32_e32 v26, 0xbfb8aa3b, v34
	v_exp_f32_e32 v28, v28
	v_exp_f32_e32 v29, v26
	v_pk_mul_f32 v[32:33], v[46:47], v[32:33] op_sel_hi:[0,1]
	s_waitcnt lgkmcnt(0)
; #define LAS __attribute__((address_space(3)))
; __device__ __forceinline__ unsigned cvtpk(float lo, float hi) { f32x2_t v = {lo, hi}; bf16x2_t b = __builtin_convertvector(v, bf16x2_t); return __builtin_bit_cast(unsigned, b); }
; __device__ __forceinline__ float silu_f(float x) { return x / (1.0f + __expf(-x)); }
; __device__ __forceinline__ void dil_attn_unit(LAS unsigned char* lds, bf16_t* proj, float* lse, int unit, int Tc, bf16_t* ybuf) {
;     ...
;             for (int i = 0; i < 4; ++i) { const int row = (half * 4 + i) * 4 + (lane >> 4), d8 = (lane & 15) * 8; const int tok = tok0 + row;
;                 const float l0 = lsr[row]; const float mxl = fmaxf(l0, fmaxf(l1[i], l2[i]));
;                 float w0 = __builtin_amdgcn_exp2f(l0 - mxl), w1 = __builtin_amdgcn_exp2f(l1[i] - mxl), w2 = __builtin_amdgcn_exp2f(l2[i] - mxl);
;                 const float iw = 1.0f / (w0 + w1 + w2); w0 *= iw; w1 *= iw; w2 *= iw;
;                 const f32x4 x0 = *(const LAS f32x4*)(stf + row * 132 + d8), x1 = *(const LAS f32x4*)(stf + row * 132 + d8 + 4);
;                 u32x4 yo;
;                 yo.x = cvtpk((w0 * x0[0] + w1 * bf_lo(o1[i].x) + w2 * bf_lo(o2[i].x)) * silu_f(bf_lo(gt[i].x)), (w0 * x0[1] + w1 * bf_hi(o1[i].x) + w2 * bf_hi(o2[i].x)) * silu_f(bf_hi(gt[i].x)));
;                 yo.y = cvtpk((w0 * x0[2] + w1 * bf_lo(o1[i].y) + w2 * bf_lo(o2[i].y)) * silu_f(bf_lo(gt[i].y)), (w0 * x0[3] + w1 * bf_hi(o1[i].y) + w2 * bf_hi(o2[i].y)) * silu_f(bf_hi(gt[i].y)));
;                 yo.z = cvtpk((w0 * x1[0] + w1 * bf_lo(o1[i].z) + w2 * bf_lo(o2[i].z)) * silu_f(bf_lo(gt[i].z)), (w0 * x1[1] + w1 * bf_hi(o1[i].z) + w2 * bf_hi(o2[i].z)) * silu_f(bf_hi(gt[i].z)));
;                 yo.w = cvtpk((w0 * x1[2] + w1 * bf_lo(o1[i].w) + w2 * bf_lo(o2[i].w)) * silu_f(bf_lo(gt[i].w)), (w0 * x1[3] + w1 * bf_hi(o1[i].w) + w2 * bf_hi(o2[i].w)) * silu_f(bf_hi(gt[i].w)));
;                 *(u32x4*)(ybuf + (size_t)tok * DM + h * 128 + d8) = yo; }
	v_pk_fma_f32 v[32:33], v[36:37], v[44:45], v[32:33] op_sel_hi:[1,0,1]
	v_lshlrev_b32_e32 v36, 16, v30
	v_pk_add_f32 v[28:29], v[28:29], 1.0 op_sel_hi:[1,0]
	v_and_b32_e32 v37, 0xffff0000, v30
	v_div_scale_f32 v26, s[0:1], v29, v29, v34
	v_rcp_f32_e32 v30, v26
	v_pk_fma_f32 v[32:33], v[42:43], v[36:37], v[32:33] op_sel_hi:[0,1,1]
	v_fma_f32 v36, -v26, v30, 1.0
	v_fmac_f32_e32 v30, v36, v30
	v_div_scale_f32 v36, vcc, v34, v29, v34
	v_mul_f32_e32 v37, v36, v30
	v_fma_f32 v45, -v26, v37, v36
	v_fmac_f32_e32 v37, v45, v30
	v_fma_f32 v26, -v26, v37, v36
	v_div_fmas_f32 v26, v26, v30, v37
	v_div_fixup_f32 v29, v26, v29, v34
	v_div_scale_f32 v26, s[0:1], v28, v28, v43
	v_rcp_f32_e32 v30, v26
	s_nop 0
	v_fma_f32 v34, -v26, v30, 1.0
	v_fmac_f32_e32 v30, v34, v30
	v_div_scale_f32 v34, vcc, v43, v28, v43
	v_mul_f32_e32 v36, v34, v30
	v_fma_f32 v37, -v26, v36, v34
	v_fmac_f32_e32 v36, v37, v30
	v_fma_f32 v26, -v26, v36, v34
	v_div_fmas_f32 v26, v26, v30, v36
	v_div_fixup_f32 v28, v26, v28, v43
	v_pk_mul_f32 v[28:29], v[28:29], v[32:33]
	v_lshlrev_b32_e32 v34, 16, v35
	v_and_b32_e32 v35, 0xffff0000, v35
	v_cvt_pk_bf16_f32 v26, v28, v29
	v_mul_f32_e32 v28, 0xbfb8aa3b, v34
	v_lshlrev_b32_e32 v32, 16, v27
	v_and_b32_e32 v33, 0xffff0000, v27
	v_mul_f32_e32 v27, 0xbfb8aa3b, v35
	v_exp_f32_e32 v28, v28
	v_exp_f32_e32 v29, v27
	v_pk_mul_f32 v[32:33], v[46:47], v[32:33] op_sel_hi:[0,1]
	v_pk_fma_f32 v[32:33], v[38:39], v[44:45], v[32:33] op_sel_hi:[1,0,1]
	v_lshlrev_b32_e32 v30, 16, v31
	v_pk_add_f32 v[28:29], v[28:29], 1.0 op_sel_hi:[1,0]
	v_and_b32_e32 v31, 0xffff0000, v31
	v_div_scale_f32 v27, s[0:1], v29, v29, v35
	v_pk_fma_f32 v[30:31], v[42:43], v[30:31], v[32:33] op_sel_hi:[0,1,1]
	v_rcp_f32_e32 v32, v27
	v_lshlrev_b32_e32 v42, 16, v12
	v_and_b32_e32 v43, 0xffff0000, v12
	v_fma_f32 v33, -v27, v32, 1.0
	v_fmac_f32_e32 v32, v33, v32
	v_div_scale_f32 v33, vcc, v35, v29, v35
	v_mul_f32_e32 v36, v33, v32
	v_fma_f32 v37, -v27, v36, v33
	v_fmac_f32_e32 v36, v37, v32
	v_fma_f32 v27, -v27, v36, v33
	v_div_fmas_f32 v27, v27, v32, v36
	v_div_fixup_f32 v29, v27, v29, v35
	v_div_scale_f32 v27, s[0:1], v28, v28, v34
	v_rcp_f32_e32 v32, v27
	s_nop 0
	v_fma_f32 v33, -v27, v32, 1.0
	v_fmac_f32_e32 v32, v33, v32
	v_div_scale_f32 v33, vcc, v34, v28, v34
	v_mul_f32_e32 v35, v33, v32
	v_fma_f32 v36, -v27, v35, v33
	v_fmac_f32_e32 v35, v36, v32
	v_fma_f32 v27, -v27, v35, v33
	v_div_fmas_f32 v27, v27, v32, v35
	v_div_fixup_f32 v28, v27, v28, v34
	v_pk_mul_f32 v[28:29], v[28:29], v[30:31]
	s_nop 0
	v_cvt_pk_bf16_f32 v27, v28, v29
	v_lshl_add_u64 v[28:29], v[52:53], 0, v[68:69]
	global_store_dwordx4 v[28:29], v[24:27], off sc1
	s_nop 1
	v_max3_f32 v24, v40, v74, v73
	v_sub_f32_e32 v25, v40, v24
	v_sub_f32_e32 v26, v74, v24
	v_exp_f32_e32 v25, v25
	v_exp_f32_e32 v26, v26
	v_sub_f32_e32 v24, v73, v24
	v_exp_f32_e32 v24, v24
	v_add_f32_e32 v27, v25, v26
	v_add_f32_e32 v27, v24, v27
	v_div_scale_f32 v28, s[0:1], v27, v27, 1.0
	v_rcp_f32_e32 v29, v28
	s_nop 0
	v_fma_f32 v30, -v28, v29, 1.0
	v_fmac_f32_e32 v29, v30, v29
	v_div_scale_f32 v30, vcc, 1.0, v27, 1.0
	v_mul_f32_e32 v31, v30, v29
	v_fma_f32 v32, -v28, v31, v30
	v_fmac_f32_e32 v31, v32, v29
	v_fma_f32 v28, -v28, v31, v30
	v_div_fmas_f32 v28, v28, v29, v31
	v_lshlrev_b32_e32 v29, 16, v20
	v_and_b32_e32 v20, 0xffff0000, v20
	v_mul_f32_e32 v31, 0xbfb8aa3b, v29
	v_mul_f32_e32 v12, 0xbfb8aa3b, v20
	v_exp_f32_e32 v38, v31
	v_exp_f32_e32 v39, v12
	v_div_fixup_f32 v27, v28, v27, 1.0
	v_mul_f32_e32 v30, v25, v27
	v_mul_f32_e32 v32, v26, v27
	v_mul_f32_e32 v28, v24, v27
	ds_read_b128 v[34:37], v57 offset:4224
	ds_read_b128 v[24:27], v57 offset:4240
	v_pk_add_f32 v[38:39], v[38:39], 1.0 op_sel_hi:[1,0]
	v_pk_mul_f32 v[42:43], v[32:33], v[42:43] op_sel_hi:[0,1]
	v_div_scale_f32 v12, s[0:1], v39, v39, v20
	s_waitcnt lgkmcnt(1)
	v_pk_fma_f32 v[34:35], v[34:35], v[30:31], v[42:43] op_sel_hi:[1,0,1]
	v_lshlrev_b32_e32 v42, 16, v16
	v_and_b32_e32 v43, 0xffff0000, v16
	v_rcp_f32_e32 v16, v12
	v_pk_fma_f32 v[34:35], v[28:29], v[42:43], v[34:35] op_sel_hi:[0,1,1]
	v_fma_f32 v31, -v12, v16, 1.0
	v_fmac_f32_e32 v16, v31, v16
	v_div_scale_f32 v31, vcc, v20, v39, v20
	v_mul_f32_e32 v33, v31, v16
	v_fma_f32 v40, -v12, v33, v31
	v_fmac_f32_e32 v33, v40, v16
	v_fma_f32 v12, -v12, v33, v31
	v_div_fmas_f32 v12, v12, v16, v33
	v_div_fixup_f32 v39, v12, v39, v20
	v_div_scale_f32 v12, s[0:1], v38, v38, v29
	v_rcp_f32_e32 v16, v12
	s_nop 0
	v_fma_f32 v20, -v12, v16, 1.0
	v_fmac_f32_e32 v16, v20, v16
	v_div_scale_f32 v20, vcc, v29, v38, v29
	v_mul_f32_e32 v31, v20, v16
	v_fma_f32 v33, -v12, v31, v20
	v_fmac_f32_e32 v31, v33, v16
	v_fma_f32 v12, -v12, v31, v20
	v_div_fmas_f32 v12, v12, v16, v31
	v_div_fixup_f32 v38, v12, v38, v29
	v_lshlrev_b32_e32 v29, 16, v21
	v_and_b32_e32 v31, 0xffff0000, v21
	v_pk_mul_f32 v[34:35], v[38:39], v[34:35]
	v_mul_f32_e32 v16, 0xbfb8aa3b, v29
	v_lshlrev_b32_e32 v20, 16, v13
	v_and_b32_e32 v21, 0xffff0000, v13
	v_mul_f32_e32 v13, 0xbfb8aa3b, v31
	v_cvt_pk_bf16_f32 v12, v34, v35
	v_exp_f32_e32 v16, v16
	v_lshlrev_b32_e32 v34, 16, v17
	v_and_b32_e32 v35, 0xffff0000, v17
	v_exp_f32_e32 v17, v13
	v_pk_mul_f32 v[20:21], v[32:33], v[20:21] op_sel_hi:[0,1]
	v_pk_fma_f32 v[20:21], v[36:37], v[30:31], v[20:21] op_sel_hi:[1,0,1]
	v_pk_add_f32 v[16:17], v[16:17], 1.0 op_sel_hi:[1,0]
	s_nop 0
	v_div_scale_f32 v13, s[0:1], v17, v17, v31
	v_rcp_f32_e32 v33, v13
	v_pk_fma_f32 v[20:21], v[28:29], v[34:35], v[20:21] op_sel_hi:[0,1,1]
	v_fma_f32 v34, -v13, v33, 1.0
	v_fmac_f32_e32 v33, v34, v33
	v_div_scale_f32 v34, vcc, v31, v17, v31
	v_mul_f32_e32 v35, v34, v33
	v_fma_f32 v36, -v13, v35, v34
	v_fmac_f32_e32 v35, v36, v33
	v_fma_f32 v13, -v13, v35, v34
	v_div_fmas_f32 v13, v13, v33, v35
	v_div_fixup_f32 v17, v13, v17, v31
	v_div_scale_f32 v13, s[0:1], v16, v16, v29
	v_rcp_f32_e32 v31, v13
	s_nop 0
	v_fma_f32 v33, -v13, v31, 1.0
	v_fmac_f32_e32 v31, v33, v31
	v_div_scale_f32 v33, vcc, v29, v16, v29
	v_mul_f32_e32 v34, v33, v31
	v_fma_f32 v35, -v13, v34, v33
	v_fmac_f32_e32 v34, v35, v31
	v_fma_f32 v13, -v13, v34, v33
	v_div_fmas_f32 v13, v13, v31, v34
	v_div_fixup_f32 v16, v13, v16, v29
	v_pk_mul_f32 v[16:17], v[16:17], v[20:21]
	v_lshlrev_b32_e32 v29, 16, v22
	v_and_b32_e32 v22, 0xffff0000, v22
	v_cvt_pk_bf16_f32 v13, v16, v17
	v_mul_f32_e32 v16, 0xbfb8aa3b, v29
	v_lshlrev_b32_e32 v20, 16, v14
	v_and_b32_e32 v21, 0xffff0000, v14
	v_mul_f32_e32 v14, 0xbfb8aa3b, v22
	v_exp_f32_e32 v16, v16
	v_exp_f32_e32 v17, v14
	v_pk_mul_f32 v[20:21], v[32:33], v[20:21] op_sel_hi:[0,1]
	s_waitcnt lgkmcnt(0)
; #define LAS __attribute__((address_space(3)))
; __device__ __forceinline__ unsigned cvtpk(float lo, float hi) { f32x2_t v = {lo, hi}; bf16x2_t b = __builtin_convertvector(v, bf16x2_t); return __builtin_bit_cast(unsigned, b); }
; __device__ __forceinline__ float silu_f(float x) { return x / (1.0f + __expf(-x)); }
; __device__ __forceinline__ void dil_attn_unit(LAS unsigned char* lds, bf16_t* proj, float* lse, int unit, int Tc, bf16_t* ybuf) {
;     ...
;             for (int i = 0; i < 4; ++i) { const int row = (half * 4 + i) * 4 + (lane >> 4), d8 = (lane & 15) * 8; const int tok = tok0 + row;
;                 const float l0 = lsr[row]; const float mxl = fmaxf(l0, fmaxf(l1[i], l2[i]));
;                 float w0 = __builtin_amdgcn_exp2f(l0 - mxl), w1 = __builtin_amdgcn_exp2f(l1[i] - mxl), w2 = __builtin_amdgcn_exp2f(l2[i] - mxl);
;                 const float iw = 1.0f / (w0 + w1 + w2); w0 *= iw; w1 *= iw; w2 *= iw;
;                 const f32x4 x0 = *(const LAS f32x4*)(stf + row * 132 + d8), x1 = *(const LAS f32x4*)(stf + row * 132 + d8 + 4);
;                 u32x4 yo;
;                 yo.x = cvtpk((w0 * x0[0] + w1 * bf_lo(o1[i].x) + w2 * bf_lo(o2[i].x)) * silu_f(bf_lo(gt[i].x)), (w0 * x0[1] + w1 * bf_hi(o1[i].x) + w2 * bf_hi(o2[i].x)) * silu_f(bf_hi(gt[i].x)));
;                 yo.y = cvtpk((w0 * x0[2] + w1 * bf_lo(o1[i].y) + w2 * bf_lo(o2[i].y)) * silu_f(bf_lo(gt[i].y)), (w0 * x0[3] + w1 * bf_hi(o1[i].y) + w2 * bf_hi(o2[i].y)) * silu_f(bf_hi(gt[i].y)));
;                 yo.z = cvtpk((w0 * x1[0] + w1 * bf_lo(o1[i].z) + w2 * bf_lo(o2[i].z)) * silu_f(bf_lo(gt[i].z)), (w0 * x1[1] + w1 * bf_hi(o1[i].z) + w2 * bf_hi(o2[i].z)) * silu_f(bf_hi(gt[i].z)));
;                 yo.w = cvtpk((w0 * x1[2] + w1 * bf_lo(o1[i].w) + w2 * bf_lo(o2[i].w)) * silu_f(bf_lo(gt[i].w)), (w0 * x1[3] + w1 * bf_hi(o1[i].w) + w2 * bf_hi(o2[i].w)) * silu_f(bf_hi(gt[i].w)));
;                 *(u32x4*)(ybuf + (size_t)tok * DM + h * 128 + d8) = yo; }
	v_pk_fma_f32 v[20:21], v[24:25], v[30:31], v[20:21] op_sel_hi:[1,0,1]
	v_lshlrev_b32_e32 v24, 16, v18
	v_pk_add_f32 v[16:17], v[16:17], 1.0 op_sel_hi:[1,0]
	v_and_b32_e32 v25, 0xffff0000, v18
	v_div_scale_f32 v14, s[0:1], v17, v17, v22
	v_rcp_f32_e32 v18, v14
	v_pk_fma_f32 v[20:21], v[28:29], v[24:25], v[20:21] op_sel_hi:[0,1,1]
	v_fma_f32 v24, -v14, v18, 1.0
	v_fmac_f32_e32 v18, v24, v18
	v_div_scale_f32 v24, vcc, v22, v17, v22
	v_mul_f32_e32 v25, v24, v18
	v_fma_f32 v31, -v14, v25, v24
	v_fmac_f32_e32 v25, v31, v18
	v_fma_f32 v14, -v14, v25, v24
	v_div_fmas_f32 v14, v14, v18, v25
	v_div_fixup_f32 v17, v14, v17, v22
	v_div_scale_f32 v14, s[0:1], v16, v16, v29
	v_rcp_f32_e32 v18, v14
	s_nop 0
	v_fma_f32 v22, -v14, v18, 1.0
	v_fmac_f32_e32 v18, v22, v18
	v_div_scale_f32 v22, vcc, v29, v16, v29
	v_mul_f32_e32 v24, v22, v18
	v_fma_f32 v25, -v14, v24, v22
	v_fmac_f32_e32 v24, v25, v18
	v_fma_f32 v14, -v14, v24, v22
	v_div_fmas_f32 v14, v14, v18, v24
	v_div_fixup_f32 v16, v14, v16, v29
	v_pk_mul_f32 v[16:17], v[16:17], v[20:21]
	v_lshlrev_b32_e32 v22, 16, v23
	v_and_b32_e32 v23, 0xffff0000, v23
	v_cvt_pk_bf16_f32 v14, v16, v17
	v_mul_f32_e32 v16, 0xbfb8aa3b, v22
	v_lshlrev_b32_e32 v20, 16, v15
	v_and_b32_e32 v21, 0xffff0000, v15
	v_mul_f32_e32 v15, 0xbfb8aa3b, v23
	v_exp_f32_e32 v16, v16
	v_exp_f32_e32 v17, v15
	v_pk_mul_f32 v[20:21], v[32:33], v[20:21] op_sel_hi:[0,1]
	v_pk_fma_f32 v[20:21], v[26:27], v[30:31], v[20:21] op_sel_hi:[1,0,1]
	v_lshlrev_b32_e32 v18, 16, v19
	v_pk_add_f32 v[16:17], v[16:17], 1.0 op_sel_hi:[1,0]
	v_and_b32_e32 v19, 0xffff0000, v19
	v_div_scale_f32 v15, s[0:1], v17, v17, v23
	v_pk_fma_f32 v[18:19], v[28:29], v[18:19], v[20:21] op_sel_hi:[0,1,1]
	v_rcp_f32_e32 v20, v15
	s_waitcnt vmcnt(4)
	v_lshlrev_b32_e32 v28, 16, v0
	v_and_b32_e32 v29, 0xffff0000, v0
	v_fma_f32 v21, -v15, v20, 1.0
	v_fmac_f32_e32 v20, v21, v20
	v_div_scale_f32 v21, vcc, v23, v17, v23
	v_mul_f32_e32 v24, v21, v20
	v_fma_f32 v25, -v15, v24, v21
	v_fmac_f32_e32 v24, v25, v20
	v_fma_f32 v15, -v15, v24, v21
	v_div_fmas_f32 v15, v15, v20, v24
	v_div_fixup_f32 v17, v15, v17, v23
	v_div_scale_f32 v15, s[0:1], v16, v16, v22
	v_rcp_f32_e32 v20, v15
	s_nop 0
	v_fma_f32 v21, -v15, v20, 1.0
	v_fmac_f32_e32 v20, v21, v20
	v_div_scale_f32 v21, vcc, v22, v16, v22
	v_mul_f32_e32 v23, v21, v20
	v_fma_f32 v24, -v15, v23, v21
	v_fmac_f32_e32 v23, v24, v20
	v_fma_f32 v15, -v15, v23, v21
	v_div_fmas_f32 v15, v15, v20, v23
	v_div_fixup_f32 v16, v15, v16, v22
	v_pk_mul_f32 v[16:17], v[16:17], v[18:19]
	s_nop 0
	v_cvt_pk_bf16_f32 v15, v16, v17
	v_lshl_add_u64 v[16:17], v[52:53], 0, v[66:67]
	global_store_dwordx4 v[16:17], v[12:15], off sc1
	s_nop 1
	v_max3_f32 v12, v41, v72, v61
	v_sub_f32_e32 v13, v41, v12
	v_sub_f32_e32 v14, v72, v12
	v_exp_f32_e32 v13, v13
	v_exp_f32_e32 v14, v14
	v_sub_f32_e32 v12, v61, v12
	v_exp_f32_e32 v12, v12
	v_add_f32_e32 v15, v13, v14
	v_add_f32_e32 v15, v12, v15
	v_div_scale_f32 v16, s[0:1], v15, v15, 1.0
	v_rcp_f32_e32 v17, v16
	s_nop 0
	v_fma_f32 v18, -v16, v17, 1.0
	v_fmac_f32_e32 v17, v18, v17
	v_div_scale_f32 v18, vcc, 1.0, v15, 1.0
	v_mul_f32_e32 v19, v18, v17
	v_fma_f32 v20, -v16, v19, v18
	v_fmac_f32_e32 v19, v20, v17
	v_fma_f32 v16, -v16, v19, v18
	v_div_fmas_f32 v16, v16, v17, v19
	s_waitcnt vmcnt(3)
	v_lshlrev_b32_e32 v17, 16, v8
	v_and_b32_e32 v8, 0xffff0000, v8
	v_mul_f32_e32 v19, 0xbfb8aa3b, v17
	v_mul_f32_e32 v0, 0xbfb8aa3b, v8
	v_exp_f32_e32 v26, v19
	v_exp_f32_e32 v27, v0
	v_div_fixup_f32 v15, v16, v15, 1.0
	v_mul_f32_e32 v18, v13, v15
	v_mul_f32_e32 v20, v14, v15
	v_mul_f32_e32 v16, v12, v15
	ds_read_b128 v[22:25], v57 offset:6336
	ds_read_b128 v[12:15], v57 offset:6352
	v_pk_add_f32 v[26:27], v[26:27], 1.0 op_sel_hi:[1,0]
	v_pk_mul_f32 v[28:29], v[20:21], v[28:29] op_sel_hi:[0,1]
	v_div_scale_f32 v0, s[0:1], v27, v27, v8
	s_waitcnt lgkmcnt(1)
; #define LAS __attribute__((address_space(3)))
; __device__ __forceinline__ unsigned cvtpk(float lo, float hi) { f32x2_t v = {lo, hi}; bf16x2_t b = __builtin_convertvector(v, bf16x2_t); return __builtin_bit_cast(unsigned, b); }
; __device__ __forceinline__ float silu_f(float x) { return x / (1.0f + __expf(-x)); }
; __device__ __forceinline__ void dil_attn_unit(LAS unsigned char* lds, bf16_t* proj, float* lse, int unit, int Tc, bf16_t* ybuf) {
;     ...
;             for (int i = 0; i < 4; ++i) { const int row = (half * 4 + i) * 4 + (lane >> 4), d8 = (lane & 15) * 8; const int tok = tok0 + row;
;                 const float l0 = lsr[row]; const float mxl = fmaxf(l0, fmaxf(l1[i], l2[i]));
;                 float w0 = __builtin_amdgcn_exp2f(l0 - mxl), w1 = __builtin_amdgcn_exp2f(l1[i] - mxl), w2 = __builtin_amdgcn_exp2f(l2[i] - mxl);
;                 const float iw = 1.0f / (w0 + w1 + w2); w0 *= iw; w1 *= iw; w2 *= iw;
;                 const f32x4 x0 = *(const LAS f32x4*)(stf + row * 132 + d8), x1 = *(const LAS f32x4*)(stf + row * 132 + d8 + 4);
;                 u32x4 yo;
;                 yo.x = cvtpk((w0 * x0[0] + w1 * bf_lo(o1[i].x) + w2 * bf_lo(o2[i].x)) * silu_f(bf_lo(gt[i].x)), (w0 * x0[1] + w1 * bf_hi(o1[i].x) + w2 * bf_hi(o2[i].x)) * silu_f(bf_hi(gt[i].x)));
;                 yo.y = cvtpk((w0 * x0[2] + w1 * bf_lo(o1[i].y) + w2 * bf_lo(o2[i].y)) * silu_f(bf_lo(gt[i].y)), (w0 * x0[3] + w1 * bf_hi(o1[i].y) + w2 * bf_hi(o2[i].y)) * silu_f(bf_hi(gt[i].y)));
;                 yo.z = cvtpk((w0 * x1[0] + w1 * bf_lo(o1[i].z) + w2 * bf_lo(o2[i].z)) * silu_f(bf_lo(gt[i].z)), (w0 * x1[1] + w1 * bf_hi(o1[i].z) + w2 * bf_hi(o2[i].z)) * silu_f(bf_hi(gt[i].z)));
;                 yo.w = cvtpk((w0 * x1[2] + w1 * bf_lo(o1[i].w) + w2 * bf_lo(o2[i].w)) * silu_f(bf_lo(gt[i].w)), (w0 * x1[3] + w1 * bf_hi(o1[i].w) + w2 * bf_hi(o2[i].w)) * silu_f(bf_hi(gt[i].w)));
;                 *(u32x4*)(ybuf + (size_t)tok * DM + h * 128 + d8) = yo; }
	v_pk_fma_f32 v[22:23], v[22:23], v[18:19], v[28:29] op_sel_hi:[1,0,1]
	v_lshlrev_b32_e32 v28, 16, v4
	v_and_b32_e32 v29, 0xffff0000, v4
	v_rcp_f32_e32 v4, v0
	v_pk_fma_f32 v[22:23], v[16:17], v[28:29], v[22:23] op_sel_hi:[0,1,1]
	v_fma_f32 v19, -v0, v4, 1.0
	v_fmac_f32_e32 v4, v19, v4
	v_div_scale_f32 v19, vcc, v8, v27, v8
	v_mul_f32_e32 v21, v19, v4
	v_fma_f32 v28, -v0, v21, v19
	v_fmac_f32_e32 v21, v28, v4
	v_fma_f32 v0, -v0, v21, v19
	v_div_fmas_f32 v0, v0, v4, v21
	v_div_fixup_f32 v27, v0, v27, v8
	v_div_scale_f32 v0, s[0:1], v26, v26, v17
	v_rcp_f32_e32 v4, v0
	s_nop 0
	v_fma_f32 v8, -v0, v4, 1.0
	v_fmac_f32_e32 v4, v8, v4
	v_div_scale_f32 v8, vcc, v17, v26, v17
	v_mul_f32_e32 v19, v8, v4
	v_fma_f32 v21, -v0, v19, v8
	v_fmac_f32_e32 v19, v21, v4
	v_fma_f32 v0, -v0, v19, v8
	v_div_fmas_f32 v0, v0, v4, v19
	v_div_fixup_f32 v26, v0, v26, v17
	v_lshlrev_b32_e32 v17, 16, v9
	v_and_b32_e32 v19, 0xffff0000, v9
	v_pk_mul_f32 v[22:23], v[26:27], v[22:23]
	v_mul_f32_e32 v4, 0xbfb8aa3b, v17
	v_lshlrev_b32_e32 v8, 16, v1
	v_and_b32_e32 v9, 0xffff0000, v1
	v_mul_f32_e32 v1, 0xbfb8aa3b, v19
	v_cvt_pk_bf16_f32 v0, v22, v23
	v_exp_f32_e32 v4, v4
	v_lshlrev_b32_e32 v22, 16, v5
	v_and_b32_e32 v23, 0xffff0000, v5
	v_exp_f32_e32 v5, v1
	v_pk_mul_f32 v[8:9], v[20:21], v[8:9] op_sel_hi:[0,1]
	v_pk_fma_f32 v[8:9], v[24:25], v[18:19], v[8:9] op_sel_hi:[1,0,1]
	v_pk_add_f32 v[4:5], v[4:5], 1.0 op_sel_hi:[1,0]
	s_nop 0
	v_div_scale_f32 v1, s[0:1], v5, v5, v19
	v_rcp_f32_e32 v21, v1
	v_pk_fma_f32 v[8:9], v[16:17], v[22:23], v[8:9] op_sel_hi:[0,1,1]
	v_fma_f32 v22, -v1, v21, 1.0
	v_fmac_f32_e32 v21, v22, v21
	v_div_scale_f32 v22, vcc, v19, v5, v19
	v_mul_f32_e32 v23, v22, v21
	v_fma_f32 v24, -v1, v23, v22
	v_fmac_f32_e32 v23, v24, v21
	v_fma_f32 v1, -v1, v23, v22
	v_div_fmas_f32 v1, v1, v21, v23
	v_div_fixup_f32 v5, v1, v5, v19
	v_div_scale_f32 v1, s[0:1], v4, v4, v17
	v_rcp_f32_e32 v19, v1
	s_nop 0
	v_fma_f32 v21, -v1, v19, 1.0
	v_fmac_f32_e32 v19, v21, v19
	v_div_scale_f32 v21, vcc, v17, v4, v17
	v_mul_f32_e32 v22, v21, v19
	v_fma_f32 v23, -v1, v22, v21
	v_fmac_f32_e32 v22, v23, v19
	v_fma_f32 v1, -v1, v22, v21
	v_div_fmas_f32 v1, v1, v19, v22
	v_div_fixup_f32 v4, v1, v4, v17
	v_pk_mul_f32 v[4:5], v[4:5], v[8:9]
	v_lshlrev_b32_e32 v17, 16, v10
	v_and_b32_e32 v10, 0xffff0000, v10
	v_cvt_pk_bf16_f32 v1, v4, v5
	v_mul_f32_e32 v4, 0xbfb8aa3b, v17
	v_lshlrev_b32_e32 v8, 16, v2
	v_and_b32_e32 v9, 0xffff0000, v2
	v_mul_f32_e32 v2, 0xbfb8aa3b, v10
	v_exp_f32_e32 v4, v4
	v_exp_f32_e32 v5, v2
	v_pk_mul_f32 v[8:9], v[20:21], v[8:9] op_sel_hi:[0,1]
	s_waitcnt lgkmcnt(0)
	v_pk_fma_f32 v[8:9], v[12:13], v[18:19], v[8:9] op_sel_hi:[1,0,1]
	v_lshlrev_b32_e32 v12, 16, v6
	v_pk_add_f32 v[4:5], v[4:5], 1.0 op_sel_hi:[1,0]
	v_and_b32_e32 v13, 0xffff0000, v6
	v_div_scale_f32 v2, s[0:1], v5, v5, v10
	v_rcp_f32_e32 v6, v2
	v_pk_fma_f32 v[8:9], v[16:17], v[12:13], v[8:9] op_sel_hi:[0,1,1]
	v_fma_f32 v12, -v2, v6, 1.0
	v_fmac_f32_e32 v6, v12, v6
	v_div_scale_f32 v12, vcc, v10, v5, v10
	v_mul_f32_e32 v13, v12, v6
	v_fma_f32 v19, -v2, v13, v12
	v_fmac_f32_e32 v13, v19, v6
	v_fma_f32 v2, -v2, v13, v12
	v_div_fmas_f32 v2, v2, v6, v13
	v_div_fixup_f32 v5, v2, v5, v10
	v_div_scale_f32 v2, s[0:1], v4, v4, v17
	v_rcp_f32_e32 v6, v2
	s_nop 0
	v_fma_f32 v10, -v2, v6, 1.0
	v_fmac_f32_e32 v6, v10, v6
	v_div_scale_f32 v10, vcc, v17, v4, v17
	v_mul_f32_e32 v12, v10, v6
	v_fma_f32 v13, -v2, v12, v10
	v_fmac_f32_e32 v12, v13, v6
	v_fma_f32 v2, -v2, v12, v10
	v_div_fmas_f32 v2, v2, v6, v12
	v_div_fixup_f32 v4, v2, v4, v17
	v_pk_mul_f32 v[4:5], v[4:5], v[8:9]
	v_lshlrev_b32_e32 v10, 16, v11
	v_and_b32_e32 v11, 0xffff0000, v11
	v_cvt_pk_bf16_f32 v2, v4, v5
	v_mul_f32_e32 v4, 0xbfb8aa3b, v10
	v_lshlrev_b32_e32 v8, 16, v3
	v_and_b32_e32 v9, 0xffff0000, v3
	v_mul_f32_e32 v3, 0xbfb8aa3b, v11
	v_exp_f32_e32 v4, v4
	v_exp_f32_e32 v5, v3
	v_pk_mul_f32 v[8:9], v[20:21], v[8:9] op_sel_hi:[0,1]
	v_pk_fma_f32 v[8:9], v[14:15], v[18:19], v[8:9] op_sel_hi:[1,0,1]
	v_lshlrev_b32_e32 v6, 16, v7
	v_pk_add_f32 v[4:5], v[4:5], 1.0 op_sel_hi:[1,0]
	v_and_b32_e32 v7, 0xffff0000, v7
	v_div_scale_f32 v3, s[0:1], v5, v5, v11
	v_pk_fma_f32 v[6:7], v[16:17], v[6:7], v[8:9] op_sel_hi:[0,1,1]
	v_rcp_f32_e32 v8, v3
	s_nop 0
	v_fma_f32 v9, -v3, v8, 1.0
	v_fmac_f32_e32 v8, v9, v8
	v_div_scale_f32 v9, vcc, v11, v5, v11
	v_mul_f32_e32 v12, v9, v8
	v_fma_f32 v13, -v3, v12, v9
	v_fmac_f32_e32 v12, v13, v8
	v_fma_f32 v3, -v3, v12, v9
	v_div_fmas_f32 v3, v3, v8, v12
	v_div_fixup_f32 v5, v3, v5, v11
	v_div_scale_f32 v3, s[0:1], v4, v4, v10
	v_rcp_f32_e32 v8, v3
	s_nop 0
	v_fma_f32 v9, -v3, v8, 1.0
	v_fmac_f32_e32 v8, v9, v8
	v_div_scale_f32 v9, vcc, v10, v4, v10
	v_mul_f32_e32 v11, v9, v8
	v_fma_f32 v12, -v3, v11, v9
	v_fmac_f32_e32 v11, v12, v8
	v_fma_f32 v3, -v3, v11, v9
	v_div_fmas_f32 v3, v3, v8, v11
	v_div_fixup_f32 v4, v3, v4, v10
	v_pk_mul_f32 v[4:5], v[4:5], v[6:7]
	s_nop 0
	v_cvt_pk_bf16_f32 v3, v4, v5
	v_lshl_add_u64 v[4:5], v[52:53], 0, v[54:55]
	global_store_dwordx4 v[4:5], v[0:3], off sc1

; __device__ __forceinline__ void dil_attn_unit(LAS unsigned char* lds, bf16_t* proj, float* lse, int unit, int Tc, bf16_t* ybuf) {
;     ...
;     mx = fmaxf(mx, __shfl_xor(mx, 32));
;     float ls = 0.f;
; #pragma unroll
;     for (int j = 0; j < 5; ++j)
; #pragma unroll
;         for (int rr = 0; rr < 16; ++rr) { const float e = __builtin_amdgcn_exp2f(p[j][rr] - mx); p[j][rr] = e; ls += e; }
;     ls += __shfl_xor(ls, 32);
.LBB0_261:
	v_xor_b32_e32 v0, 32, v199
	v_cmp_lt_i32_e32 vcc, v0, v211
	v_max_f32_e32 v1, v181, v181
	s_nop 0
	v_cndmask_b32_e32 v0, v199, v0, vcc
	v_lshlrev_b32_e32 v48, 2, v0
	ds_bpermute_b32 v0, v48, v181
	s_waitcnt lgkmcnt(0)
	v_max_f32_e32 v0, v0, v0
	v_max_f32_e32 v49, v1, v0
	v_sub_f32_e32 v0, v208, v49
	v_sub_f32_e32 v1, v209, v49
	v_exp_f32_e32 v0, v0
	v_exp_f32_e32 v1, v1
	v_sub_f32_e32 v2, v214, v49
	v_exp_f32_e32 v2, v2
	v_sub_f32_e32 v3, v215, v49
	v_exp_f32_e32 v3, v3
	v_add_f32_e32 v4, 0, v0
	v_add_f32_e32 v4, v1, v4
	v_add_f32_e32 v4, v2, v4
	v_add_f32_e32 v8, v3, v4
	v_sub_f32_e32 v4, v216, v49
	v_exp_f32_e32 v4, v4
	v_sub_f32_e32 v5, v217, v49
	v_exp_f32_e32 v5, v5
	v_sub_f32_e32 v6, v218, v49
	v_exp_f32_e32 v6, v6
	v_sub_f32_e32 v7, v219, v49
	v_exp_f32_e32 v7, v7
	v_add_f32_e32 v8, v4, v8
	v_add_f32_e32 v8, v5, v8
	v_add_f32_e32 v8, v6, v8
	v_add_f32_e32 v12, v7, v8
	v_sub_f32_e32 v8, v220, v49
	v_exp_f32_e32 v8, v8
	v_sub_f32_e32 v9, v221, v49
	v_exp_f32_e32 v9, v9
	v_sub_f32_e32 v10, v222, v49
	v_exp_f32_e32 v10, v10
	v_sub_f32_e32 v11, v223, v49
	v_exp_f32_e32 v11, v11
	v_add_f32_e32 v12, v8, v12
	v_add_f32_e32 v12, v9, v12
	v_add_f32_e32 v12, v10, v12
	v_add_f32_e32 v16, v11, v12
	v_sub_f32_e32 v12, v224, v49
	v_exp_f32_e32 v12, v12
	v_sub_f32_e32 v13, v225, v49
	v_exp_f32_e32 v13, v13
	v_sub_f32_e32 v14, v226, v49
	v_exp_f32_e32 v14, v14
	v_sub_f32_e32 v15, v227, v49
	v_exp_f32_e32 v15, v15
	v_sub_f32_e32 v17, v130, v49
	v_add_f32_e32 v16, v12, v16
	v_exp_f32_e32 v30, v17
	v_sub_f32_e32 v17, v131, v49
	v_add_f32_e32 v16, v13, v16
	v_exp_f32_e32 v31, v17
	v_sub_f32_e32 v17, v132, v49
	v_add_f32_e32 v16, v14, v16
	v_exp_f32_e32 v46, v17
	v_sub_f32_e32 v17, v133, v49
	v_add_f32_e32 v16, v15, v16
	v_exp_f32_e32 v47, v17
	v_sub_f32_e32 v17, v134, v49
	v_add_f32_e32 v16, v30, v16
	v_exp_f32_e32 v64, v17
	v_sub_f32_e32 v17, v135, v49
	v_add_f32_e32 v16, v31, v16
	v_exp_f32_e32 v65, v17
	v_sub_f32_e32 v17, v136, v49
	v_add_f32_e32 v16, v46, v16
	v_exp_f32_e32 v66, v17
	v_sub_f32_e32 v17, v137, v49
	v_add_f32_e32 v16, v47, v16
	v_exp_f32_e32 v67, v17
	v_sub_f32_e32 v17, v138, v49
	v_add_f32_e32 v16, v64, v16
	v_exp_f32_e32 v68, v17
	v_sub_f32_e32 v17, v139, v49
	v_add_f32_e32 v16, v65, v16
	v_exp_f32_e32 v69, v17
	v_sub_f32_e32 v17, v140, v49
	v_add_f32_e32 v16, v66, v16
	v_exp_f32_e32 v70, v17
	v_sub_f32_e32 v17, v141, v49
	v_add_f32_e32 v16, v67, v16
	v_exp_f32_e32 v71, v17
	v_sub_f32_e32 v17, v142, v49
	v_add_f32_e32 v16, v68, v16
	v_exp_f32_e32 v72, v17
	v_sub_f32_e32 v17, v143, v49
	v_add_f32_e32 v16, v69, v16
	v_exp_f32_e32 v73, v17
	v_sub_f32_e32 v17, v144, v49
	v_add_f32_e32 v16, v70, v16
	v_exp_f32_e32 v74, v17
	v_sub_f32_e32 v17, v145, v49
	v_add_f32_e32 v16, v71, v16
	v_exp_f32_e32 v75, v17
	v_sub_f32_e32 v17, v146, v49
	v_add_f32_e32 v16, v72, v16
	v_exp_f32_e32 v76, v17
	v_sub_f32_e32 v17, v147, v49
	v_add_f32_e32 v16, v73, v16
	v_exp_f32_e32 v77, v17
	v_sub_f32_e32 v17, v148, v49
	v_add_f32_e32 v16, v74, v16
	v_exp_f32_e32 v78, v17
	v_sub_f32_e32 v17, v149, v49
	v_add_f32_e32 v16, v75, v16
	v_exp_f32_e32 v79, v17
	v_sub_f32_e32 v17, v150, v49
	v_add_f32_e32 v16, v76, v16
	v_exp_f32_e32 v143, v17
	v_sub_f32_e32 v17, v151, v49
	v_add_f32_e32 v16, v77, v16
	v_exp_f32_e32 v144, v17
	v_sub_f32_e32 v17, v152, v49
	v_add_f32_e32 v16, v78, v16
	v_exp_f32_e32 v145, v17
	v_sub_f32_e32 v17, v153, v49
	v_add_f32_e32 v16, v79, v16
	v_exp_f32_e32 v146, v17
	v_add_f32_e32 v16, v143, v16
	v_add_f32_e32 v16, v144, v16
	v_add_f32_e32 v16, v145, v16
	v_add_f32_e32 v20, v146, v16
	v_sub_f32_e32 v16, v154, v49
	v_exp_f32_e32 v16, v16
	v_sub_f32_e32 v17, v155, v49
	v_exp_f32_e32 v17, v17
	v_sub_f32_e32 v18, v160, v49
	v_exp_f32_e32 v18, v18
	v_sub_f32_e32 v19, v161, v49
	v_exp_f32_e32 v19, v19
	v_add_f32_e32 v20, v16, v20
	v_add_f32_e32 v20, v17, v20
	v_add_f32_e32 v20, v18, v20
	v_add_f32_e32 v24, v19, v20
	v_sub_f32_e32 v20, v162, v49
	v_exp_f32_e32 v20, v20
	v_sub_f32_e32 v21, v163, v49
	v_exp_f32_e32 v21, v21
	v_sub_f32_e32 v22, v164, v49
	v_exp_f32_e32 v22, v22
	v_sub_f32_e32 v23, v165, v49
	v_exp_f32_e32 v23, v23
	v_add_f32_e32 v24, v20, v24
	v_add_f32_e32 v24, v21, v24
	v_add_f32_e32 v24, v22, v24
	v_add_f32_e32 v28, v23, v24
	v_sub_f32_e32 v24, v166, v49
	v_exp_f32_e32 v24, v24
	v_sub_f32_e32 v25, v167, v49
	v_exp_f32_e32 v25, v25
	v_sub_f32_e32 v26, v168, v49
	v_exp_f32_e32 v26, v26
	v_sub_f32_e32 v27, v169, v49
	v_exp_f32_e32 v27, v27
	v_add_f32_e32 v28, v24, v28
	v_add_f32_e32 v28, v25, v28
	v_add_f32_e32 v28, v26, v28
	v_add_f32_e32 v34, v27, v28
	v_sub_f32_e32 v28, v170, v49
	v_exp_f32_e32 v28, v28
	v_sub_f32_e32 v29, v171, v49
	v_exp_f32_e32 v29, v29
	v_sub_f32_e32 v32, v172, v49
	v_exp_f32_e32 v32, v32
	v_sub_f32_e32 v33, v173, v49
	v_exp_f32_e32 v33, v33
	v_add_f32_e32 v34, v28, v34
	v_add_f32_e32 v34, v29, v34
	v_add_f32_e32 v34, v32, v34
	v_add_f32_e32 v38, v33, v34
	v_sub_f32_e32 v34, v174, v49
	v_exp_f32_e32 v34, v34
	v_sub_f32_e32 v35, v175, v49
	v_exp_f32_e32 v35, v35
	v_sub_f32_e32 v36, v182, v49
	v_exp_f32_e32 v36, v36
	v_sub_f32_e32 v37, v183, v49
	v_exp_f32_e32 v37, v37
	v_add_f32_e32 v38, v34, v38
	v_add_f32_e32 v38, v35, v38
	v_add_f32_e32 v38, v36, v38
	v_add_f32_e32 v42, v37, v38
	v_sub_f32_e32 v38, v184, v49
	v_exp_f32_e32 v38, v38
	v_sub_f32_e32 v39, v185, v49
	v_exp_f32_e32 v39, v39
	v_sub_f32_e32 v40, v186, v49
	v_exp_f32_e32 v40, v40
	v_sub_f32_e32 v41, v187, v49
	v_exp_f32_e32 v41, v41
	v_add_f32_e32 v42, v38, v42
	v_add_f32_e32 v42, v39, v42
	v_add_f32_e32 v42, v40, v42
	v_add_f32_e32 v50, v41, v42
	v_sub_f32_e32 v42, v228, v49
	v_exp_f32_e32 v42, v42
	v_sub_f32_e32 v43, v229, v49
	v_exp_f32_e32 v43, v43
	v_sub_f32_e32 v44, v230, v49
	v_exp_f32_e32 v44, v44
	v_sub_f32_e32 v45, v231, v49
	v_exp_f32_e32 v45, v45
	v_sub_f32_e32 v51, v178, v49
	v_add_f32_e32 v50, v42, v50
	v_exp_f32_e32 v52, v51
	v_sub_f32_e32 v51, v232, v49
	v_add_f32_e32 v50, v43, v50
	v_exp_f32_e32 v53, v51
	v_sub_f32_e32 v51, v233, v49
	v_add_f32_e32 v50, v44, v50
	v_exp_f32_e32 v54, v51
	v_sub_f32_e32 v51, v234, v49
	v_add_f32_e32 v50, v45, v50
	v_exp_f32_e32 v55, v51
	v_sub_f32_e32 v51, v235, v49
	v_add_f32_e32 v50, v52, v50
	v_exp_f32_e32 v56, v51
	v_sub_f32_e32 v51, v236, v49
	v_add_f32_e32 v50, v53, v50
	v_exp_f32_e32 v57, v51
	v_sub_f32_e32 v51, v237, v49
	v_add_f32_e32 v50, v54, v50
	v_exp_f32_e32 v58, v51
	v_sub_f32_e32 v51, v238, v49
	v_add_f32_e32 v50, v55, v50
	v_exp_f32_e32 v59, v51
	v_sub_f32_e32 v51, v239, v49
	v_add_f32_e32 v50, v56, v50
	v_exp_f32_e32 v60, v51
	v_sub_f32_e32 v51, v240, v49
	v_add_f32_e32 v50, v57, v50
	v_exp_f32_e32 v61, v51
	v_sub_f32_e32 v51, v241, v49
	v_add_f32_e32 v50, v58, v50
	v_exp_f32_e32 v62, v51
	v_sub_f32_e32 v51, v128, v49
	v_add_f32_e32 v50, v59, v50
	v_exp_f32_e32 v63, v51
	v_add_f32_e32 v50, v60, v50
	v_add_f32_e32 v50, v61, v50
	v_add_f32_e32 v50, v62, v50
	v_add_f32_e32 v50, v63, v50
	ds_bpermute_b32 v48, v48, v50
	v_and_b32_e32 v141, 63, v189
	v_cmp_gt_u32_e32 vcc, 32, v141
	s_and_b64 s[36:37], s[90:91], vcc
	s_waitcnt lgkmcnt(0)
; #define LAS __attribute__((address_space(3)))
; __device__ __forceinline__ unsigned cvtpk(float lo, float hi) { f32x2_t v = {lo, hi}; bf16x2_t b = __builtin_convertvector(v, bf16x2_t); return __builtin_bit_cast(unsigned, b); }
; __device__ __forceinline__ void dil_attn_unit(LAS unsigned char* lds, bf16_t* proj, float* lse, int unit, int Tc, bf16_t* ybuf) {
;     ...
;     ls += __shfl_xor(ls, 32);
;     const float inv = 1.0f / ls;
;     const float lse2 = mx + __builtin_amdgcn_logf(ls);
;     if (hi == 0 && !ybuf) lse[(rowbase + ((size_t)uq << dsh)) * 24 + g * 8 + h] = lse2;
;     u32x4 pa[5][2];
; #pragma unroll
;     for (int j = 0; j < 5; ++j)
; #pragma unroll
;         for (int s2 = 0; s2 < 2; ++s2) { pa[j][s2].x = cvtpk(p[j][8 * s2 + 0], p[j][8 * s2 + 1]); pa[j][s2].y = cvtpk(p[j][8 * s2 + 2], p[j][8 * s2 + 3]);
;             pa[j][s2].z = cvtpk(p[j][8 * s2 + 4], p[j][8 * s2 + 5]); pa[j][s2].w = cvtpk(p[j][8 * s2 + 6], p[j][8 * s2 + 7]); }
;     __syncthreads();
; #pragma unroll
;     for (int it = 0; it < 12; ++it) { const int id = it * 512 + tid, row = id >> 4, ch = id & 15; const int uk = U0 - 64 + row; const bool ok = (uk >= 0) && (uk < L);
;         u32x4 z = vv[it]; if (!ok) z = (u32x4){0u, 0u, 0u, 0u}; *(LAS u32x4*)(lds + row * 320 + ch * 16) = z; }
;     __syncthreads();
	v_add_f32_e32 v48, v50, v48
	v_log_f32_e32 v50, v48
	s_nop 0
	v_add_f32_e32 v140, v49, v50
	s_and_saveexec_b64 s[0:1], s[36:37]
	s_cbranch_execz .LBB0_263
	s_add_u32 s36, s98, s76
	s_addc_u32 s37, s99, 0
	v_lshlrev_b64 v[50:51], s52, v[158:159]
	v_lshl_add_u64 v[50:51], s[36:37], 0, v[50:51]
	v_readlane_b32 s36, v254, 11
	v_readlane_b32 s37, v254, 12
	s_lshl_b32 s76, s53, 2
	s_nop 0
	v_mov_b64_e32 v[128:129], s[36:37]
	v_mad_u64_u32 v[128:129], s[36:37], v50, s66, v[128:129]
	v_mad_i32_i24 v129, v51, s66, v129
	v_lshl_add_u64 v[50:51], v[128:129], 0, s[76:77]
	s_lshl_b32 s76, s34, 2
	v_lshl_add_u64 v[50:51], v[50:51], 0, s[76:77]
	global_store_dword v[50:51], v140, off sc1
.LBB0_263:
	s_or_b64 exec, exec, s[0:1]
	v_div_scale_f32 v49, s[0:1], v48, v48, 1.0
	v_rcp_f32_e32 v50, v49
	v_div_scale_f32 v51, vcc, 1.0, v48, 1.0
	v_fma_f32 v128, -v49, v50, 1.0
	v_fmac_f32_e32 v50, v128, v50
	v_mul_f32_e32 v128, v51, v50
	v_fma_f32 v129, -v49, v128, v51
	v_fmac_f32_e32 v128, v129, v50
	v_fma_f32 v49, -v49, v128, v51
	v_div_fmas_f32 v49, v49, v50, v128
	v_div_fixup_f32 v142, v49, v48, 1.0
	v_cvt_pk_bf16_f32 v48, v0, v1
	v_cvt_pk_bf16_f32 v49, v2, v3
	v_cvt_pk_bf16_f32 v50, v4, v5
	s_waitcnt vmcnt(11)
	v_cndmask_b32_e64 v3, 0, v127, s[6:7]
	v_cndmask_b32_e64 v2, 0, v126, s[6:7]
	v_cndmask_b32_e64 v1, 0, v125, s[6:7]
	v_cndmask_b32_e64 v0, 0, v124, s[6:7]
	v_mad_u64_u32 v[4:5], s[0:1], v192, s59, v[156:157]
	s_barrier
	ds_write_b128 v4, v[0:3]
	s_waitcnt vmcnt(10)
	v_cndmask_b32_e64 v3, 0, v123, s[8:9]
	v_cndmask_b32_e64 v2, 0, v122, s[8:9]
	v_cndmask_b32_e64 v1, 0, v121, s[8:9]
	v_cndmask_b32_e64 v0, 0, v120, s[8:9]
	v_mad_u64_u32 v[4:5], s[0:1], v193, s59, v[156:157]
	ds_write_b128 v4, v[0:3]
	s_waitcnt vmcnt(9)
	v_cndmask_b32_e64 v3, 0, v119, s[10:11]
	v_cndmask_b32_e64 v2, 0, v118, s[10:11]
	v_cndmask_b32_e64 v1, 0, v117, s[10:11]
	v_cndmask_b32_e64 v0, 0, v116, s[10:11]
	v_mad_u64_u32 v[4:5], s[0:1], v194, s59, v[156:157]
	ds_write_b128 v4, v[0:3]
	s_waitcnt vmcnt(8)
	v_cndmask_b32_e64 v3, 0, v115, s[12:13]
	v_cndmask_b32_e64 v2, 0, v114, s[12:13]
	v_cndmask_b32_e64 v1, 0, v113, s[12:13]
	v_cndmask_b32_e64 v0, 0, v112, s[12:13]
	v_mad_u64_u32 v[4:5], s[0:1], v196, s59, v[156:157]
	ds_write_b128 v4, v[0:3]
	s_waitcnt vmcnt(7)
	v_cndmask_b32_e64 v3, 0, v111, s[14:15]
	v_cndmask_b32_e64 v2, 0, v110, s[14:15]
	v_cndmask_b32_e64 v1, 0, v109, s[14:15]
	v_cndmask_b32_e64 v0, 0, v108, s[14:15]
	v_mad_u64_u32 v[4:5], s[0:1], v198, s59, v[156:157]
	ds_write_b128 v4, v[0:3]
	s_waitcnt vmcnt(6)
	v_cndmask_b32_e64 v3, 0, v107, s[16:17]
	v_cndmask_b32_e64 v2, 0, v106, s[16:17]
	v_cndmask_b32_e64 v1, 0, v105, s[16:17]
	v_cndmask_b32_e64 v0, 0, v104, s[16:17]
	v_mad_u64_u32 v[4:5], s[0:1], v200, s59, v[156:157]
	ds_write_b128 v4, v[0:3]
	s_waitcnt vmcnt(5)
	v_cndmask_b32_e64 v3, 0, v103, s[18:19]
	v_cndmask_b32_e64 v2, 0, v102, s[18:19]
	v_cndmask_b32_e64 v1, 0, v101, s[18:19]
	v_cndmask_b32_e64 v0, 0, v100, s[18:19]
	v_mad_u64_u32 v[4:5], s[0:1], v201, s59, v[156:157]
	ds_write_b128 v4, v[0:3]
	s_waitcnt vmcnt(4)
	v_cndmask_b32_e64 v3, 0, v99, s[20:21]
	v_cndmask_b32_e64 v2, 0, v98, s[20:21]
	v_cndmask_b32_e64 v1, 0, v97, s[20:21]
	v_cndmask_b32_e64 v0, 0, v96, s[20:21]
	v_mad_u64_u32 v[4:5], s[0:1], v202, s59, v[156:157]
	ds_write_b128 v4, v[0:3]
	s_waitcnt vmcnt(3)
	v_cndmask_b32_e64 v3, 0, v95, s[22:23]
	v_cndmask_b32_e64 v2, 0, v94, s[22:23]
	v_cndmask_b32_e64 v1, 0, v93, s[22:23]
	v_cndmask_b32_e64 v0, 0, v92, s[22:23]
	v_mad_u64_u32 v[4:5], s[0:1], v203, s59, v[156:157]
	ds_write_b128 v4, v[0:3]
	s_waitcnt vmcnt(2)
	v_cndmask_b32_e64 v3, 0, v91, s[24:25]
	v_cndmask_b32_e64 v2, 0, v90, s[24:25]
	v_cndmask_b32_e64 v1, 0, v89, s[24:25]
	v_cndmask_b32_e64 v0, 0, v88, s[24:25]
	v_mad_u64_u32 v[4:5], s[0:1], v204, s59, v[156:157]
	ds_write_b128 v4, v[0:3]
	s_waitcnt vmcnt(1)
	v_cndmask_b32_e64 v3, 0, v87, s[26:27]
	v_cndmask_b32_e64 v2, 0, v86, s[26:27]
	v_cndmask_b32_e64 v1, 0, v85, s[26:27]
	v_cndmask_b32_e64 v0, 0, v84, s[26:27]
	v_mad_u64_u32 v[4:5], s[0:1], v205, s59, v[156:157]
	ds_write_b128 v4, v[0:3]
	s_waitcnt vmcnt(0)
	v_cndmask_b32_e64 v3, 0, v83, s[28:29]
	v_cndmask_b32_e64 v2, 0, v82, s[28:29]
	v_cndmask_b32_e64 v1, 0, v81, s[28:29]
	v_cndmask_b32_e64 v0, 0, v80, s[28:29]
	v_mad_u64_u32 v[4:5], s[0:1], v206, s59, v[156:157]
	ds_write_b128 v4, v[0:3]
	v_bfe_u32 v0, v189, 2, 2
	v_and_b32_e32 v1, 16, v189
	v_lshlrev_b32_e32 v2, 2, v189
	v_or3_b32 v0, v0, v190, s49
	v_and_or_b32 v1, v2, 12, v1
	v_mul_lo_u32 v0, v0, s59
	v_lshlrev_b32_e32 v1, 1, v1
	v_add3_u32 v89, 0, v0, v1
	v_cvt_pk_bf16_f32 v51, v6, v7
	v_cvt_pk_bf16_f32 v134, v64, v65
	v_cvt_pk_bf16_f32 v135, v66, v67
	s_waitcnt lgkmcnt(0)
	s_barrier
; #define LAS __attribute__((address_space(3)))
; __device__ __forceinline__ void dil_attn_unit(LAS unsigned char* lds, bf16_t* proj, float* lse, int unit, int Tc, bf16_t* ybuf) {
;     ...
;     f32x16 o[4];
; #pragma unroll
;     for (int db = 0; db < 4; ++db) o[db] = (f32x16){0.f, 0.f, 0.f, 0.f, 0.f, 0.f, 0.f, 0.f, 0.f, 0.f, 0.f, 0.f, 0.f, 0.f, 0.f, 0.f};
;     const LAS unsigned char* vbase = lds + (32 * w + 4 * hi + ((lane & 15) >> 2)) * 320 + (16 * ((lane >> 4) & 1) + 4 * (lane & 3)) * 2;
; #pragma unroll
;     for (int j = 0; j < 5; ++j)
; #pragma unroll
;         for (int s2 = 0; s2 < 2; ++s2)
; #pragma unroll
;             for (int db = 0; db < 4; ++db) {
;                 const LAS unsigned char* vp = vbase + (32 * j + 16 * s2) * 320 + db * 64;
;                 const v4i16_t lo = __builtin_amdgcn_ds_read_tr16_b64_v4i16((LAS v4i16_t*)vp);
;                 const v4i16_t hh = __builtin_amdgcn_ds_read_tr16_b64_v4i16((LAS v4i16_t*)(vp + 8 * 320));
;                 const bf16x8 vf = (bf16x8){lo[0], lo[1], lo[2], lo[3], hh[0], hh[1], hh[2], hh[3]};
;                 o[db] = __builtin_amdgcn_mfma_f32_32x32x16_bf16(__builtin_bit_cast(bf16x8, pa[j][s2]), vf, o[db], 0, 0, 0);
;                 if (db == 3) __builtin_amdgcn_sched_barrier(0);
;             }
	ds_read_b64_tr_b16 v[2:3], v89 offset:2560
	ds_read_b64_tr_b16 v[0:1], v89
	ds_read_b64_tr_b16 v[64:65], v89 offset:64
	ds_read_b64_tr_b16 v[90:91], v89 offset:128
	ds_read_b64_tr_b16 v[94:95], v89 offset:192
	ds_read_b64_tr_b16 v[66:67], v89 offset:2624
	ds_read_b64_tr_b16 v[92:93], v89 offset:2688
	ds_read_b64_tr_b16 v[96:97], v89 offset:2752
	v_cvt_pk_bf16_f32 v136, v8, v9
	v_cvt_pk_bf16_f32 v137, v10, v11
	v_cvt_pk_bf16_f32 v138, v12, v13
	v_cvt_pk_bf16_f32 v139, v14, v15
	v_cvt_pk_bf16_f32 v132, v30, v31
	v_cvt_pk_bf16_f32 v133, v46, v47
	v_cvt_pk_bf16_f32 v128, v68, v69
	v_cvt_pk_bf16_f32 v129, v70, v71
	v_cvt_pk_bf16_f32 v130, v72, v73
	v_cvt_pk_bf16_f32 v72, v76, v77
	v_cvt_pk_bf16_f32 v73, v78, v79
	s_waitcnt lgkmcnt(6)
	v_mfma_f32_32x32x16_bf16 v[0:15], v[48:51], v[0:3], 0
	v_cvt_pk_bf16_f32 v84, v16, v17
	v_cvt_pk_bf16_f32 v85, v18, v19
	v_cvt_pk_bf16_f32 v86, v20, v21
	v_cvt_pk_bf16_f32 v87, v22, v23
	v_cvt_pk_bf16_f32 v80, v24, v25
	v_cvt_pk_bf16_f32 v81, v26, v27
	v_cvt_pk_bf16_f32 v82, v28, v29
	s_waitcnt lgkmcnt(2)
	v_mfma_f32_32x32x16_bf16 v[16:31], v[48:51], v[64:67], 0
	v_cvt_pk_bf16_f32 v83, v32, v33
	v_cvt_pk_bf16_f32 v76, v34, v35
	v_cvt_pk_bf16_f32 v77, v36, v37
	v_cvt_pk_bf16_f32 v78, v38, v39
	v_cvt_pk_bf16_f32 v79, v40, v41
	v_cvt_pk_bf16_f32 v68, v42, v43
	v_cvt_pk_bf16_f32 v69, v44, v45
	s_waitcnt lgkmcnt(1)
	v_mfma_f32_32x32x16_bf16 v[32:47], v[48:51], v[90:93], 0
	v_cvt_pk_bf16_f32 v70, v52, v53
	v_cvt_pk_bf16_f32 v71, v54, v55
	v_cvt_pk_bf16_f32 v64, v56, v57
	v_cvt_pk_bf16_f32 v65, v58, v59
	v_cvt_pk_bf16_f32 v66, v60, v61
	v_cvt_pk_bf16_f32 v67, v62, v63
	v_cvt_pk_bf16_f32 v131, v74, v75
	s_waitcnt lgkmcnt(0)
	v_mfma_f32_32x32x16_bf16 v[48:63], v[48:51], v[94:97], 0
	v_cvt_pk_bf16_f32 v74, v143, v144
	v_cvt_pk_bf16_f32 v75, v145, v146
	v_and_b32_e32 v88, 15, v189
	ds_read_b64_tr_b16 v[90:91], v89 offset:5120
	ds_read_b64_tr_b16 v[92:93], v89 offset:7680
	s_waitcnt lgkmcnt(0)
	v_mfma_f32_32x32x16_bf16 v[0:15], v[136:139], v[90:93], v[0:15]
	ds_read_b64_tr_b16 v[90:91], v89 offset:5184
	ds_read_b64_tr_b16 v[92:93], v89 offset:7744
	s_waitcnt lgkmcnt(0)
	v_mfma_f32_32x32x16_bf16 v[16:31], v[136:139], v[90:93], v[16:31]
	ds_read_b64_tr_b16 v[90:91], v89 offset:5248
	ds_read_b64_tr_b16 v[92:93], v89 offset:7808
	s_waitcnt lgkmcnt(0)
	v_mfma_f32_32x32x16_bf16 v[32:47], v[136:139], v[90:93], v[32:47]
	ds_read_b64_tr_b16 v[90:91], v89 offset:5312
	ds_read_b64_tr_b16 v[92:93], v89 offset:7872
	s_waitcnt lgkmcnt(0)
	v_mfma_f32_32x32x16_bf16 v[48:63], v[136:139], v[90:93], v[48:63]
	ds_read_b64_tr_b16 v[90:91], v89 offset:10240
	ds_read_b64_tr_b16 v[92:93], v89 offset:12800
	s_waitcnt lgkmcnt(0)
	v_mfma_f32_32x32x16_bf16 v[0:15], v[132:135], v[90:93], v[0:15]
	ds_read_b64_tr_b16 v[90:91], v89 offset:10304
	ds_read_b64_tr_b16 v[92:93], v89 offset:12864
	s_waitcnt lgkmcnt(0)
	v_mfma_f32_32x32x16_bf16 v[16:31], v[132:135], v[90:93], v[16:31]
	ds_read_b64_tr_b16 v[90:91], v89 offset:10368
	ds_read_b64_tr_b16 v[92:93], v89 offset:12928
	s_waitcnt lgkmcnt(0)
	v_mfma_f32_32x32x16_bf16 v[32:47], v[132:135], v[90:93], v[32:47]
	ds_read_b64_tr_b16 v[90:91], v89 offset:10432
	ds_read_b64_tr_b16 v[92:93], v89 offset:12992
	s_waitcnt lgkmcnt(0)
	v_mfma_f32_32x32x16_bf16 v[48:63], v[132:135], v[90:93], v[48:63]
	ds_read_b64_tr_b16 v[90:91], v89 offset:15360
	ds_read_b64_tr_b16 v[92:93], v89 offset:17920
	s_waitcnt lgkmcnt(0)
	v_mfma_f32_32x32x16_bf16 v[0:15], v[128:131], v[90:93], v[0:15]
	ds_read_b64_tr_b16 v[90:91], v89 offset:15424
	ds_read_b64_tr_b16 v[92:93], v89 offset:17984
	s_waitcnt lgkmcnt(0)
	v_mfma_f32_32x32x16_bf16 v[16:31], v[128:131], v[90:93], v[16:31]
	ds_read_b64_tr_b16 v[90:91], v89 offset:15488
	ds_read_b64_tr_b16 v[92:93], v89 offset:18048
	s_waitcnt lgkmcnt(0)
	v_mfma_f32_32x32x16_bf16 v[32:47], v[128:131], v[90:93], v[32:47]
	ds_read_b64_tr_b16 v[90:91], v89 offset:15552
	ds_read_b64_tr_b16 v[92:93], v89 offset:18112
	s_waitcnt lgkmcnt(0)
	v_mfma_f32_32x32x16_bf16 v[48:63], v[128:131], v[90:93], v[48:63]
	ds_read_b64_tr_b16 v[90:91], v89 offset:20480
	ds_read_b64_tr_b16 v[92:93], v89 offset:23040
	s_waitcnt lgkmcnt(0)
	v_mfma_f32_32x32x16_bf16 v[0:15], v[72:75], v[90:93], v[0:15]
	ds_read_b64_tr_b16 v[90:91], v89 offset:20544
	ds_read_b64_tr_b16 v[92:93], v89 offset:23104
	s_waitcnt lgkmcnt(0)
	v_mfma_f32_32x32x16_bf16 v[16:31], v[72:75], v[90:93], v[16:31]
	ds_read_b64_tr_b16 v[90:91], v89 offset:20608
	ds_read_b64_tr_b16 v[92:93], v89 offset:23168
	s_waitcnt lgkmcnt(0)
	v_mfma_f32_32x32x16_bf16 v[32:47], v[72:75], v[90:93], v[32:47]
	ds_read_b64_tr_b16 v[90:91], v89 offset:20672
	ds_read_b64_tr_b16 v[92:93], v89 offset:23232
	s_waitcnt lgkmcnt(0)
	v_mfma_f32_32x32x16_bf16 v[48:63], v[72:75], v[90:93], v[48:63]
	ds_read_b64_tr_b16 v[72:73], v89 offset:25600
	ds_read_b64_tr_b16 v[74:75], v89 offset:28160
	s_waitcnt lgkmcnt(0)
	v_mfma_f32_32x32x16_bf16 v[0:15], v[84:87], v[72:75], v[0:15]
	ds_read_b64_tr_b16 v[72:73], v89 offset:25664
	ds_read_b64_tr_b16 v[74:75], v89 offset:28224
	s_waitcnt lgkmcnt(0)
	v_mfma_f32_32x32x16_bf16 v[16:31], v[84:87], v[72:75], v[16:31]
	ds_read_b64_tr_b16 v[72:73], v89 offset:25728
	ds_read_b64_tr_b16 v[74:75], v89 offset:28288
	s_waitcnt lgkmcnt(0)
	v_mfma_f32_32x32x16_bf16 v[32:47], v[84:87], v[72:75], v[32:47]
	ds_read_b64_tr_b16 v[72:73], v89 offset:25792
	ds_read_b64_tr_b16 v[74:75], v89 offset:28352
	s_waitcnt lgkmcnt(0)
	v_mfma_f32_32x32x16_bf16 v[48:63], v[84:87], v[72:75], v[48:63]
	ds_read_b64_tr_b16 v[72:73], v89 offset:30720
	ds_read_b64_tr_b16 v[74:75], v89 offset:33280
	s_waitcnt lgkmcnt(0)
; #define LAS __attribute__((address_space(3)))
; __device__ __forceinline__ unsigned cvtpk(float lo, float hi) { f32x2_t v = {lo, hi}; bf16x2_t b = __builtin_convertvector(v, bf16x2_t); return __builtin_bit_cast(unsigned, b); }
; __device__ __forceinline__ int crow(int r, int hi) { return (r & 3) + 8 * (r >> 2) + 4 * hi; }
; __device__ __forceinline__ void dil_attn_unit(LAS unsigned char* lds, bf16_t* proj, float* lse, int unit, int Tc, bf16_t* ybuf) {
;     ...
;     f32x16 o[4];
; #pragma unroll
;     for (int db = 0; db < 4; ++db) o[db] = (f32x16){0.f, 0.f, 0.f, 0.f, 0.f, 0.f, 0.f, 0.f, 0.f, 0.f, 0.f, 0.f, 0.f, 0.f, 0.f, 0.f};
;     const LAS unsigned char* vbase = lds + (32 * w + 4 * hi + ((lane & 15) >> 2)) * 320 + (16 * ((lane >> 4) & 1) + 4 * (lane & 3)) * 2;
; #pragma unroll
;     for (int j = 0; j < 5; ++j)
; #pragma unroll
;         for (int s2 = 0; s2 < 2; ++s2)
; #pragma unroll
;             for (int db = 0; db < 4; ++db) {
;                 const LAS unsigned char* vp = vbase + (32 * j + 16 * s2) * 320 + db * 64;
;                 const v4i16_t lo = __builtin_amdgcn_ds_read_tr16_b64_v4i16((LAS v4i16_t*)vp);
;                 const v4i16_t hh = __builtin_amdgcn_ds_read_tr16_b64_v4i16((LAS v4i16_t*)(vp + 8 * 320));
;                 const bf16x8 vf = (bf16x8){lo[0], lo[1], lo[2], lo[3], hh[0], hh[1], hh[2], hh[3]};
;                 o[db] = __builtin_amdgcn_mfma_f32_32x32x16_bf16(__builtin_bit_cast(bf16x8, pa[j][s2]), vf, o[db], 0, 0, 0);
;                 if (db == 3) __builtin_amdgcn_sched_barrier(0);
;             }
;     __syncthreads();
;     if (!ybuf) {
;         LAS bf16_t* stg = (LAS bf16_t*)(lds + w * 8704);
; #pragma unroll
;         for (int rr = 0; rr < 16; ++rr) { const int qi = crow(rr, hi); const float a = __shfl(inv, qi);
; #pragma unroll
;             for (int db = 0; db < 4; ++db) stg[qi * 136 + db * 32 + r32] = (bf16_t)(cvtpk(o[db][rr] * a, 0.f) & 0xffffu); }
	v_mfma_f32_32x32x16_bf16 v[0:15], v[80:83], v[72:75], v[0:15]
	ds_read_b64_tr_b16 v[72:73], v89 offset:30784
	ds_read_b64_tr_b16 v[74:75], v89 offset:33344
	s_waitcnt lgkmcnt(0)
	v_mfma_f32_32x32x16_bf16 v[16:31], v[80:83], v[72:75], v[16:31]
	ds_read_b64_tr_b16 v[72:73], v89 offset:30848
	ds_read_b64_tr_b16 v[74:75], v89 offset:33408
	s_waitcnt lgkmcnt(0)
	v_mfma_f32_32x32x16_bf16 v[32:47], v[80:83], v[72:75], v[32:47]
	ds_read_b64_tr_b16 v[72:73], v89 offset:30912
	ds_read_b64_tr_b16 v[74:75], v89 offset:33472
	s_waitcnt lgkmcnt(0)
	v_mfma_f32_32x32x16_bf16 v[48:63], v[80:83], v[72:75], v[48:63]
	ds_read_b64_tr_b16 v[72:73], v89 offset:35840
	ds_read_b64_tr_b16 v[74:75], v89 offset:38400
	s_waitcnt lgkmcnt(0)
	v_mfma_f32_32x32x16_bf16 v[0:15], v[76:79], v[72:75], v[0:15]
	ds_read_b64_tr_b16 v[72:73], v89 offset:35904
	ds_read_b64_tr_b16 v[74:75], v89 offset:38464
	s_waitcnt lgkmcnt(0)
	v_mfma_f32_32x32x16_bf16 v[16:31], v[76:79], v[72:75], v[16:31]
	ds_read_b64_tr_b16 v[72:73], v89 offset:35968
	ds_read_b64_tr_b16 v[74:75], v89 offset:38528
	s_waitcnt lgkmcnt(0)
	v_mfma_f32_32x32x16_bf16 v[32:47], v[76:79], v[72:75], v[32:47]
	ds_read_b64_tr_b16 v[72:73], v89 offset:36032
	ds_read_b64_tr_b16 v[74:75], v89 offset:38592
	s_waitcnt lgkmcnt(0)
	v_mfma_f32_32x32x16_bf16 v[48:63], v[76:79], v[72:75], v[48:63]
	ds_read_b64_tr_b16 v[72:73], v89 offset:40960
	ds_read_b64_tr_b16 v[74:75], v89 offset:43520
	s_waitcnt lgkmcnt(0)
	v_mfma_f32_32x32x16_bf16 v[0:15], v[68:71], v[72:75], v[0:15]
	ds_read_b64_tr_b16 v[72:73], v89 offset:41024
	ds_read_b64_tr_b16 v[74:75], v89 offset:43584
	s_waitcnt lgkmcnt(0)
	v_mfma_f32_32x32x16_bf16 v[16:31], v[68:71], v[72:75], v[16:31]
	ds_read_b64_tr_b16 v[72:73], v89 offset:41088
	ds_read_b64_tr_b16 v[74:75], v89 offset:43648
	s_waitcnt lgkmcnt(0)
	v_mfma_f32_32x32x16_bf16 v[32:47], v[68:71], v[72:75], v[32:47]
	ds_read_b64_tr_b16 v[72:73], v89 offset:41152
	ds_read_b64_tr_b16 v[74:75], v89 offset:43712
	s_waitcnt lgkmcnt(0)
	v_mfma_f32_32x32x16_bf16 v[48:63], v[68:71], v[72:75], v[48:63]
	ds_read_b64_tr_b16 v[68:69], v89 offset:46080
	ds_read_b64_tr_b16 v[70:71], v89 offset:48640
	s_waitcnt lgkmcnt(0)
	v_mfma_f32_32x32x16_bf16 v[0:15], v[64:67], v[68:71], v[0:15]
	ds_read_b64_tr_b16 v[68:69], v89 offset:46144
	ds_read_b64_tr_b16 v[70:71], v89 offset:48704
	s_waitcnt lgkmcnt(0)
	v_mfma_f32_32x32x16_bf16 v[16:31], v[64:67], v[68:71], v[16:31]
	ds_read_b64_tr_b16 v[68:69], v89 offset:46208
	ds_read_b64_tr_b16 v[70:71], v89 offset:48768
	s_waitcnt lgkmcnt(0)
	v_mfma_f32_32x32x16_bf16 v[32:47], v[64:67], v[68:71], v[32:47]
	ds_read_b64_tr_b16 v[68:69], v89 offset:46272
	ds_read_b64_tr_b16 v[70:71], v89 offset:48832
	s_waitcnt lgkmcnt(0)
	v_mfma_f32_32x32x16_bf16 v[48:63], v[64:67], v[68:71], v[48:63]
	v_or_b32_e32 v64, v210, v190
	v_lshlrev_b32_e32 v80, 2, v64
	v_lshrrev_b32_e32 v75, 4, v141
	s_mov_b64 s[0:1], -1
	s_and_b64 vcc, exec, s[4:5]
	v_lshlrev_b32_e32 v178, 4, v88
	v_or_b32_e32 v79, v210, v207
	v_or_b32_e32 v78, 8, v80
	v_or_b32_e32 v77, 12, v80
	v_or_b32_e32 v76, 32, v80
	v_or_b32_e32 v74, 36, v80
	v_or_b32_e32 v73, 40, v80
	v_or_b32_e32 v72, 44, v80
	v_or_b32_e32 v71, 64, v80
	v_or_b32_e32 v70, 0x44, v80
	v_or_b32_e32 v69, 0x48, v80
	v_or_b32_e32 v68, 0x4c, v80
	v_or_b32_e32 v67, 0x60, v80
	v_or_b32_e32 v66, 0x64, v80
	v_or_b32_e32 v65, 0x68, v80
	v_or_b32_e32 v64, 0x6c, v80
	s_barrier
	s_cbranch_vccnz .LBB0_265
	ds_bpermute_b32 v82, v80, v142
	s_mul_i32 s0, s48, 0x2200
	s_add_i32 s0, s0, 0
	v_lshl_add_u32 v81, v188, 1, s0
	s_movk_i32 s1, 0x440
	s_waitcnt lgkmcnt(0)
	v_mul_f32_e32 v84, v0, v82
	v_mad_u32_u24 v83, v157, s1, v81
	v_cvt_pk_bf16_f32 v84, v84, s0
	ds_write_b16 v83, v84
	v_mul_f32_e32 v84, v16, v82
	v_cvt_pk_bf16_f32 v84, v84, s0
	ds_write_b16 v83, v84 offset:64
	v_mul_f32_e32 v84, v32, v82
	v_mul_f32_e32 v82, v48, v82
	v_cvt_pk_bf16_f32 v82, v82, s0
	ds_write_b16 v83, v82 offset:192
	v_lshlrev_b32_e32 v82, 2, v79
	ds_bpermute_b32 v82, v82, v142
	v_cvt_pk_bf16_f32 v84, v84, s0
	ds_write_b16 v83, v84 offset:128
	v_mad_u32_u24 v81, v207, s67, v81
	s_ashr_i32 s1, s41, 31
	s_waitcnt lgkmcnt(1)
	v_mul_f32_e32 v83, v1, v82
	v_cvt_pk_bf16_f32 v83, v83, s0
	ds_write_b16 v81, v83
	v_mul_f32_e32 v83, v17, v82
	v_cvt_pk_bf16_f32 v83, v83, s0
	ds_write_b16 v81, v83 offset:64
	v_mul_f32_e32 v83, v33, v82
	v_mul_f32_e32 v82, v49, v82
	v_cvt_pk_bf16_f32 v82, v82, s0
	ds_write_b16 v81, v82 offset:192
	ds_bpermute_b32 v82, v78, v142
	v_cvt_pk_bf16_f32 v83, v83, s0
	ds_write_b16 v81, v83 offset:128
	s_add_u32 s4, s94, s41
	s_addc_u32 s5, s95, s1
	s_waitcnt lgkmcnt(1)
	v_mul_f32_e32 v83, v2, v82
	v_cvt_pk_bf16_f32 v83, v83, s0
	ds_write_b16 v81, v83 offset:272
	v_mul_f32_e32 v83, v18, v82
	v_cvt_pk_bf16_f32 v83, v83, s0
	ds_write_b16 v81, v83 offset:336
	v_mul_f32_e32 v83, v34, v82
	v_mul_f32_e32 v82, v50, v82
	v_cvt_pk_bf16_f32 v82, v82, s0
	ds_write_b16 v81, v82 offset:464
	ds_bpermute_b32 v82, v77, v142
	v_cvt_pk_bf16_f32 v83, v83, s0
	ds_write_b16 v81, v83 offset:400
	s_lshl_b64 s[4:5], s[4:5], 8
	s_add_u32 s4, s96, s4
	s_waitcnt lgkmcnt(1)
	v_mul_f32_e32 v83, v3, v82
	v_cvt_pk_bf16_f32 v83, v83, s0
	ds_write_b16 v81, v83 offset:544
	v_mul_f32_e32 v83, v19, v82
	v_cvt_pk_bf16_f32 v83, v83, s0
	ds_write_b16 v81, v83 offset:608
	v_mul_f32_e32 v83, v35, v82
	v_mul_f32_e32 v82, v51, v82
	v_cvt_pk_bf16_f32 v82, v82, s0
	ds_write_b16 v81, v82 offset:736
	ds_bpermute_b32 v82, v76, v142
	v_cvt_pk_bf16_f32 v83, v83, s0
	ds_write_b16 v81, v83 offset:672
	s_addc_u32 s5, s97, s5
	v_lshl_add_u64 v[86:87], s[4:5], 0, v[178:179]
	s_waitcnt lgkmcnt(1)
; #define LAS __attribute__((address_space(3)))
; __device__ __forceinline__ unsigned cvtpk(float lo, float hi) { f32x2_t v = {lo, hi}; bf16x2_t b = __builtin_convertvector(v, bf16x2_t); return __builtin_bit_cast(unsigned, b); }
; __device__ __forceinline__ int crow(int r, int hi) { return (r & 3) + 8 * (r >> 2) + 4 * hi; }
; __device__ __forceinline__ void dil_attn_unit(LAS unsigned char* lds, bf16_t* proj, float* lse, int unit, int Tc, bf16_t* ybuf) {
;     ...
;         LAS bf16_t* stg = (LAS bf16_t*)(lds + w * 8704);
; #pragma unroll
;         for (int rr = 0; rr < 16; ++rr) { const int qi = crow(rr, hi); const float a = __shfl(inv, qi);
; #pragma unroll
;             for (int db = 0; db < 4; ++db) stg[qi * 136 + db * 32 + r32] = (bf16_t)(cvtpk(o[db][rr] * a, 0.f) & 0xffffu); }
;         asm volatile("s_waitcnt lgkmcnt(0)" ::: "memory");
;         bf16_t* obase = qblk + (pbase + (U0 + 32 * w)) * 128;
; #pragma unroll
;         for (int i = 0; i < 8; ++i) { const int row = i * 4 + (lane >> 4), c16 = lane & 15;
;             const u32x4 x = *(const LAS u32x4*)(stg + row * 136 + c16 * 8);
;             *(u32x4*)(obase + row * 128 + c16 * 8) = x; }
	v_mul_f32_e32 v83, v4, v82
	v_cvt_pk_bf16_f32 v83, v83, s0
	ds_write_b16 v81, v83 offset:1904
	v_mul_f32_e32 v83, v20, v82
	v_cvt_pk_bf16_f32 v83, v83, s0
	ds_write_b16 v81, v83 offset:1968
	v_mul_f32_e32 v83, v36, v82
	v_mul_f32_e32 v82, v52, v82
	v_cvt_pk_bf16_f32 v82, v82, s0
	ds_write_b16 v81, v82 offset:2096
	ds_bpermute_b32 v82, v74, v142
	v_cvt_pk_bf16_f32 v83, v83, s0
	ds_write_b16 v81, v83 offset:2032
	v_lshlrev_b32_e32 v90, 8, v75
	v_mov_b32_e32 v91, v179
	s_waitcnt lgkmcnt(1)
	v_mul_f32_e32 v83, v5, v82
	v_cvt_pk_bf16_f32 v83, v83, s0
	ds_write_b16 v81, v83 offset:2176
	v_mul_f32_e32 v83, v21, v82
	v_cvt_pk_bf16_f32 v83, v83, s0
	ds_write_b16 v81, v83 offset:2240
	v_mul_f32_e32 v83, v37, v82
	v_mul_f32_e32 v82, v53, v82
	v_cvt_pk_bf16_f32 v82, v82, s0
	ds_write_b16 v81, v82 offset:2368
	ds_bpermute_b32 v82, v73, v142
	v_cvt_pk_bf16_f32 v83, v83, s0
	ds_write_b16 v81, v83 offset:2304
	v_lshl_add_u64 v[92:93], v[86:87], 0, v[90:91]
	s_waitcnt lgkmcnt(1)
	v_mul_f32_e32 v83, v6, v82
	v_cvt_pk_bf16_f32 v83, v83, s0
	ds_write_b16 v81, v83 offset:2448
	v_mul_f32_e32 v83, v22, v82
	v_cvt_pk_bf16_f32 v83, v83, s0
	ds_write_b16 v81, v83 offset:2512
	v_mul_f32_e32 v83, v38, v82
	v_mul_f32_e32 v82, v54, v82
	v_cvt_pk_bf16_f32 v82, v82, s0
	ds_write_b16 v81, v82 offset:2640
	ds_bpermute_b32 v82, v72, v142
	v_cvt_pk_bf16_f32 v83, v83, s0
	ds_write_b16 v81, v83 offset:2576
	s_waitcnt lgkmcnt(1)
	v_mul_f32_e32 v83, v7, v82
	v_cvt_pk_bf16_f32 v83, v83, s0
	ds_write_b16 v81, v83 offset:2720
	v_mul_f32_e32 v83, v23, v82
	v_cvt_pk_bf16_f32 v83, v83, s0
	ds_write_b16 v81, v83 offset:2784
	v_mul_f32_e32 v83, v39, v82
	v_mul_f32_e32 v82, v55, v82
	v_cvt_pk_bf16_f32 v82, v82, s0
	ds_write_b16 v81, v82 offset:2912
	ds_bpermute_b32 v82, v71, v142
	v_cvt_pk_bf16_f32 v83, v83, s0
	ds_write_b16 v81, v83 offset:2848
	s_waitcnt lgkmcnt(1)
	v_mul_f32_e32 v83, v8, v82
	v_cvt_pk_bf16_f32 v83, v83, s0
	ds_write_b16 v81, v83 offset:4080
	v_mul_f32_e32 v83, v24, v82
	v_cvt_pk_bf16_f32 v83, v83, s0
	ds_write_b16 v81, v83 offset:4144
	v_mul_f32_e32 v83, v40, v82
	v_mul_f32_e32 v82, v56, v82
	v_cvt_pk_bf16_f32 v82, v82, s0
	ds_write_b16 v81, v82 offset:4272
	ds_bpermute_b32 v82, v70, v142
	v_cvt_pk_bf16_f32 v83, v83, s0
	ds_write_b16 v81, v83 offset:4208
	s_waitcnt lgkmcnt(1)
	v_mul_f32_e32 v83, v9, v82
	v_cvt_pk_bf16_f32 v83, v83, s0
	ds_write_b16 v81, v83 offset:4352
	v_mul_f32_e32 v83, v25, v82
	v_cvt_pk_bf16_f32 v83, v83, s0
	ds_write_b16 v81, v83 offset:4416
	v_mul_f32_e32 v83, v41, v82
	v_mul_f32_e32 v82, v57, v82
	v_cvt_pk_bf16_f32 v82, v82, s0
	ds_write_b16 v81, v82 offset:4544
	ds_bpermute_b32 v82, v69, v142
	v_cvt_pk_bf16_f32 v83, v83, s0
	ds_write_b16 v81, v83 offset:4480
	s_waitcnt lgkmcnt(1)
	v_mul_f32_e32 v83, v10, v82
	v_cvt_pk_bf16_f32 v83, v83, s0
	ds_write_b16 v81, v83 offset:4624
	v_mul_f32_e32 v83, v26, v82
	v_cvt_pk_bf16_f32 v83, v83, s0
	ds_write_b16 v81, v83 offset:4688
	v_mul_f32_e32 v83, v42, v82
	v_mul_f32_e32 v82, v58, v82
	v_cvt_pk_bf16_f32 v82, v82, s0
	ds_write_b16 v81, v82 offset:4816
	ds_bpermute_b32 v82, v68, v142
	v_cvt_pk_bf16_f32 v83, v83, s0
	ds_write_b16 v81, v83 offset:4752
	s_waitcnt lgkmcnt(1)
	v_mul_f32_e32 v83, v11, v82
	v_cvt_pk_bf16_f32 v83, v83, s0
	ds_write_b16 v81, v83 offset:4896
	v_mul_f32_e32 v83, v27, v82
	v_cvt_pk_bf16_f32 v83, v83, s0
	ds_write_b16 v81, v83 offset:4960
	v_mul_f32_e32 v83, v43, v82
	v_mul_f32_e32 v82, v59, v82
	v_cvt_pk_bf16_f32 v82, v82, s0
	ds_write_b16 v81, v82 offset:5088
	ds_bpermute_b32 v82, v67, v142
	v_cvt_pk_bf16_f32 v83, v83, s0
	ds_write_b16 v81, v83 offset:5024
	s_waitcnt lgkmcnt(1)
	v_mul_f32_e32 v83, v12, v82
	v_cvt_pk_bf16_f32 v83, v83, s0
	ds_write_b16 v81, v83 offset:6256
	v_mul_f32_e32 v83, v28, v82
	v_cvt_pk_bf16_f32 v83, v83, s0
	ds_write_b16 v81, v83 offset:6320
	v_mul_f32_e32 v83, v44, v82
	v_mul_f32_e32 v82, v60, v82
	v_cvt_pk_bf16_f32 v82, v82, s0
	ds_write_b16 v81, v82 offset:6448
	ds_bpermute_b32 v82, v66, v142
	v_cvt_pk_bf16_f32 v83, v83, s0
	ds_write_b16 v81, v83 offset:6384
	s_waitcnt lgkmcnt(1)
	v_mul_f32_e32 v83, v13, v82
	v_cvt_pk_bf16_f32 v83, v83, s0
	ds_write_b16 v81, v83 offset:6528
	v_mul_f32_e32 v83, v29, v82
	v_cvt_pk_bf16_f32 v83, v83, s0
	ds_write_b16 v81, v83 offset:6592
	v_mul_f32_e32 v83, v45, v82
	v_mul_f32_e32 v82, v61, v82
	v_cvt_pk_bf16_f32 v82, v82, s0
	ds_write_b16 v81, v82 offset:6720
	ds_bpermute_b32 v82, v65, v142
	v_cvt_pk_bf16_f32 v83, v83, s0
	ds_write_b16 v81, v83 offset:6656
	s_waitcnt lgkmcnt(1)
	v_mul_f32_e32 v83, v14, v82
	v_cvt_pk_bf16_f32 v83, v83, s0
	ds_write_b16 v81, v83 offset:6800
	v_mul_f32_e32 v83, v30, v82
	v_cvt_pk_bf16_f32 v83, v83, s0
	ds_write_b16 v81, v83 offset:6864
	v_mul_f32_e32 v83, v46, v82
	v_mul_f32_e32 v82, v62, v82
	v_cvt_pk_bf16_f32 v82, v82, s0
	ds_write_b16 v81, v82 offset:6992
	ds_bpermute_b32 v82, v64, v142
	v_cvt_pk_bf16_f32 v83, v83, s0
	ds_write_b16 v81, v83 offset:6928
	s_waitcnt lgkmcnt(1)
	v_mul_f32_e32 v83, v15, v82
	v_cvt_pk_bf16_f32 v83, v83, s0
	ds_write_b16 v81, v83 offset:7072
	v_mul_f32_e32 v83, v31, v82
	v_cvt_pk_bf16_f32 v83, v83, s0
	ds_write_b16 v81, v83 offset:7136
	v_mul_f32_e32 v83, v47, v82
	v_mul_f32_e32 v82, v63, v82
	v_cvt_pk_bf16_f32 v83, v83, s0
	v_cvt_pk_bf16_f32 v82, v82, s0
	ds_write_b16 v81, v83 offset:7200
	ds_write_b16 v81, v82 offset:7264
	v_mul_u32_u24_e32 v81, 0x110, v75
	s_waitcnt lgkmcnt(0)
	v_add3_u32 v81, s0, v178, v81
	ds_read_b128 v[82:85], v81
	s_mov_b64 s[0:1], 0
	s_waitcnt lgkmcnt(0)
	global_store_dwordx4 v[92:93], v[82:85], off sc1
	ds_read_b128 v[82:85], v81 offset:1088
	v_or_b32_e32 v92, 0x400, v90
	v_mov_b32_e32 v93, v179
	v_lshl_add_u64 v[92:93], v[86:87], 0, v[92:93]
	s_waitcnt lgkmcnt(0)
	global_store_dwordx4 v[92:93], v[82:85], off sc1
	ds_read_b128 v[82:85], v81 offset:2176
	v_or_b32_e32 v92, 0x800, v90
	v_mov_b32_e32 v93, v179
	v_lshl_add_u64 v[92:93], v[86:87], 0, v[92:93]
	s_waitcnt lgkmcnt(0)
	global_store_dwordx4 v[92:93], v[82:85], off sc1
	ds_read_b128 v[82:85], v81 offset:3264
	v_or_b32_e32 v92, 0xc00, v90
	v_mov_b32_e32 v93, v179
	v_lshl_add_u64 v[92:93], v[86:87], 0, v[92:93]
	s_waitcnt lgkmcnt(0)
	global_store_dwordx4 v[92:93], v[82:85], off sc1
	ds_read_b128 v[82:85], v81 offset:4352
	v_or_b32_e32 v92, 0x1000, v90
	v_mov_b32_e32 v93, v179
	v_lshl_add_u64 v[92:93], v[86:87], 0, v[92:93]
	s_waitcnt lgkmcnt(0)
	global_store_dwordx4 v[92:93], v[82:85], off sc1
	ds_read_b128 v[82:85], v81 offset:5440
	v_or_b32_e32 v92, 0x1400, v90
	v_mov_b32_e32 v93, v179
	v_lshl_add_u64 v[92:93], v[86:87], 0, v[92:93]
	s_waitcnt lgkmcnt(0)
	global_store_dwordx4 v[92:93], v[82:85], off sc1
	ds_read_b128 v[82:85], v81 offset:6528
	v_or_b32_e32 v92, 0x1800, v90
	v_mov_b32_e32 v93, v179
	v_lshl_add_u64 v[92:93], v[86:87], 0, v[92:93]
	v_or_b32_e32 v90, 0x1c00, v90
	s_waitcnt lgkmcnt(0)
	global_store_dwordx4 v[92:93], v[82:85], off sc1
	ds_read_b128 v[82:85], v81 offset:7616
	v_lshl_add_u64 v[86:87], v[86:87], 0, v[90:91]
	s_waitcnt lgkmcnt(0)
	global_store_dwordx4 v[86:87], v[82:85], off sc1

; __device__ __forceinline__ unsigned cvtpk(float lo, float hi) { f32x2_t v = {lo, hi}; bf16x2_t b = __builtin_convertvector(v, bf16x2_t); return __builtin_bit_cast(unsigned, b); }
;     __device__ __forceinline__ void operator()(const f32x4 (&acc)[2][2][4][2], const pg8::Unit& u, int wr, int wc, int fr, int fq) const {
;     ...
;                 for (int m = 0; m < 4; ++m) { const int row = row0 + ai * 128 + m * 16; bf16_t* rowp = O + (size_t)row * ldc + col0; const int pos = row & (SEQ - 1);
;                     const int dcol = wc * 32 + 8 * fq, sq4 = row & ~(SEQ - 1);
; #pragma unroll
;                     for (int bj = 0; bj < 2; ++bj) { f32x4 v0 = acc[ai][bj][m][0], v1 = acc[ai][bj][m][1];
;                         if (mode == 1) {
;                             const int col = col0 + bj * 128; const int d = col % 96;
;                             if (d >= 64) { const int f0 = (d - 64) >> 1;
;                                 const f32x4 c = *(const f32x4*)(cs + pos * 32 + f0), s = *(const f32x4*)(cs + pos * 32 + 16 + f0);
;                                 f32x4 a0, a1;
;                                 a0[0] = v0[0] * c[0] - v0[1] * s[0]; a0[1] = v0[0] * s[0] + v0[1] * c[0];
;                                 a0[2] = v0[2] * c[1] - v0[3] * s[1]; a0[3] = v0[2] * s[1] + v0[3] * c[1];
;                                 a1[0] = v1[0] * c[2] - v1[1] * s[2]; a1[1] = v1[0] * s[2] + v1[1] * c[2];
;                                 a1[2] = v1[2] * c[3] - v1[3] * s[3]; a1[3] = v1[2] * s[3] + v1[3] * c[3];
;                                 v0 = a0; v1 = a1; }
;                             v0 = v0 * scale; v1 = v1 * scale; }
;                         u32x4 w; w.x = cvtpk(v0[0], v0[1]); w.y = cvtpk(v0[2], v0[3]); w.z = cvtpk(v1[0], v1[1]); w.w = cvtpk(v1[2], v1[3]);
;                         if (mode == 3) { const int cb = u.pn * 2 + bj;
;                             bf16_t* dst;
;                             if (cb < 72) { const int dsh = 2 * (cb / 24); const int tp = sq4 + ((pos & ((1 << dsh) - 1)) << (12 - dsh)) + (pos >> dsh); dst = O + ((size_t)cb * ldc + tp) * 128 + dcol; }
;                             else dst = O + (size_t)9216 * ldc + (size_t)row * 1024 + (cb - 72) * 128 + dcol;
;                             *(u32x4*)dst = w; }
;                         else *(u32x4*)(rowp + bj * 128) = w; }
.LBB0_317:
	v_mad_i64_i32 v[138:139], s[10:11], v164, s40, 0
	v_ashrrev_i32_e32 v137, 31, v136
	v_lshl_add_u64 v[138:139], v[138:139], 1, s[22:23]
	v_lshl_add_u64 v[138:139], v[136:137], 1, v[138:139]
	v_cvt_pk_bf16_f32 v128, v128, v129
	v_cvt_pk_bf16_f32 v129, v130, v131
	v_cvt_pk_bf16_f32 v130, v132, v133
	v_cvt_pk_bf16_f32 v131, v134, v135
	s_mov_b64 s[10:11], -1
	s_and_b64 vcc, exec, s[28:29]
	s_cbranch_vccz .LBB0_319
	global_store_dwordx4 v[138:139], v[128:131], off sc1
	s_mov_b64 s[10:11], 0

; __device__ __forceinline__ unsigned cvtpk(float lo, float hi) { f32x2_t v = {lo, hi}; bf16x2_t b = __builtin_convertvector(v, bf16x2_t); return __builtin_bit_cast(unsigned, b); }
;     __device__ __forceinline__ void operator()(const f32x4 (&acc)[2][2][4][2], const pg8::Unit& u, int wr, int wc, int fr, int fq) const {
;     ...
;                         u32x4 w; w.x = cvtpk(v0[0], v0[1]); w.y = cvtpk(v0[2], v0[3]); w.z = cvtpk(v1[0], v1[1]); w.w = cvtpk(v1[2], v1[3]);
;                         if (mode == 3) { const int cb = u.pn * 2 + bj;
;                             bf16_t* dst;
;                             if (cb < 72) { const int dsh = 2 * (cb / 24); const int tp = sq4 + ((pos & ((1 << dsh) - 1)) << (12 - dsh)) + (pos >> dsh); dst = O + ((size_t)cb * ldc + tp) * 128 + dcol; }
;                             else dst = O + (size_t)9216 * ldc + (size_t)row * 1024 + (cb - 72) * 128 + dcol;
;                             *(u32x4*)dst = w; }
;                         else *(u32x4*)(rowp + bj * 128) = w; }
.LBB0_324:
	v_lshlrev_b32_e32 v178, 1, v158
	v_lshl_add_u64 v[132:133], v[132:133], 0, v[178:179]
	global_store_dwordx4 v[132:133], v[128:131], off sc1

; __device__ __forceinline__ unsigned cvtpk(float lo, float hi) { f32x2_t v = {lo, hi}; bf16x2_t b = __builtin_convertvector(v, bf16x2_t); return __builtin_bit_cast(unsigned, b); }
;     __device__ __forceinline__ void operator()(const f32x4 (&acc)[2][2][4][2], const pg8::Unit& u, int wr, int wc, int fr, int fq) const {
;     ...
;                         u32x4 w; w.x = cvtpk(v0[0], v0[1]); w.y = cvtpk(v0[2], v0[3]); w.z = cvtpk(v1[0], v1[1]); w.w = cvtpk(v1[2], v1[3]);
;                         if (mode == 3) { const int cb = u.pn * 2 + bj;
;                             bf16_t* dst;
;                             if (cb < 72) { const int dsh = 2 * (cb / 24); const int tp = sq4 + ((pos & ((1 << dsh) - 1)) << (12 - dsh)) + (pos >> dsh); dst = O + ((size_t)cb * ldc + tp) * 128 + dcol; }
;                             else dst = O + (size_t)9216 * ldc + (size_t)row * 1024 + (cb - 72) * 128 + dcol;
;                             *(u32x4*)dst = w; }
;                         else *(u32x4*)(rowp + bj * 128) = w; }
.LBB0_329:
	v_cvt_pk_bf16_f32 v128, v128, v129
	v_cvt_pk_bf16_f32 v129, v130, v131
	v_cvt_pk_bf16_f32 v130, v132, v133
	v_cndmask_b32_e64 v132, 0, 1, s[28:29]
	v_cvt_pk_bf16_f32 v131, v134, v135
	v_cmp_ne_u32_e64 s[10:11], 1, v132
	s_andn2_b64 vcc, exec, s[28:29]
	s_mov_b64 s[86:87], -1
	s_cbranch_vccnz .LBB0_331
	s_mov_b64 s[86:87], 0
	global_store_dwordx4 v[138:139], v[128:131], off offset:256 sc1

; __device__ __forceinline__ unsigned cvtpk(float lo, float hi) { f32x2_t v = {lo, hi}; bf16x2_t b = __builtin_convertvector(v, bf16x2_t); return __builtin_bit_cast(unsigned, b); }
;     __device__ __forceinline__ void operator()(const f32x4 (&acc)[2][2][4][2], const pg8::Unit& u, int wr, int wc, int fr, int fq) const {
;     ...
;                 for (int m = 0; m < 4; ++m) { const int row = row0 + ai * 128 + m * 16; bf16_t* rowp = O + (size_t)row * ldc + col0; const int pos = row & (SEQ - 1);
;                     const int dcol = wc * 32 + 8 * fq, sq4 = row & ~(SEQ - 1);
; #pragma unroll
;                     for (int bj = 0; bj < 2; ++bj) { f32x4 v0 = acc[ai][bj][m][0], v1 = acc[ai][bj][m][1];
;                         if (mode == 1) {
;                             const int col = col0 + bj * 128; const int d = col % 96;
;                             if (d >= 64) { const int f0 = (d - 64) >> 1;
;                                 const f32x4 c = *(const f32x4*)(cs + pos * 32 + f0), s = *(const f32x4*)(cs + pos * 32 + 16 + f0);
;                                 f32x4 a0, a1;
;                                 a0[0] = v0[0] * c[0] - v0[1] * s[0]; a0[1] = v0[0] * s[0] + v0[1] * c[0];
;                                 a0[2] = v0[2] * c[1] - v0[3] * s[1]; a0[3] = v0[2] * s[1] + v0[3] * c[1];
;                                 a1[0] = v1[0] * c[2] - v1[1] * s[2]; a1[1] = v1[0] * s[2] + v1[1] * c[2];
;                                 a1[2] = v1[2] * c[3] - v1[3] * s[3]; a1[3] = v1[2] * s[3] + v1[3] * c[3];
;                                 v0 = a0; v1 = a1; }
;                             v0 = v0 * scale; v1 = v1 * scale; }
;                         u32x4 w; w.x = cvtpk(v0[0], v0[1]); w.y = cvtpk(v0[2], v0[3]); w.z = cvtpk(v1[0], v1[1]); w.w = cvtpk(v1[2], v1[3]);
;                         if (mode == 3) { const int cb = u.pn * 2 + bj;
;                             bf16_t* dst;
;                             if (cb < 72) { const int dsh = 2 * (cb / 24); const int tp = sq4 + ((pos & ((1 << dsh) - 1)) << (12 - dsh)) + (pos >> dsh); dst = O + ((size_t)cb * ldc + tp) * 128 + dcol; }
;                             else dst = O + (size_t)9216 * ldc + (size_t)row * 1024 + (cb - 72) * 128 + dcol;
;                             *(u32x4*)dst = w; }
;                         else *(u32x4*)(rowp + bj * 128) = w; }
.LBB0_341:
	v_or_b32_e32 v138, 16, v164
	v_mad_i64_i32 v[140:141], s[74:75], v138, s40, 0
	v_lshl_add_u64 v[140:141], v[140:141], 1, s[22:23]
	v_lshl_add_u64 v[140:141], v[136:137], 1, v[140:141]
	v_cvt_pk_bf16_f32 v128, v128, v129
	v_cvt_pk_bf16_f32 v129, v130, v131
	v_cvt_pk_bf16_f32 v130, v132, v133
	v_cvt_pk_bf16_f32 v131, v134, v135
	s_and_b64 vcc, exec, s[10:11]
	s_mov_b64 s[86:87], -1
	s_cbranch_vccnz .LBB0_343
	s_mov_b64 s[86:87], 0
	global_store_dwordx4 v[140:141], v[128:131], off sc1

; __device__ __forceinline__ unsigned cvtpk(float lo, float hi) { f32x2_t v = {lo, hi}; bf16x2_t b = __builtin_convertvector(v, bf16x2_t); return __builtin_bit_cast(unsigned, b); }
;     __device__ __forceinline__ void operator()(const f32x4 (&acc)[2][2][4][2], const pg8::Unit& u, int wr, int wc, int fr, int fq) const {
;     ...
;                         u32x4 w; w.x = cvtpk(v0[0], v0[1]); w.y = cvtpk(v0[2], v0[3]); w.z = cvtpk(v1[0], v1[1]); w.w = cvtpk(v1[2], v1[3]);
;                         if (mode == 3) { const int cb = u.pn * 2 + bj;
;                             bf16_t* dst;
;                             if (cb < 72) { const int dsh = 2 * (cb / 24); const int tp = sq4 + ((pos & ((1 << dsh) - 1)) << (12 - dsh)) + (pos >> dsh); dst = O + ((size_t)cb * ldc + tp) * 128 + dcol; }
;                             else dst = O + (size_t)9216 * ldc + (size_t)row * 1024 + (cb - 72) * 128 + dcol;
;                             *(u32x4*)dst = w; }
;                         else *(u32x4*)(rowp + bj * 128) = w; }
.LBB0_353:
	v_cvt_pk_bf16_f32 v128, v128, v129
	v_cvt_pk_bf16_f32 v129, v130, v131
	v_cvt_pk_bf16_f32 v130, v132, v133
	v_cvt_pk_bf16_f32 v131, v134, v135
	s_and_b64 vcc, exec, s[10:11]
	s_mov_b64 s[86:87], -1
	s_cbranch_vccnz .LBB0_355
	s_mov_b64 s[86:87], 0
	global_store_dwordx4 v[140:141], v[128:131], off offset:256 sc1

; __device__ __forceinline__ unsigned cvtpk(float lo, float hi) { f32x2_t v = {lo, hi}; bf16x2_t b = __builtin_convertvector(v, bf16x2_t); return __builtin_bit_cast(unsigned, b); }
;     __device__ __forceinline__ void operator()(const f32x4 (&acc)[2][2][4][2], const pg8::Unit& u, int wr, int wc, int fr, int fq) const {
;     ...
;                 for (int m = 0; m < 4; ++m) { const int row = row0 + ai * 128 + m * 16; bf16_t* rowp = O + (size_t)row * ldc + col0; const int pos = row & (SEQ - 1);
;                     const int dcol = wc * 32 + 8 * fq, sq4 = row & ~(SEQ - 1);
; #pragma unroll
;                     for (int bj = 0; bj < 2; ++bj) { f32x4 v0 = acc[ai][bj][m][0], v1 = acc[ai][bj][m][1];
;                         if (mode == 1) {
;                             const int col = col0 + bj * 128; const int d = col % 96;
;                             if (d >= 64) { const int f0 = (d - 64) >> 1;
;                                 const f32x4 c = *(const f32x4*)(cs + pos * 32 + f0), s = *(const f32x4*)(cs + pos * 32 + 16 + f0);
;                                 f32x4 a0, a1;
;                                 a0[0] = v0[0] * c[0] - v0[1] * s[0]; a0[1] = v0[0] * s[0] + v0[1] * c[0];
;                                 a0[2] = v0[2] * c[1] - v0[3] * s[1]; a0[3] = v0[2] * s[1] + v0[3] * c[1];
;                                 a1[0] = v1[0] * c[2] - v1[1] * s[2]; a1[1] = v1[0] * s[2] + v1[1] * c[2];
;                                 a1[2] = v1[2] * c[3] - v1[3] * s[3]; a1[3] = v1[2] * s[3] + v1[3] * c[3];
;                                 v0 = a0; v1 = a1; }
;                             v0 = v0 * scale; v1 = v1 * scale; }
;                         u32x4 w; w.x = cvtpk(v0[0], v0[1]); w.y = cvtpk(v0[2], v0[3]); w.z = cvtpk(v1[0], v1[1]); w.w = cvtpk(v1[2], v1[3]);
;                         if (mode == 3) { const int cb = u.pn * 2 + bj;
;                             bf16_t* dst;
;                             if (cb < 72) { const int dsh = 2 * (cb / 24); const int tp = sq4 + ((pos & ((1 << dsh) - 1)) << (12 - dsh)) + (pos >> dsh); dst = O + ((size_t)cb * ldc + tp) * 128 + dcol; }
;                             else dst = O + (size_t)9216 * ldc + (size_t)row * 1024 + (cb - 72) * 128 + dcol;
;                             *(u32x4*)dst = w; }
;                         else *(u32x4*)(rowp + bj * 128) = w; }
.LBB0_365:
	v_or_b32_e32 v138, 32, v164
	v_mad_i64_i32 v[140:141], s[74:75], v138, s40, 0
	v_lshl_add_u64 v[140:141], v[140:141], 1, s[22:23]
	v_lshl_add_u64 v[140:141], v[136:137], 1, v[140:141]
	v_cvt_pk_bf16_f32 v128, v128, v129
	v_cvt_pk_bf16_f32 v129, v130, v131
	v_cvt_pk_bf16_f32 v130, v132, v133
	v_cvt_pk_bf16_f32 v131, v134, v135
	s_and_b64 vcc, exec, s[10:11]
	s_mov_b64 s[86:87], -1
	s_cbranch_vccnz .LBB0_367
	s_mov_b64 s[86:87], 0
	global_store_dwordx4 v[140:141], v[128:131], off sc1

; __device__ __forceinline__ unsigned cvtpk(float lo, float hi) { f32x2_t v = {lo, hi}; bf16x2_t b = __builtin_convertvector(v, bf16x2_t); return __builtin_bit_cast(unsigned, b); }
;     __device__ __forceinline__ void operator()(const f32x4 (&acc)[2][2][4][2], const pg8::Unit& u, int wr, int wc, int fr, int fq) const {
;     ...
;                 for (int m = 0; m < 4; ++m) { const int row = row0 + ai * 128 + m * 16; bf16_t* rowp = O + (size_t)row * ldc + col0; const int pos = row & (SEQ - 1);
;                     const int dcol = wc * 32 + 8 * fq, sq4 = row & ~(SEQ - 1);
; #pragma unroll
;                     for (int bj = 0; bj < 2; ++bj) { f32x4 v0 = acc[ai][bj][m][0], v1 = acc[ai][bj][m][1];
;                         if (mode == 1) {
;                             const int col = col0 + bj * 128; const int d = col % 96;
;                             if (d >= 64) { const int f0 = (d - 64) >> 1;
;                                 const f32x4 c = *(const f32x4*)(cs + pos * 32 + f0), s = *(const f32x4*)(cs + pos * 32 + 16 + f0);
;                                 f32x4 a0, a1;
;                                 a0[0] = v0[0] * c[0] - v0[1] * s[0]; a0[1] = v0[0] * s[0] + v0[1] * c[0];
;                                 a0[2] = v0[2] * c[1] - v0[3] * s[1]; a0[3] = v0[2] * s[1] + v0[3] * c[1];
;                                 a1[0] = v1[0] * c[2] - v1[1] * s[2]; a1[1] = v1[0] * s[2] + v1[1] * c[2];
;                                 a1[2] = v1[2] * c[3] - v1[3] * s[3]; a1[3] = v1[2] * s[3] + v1[3] * c[3];
;                                 v0 = a0; v1 = a1; }
;                             v0 = v0 * scale; v1 = v1 * scale; }
;                         u32x4 w; w.x = cvtpk(v0[0], v0[1]); w.y = cvtpk(v0[2], v0[3]); w.z = cvtpk(v1[0], v1[1]); w.w = cvtpk(v1[2], v1[3]);
;                         if (mode == 3) { const int cb = u.pn * 2 + bj;
;                             bf16_t* dst;
;                             if (cb < 72) { const int dsh = 2 * (cb / 24); const int tp = sq4 + ((pos & ((1 << dsh) - 1)) << (12 - dsh)) + (pos >> dsh); dst = O + ((size_t)cb * ldc + tp) * 128 + dcol; }
;                             else dst = O + (size_t)9216 * ldc + (size_t)row * 1024 + (cb - 72) * 128 + dcol;
;                             *(u32x4*)dst = w; }
;                         else *(u32x4*)(rowp + bj * 128) = w; }
.LBB0_389:
	v_or_b32_e32 v138, 48, v164
	v_mad_i64_i32 v[140:141], s[74:75], v138, s40, 0
	v_lshl_add_u64 v[140:141], v[140:141], 1, s[22:23]
	v_lshl_add_u64 v[140:141], v[136:137], 1, v[140:141]
	v_cvt_pk_bf16_f32 v128, v128, v129
	v_cvt_pk_bf16_f32 v129, v130, v131
	v_cvt_pk_bf16_f32 v130, v132, v133
	v_cvt_pk_bf16_f32 v131, v134, v135
	s_and_b64 vcc, exec, s[10:11]
	s_mov_b64 s[86:87], -1
	s_cbranch_vccnz .LBB0_391
	s_mov_b64 s[86:87], 0
	global_store_dwordx4 v[140:141], v[128:131], off sc1

; __device__ __forceinline__ unsigned cvtpk(float lo, float hi) { f32x2_t v = {lo, hi}; bf16x2_t b = __builtin_convertvector(v, bf16x2_t); return __builtin_bit_cast(unsigned, b); }
;     __device__ __forceinline__ void operator()(const f32x4 (&acc)[2][2][4][2], const pg8::Unit& u, int wr, int wc, int fr, int fq) const {
;     ...
;                 for (int m = 0; m < 4; ++m) { const int row = row0 + ai * 128 + m * 16; bf16_t* rowp = O + (size_t)row * ldc + col0; const int pos = row & (SEQ - 1);
;                     const int dcol = wc * 32 + 8 * fq, sq4 = row & ~(SEQ - 1);
; #pragma unroll
;                     for (int bj = 0; bj < 2; ++bj) { f32x4 v0 = acc[ai][bj][m][0], v1 = acc[ai][bj][m][1];
;                         if (mode == 1) {
;                             const int col = col0 + bj * 128; const int d = col % 96;
;                             if (d >= 64) { const int f0 = (d - 64) >> 1;
;                                 const f32x4 c = *(const f32x4*)(cs + pos * 32 + f0), s = *(const f32x4*)(cs + pos * 32 + 16 + f0);
;                                 f32x4 a0, a1;
;                                 a0[0] = v0[0] * c[0] - v0[1] * s[0]; a0[1] = v0[0] * s[0] + v0[1] * c[0];
;                                 a0[2] = v0[2] * c[1] - v0[3] * s[1]; a0[3] = v0[2] * s[1] + v0[3] * c[1];
;                                 a1[0] = v1[0] * c[2] - v1[1] * s[2]; a1[1] = v1[0] * s[2] + v1[1] * c[2];
;                                 a1[2] = v1[2] * c[3] - v1[3] * s[3]; a1[3] = v1[2] * s[3] + v1[3] * c[3];
;                                 v0 = a0; v1 = a1; }
;                             v0 = v0 * scale; v1 = v1 * scale; }
;                         u32x4 w; w.x = cvtpk(v0[0], v0[1]); w.y = cvtpk(v0[2], v0[3]); w.z = cvtpk(v1[0], v1[1]); w.w = cvtpk(v1[2], v1[3]);
;                         if (mode == 3) { const int cb = u.pn * 2 + bj;
;                             bf16_t* dst;
;                             if (cb < 72) { const int dsh = 2 * (cb / 24); const int tp = sq4 + ((pos & ((1 << dsh) - 1)) << (12 - dsh)) + (pos >> dsh); dst = O + ((size_t)cb * ldc + tp) * 128 + dcol; }
;                             else dst = O + (size_t)9216 * ldc + (size_t)row * 1024 + (cb - 72) * 128 + dcol;
;                             *(u32x4*)dst = w; }
;                         else *(u32x4*)(rowp + bj * 128) = w; }
.LBB0_413:
	v_mad_i64_i32 v[140:141], s[74:75], v138, s40, 0
	v_lshl_add_u64 v[140:141], v[140:141], 1, s[22:23]
	v_lshl_add_u64 v[140:141], v[136:137], 1, v[140:141]
	v_cvt_pk_bf16_f32 v128, v128, v129
	v_cvt_pk_bf16_f32 v129, v130, v131
	v_cvt_pk_bf16_f32 v130, v132, v133
	v_cvt_pk_bf16_f32 v131, v134, v135
	s_and_b64 vcc, exec, s[10:11]
	s_mov_b64 s[86:87], -1
	s_cbranch_vccnz .LBB0_415
	s_mov_b64 s[86:87], 0
	global_store_dwordx4 v[140:141], v[128:131], off sc1

; __device__ __forceinline__ unsigned cvtpk(float lo, float hi) { f32x2_t v = {lo, hi}; bf16x2_t b = __builtin_convertvector(v, bf16x2_t); return __builtin_bit_cast(unsigned, b); }
;     __device__ __forceinline__ void operator()(const f32x4 (&acc)[2][2][4][2], const pg8::Unit& u, int wr, int wc, int fr, int fq) const {
;     ...
;                         u32x4 w; w.x = cvtpk(v0[0], v0[1]); w.y = cvtpk(v0[2], v0[3]); w.z = cvtpk(v1[0], v1[1]); w.w = cvtpk(v1[2], v1[3]);
;                         if (mode == 3) { const int cb = u.pn * 2 + bj;
;                             bf16_t* dst;
;                             if (cb < 72) { const int dsh = 2 * (cb / 24); const int tp = sq4 + ((pos & ((1 << dsh) - 1)) << (12 - dsh)) + (pos >> dsh); dst = O + ((size_t)cb * ldc + tp) * 128 + dcol; }
;                             else dst = O + (size_t)9216 * ldc + (size_t)row * 1024 + (cb - 72) * 128 + dcol;
;                             *(u32x4*)dst = w; }
;                         else *(u32x4*)(rowp + bj * 128) = w; }
.LBB0_497:
	v_cvt_pk_bf16_f32 v128, v128, v129
	v_cvt_pk_bf16_f32 v129, v130, v131
	v_cvt_pk_bf16_f32 v130, v132, v133
	v_cvt_pk_bf16_f32 v131, v134, v135
	s_and_b64 vcc, exec, s[10:11]
	s_mov_b64 s[10:11], -1
	s_cbranch_vccnz .LBB0_499
	s_mov_b64 s[10:11], 0
	global_store_dwordx4 v[140:141], v[128:131], off offset:256 sc1

;     __device__ __forceinline__ void operator()(const f32x4 (&acc)[2][2][4][2], const pg8::Unit& u, int wr, int wc, int fr, int fq) const {
;     ...
;                     for (int m = 0; m < 4; ++m) { const size_t off = (size_t)(row0 + ai * 128 + m * 16) * DM + col0;
; #pragma unroll
;                         for (int bj = 0; bj < 2; ++bj) { bv[m][bj][0] = *(const f32x4*)(base + off + bj * 128); bv[m][bj][1] = *(const f32x4*)(base + off + bj * 128 + 4); } }
;                     asm volatile("" ::: "memory");
; #pragma unroll
;                     for (int m = 0; m < 4; ++m) { const size_t off = (size_t)(row0 + ai * 128 + m * 16) * DM + col0;
; #pragma unroll
;                         for (int bj = 0; bj < 2; ++bj) { const f32x4 x0 = bv[m][bj][0] + acc[ai][bj][m][0], x1 = bv[m][bj][1] + acc[ai][bj][m][1];
;                             const f32x8 xx = {x0[0], x0[1], x0[2], x0[3], x1[0], x1[1], x1[2], x1[3]};
;                             *(f16x8*)(xh + off + bj * 128) = __builtin_convertvector(xx, f16x8); } }
;                     asm volatile("" ::: "memory");
.LBB0_506:
	s_and_b64 vcc, exec, s[10:11]
	s_cbranch_vccz .LBB0_510
	v_ashrrev_i32_e32 v165, 31, v164
	v_ashrrev_i32_e32 v137, 31, v136
	v_or_b32_e32 v132, 16, v164
	v_or_b32_e32 v130, 32, v164
	v_or_b32_e32 v128, 48, v164
	v_lshlrev_b64 v[134:135], 11, v[164:165]
	s_andn2_b64 vcc, exec, s[6:7]
	v_lshlrev_b64 v[166:167], 1, v[136:137]
	v_ashrrev_i32_e32 v133, 31, v132
	v_ashrrev_i32_e32 v131, 31, v130
	v_ashrrev_i32_e32 v129, 31, v128
	v_lshl_add_u64 v[174:175], s[50:51], 0, v[134:135]
	s_cbranch_vccnz .LBB0_513
	v_lshl_add_u64 v[136:137], v[136:137], 2, v[148:149]
	v_lshlrev_b64 v[138:139], 12, v[164:165]
	v_lshl_add_u64 v[146:147], v[136:137], 0, v[138:139]
	v_lshlrev_b64 v[172:173], 12, v[132:133]
	global_load_dwordx4 v[138:141], v[146:147], off
	global_load_dwordx4 v[142:145], v[146:147], off offset:16
	global_load_dwordx4 v[168:171], v[146:147], off offset:512
	global_load_dwordx4 v[186:189], v[146:147], off offset:528
	v_lshl_add_u64 v[146:147], v[136:137], 0, v[172:173]
	global_load_dwordx4 v[200:203], v[146:147], off
	global_load_dwordx4 v[204:207], v[146:147], off offset:16
	global_load_dwordx4 v[214:217], v[146:147], off offset:512
	v_lshlrev_b64 v[172:173], 12, v[130:131]
	global_load_dwordx4 v[218:221], v[146:147], off offset:528
	v_lshl_add_u64 v[146:147], v[136:137], 0, v[172:173]
	global_load_dwordx4 v[222:225], v[146:147], off
	global_load_dwordx4 v[226:229], v[146:147], off offset:16
	global_load_dwordx4 v[230:233], v[146:147], off offset:512
	global_load_dwordx4 v[234:237], v[146:147], off offset:528
	v_lshlrev_b64 v[146:147], 12, v[128:129]
	v_lshl_add_u64 v[146:147], v[136:137], 0, v[146:147]
	global_load_dwordx4 v[238:241], v[146:147], off
	global_load_dwordx4 v[242:245], v[146:147], off offset:16
	global_load_dwordx4 v[246:249], v[146:147], off offset:512
	global_load_dwordx4 v[250:253], v[146:147], off offset:528
	v_lshlrev_b64 v[172:173], 11, v[132:133]
	v_lshlrev_b64 v[182:183], 11, v[130:131]
	v_lshl_add_u64 v[146:147], v[174:175], 0, v[166:167]
	v_lshl_add_u64 v[172:173], s[50:51], 0, v[172:173]
	v_lshl_add_u64 v[182:183], s[50:51], 0, v[182:183]
	v_lshl_add_u64 v[172:173], v[172:173], 0, v[166:167]
	v_lshl_add_u64 v[182:183], v[182:183], 0, v[166:167]
	s_waitcnt vmcnt(0)
	v_pk_add_f32 v[190:191], v[126:127], v[140:141]
	v_pk_add_f32 v[192:193], v[124:125], v[138:139]
	v_pk_add_f32 v[138:139], v[122:123], v[144:145]
	v_pk_add_f32 v[142:143], v[120:121], v[142:143]
	v_pk_add_f32 v[170:171], v[110:111], v[170:171]
	v_pk_add_f32 v[168:169], v[108:109], v[168:169]
	v_pk_add_f32 v[144:145], v[106:107], v[188:189]
	v_pk_add_f32 v[186:187], v[104:105], v[186:187]
	v_pk_add_f32 v[188:189], v[118:119], v[202:203]
	v_pk_add_f32 v[200:201], v[116:117], v[200:201]
	v_pk_add_f32 v[202:203], v[114:115], v[206:207]
	v_pk_add_f32 v[204:205], v[112:113], v[204:205]
	v_pk_add_f32 v[206:207], v[102:103], v[216:217]
	v_pk_add_f32 v[208:209], v[100:101], v[214:215]
	v_pk_add_f32 v[214:215], v[98:99], v[220:221]
	v_pk_add_f32 v[216:217], v[96:97], v[218:219]
	v_pk_add_f32 v[218:219], v[94:95], v[224:225]
	v_pk_add_f32 v[220:221], v[92:93], v[222:223]
	v_pk_add_f32 v[222:223], v[90:91], v[228:229]
	v_pk_add_f32 v[224:225], v[88:89], v[226:227]
	v_cvt_pk_f16_f32 v141, v138, v139
	v_cvt_pk_f16_f32 v139, v190, v191
	v_cvt_pk_f16_f32 v140, v142, v143
	v_cvt_pk_f16_f32 v138, v192, v193
	v_cvt_pk_f16_f32 v143, v170, v171
	v_cvt_pk_f16_f32 v142, v168, v169
	v_cvt_pk_f16_f32 v145, v144, v145
	v_cvt_pk_f16_f32 v144, v186, v187
	v_cvt_pk_f16_f32 v171, v202, v203
	v_cvt_pk_f16_f32 v169, v188, v189
	v_cvt_pk_f16_f32 v170, v204, v205
	v_cvt_pk_f16_f32 v168, v200, v201
	v_cvt_pk_f16_f32 v189, v214, v215
	v_cvt_pk_f16_f32 v187, v206, v207
	v_cvt_pk_f16_f32 v188, v216, v217
	v_cvt_pk_f16_f32 v186, v208, v209
	v_cvt_pk_f16_f32 v203, v222, v223
	v_cvt_pk_f16_f32 v201, v218, v219
	v_cvt_pk_f16_f32 v202, v224, v225
	v_cvt_pk_f16_f32 v200, v220, v221
	global_store_dwordx4 v[146:147], v[138:141], off sc1
	global_store_dwordx4 v[146:147], v[142:145], off offset:256 sc1
	global_store_dwordx4 v[172:173], v[168:171], off sc1
	global_store_dwordx4 v[172:173], v[186:189], off offset:256 sc1
	global_store_dwordx4 v[182:183], v[200:203], off sc1
	v_lshlrev_b64 v[142:143], 11, v[128:129]
	v_pk_add_f32 v[138:139], v[78:79], v[240:241]
	v_pk_add_f32 v[144:145], v[76:77], v[238:239]
	v_pk_add_f32 v[140:141], v[74:75], v[244:245]
	v_pk_add_f32 v[146:147], v[72:73], v[242:243]
	v_lshl_add_u64 v[142:143], s[50:51], 0, v[142:143]
	v_cvt_pk_f16_f32 v141, v140, v141
	v_cvt_pk_f16_f32 v139, v138, v139
	v_cvt_pk_f16_f32 v140, v146, v147
	v_cvt_pk_f16_f32 v138, v144, v145
	v_lshl_add_u64 v[142:143], v[142:143], 0, v[166:167]
	global_store_dwordx4 v[142:143], v[138:141], off sc1
	v_pk_add_f32 v[146:147], v[64:65], v[250:251]
	v_pk_add_f32 v[226:227], v[86:87], v[232:233]
	v_pk_add_f32 v[140:141], v[66:67], v[252:253]
	v_pk_add_f32 v[228:229], v[84:85], v[230:231]
	v_pk_add_f32 v[230:231], v[82:83], v[236:237]
	v_pk_add_f32 v[232:233], v[80:81], v[234:235]
	v_pk_add_f32 v[138:139], v[70:71], v[248:249]
	v_pk_add_f32 v[144:145], v[68:69], v[246:247]
	v_cvt_pk_f16_f32 v141, v140, v141
	v_cvt_pk_f16_f32 v140, v146, v147
	v_add_u32_e32 v146, 0x80, v164
	v_cvt_pk_f16_f32 v207, v230, v231
	v_cvt_pk_f16_f32 v205, v226, v227
	v_cvt_pk_f16_f32 v206, v232, v233
	v_cvt_pk_f16_f32 v204, v228, v229
	v_cvt_pk_f16_f32 v139, v138, v139
	v_cvt_pk_f16_f32 v138, v144, v145
	v_ashrrev_i32_e32 v147, 31, v146
	global_store_dwordx4 v[182:183], v[204:207], off offset:256 sc1
	global_store_dwordx4 v[142:143], v[138:141], off offset:256 sc1
	s_nop 1
	v_lshlrev_b64 v[138:139], 12, v[146:147]
;     __device__ __forceinline__ void operator()(const f32x4 (&acc)[2][2][4][2], const pg8::Unit& u, int wr, int wc, int fr, int fq) const {
;     ...
;                     for (int m = 0; m < 4; ++m) { const size_t off = (size_t)(row0 + ai * 128 + m * 16) * DM + col0;
; #pragma unroll
;                         for (int bj = 0; bj < 2; ++bj) { bv[m][bj][0] = *(const f32x4*)(base + off + bj * 128); bv[m][bj][1] = *(const f32x4*)(base + off + bj * 128 + 4); } }
;                     asm volatile("" ::: "memory");
; #pragma unroll
;                     for (int m = 0; m < 4; ++m) { const size_t off = (size_t)(row0 + ai * 128 + m * 16) * DM + col0;
; #pragma unroll
;                         for (int bj = 0; bj < 2; ++bj) { const f32x4 x0 = bv[m][bj][0] + acc[ai][bj][m][0], x1 = bv[m][bj][1] + acc[ai][bj][m][1];
;                             const f32x8 xx = {x0[0], x0[1], x0[2], x0[3], x1[0], x1[1], x1[2], x1[3]};
;                             *(f16x8*)(xh + off + bj * 128) = __builtin_convertvector(xx, f16x8); } }
;                     asm volatile("" ::: "memory");
	v_lshl_add_u64 v[172:173], v[136:137], 0, v[138:139]
	global_load_dwordx4 v[138:141], v[172:173], off
	global_load_dwordx4 v[142:145], v[172:173], off offset:16
	global_load_dwordx4 v[168:171], v[172:173], off offset:528
	global_load_dwordx4 v[186:189], v[172:173], off offset:512
	v_add_u32_e32 v172, 0x90, v164
	v_ashrrev_i32_e32 v173, 31, v172
	v_lshlrev_b64 v[182:183], 12, v[172:173]
	v_lshl_add_u64 v[182:183], v[136:137], 0, v[182:183]
	global_load_dwordx4 v[200:203], v[182:183], off
	global_load_dwordx4 v[204:207], v[182:183], off offset:16
	global_load_dwordx4 v[214:217], v[182:183], off offset:512
	global_load_dwordx4 v[218:221], v[182:183], off offset:528
	v_add_u32_e32 v182, 0xa0, v164
	v_ashrrev_i32_e32 v183, 31, v182
	v_lshlrev_b64 v[190:191], 12, v[182:183]
	v_lshl_add_u64 v[190:191], v[136:137], 0, v[190:191]
	global_load_dwordx4 v[222:225], v[190:191], off
	global_load_dwordx4 v[226:229], v[190:191], off offset:16
	global_load_dwordx4 v[230:233], v[190:191], off offset:512
	global_load_dwordx4 v[234:237], v[190:191], off offset:528
	v_add_u32_e32 v190, 0xb0, v164
	v_ashrrev_i32_e32 v191, 31, v190
	v_lshlrev_b64 v[192:193], 12, v[190:191]
	v_lshl_add_u64 v[136:137], v[136:137], 0, v[192:193]
	global_load_dwordx4 v[238:241], v[136:137], off
	global_load_dwordx4 v[242:245], v[136:137], off offset:16
	global_load_dwordx4 v[246:249], v[136:137], off offset:512
	global_load_dwordx4 v[250:253], v[136:137], off offset:528
	v_lshlrev_b64 v[136:137], 11, v[146:147]
	v_lshl_add_u64 v[136:137], s[50:51], 0, v[136:137]
	v_lshlrev_b64 v[146:147], 11, v[172:173]
	v_lshl_add_u64 v[172:173], v[136:137], 0, v[166:167]
	s_waitcnt vmcnt(15)
	v_pk_add_f32 v[136:137], v[62:63], v[140:141]
	v_pk_add_f32 v[140:141], v[60:61], v[138:139]
	s_waitcnt vmcnt(14)
	v_pk_add_f32 v[138:139], v[58:59], v[144:145]
	v_pk_add_f32 v[142:143], v[56:57], v[142:143]
	s_waitcnt vmcnt(12)
	v_pk_add_f32 v[144:145], v[54:55], v[188:189]
	v_pk_add_f32 v[186:187], v[52:53], v[186:187]
	v_pk_add_f32 v[170:171], v[50:51], v[170:171]
	v_pk_add_f32 v[168:169], v[48:49], v[168:169]
	v_cvt_pk_f16_f32 v139, v138, v139
	v_cvt_pk_f16_f32 v137, v136, v137
	v_cvt_pk_f16_f32 v138, v142, v143
	v_cvt_pk_f16_f32 v136, v140, v141
	s_waitcnt vmcnt(11)
	v_pk_add_f32 v[188:189], v[46:47], v[202:203]
	v_pk_add_f32 v[192:193], v[44:45], v[200:201]
	s_waitcnt vmcnt(10)
	v_pk_add_f32 v[200:201], v[42:43], v[206:207]
	v_pk_add_f32 v[202:203], v[40:41], v[204:205]
	v_cvt_pk_f16_f32 v143, v170, v171
	v_cvt_pk_f16_f32 v141, v144, v145
	v_cvt_pk_f16_f32 v142, v168, v169
	v_cvt_pk_f16_f32 v140, v186, v187
	global_store_dwordx4 v[172:173], v[136:139], off sc1
	global_store_dwordx4 v[172:173], v[140:143], off offset:256 sc1
	v_cvt_pk_f16_f32 v145, v200, v201
	v_lshl_add_u64 v[136:137], s[50:51], 0, v[146:147]
	v_cvt_pk_f16_f32 v143, v188, v189
	v_cvt_pk_f16_f32 v144, v202, v203
	v_cvt_pk_f16_f32 v142, v192, v193
	v_lshl_add_u64 v[140:141], v[136:137], 0, v[166:167]
	global_store_dwordx4 v[140:141], v[142:145], off sc1
	s_waitcnt vmcnt(12)
	v_pk_add_f32 v[136:137], v[38:39], v[216:217]
	s_waitcnt vmcnt(11)
	v_pk_add_f32 v[138:139], v[34:35], v[220:221]
	v_pk_add_f32 v[142:143], v[36:37], v[214:215]
	v_pk_add_f32 v[144:145], v[32:33], v[218:219]
	v_cvt_pk_f16_f32 v139, v138, v139
	v_cvt_pk_f16_f32 v137, v136, v137
	v_cvt_pk_f16_f32 v138, v144, v145
	v_cvt_pk_f16_f32 v136, v142, v143
	global_store_dwordx4 v[140:141], v[136:139], off offset:256 sc1
	v_lshlrev_b64 v[140:141], 11, v[182:183]
	s_waitcnt vmcnt(11)
	v_pk_add_f32 v[142:143], v[28:29], v[222:223]
	v_pk_add_f32 v[136:137], v[30:31], v[224:225]
	s_waitcnt vmcnt(10)
	v_pk_add_f32 v[138:139], v[26:27], v[228:229]
	v_pk_add_f32 v[144:145], v[24:25], v[226:227]
	v_lshl_add_u64 v[140:141], s[50:51], 0, v[140:141]
	v_cvt_pk_f16_f32 v139, v138, v139
	v_cvt_pk_f16_f32 v137, v136, v137
	v_cvt_pk_f16_f32 v138, v144, v145
	v_cvt_pk_f16_f32 v136, v142, v143
	v_lshl_add_u64 v[140:141], v[140:141], 0, v[166:167]
	global_store_dwordx4 v[140:141], v[136:139], off sc1
	s_waitcnt vmcnt(10)
	v_pk_add_f32 v[142:143], v[20:21], v[230:231]
	s_waitcnt vmcnt(9)
	v_pk_add_f32 v[144:145], v[16:17], v[234:235]
	v_pk_add_f32 v[136:137], v[22:23], v[232:233]
	v_pk_add_f32 v[138:139], v[18:19], v[236:237]
	v_cvt_pk_f16_f32 v137, v136, v137
	v_cvt_pk_f16_f32 v139, v138, v139
	v_cvt_pk_f16_f32 v138, v144, v145
	v_cvt_pk_f16_f32 v136, v142, v143
	global_store_dwordx4 v[140:141], v[136:139], off offset:256 sc1
	v_lshlrev_b64 v[140:141], 11, v[190:191]
	s_waitcnt vmcnt(9)
	v_pk_add_f32 v[142:143], v[12:13], v[238:239]
	v_pk_add_f32 v[136:137], v[14:15], v[240:241]
	s_waitcnt vmcnt(8)
	v_pk_add_f32 v[138:139], v[10:11], v[244:245]
	v_pk_add_f32 v[144:145], v[8:9], v[242:243]
	v_lshl_add_u64 v[140:141], s[50:51], 0, v[140:141]
	v_cvt_pk_f16_f32 v139, v138, v139
	v_cvt_pk_f16_f32 v137, v136, v137
	v_cvt_pk_f16_f32 v138, v144, v145
	v_cvt_pk_f16_f32 v136, v142, v143
	v_lshl_add_u64 v[140:141], v[140:141], 0, v[166:167]
	global_store_dwordx4 v[140:141], v[136:139], off sc1
	s_waitcnt vmcnt(8)
	v_pk_add_f32 v[142:143], v[4:5], v[246:247]
	s_waitcnt vmcnt(7)
	v_pk_add_f32 v[144:145], v[0:1], v[250:251]
	v_pk_add_f32 v[136:137], v[6:7], v[248:249]
	v_pk_add_f32 v[138:139], v[2:3], v[252:253]
	v_cvt_pk_f16_f32 v137, v136, v137
	v_cvt_pk_f16_f32 v139, v138, v139
	v_cvt_pk_f16_f32 v138, v144, v145
	v_cvt_pk_f16_f32 v136, v142, v143
	global_store_dwordx4 v[140:141], v[136:139], off offset:256 sc1
	s_cbranch_execnz .LBB0_510
;     __device__ __forceinline__ void operator()(const f32x4 (&acc)[2][2][4][2], const pg8::Unit& u, int wr, int wc, int fr, int fq) const {
;     ...
;                     for (int m = 0; m < 4; ++m) { const size_t off = (size_t)(row0 + ai * 128 + m * 16) * DM + col0;
; #pragma unroll
;                         for (int bj = 0; bj < 2; ++bj) hv[m][bj] = *(const f16x8*)(xh + off + bj * 128); }
;                     asm volatile("" ::: "memory");
; #pragma unroll
;                     for (int m = 0; m < 4; ++m) { const size_t off = (size_t)(row0 + ai * 128 + m * 16) * DM + col0;
; #pragma unroll
;                         for (int bj = 0; bj < 2; ++bj) { const f32x8 b8 = __builtin_convertvector(hv[m][bj], f32x8); const f32x4 a0 = acc[ai][bj][m][0], a1 = acc[ai][bj][m][1];
;                             const f32x8 xx = {b8[0] + a0[0], b8[1] + a0[1], b8[2] + a0[2], b8[3] + a0[3], b8[4] + a1[0], b8[5] + a1[1], b8[6] + a1[2], b8[7] + a1[3]};
;                             *(f16x8*)(xh + off + bj * 128) = __builtin_convertvector(xx, f16x8); } }
;                     asm volatile("" ::: "memory");
.LBB0_509:
	v_lshl_add_u64 v[168:169], s[50:51], 0, v[166:167]
	v_lshl_add_u64 v[134:135], v[168:169], 0, v[134:135]
	global_load_dwordx4 v[186:189], v[134:135], off
	global_load_dwordx4 v[200:203], v[134:135], off offset:256
	v_lshlrev_b64 v[182:183], 11, v[132:133]
	v_lshl_add_u64 v[132:133], v[168:169], 0, v[182:183]
	global_load_dwordx4 v[204:207], v[132:133], off
	global_load_dwordx4 v[144:147], v[132:133], off offset:256
	v_lshlrev_b64 v[172:173], 11, v[130:131]
	v_lshl_add_u64 v[130:131], v[168:169], 0, v[172:173]
	global_load_dwordx4 v[140:143], v[130:131], off
	global_load_dwordx4 v[136:139], v[130:131], off offset:256
	v_lshlrev_b64 v[170:171], 11, v[128:129]
	v_lshl_add_u64 v[128:129], v[168:169], 0, v[170:171]
	global_load_dwordx4 v[132:135], v[128:129], off
	s_nop 0
	global_load_dwordx4 v[128:131], v[128:129], off offset:256
	s_mov_b64 s[10:11], 0x40000
	s_waitcnt vmcnt(0)
	v_cvt_f32_f16_e32 v190, v189
	v_cvt_f32_f16_sdwa v191, v189 dst_sel:DWORD dst_unused:UNUSED_PAD src0_sel:WORD_1
	v_cvt_f32_f16_e32 v192, v188
	v_cvt_f32_f16_sdwa v193, v188 dst_sel:DWORD dst_unused:UNUSED_PAD src0_sel:WORD_1
	v_cvt_f32_f16_e32 v188, v187
	v_cvt_f32_f16_sdwa v189, v187 dst_sel:DWORD dst_unused:UNUSED_PAD src0_sel:WORD_1
	v_cvt_f32_f16_e32 v208, v186
	v_cvt_f32_f16_sdwa v209, v186 dst_sel:DWORD dst_unused:UNUSED_PAD src0_sel:WORD_1
	v_pk_add_f32 v[120:121], v[120:121], v[192:193]
	v_pk_add_f32 v[126:127], v[126:127], v[188:189]
	v_pk_add_f32 v[122:123], v[122:123], v[190:191]
	v_pk_add_f32 v[124:125], v[124:125], v[208:209]
	v_cvt_pk_f16_f32 v123, v122, v123
	v_cvt_pk_f16_f32 v122, v120, v121
	v_cvt_pk_f16_f32 v121, v126, v127
	v_cvt_pk_f16_f32 v120, v124, v125
	v_lshl_add_u64 v[124:125], v[174:175], 0, v[166:167]
	global_store_dwordx4 v[124:125], v[120:123], off sc1
	v_cvt_f32_f16_e32 v126, v201
	v_cvt_f32_f16_sdwa v127, v201 dst_sel:DWORD dst_unused:UNUSED_PAD src0_sel:WORD_1
	v_cvt_f32_f16_e32 v120, v203
	v_cvt_f32_f16_sdwa v121, v203 dst_sel:DWORD dst_unused:UNUSED_PAD src0_sel:WORD_1
	v_cvt_f32_f16_e32 v122, v202
	v_cvt_f32_f16_sdwa v123, v202 dst_sel:DWORD dst_unused:UNUSED_PAD src0_sel:WORD_1
	v_cvt_f32_f16_e32 v174, v200
	v_cvt_f32_f16_sdwa v175, v200 dst_sel:DWORD dst_unused:UNUSED_PAD src0_sel:WORD_1
	v_pk_add_f32 v[110:111], v[110:111], v[126:127]
	v_pk_add_f32 v[104:105], v[104:105], v[122:123]
	v_pk_add_f32 v[106:107], v[106:107], v[120:121]
	v_pk_add_f32 v[108:109], v[108:109], v[174:175]
	v_cvt_pk_f16_f32 v107, v106, v107
	v_cvt_pk_f16_f32 v106, v104, v105
	v_cvt_pk_f16_f32 v105, v110, v111
	v_cvt_pk_f16_f32 v104, v108, v109
	global_store_dwordx4 v[124:125], v[104:107], off offset:256 sc1
	v_cvt_f32_f16_e32 v108, v205
	v_cvt_f32_f16_sdwa v109, v205 dst_sel:DWORD dst_unused:UNUSED_PAD src0_sel:WORD_1
	v_cvt_f32_f16_e32 v104, v207
	v_cvt_f32_f16_sdwa v105, v207 dst_sel:DWORD dst_unused:UNUSED_PAD src0_sel:WORD_1
	v_cvt_f32_f16_e32 v106, v206
	v_cvt_f32_f16_sdwa v107, v206 dst_sel:DWORD dst_unused:UNUSED_PAD src0_sel:WORD_1
	v_cvt_f32_f16_e32 v110, v204
	v_cvt_f32_f16_sdwa v111, v204 dst_sel:DWORD dst_unused:UNUSED_PAD src0_sel:WORD_1
	v_pk_add_f32 v[108:109], v[118:119], v[108:109]
	v_pk_add_f32 v[104:105], v[114:115], v[104:105]
	v_pk_add_f32 v[112:113], v[112:113], v[106:107]
	v_pk_add_f32 v[110:111], v[116:117], v[110:111]
	v_cvt_pk_f16_f32 v107, v104, v105
	v_cvt_pk_f16_f32 v105, v108, v109
	v_lshl_add_u64 v[108:109], s[50:51], 0, v[182:183]
	v_cvt_pk_f16_f32 v106, v112, v113
	v_cvt_pk_f16_f32 v104, v110, v111
	v_lshl_add_u64 v[108:109], v[108:109], 0, v[166:167]
	global_store_dwordx4 v[108:109], v[104:107], off sc1
	v_cvt_f32_f16_e32 v110, v145
	v_cvt_f32_f16_sdwa v111, v145 dst_sel:DWORD dst_unused:UNUSED_PAD src0_sel:WORD_1
	v_cvt_f32_f16_e32 v104, v147
	v_cvt_f32_f16_sdwa v105, v147 dst_sel:DWORD dst_unused:UNUSED_PAD src0_sel:WORD_1
	v_cvt_f32_f16_e32 v106, v146
	v_cvt_f32_f16_sdwa v107, v146 dst_sel:DWORD dst_unused:UNUSED_PAD src0_sel:WORD_1
	v_cvt_f32_f16_e32 v112, v144
	v_cvt_f32_f16_sdwa v113, v144 dst_sel:DWORD dst_unused:UNUSED_PAD src0_sel:WORD_1
	v_pk_add_f32 v[102:103], v[102:103], v[110:111]
	v_pk_add_f32 v[96:97], v[96:97], v[106:107]
	v_pk_add_f32 v[98:99], v[98:99], v[104:105]
	v_pk_add_f32 v[100:101], v[100:101], v[112:113]
	v_cvt_pk_f16_f32 v99, v98, v99
	v_cvt_pk_f16_f32 v98, v96, v97
	v_cvt_pk_f16_f32 v97, v102, v103
	v_cvt_pk_f16_f32 v96, v100, v101
	global_store_dwordx4 v[108:109], v[96:99], off offset:256 sc1
	v_cvt_f32_f16_e32 v102, v140
	v_cvt_f32_f16_sdwa v103, v140 dst_sel:DWORD dst_unused:UNUSED_PAD src0_sel:WORD_1
	v_cvt_f32_f16_e32 v96, v143
	v_cvt_f32_f16_sdwa v97, v143 dst_sel:DWORD dst_unused:UNUSED_PAD src0_sel:WORD_1
	v_cvt_f32_f16_e32 v98, v142
	v_cvt_f32_f16_sdwa v99, v142 dst_sel:DWORD dst_unused:UNUSED_PAD src0_sel:WORD_1
	v_cvt_f32_f16_e32 v100, v141
	v_cvt_f32_f16_sdwa v101, v141 dst_sel:DWORD dst_unused:UNUSED_PAD src0_sel:WORD_1
	v_pk_add_f32 v[92:93], v[92:93], v[102:103]
	v_pk_add_f32 v[88:89], v[88:89], v[98:99]
	v_pk_add_f32 v[90:91], v[90:91], v[96:97]
	v_pk_add_f32 v[94:95], v[94:95], v[100:101]
	v_cvt_pk_f16_f32 v91, v90, v91
	v_cvt_pk_f16_f32 v90, v88, v89
	v_cvt_pk_f16_f32 v88, v92, v93
	v_lshl_add_u64 v[92:93], s[50:51], 0, v[172:173]
	v_cvt_pk_f16_f32 v89, v94, v95
	v_lshl_add_u64 v[92:93], v[92:93], 0, v[166:167]
	global_store_dwordx4 v[92:93], v[88:91], off sc1
	v_cvt_f32_f16_e32 v94, v137
	v_cvt_f32_f16_sdwa v95, v137 dst_sel:DWORD dst_unused:UNUSED_PAD src0_sel:WORD_1
	v_cvt_f32_f16_e32 v88, v139
	v_cvt_f32_f16_sdwa v89, v139 dst_sel:DWORD dst_unused:UNUSED_PAD src0_sel:WORD_1
	v_cvt_f32_f16_e32 v90, v138
	v_cvt_f32_f16_sdwa v91, v138 dst_sel:DWORD dst_unused:UNUSED_PAD src0_sel:WORD_1
;     __device__ __forceinline__ void operator()(const f32x4 (&acc)[2][2][4][2], const pg8::Unit& u, int wr, int wc, int fr, int fq) const {
;     ...
;                     for (int m = 0; m < 4; ++m) { const size_t off = (size_t)(row0 + ai * 128 + m * 16) * DM + col0;
; #pragma unroll
;                         for (int bj = 0; bj < 2; ++bj) hv[m][bj] = *(const f16x8*)(xh + off + bj * 128); }
;                     asm volatile("" ::: "memory");
; #pragma unroll
;                     for (int m = 0; m < 4; ++m) { const size_t off = (size_t)(row0 + ai * 128 + m * 16) * DM + col0;
; #pragma unroll
;                         for (int bj = 0; bj < 2; ++bj) { const f32x8 b8 = __builtin_convertvector(hv[m][bj], f32x8); const f32x4 a0 = acc[ai][bj][m][0], a1 = acc[ai][bj][m][1];
;                             const f32x8 xx = {b8[0] + a0[0], b8[1] + a0[1], b8[2] + a0[2], b8[3] + a0[3], b8[4] + a1[0], b8[5] + a1[1], b8[6] + a1[2], b8[7] + a1[3]};
;                             *(f16x8*)(xh + off + bj * 128) = __builtin_convertvector(xx, f16x8); } }
;                     asm volatile("" ::: "memory");
	v_cvt_f32_f16_e32 v96, v136
	v_cvt_f32_f16_sdwa v97, v136 dst_sel:DWORD dst_unused:UNUSED_PAD src0_sel:WORD_1
	v_pk_add_f32 v[86:87], v[86:87], v[94:95]
	v_pk_add_f32 v[80:81], v[80:81], v[90:91]
	v_pk_add_f32 v[82:83], v[82:83], v[88:89]
	v_pk_add_f32 v[84:85], v[84:85], v[96:97]
	v_cvt_pk_f16_f32 v83, v82, v83
	v_cvt_pk_f16_f32 v82, v80, v81
	v_cvt_pk_f16_f32 v81, v86, v87
	v_cvt_pk_f16_f32 v80, v84, v85
	global_store_dwordx4 v[92:93], v[80:83], off offset:256 sc1
	v_cvt_f32_f16_e32 v86, v132
	v_cvt_f32_f16_sdwa v87, v132 dst_sel:DWORD dst_unused:UNUSED_PAD src0_sel:WORD_1
	v_cvt_f32_f16_e32 v80, v135
	v_cvt_f32_f16_sdwa v81, v135 dst_sel:DWORD dst_unused:UNUSED_PAD src0_sel:WORD_1
	v_cvt_f32_f16_e32 v82, v134
	v_cvt_f32_f16_sdwa v83, v134 dst_sel:DWORD dst_unused:UNUSED_PAD src0_sel:WORD_1
	v_cvt_f32_f16_e32 v84, v133
	v_cvt_f32_f16_sdwa v85, v133 dst_sel:DWORD dst_unused:UNUSED_PAD src0_sel:WORD_1
	v_pk_add_f32 v[76:77], v[76:77], v[86:87]
	v_pk_add_f32 v[72:73], v[72:73], v[82:83]
	v_pk_add_f32 v[74:75], v[74:75], v[80:81]
	v_pk_add_f32 v[78:79], v[78:79], v[84:85]
	v_cvt_pk_f16_f32 v75, v74, v75
	v_cvt_pk_f16_f32 v74, v72, v73
	v_cvt_pk_f16_f32 v72, v76, v77
	v_lshl_add_u64 v[76:77], s[50:51], 0, v[170:171]
	v_cvt_pk_f16_f32 v73, v78, v79
	v_lshl_add_u64 v[76:77], v[76:77], 0, v[166:167]
	global_store_dwordx4 v[76:77], v[72:75], off sc1
	v_cvt_f32_f16_e32 v78, v129
	v_cvt_f32_f16_sdwa v79, v129 dst_sel:DWORD dst_unused:UNUSED_PAD src0_sel:WORD_1
	v_cvt_f32_f16_e32 v72, v131
	v_cvt_f32_f16_sdwa v73, v131 dst_sel:DWORD dst_unused:UNUSED_PAD src0_sel:WORD_1
	v_cvt_f32_f16_e32 v74, v130
	v_cvt_f32_f16_sdwa v75, v130 dst_sel:DWORD dst_unused:UNUSED_PAD src0_sel:WORD_1
	v_cvt_f32_f16_e32 v80, v128
	v_cvt_f32_f16_sdwa v81, v128 dst_sel:DWORD dst_unused:UNUSED_PAD src0_sel:WORD_1
	v_pk_add_f32 v[70:71], v[70:71], v[78:79]
	v_pk_add_f32 v[64:65], v[64:65], v[74:75]
	v_pk_add_f32 v[66:67], v[66:67], v[72:73]
	v_pk_add_f32 v[68:69], v[68:69], v[80:81]
	v_cvt_pk_f16_f32 v67, v66, v67
	v_cvt_pk_f16_f32 v66, v64, v65
	v_cvt_pk_f16_f32 v65, v70, v71
	v_cvt_pk_f16_f32 v64, v68, v69
	global_store_dwordx4 v[76:77], v[64:67], off offset:256 sc1
	s_nop 1
	v_lshlrev_b64 v[64:65], 11, v[164:165]
	v_lshl_add_u64 v[100:101], v[64:65], 0, s[10:11]
	v_lshl_add_u64 v[66:67], v[168:169], 0, v[100:101]
	global_load_dwordx4 v[84:87], v[66:67], off
	global_load_dwordx4 v[88:91], v[66:67], off offset:256
	s_mov_b64 s[10:11], 0x48000
	v_lshl_add_u64 v[102:103], v[64:65], 0, s[10:11]
	v_lshl_add_u64 v[66:67], v[168:169], 0, v[102:103]
	global_load_dwordx4 v[92:95], v[66:67], off
	global_load_dwordx4 v[96:99], v[66:67], off offset:256
	s_mov_b64 s[10:11], 0x50000
	v_lshl_add_u64 v[82:83], v[64:65], 0, s[10:11]
	v_lshl_add_u64 v[66:67], v[168:169], 0, v[82:83]
	global_load_dwordx4 v[76:79], v[66:67], off
	global_load_dwordx4 v[72:75], v[66:67], off offset:256
	s_mov_b64 s[10:11], 0x58000
	v_lshl_add_u64 v[80:81], v[64:65], 0, s[10:11]
	v_lshl_add_u64 v[64:65], v[168:169], 0, v[80:81]
	global_load_dwordx4 v[68:71], v[64:65], off
	s_nop 0
	global_load_dwordx4 v[64:67], v[64:65], off offset:256
	s_waitcnt vmcnt(7)
	v_cvt_f32_f16_e32 v104, v87
	v_cvt_f32_f16_sdwa v105, v87 dst_sel:DWORD dst_unused:UNUSED_PAD src0_sel:WORD_1
	v_cvt_f32_f16_e32 v106, v86
	v_cvt_f32_f16_sdwa v107, v86 dst_sel:DWORD dst_unused:UNUSED_PAD src0_sel:WORD_1
	v_cvt_f32_f16_e32 v108, v84
	v_cvt_f32_f16_sdwa v109, v84 dst_sel:DWORD dst_unused:UNUSED_PAD src0_sel:WORD_1
	v_cvt_f32_f16_e32 v86, v85
	v_cvt_f32_f16_sdwa v87, v85 dst_sel:DWORD dst_unused:UNUSED_PAD src0_sel:WORD_1
	v_pk_add_f32 v[56:57], v[56:57], v[106:107]
	v_pk_add_f32 v[60:61], v[60:61], v[108:109]
	v_pk_add_f32 v[58:59], v[58:59], v[104:105]
	v_pk_add_f32 v[62:63], v[62:63], v[86:87]
	v_cvt_pk_f16_f32 v59, v58, v59
	v_cvt_pk_f16_f32 v58, v56, v57
	v_cvt_pk_f16_f32 v56, v60, v61
	v_lshl_add_u64 v[60:61], s[50:51], 0, v[100:101]
	v_cvt_pk_f16_f32 v57, v62, v63
	v_lshl_add_u64 v[60:61], v[60:61], 0, v[166:167]
	global_store_dwordx4 v[60:61], v[56:59], off sc1
	s_waitcnt vmcnt(7)
	v_cvt_f32_f16_e32 v62, v89
	v_cvt_f32_f16_sdwa v63, v89 dst_sel:DWORD dst_unused:UNUSED_PAD src0_sel:WORD_1
	v_cvt_f32_f16_e32 v56, v91
	v_cvt_f32_f16_sdwa v57, v91 dst_sel:DWORD dst_unused:UNUSED_PAD src0_sel:WORD_1
	v_cvt_f32_f16_e32 v58, v90
	v_cvt_f32_f16_sdwa v59, v90 dst_sel:DWORD dst_unused:UNUSED_PAD src0_sel:WORD_1
	v_cvt_f32_f16_e32 v84, v88
	v_cvt_f32_f16_sdwa v85, v88 dst_sel:DWORD dst_unused:UNUSED_PAD src0_sel:WORD_1
	v_pk_add_f32 v[54:55], v[54:55], v[62:63]
	v_pk_add_f32 v[48:49], v[48:49], v[58:59]
	v_pk_add_f32 v[50:51], v[50:51], v[56:57]
	v_pk_add_f32 v[52:53], v[52:53], v[84:85]
	v_cvt_pk_f16_f32 v51, v50, v51
	v_cvt_pk_f16_f32 v50, v48, v49
	v_cvt_pk_f16_f32 v49, v54, v55
	v_cvt_pk_f16_f32 v48, v52, v53
	global_store_dwordx4 v[60:61], v[48:51], off offset:256 sc1
	s_waitcnt vmcnt(7)
;     __device__ __forceinline__ void operator()(const f32x4 (&acc)[2][2][4][2], const pg8::Unit& u, int wr, int wc, int fr, int fq) const {
;     ...
;                     for (int m = 0; m < 4; ++m) { const size_t off = (size_t)(row0 + ai * 128 + m * 16) * DM + col0;
; #pragma unroll
;                         for (int bj = 0; bj < 2; ++bj) hv[m][bj] = *(const f16x8*)(xh + off + bj * 128); }
;                     asm volatile("" ::: "memory");
; #pragma unroll
;                     for (int m = 0; m < 4; ++m) { const size_t off = (size_t)(row0 + ai * 128 + m * 16) * DM + col0;
; #pragma unroll
;                         for (int bj = 0; bj < 2; ++bj) { const f32x8 b8 = __builtin_convertvector(hv[m][bj], f32x8); const f32x4 a0 = acc[ai][bj][m][0], a1 = acc[ai][bj][m][1];
;                             const f32x8 xx = {b8[0] + a0[0], b8[1] + a0[1], b8[2] + a0[2], b8[3] + a0[3], b8[4] + a1[0], b8[5] + a1[1], b8[6] + a1[2], b8[7] + a1[3]};
;                             *(f16x8*)(xh + off + bj * 128) = __builtin_convertvector(xx, f16x8); } }
;                     asm volatile("" ::: "memory");
	v_cvt_f32_f16_e32 v54, v92
	v_cvt_f32_f16_sdwa v55, v92 dst_sel:DWORD dst_unused:UNUSED_PAD src0_sel:WORD_1
	v_cvt_f32_f16_e32 v48, v95
	v_cvt_f32_f16_sdwa v49, v95 dst_sel:DWORD dst_unused:UNUSED_PAD src0_sel:WORD_1
	v_cvt_f32_f16_e32 v50, v94
	v_cvt_f32_f16_sdwa v51, v94 dst_sel:DWORD dst_unused:UNUSED_PAD src0_sel:WORD_1
	v_cvt_f32_f16_e32 v52, v93
	v_cvt_f32_f16_sdwa v53, v93 dst_sel:DWORD dst_unused:UNUSED_PAD src0_sel:WORD_1
	v_pk_add_f32 v[44:45], v[44:45], v[54:55]
	v_pk_add_f32 v[40:41], v[40:41], v[50:51]
	v_pk_add_f32 v[42:43], v[42:43], v[48:49]
	v_pk_add_f32 v[46:47], v[46:47], v[52:53]
	v_cvt_pk_f16_f32 v43, v42, v43
	v_cvt_pk_f16_f32 v42, v40, v41
	v_cvt_pk_f16_f32 v40, v44, v45
	v_lshl_add_u64 v[44:45], s[50:51], 0, v[102:103]
	v_cvt_pk_f16_f32 v41, v46, v47
	v_lshl_add_u64 v[44:45], v[44:45], 0, v[166:167]
	global_store_dwordx4 v[44:45], v[40:43], off sc1
	s_waitcnt vmcnt(7)
	v_cvt_f32_f16_e32 v46, v97
	v_cvt_f32_f16_sdwa v47, v97 dst_sel:DWORD dst_unused:UNUSED_PAD src0_sel:WORD_1
	v_cvt_f32_f16_e32 v40, v99
	v_cvt_f32_f16_sdwa v41, v99 dst_sel:DWORD dst_unused:UNUSED_PAD src0_sel:WORD_1
	v_cvt_f32_f16_e32 v42, v98
	v_cvt_f32_f16_sdwa v43, v98 dst_sel:DWORD dst_unused:UNUSED_PAD src0_sel:WORD_1
	v_cvt_f32_f16_e32 v48, v96
	v_cvt_f32_f16_sdwa v49, v96 dst_sel:DWORD dst_unused:UNUSED_PAD src0_sel:WORD_1
	v_pk_add_f32 v[38:39], v[38:39], v[46:47]
	v_pk_add_f32 v[32:33], v[32:33], v[42:43]
	v_pk_add_f32 v[34:35], v[34:35], v[40:41]
	v_pk_add_f32 v[36:37], v[36:37], v[48:49]
	v_cvt_pk_f16_f32 v35, v34, v35
	v_cvt_pk_f16_f32 v34, v32, v33
	v_cvt_pk_f16_f32 v33, v38, v39
	v_cvt_pk_f16_f32 v32, v36, v37
	global_store_dwordx4 v[44:45], v[32:35], off offset:256 sc1
	s_waitcnt vmcnt(7)
	v_cvt_f32_f16_e32 v38, v76
	v_cvt_f32_f16_sdwa v39, v76 dst_sel:DWORD dst_unused:UNUSED_PAD src0_sel:WORD_1
	v_cvt_f32_f16_e32 v32, v79
	v_cvt_f32_f16_sdwa v33, v79 dst_sel:DWORD dst_unused:UNUSED_PAD src0_sel:WORD_1
	v_cvt_f32_f16_e32 v34, v78
	v_cvt_f32_f16_sdwa v35, v78 dst_sel:DWORD dst_unused:UNUSED_PAD src0_sel:WORD_1
	v_cvt_f32_f16_e32 v36, v77
	v_cvt_f32_f16_sdwa v37, v77 dst_sel:DWORD dst_unused:UNUSED_PAD src0_sel:WORD_1
	v_pk_add_f32 v[28:29], v[28:29], v[38:39]
	v_pk_add_f32 v[24:25], v[24:25], v[34:35]
	v_pk_add_f32 v[26:27], v[26:27], v[32:33]
	v_pk_add_f32 v[30:31], v[30:31], v[36:37]
	v_cvt_pk_f16_f32 v27, v26, v27
	v_cvt_pk_f16_f32 v26, v24, v25
	v_cvt_pk_f16_f32 v24, v28, v29
	v_lshl_add_u64 v[28:29], s[50:51], 0, v[82:83]
	v_cvt_pk_f16_f32 v25, v30, v31
	v_lshl_add_u64 v[28:29], v[28:29], 0, v[166:167]
	global_store_dwordx4 v[28:29], v[24:27], off sc1
	s_waitcnt vmcnt(7)
	v_cvt_f32_f16_e32 v30, v73
	v_cvt_f32_f16_sdwa v31, v73 dst_sel:DWORD dst_unused:UNUSED_PAD src0_sel:WORD_1
	v_cvt_f32_f16_e32 v24, v75
	v_cvt_f32_f16_sdwa v25, v75 dst_sel:DWORD dst_unused:UNUSED_PAD src0_sel:WORD_1
	v_cvt_f32_f16_e32 v26, v74
	v_cvt_f32_f16_sdwa v27, v74 dst_sel:DWORD dst_unused:UNUSED_PAD src0_sel:WORD_1
	v_cvt_f32_f16_e32 v32, v72
	v_cvt_f32_f16_sdwa v33, v72 dst_sel:DWORD dst_unused:UNUSED_PAD src0_sel:WORD_1
	v_pk_add_f32 v[22:23], v[22:23], v[30:31]
	v_pk_add_f32 v[16:17], v[16:17], v[26:27]
	v_pk_add_f32 v[18:19], v[18:19], v[24:25]
	v_pk_add_f32 v[20:21], v[20:21], v[32:33]
	v_cvt_pk_f16_f32 v19, v18, v19
	v_cvt_pk_f16_f32 v18, v16, v17
	v_cvt_pk_f16_f32 v17, v22, v23
	v_cvt_pk_f16_f32 v16, v20, v21
	global_store_dwordx4 v[28:29], v[16:19], off offset:256 sc1
	s_waitcnt vmcnt(7)
	v_cvt_f32_f16_e32 v22, v68
	v_cvt_f32_f16_sdwa v23, v68 dst_sel:DWORD dst_unused:UNUSED_PAD src0_sel:WORD_1
	v_cvt_f32_f16_e32 v16, v71
	v_cvt_f32_f16_sdwa v17, v71 dst_sel:DWORD dst_unused:UNUSED_PAD src0_sel:WORD_1
	v_cvt_f32_f16_e32 v18, v70
	v_cvt_f32_f16_sdwa v19, v70 dst_sel:DWORD dst_unused:UNUSED_PAD src0_sel:WORD_1
	v_cvt_f32_f16_e32 v20, v69
	v_cvt_f32_f16_sdwa v21, v69 dst_sel:DWORD dst_unused:UNUSED_PAD src0_sel:WORD_1
	v_pk_add_f32 v[12:13], v[12:13], v[22:23]
	v_pk_add_f32 v[8:9], v[8:9], v[18:19]
	v_pk_add_f32 v[10:11], v[10:11], v[16:17]
	v_pk_add_f32 v[14:15], v[14:15], v[20:21]
	v_cvt_pk_f16_f32 v11, v10, v11
	v_cvt_pk_f16_f32 v10, v8, v9
	v_cvt_pk_f16_f32 v8, v12, v13
	v_lshl_add_u64 v[12:13], s[50:51], 0, v[80:81]
	v_cvt_pk_f16_f32 v9, v14, v15
	v_lshl_add_u64 v[12:13], v[12:13], 0, v[166:167]
	global_store_dwordx4 v[12:13], v[8:11], off sc1
	s_waitcnt vmcnt(7)
	v_cvt_f32_f16_e32 v14, v65
	v_cvt_f32_f16_sdwa v15, v65 dst_sel:DWORD dst_unused:UNUSED_PAD src0_sel:WORD_1
	v_cvt_f32_f16_e32 v8, v67
	v_cvt_f32_f16_sdwa v9, v67 dst_sel:DWORD dst_unused:UNUSED_PAD src0_sel:WORD_1
	v_cvt_f32_f16_e32 v10, v66
	v_cvt_f32_f16_sdwa v11, v66 dst_sel:DWORD dst_unused:UNUSED_PAD src0_sel:WORD_1
	v_cvt_f32_f16_e32 v16, v64
	v_cvt_f32_f16_sdwa v17, v64 dst_sel:DWORD dst_unused:UNUSED_PAD src0_sel:WORD_1
	v_pk_add_f32 v[6:7], v[6:7], v[14:15]
	v_pk_add_f32 v[0:1], v[0:1], v[10:11]
	v_pk_add_f32 v[2:3], v[2:3], v[8:9]
	v_pk_add_f32 v[4:5], v[4:5], v[16:17]
	v_cvt_pk_f16_f32 v3, v2, v3
	v_cvt_pk_f16_f32 v2, v0, v1
	v_cvt_pk_f16_f32 v1, v6, v7
	v_cvt_pk_f16_f32 v0, v4, v5
	global_store_dwordx4 v[12:13], v[0:3], off offset:256 sc1

; __device__ __forceinline__ unsigned cvtpk(float lo, float hi) { f32x2_t v = {lo, hi}; bf16x2_t b = __builtin_convertvector(v, bf16x2_t); return __builtin_bit_cast(unsigned, b); }
; __device__ __forceinline__ void norm_phase(const float* x, const _Float16* xh, const float* g, bf16_t* h, int rows) {
;     ...
;         for (int r = 0; r < 4; ++r) { float s = 0.f;
; #pragma unroll
;             for (int j = 0; j < 4; ++j) s += (v[r][j].x * v[r][j].x + v[r][j].y * v[r][j].y) + (v[r][j].z * v[r][j].z + v[r][j].w * v[r][j].w);
;             const float rstd = 1.0f / sqrtf(wave_sum(s) * (1.0f / DM) + RMS_EPS);
;             u32x2* o8 = (u32x2*)(h + (size_t)(m0 + r) * DM) + lane;
; #pragma unroll
;             for (int j = 0; j < 4; ++j) { u32x2 w; w.x = cvtpk(v[r][j].x * rstd * gv[j].x, v[r][j].y * rstd * gv[j].y); w.y = cvtpk(v[r][j].z * rstd * gv[j].z, v[r][j].w * rstd * gv[j].w); o8[64 * j] = w; } }
.LBB0_522:
	s_waitcnt vmcnt(15)
	v_pk_mul_f32 v[104:105], v[78:79], v[78:79]
	v_pk_mul_f32 v[106:107], v[76:77], v[76:77]
	v_add_u32_e32 v80, s30, v80
	v_pk_mov_b32 v[108:109], v[106:107], v[104:105] op_sel:[1,0]
	v_mov_b32_e32 v107, v105
	v_pk_add_f32 v[104:105], v[108:109], v[106:107]
	s_waitcnt vmcnt(14)
	v_pk_mul_f32 v[106:107], v[74:75], v[74:75]
	v_pk_add_f32 v[104:105], v[104:105], v[104:105] op_sel_hi:[0,1]
	v_pk_mul_f32 v[108:109], v[72:73], v[72:73]
	s_waitcnt vmcnt(13)
	v_mul_f32_e32 v104, v68, v68
	v_pk_mov_b32 v[110:111], v[108:109], v[106:107] op_sel:[1,0]
	v_mov_b32_e32 v109, v107
	v_pk_add_f32 v[106:107], v[110:111], v[108:109]
	v_pk_fma_f32 v[108:109], v[68:69], v[68:69], v[104:105] op_sel_hi:[1,1,0]
	v_mul_f32_e32 v104, v70, v70
	v_pk_add_f32 v[106:107], v[106:107], v[106:107] op_sel_hi:[0,1]
	v_pk_fma_f32 v[110:111], v[70:71], v[70:71], v[104:105] op_sel_hi:[1,1,0]
	s_waitcnt vmcnt(12)
	v_mul_f32_e32 v108, v64, v64
	v_mul_f32_e32 v110, v65, v65
	v_mul_f32_e32 v106, v66, v66
	v_mul_f32_e32 v104, v67, v67
	v_pk_add_f32 v[108:109], v[108:109], v[110:111]
	v_pk_add_f32 v[104:105], v[106:107], v[104:105]
	s_waitcnt vmcnt(11)
	v_pk_mul_f32 v[106:107], v[62:63], v[62:63]
	v_pk_add_f32 v[104:105], v[108:109], v[104:105]
	v_pk_mul_f32 v[108:109], v[60:61], v[60:61]
	v_add_f32_e32 v81, v104, v105
	ds_bpermute_b32 v104, v98, v81
	v_lshl_add_u64 v[88:89], v[88:89], 0, s[70:71]
	s_waitcnt lgkmcnt(0)
	v_add_f32_e32 v81, v81, v104
	ds_bpermute_b32 v104, v99, v81
	s_waitcnt lgkmcnt(0)
	v_add_f32_e32 v81, v81, v104
	ds_bpermute_b32 v104, v100, v81
	s_waitcnt lgkmcnt(0)
	v_add_f32_e32 v81, v81, v104
	ds_bpermute_b32 v104, v101, v81
	s_waitcnt lgkmcnt(0)
	v_add_f32_e32 v81, v81, v104
	ds_bpermute_b32 v104, v102, v81
	s_waitcnt lgkmcnt(0)
	v_add_f32_e32 v81, v81, v104
	ds_bpermute_b32 v104, v103, v81
	s_waitcnt lgkmcnt(0)
	v_add_f32_e32 v81, v81, v104
	v_fmamk_f32 v81, v81, 0x3a800000, v195
	v_mul_f32_e32 v104, 0x4f800000, v81
	v_cmp_gt_f32_e32 vcc, s33, v81
	s_nop 1
	v_cndmask_b32_e32 v81, v81, v104, vcc
	v_sqrt_f32_e32 v110, v81
	v_lshl_add_u64 v[104:105], v[90:91], 0, v[86:87]
	v_lshl_add_u64 v[86:87], v[86:87], 0, s[68:69]
	v_add_u32_e32 v111, -1, v110
	v_add_u32_e32 v112, 1, v110
	v_fma_f32 v113, -v111, v110, v81
	v_fma_f32 v114, -v112, v110, v81
	v_cmp_ge_f32_e64 s[0:1], 0, v113
	s_nop 1
	v_cndmask_b32_e64 v110, v110, v111, s[0:1]
	v_cmp_lt_f32_e64 s[0:1], 0, v114
	s_nop 1
	v_cndmask_b32_e64 v110, v110, v112, s[0:1]
	v_mul_f32_e32 v111, 0x37800000, v110
	v_cndmask_b32_e32 v110, v110, v111, vcc
	v_cmp_class_f32_e32 vcc, v81, v197
	s_nop 1
	v_cndmask_b32_e32 v81, v110, v81, vcc
	v_div_scale_f32 v112, s[0:1], v81, v81, 1.0
	v_rcp_f32_e32 v113, v112
	v_pk_mov_b32 v[110:111], v[108:109], v[106:107] op_sel:[1,0]
	v_div_scale_f32 v106, vcc, 1.0, v81, 1.0
	v_fma_f32 v109, -v112, v113, 1.0
	v_fmac_f32_e32 v113, v109, v113
	v_mul_f32_e32 v109, v106, v113
	v_fma_f32 v114, -v112, v109, v106
	v_fmac_f32_e32 v109, v114, v113
	v_fma_f32 v106, -v112, v109, v106
	v_div_fmas_f32 v106, v106, v113, v109
	v_mov_b32_e32 v109, v107
	v_pk_add_f32 v[108:109], v[110:111], v[108:109]
	s_waitcnt vmcnt(10)
	v_pk_mul_f32 v[110:111], v[58:59], v[58:59]
	v_pk_add_f32 v[108:109], v[108:109], v[108:109] op_sel_hi:[0,1]
	v_pk_mul_f32 v[112:113], v[56:57], v[56:57]
	s_waitcnt vmcnt(9)
	v_mul_f32_e32 v108, v52, v52
	v_pk_mov_b32 v[114:115], v[112:113], v[110:111] op_sel:[1,0]
	v_mov_b32_e32 v113, v111
	v_pk_add_f32 v[110:111], v[114:115], v[112:113]
	v_pk_fma_f32 v[112:113], v[52:53], v[52:53], v[108:109] op_sel_hi:[1,1,0]
	v_mul_f32_e32 v108, v54, v54
	v_pk_add_f32 v[110:111], v[110:111], v[110:111] op_sel_hi:[0,1]
	v_pk_fma_f32 v[114:115], v[54:55], v[54:55], v[108:109] op_sel_hi:[1,1,0]
	s_waitcnt vmcnt(8)
	v_mul_f32_e32 v112, v48, v48
	v_mul_f32_e32 v114, v49, v49
	v_mul_f32_e32 v110, v50, v50
	v_mul_f32_e32 v108, v51, v51
	v_pk_add_f32 v[112:113], v[112:113], v[114:115]
	v_pk_add_f32 v[108:109], v[110:111], v[108:109]
	v_div_fixup_f32 v106, v106, v81, 1.0
	v_pk_add_f32 v[108:109], v[112:113], v[108:109]
	v_pk_mul_f32 v[76:77], v[76:77], v[106:107] op_sel_hi:[1,0]
	v_add_f32_e32 v81, v108, v109
	ds_bpermute_b32 v107, v98, v81
	s_waitcnt vmcnt(0)
	v_pk_mul_f32 v[76:77], v[12:13], v[76:77]
	s_brev_b32 s0, 32
	v_cvt_pk_bf16_f32 v76, v76, v77
	s_waitcnt lgkmcnt(0)
	v_add_f32_e32 v81, v81, v107
	v_pk_mul_f32 v[78:79], v[78:79], v[106:107] op_sel_hi:[1,0]
	ds_bpermute_b32 v107, v99, v81
	v_pk_mul_f32 v[78:79], v[14:15], v[78:79]
	s_waitcnt lgkmcnt(0)
	v_add_f32_e32 v81, v81, v107
	v_cvt_pk_bf16_f32 v77, v78, v79
	v_add_co_u32_e32 v78, vcc, s0, v104
	ds_bpermute_b32 v104, v100, v81
	s_nop 0
	v_addc_co_u32_e32 v79, vcc, 0, v105, vcc
	global_store_dwordx2 v[78:79], v[76:77], off sc1
	v_pk_mul_f32 v[72:73], v[72:73], v[106:107] op_sel_hi:[1,0]
	s_waitcnt lgkmcnt(0)
	v_add_f32_e32 v76, v81, v104
	ds_bpermute_b32 v77, v101, v76
	v_pk_mul_f32 v[74:75], v[74:75], v[106:107] op_sel_hi:[1,0]
	v_pk_mul_f32 v[72:73], v[8:9], v[72:73]
	v_pk_mul_f32 v[74:75], v[10:11], v[74:75]
	v_cvt_pk_bf16_f32 v72, v72, v73
	v_cvt_pk_bf16_f32 v73, v74, v75
	global_store_dwordx2 v[78:79], v[72:73], off offset:512 sc1
	s_waitcnt lgkmcnt(0)
	v_add_f32_e32 v72, v76, v77
	ds_bpermute_b32 v73, v102, v72
	v_pk_mul_f32 v[68:69], v[68:69], v[106:107] op_sel_hi:[1,0]
	v_pk_mul_f32 v[70:71], v[70:71], v[106:107] op_sel_hi:[1,0]
	v_pk_mul_f32 v[68:69], v[4:5], v[68:69]
	v_pk_mul_f32 v[70:71], v[6:7], v[70:71]
	s_waitcnt lgkmcnt(0)
	v_add_f32_e32 v72, v72, v73
	ds_bpermute_b32 v73, v103, v72
	v_cvt_pk_bf16_f32 v68, v68, v69
	v_cvt_pk_bf16_f32 v69, v70, v71
	global_store_dwordx2 v[78:79], v[68:69], off offset:1024 sc1
	v_pk_mul_f32 v[64:65], v[64:65], v[106:107] op_sel_hi:[1,0]
	s_waitcnt lgkmcnt(0)
; __device__ __forceinline__ unsigned cvtpk(float lo, float hi) { f32x2_t v = {lo, hi}; bf16x2_t b = __builtin_convertvector(v, bf16x2_t); return __builtin_bit_cast(unsigned, b); }
; __device__ __forceinline__ void norm_phase(const float* x, const _Float16* xh, const float* g, bf16_t* h, int rows) {
;     ...
;         for (int r = 0; r < 4; ++r) { float s = 0.f;
; #pragma unroll
;             for (int j = 0; j < 4; ++j) s += (v[r][j].x * v[r][j].x + v[r][j].y * v[r][j].y) + (v[r][j].z * v[r][j].z + v[r][j].w * v[r][j].w);
;             const float rstd = 1.0f / sqrtf(wave_sum(s) * (1.0f / DM) + RMS_EPS);
;             u32x2* o8 = (u32x2*)(h + (size_t)(m0 + r) * DM) + lane;
; #pragma unroll
;             for (int j = 0; j < 4; ++j) { u32x2 w; w.x = cvtpk(v[r][j].x * rstd * gv[j].x, v[r][j].y * rstd * gv[j].y); w.y = cvtpk(v[r][j].z * rstd * gv[j].z, v[r][j].w * rstd * gv[j].w); o8[64 * j] = w; } }
	v_add_f32_e32 v68, v72, v73
	v_fmamk_f32 v68, v68, 0x3a800000, v195
	v_mul_f32_e32 v69, 0x4f800000, v68
	v_cmp_gt_f32_e32 vcc, s33, v68
	v_pk_mul_f32 v[64:65], v[0:1], v[64:65]
	v_pk_mul_f32 v[66:67], v[66:67], v[106:107] op_sel_hi:[1,0]
	v_cndmask_b32_e32 v68, v68, v69, vcc
	v_sqrt_f32_e32 v69, v68
	v_cvt_pk_bf16_f32 v64, v64, v65
	v_pk_mul_f32 v[66:67], v[2:3], v[66:67]
	v_add_u32_e32 v65, -1, v69
	v_fma_f32 v70, -v65, v69, v68
	v_cmp_ge_f32_e64 s[0:1], 0, v70
	v_add_u32_e32 v70, 1, v69
	s_nop 0
	v_cndmask_b32_e64 v65, v69, v65, s[0:1]
	v_fma_f32 v69, -v70, v69, v68
	v_cmp_lt_f32_e64 s[0:1], 0, v69
	s_nop 1
	v_cndmask_b32_e64 v65, v65, v70, s[0:1]
	v_mul_f32_e32 v69, 0x37800000, v65
	v_cndmask_b32_e32 v65, v65, v69, vcc
	v_cmp_class_f32_e32 vcc, v68, v197
	s_nop 1
	v_cndmask_b32_e32 v72, v65, v68, vcc
	v_div_scale_f32 v68, s[0:1], v72, v72, 1.0
	v_rcp_f32_e32 v69, v68
	v_cvt_pk_bf16_f32 v65, v66, v67
	global_store_dwordx2 v[78:79], v[64:65], off offset:1536 sc1
	v_fma_f32 v64, -v68, v69, 1.0
	v_fmac_f32_e32 v69, v64, v69
	v_div_scale_f32 v64, vcc, 1.0, v72, 1.0
	v_mul_f32_e32 v65, v64, v69
	v_fma_f32 v66, -v68, v65, v64
	v_fmac_f32_e32 v65, v66, v69
	v_fma_f32 v64, -v68, v65, v64
	v_div_fmas_f32 v73, v64, v69, v65
	v_pk_mul_f32 v[64:65], v[46:47], v[46:47]
	v_pk_mul_f32 v[66:67], v[44:45], v[44:45]
	s_nop 0
	v_pk_mov_b32 v[68:69], v[66:67], v[64:65] op_sel:[1,0]
	v_mov_b32_e32 v67, v65
	v_pk_add_f32 v[64:65], v[68:69], v[66:67]
	v_pk_mul_f32 v[66:67], v[42:43], v[42:43]
	v_pk_add_f32 v[64:65], v[64:65], v[64:65] op_sel_hi:[0,1]
	v_pk_mul_f32 v[68:69], v[40:41], v[40:41]
	v_mul_f32_e32 v64, v36, v36
	v_pk_mov_b32 v[70:71], v[68:69], v[66:67] op_sel:[1,0]
	v_mov_b32_e32 v69, v67
	v_pk_add_f32 v[66:67], v[70:71], v[68:69]
	v_pk_fma_f32 v[68:69], v[36:37], v[36:37], v[64:65] op_sel_hi:[1,1,0]
	v_mul_f32_e32 v64, v38, v38
	v_pk_add_f32 v[66:67], v[66:67], v[66:67] op_sel_hi:[0,1]
	v_pk_fma_f32 v[70:71], v[38:39], v[38:39], v[64:65] op_sel_hi:[1,1,0]
	v_mul_f32_e32 v68, v32, v32
	v_mul_f32_e32 v70, v33, v33
	v_mul_f32_e32 v66, v34, v34
	v_mul_f32_e32 v64, v35, v35
	v_pk_add_f32 v[68:69], v[68:69], v[70:71]
	v_pk_add_f32 v[64:65], v[66:67], v[64:65]
	v_lshl_add_u64 v[66:67], v[84:85], 0, v[96:97]
	v_pk_add_f32 v[64:65], v[68:69], v[64:65]
	s_nop 0
	v_add_f32_e32 v65, v64, v65
	ds_bpermute_b32 v68, v98, v65
	v_div_fixup_f32 v64, v73, v72, 1.0
	v_pk_mul_f32 v[60:61], v[60:61], v[64:65] op_sel_hi:[1,0]
	s_waitcnt lgkmcnt(0)
	v_add_f32_e32 v65, v65, v68
	ds_bpermute_b32 v68, v99, v65
	v_pk_mul_f32 v[62:63], v[62:63], v[64:65] op_sel_hi:[1,0]
	v_pk_mul_f32 v[60:61], v[12:13], v[60:61]
	v_pk_mul_f32 v[62:63], v[14:15], v[62:63]
	v_cvt_pk_bf16_f32 v60, v60, v61
	v_cvt_pk_bf16_f32 v61, v62, v63
	s_waitcnt lgkmcnt(0)
	v_add_f32_e32 v62, v65, v68
	ds_bpermute_b32 v63, v100, v62
	global_store_dwordx2 v[66:67], v[60:61], off sc1
	v_pk_mul_f32 v[56:57], v[56:57], v[64:65] op_sel_hi:[1,0]
	v_pk_mul_f32 v[58:59], v[58:59], v[64:65] op_sel_hi:[1,0]
	v_pk_mul_f32 v[56:57], v[8:9], v[56:57]
	s_waitcnt lgkmcnt(0)
	v_add_f32_e32 v60, v62, v63
	ds_bpermute_b32 v61, v101, v60
	v_pk_mul_f32 v[58:59], v[10:11], v[58:59]
	v_cvt_pk_bf16_f32 v56, v56, v57
	v_cvt_pk_bf16_f32 v57, v58, v59
	global_store_dwordx2 v[66:67], v[56:57], off offset:512 sc1
	s_waitcnt lgkmcnt(0)
	v_add_f32_e32 v56, v60, v61
	ds_bpermute_b32 v57, v102, v56
	v_pk_mul_f32 v[52:53], v[52:53], v[64:65] op_sel_hi:[1,0]
	v_pk_mul_f32 v[54:55], v[54:55], v[64:65] op_sel_hi:[1,0]
	v_pk_mul_f32 v[52:53], v[4:5], v[52:53]
	v_pk_mul_f32 v[54:55], v[6:7], v[54:55]
	s_waitcnt lgkmcnt(0)
	v_add_f32_e32 v56, v56, v57
	ds_bpermute_b32 v57, v103, v56
	v_cvt_pk_bf16_f32 v52, v52, v53
	v_cvt_pk_bf16_f32 v53, v54, v55
	global_store_dwordx2 v[66:67], v[52:53], off offset:1024 sc1
	v_pk_mul_f32 v[48:49], v[48:49], v[64:65] op_sel_hi:[1,0]
	s_waitcnt lgkmcnt(0)
	v_add_f32_e32 v52, v56, v57
	v_fmamk_f32 v52, v52, 0x3a800000, v195
	v_mul_f32_e32 v53, 0x4f800000, v52
	v_cmp_gt_f32_e32 vcc, s33, v52
	v_pk_mul_f32 v[48:49], v[0:1], v[48:49]
	v_pk_mul_f32 v[50:51], v[50:51], v[64:65] op_sel_hi:[1,0]
	v_cndmask_b32_e32 v52, v52, v53, vcc
	v_sqrt_f32_e32 v53, v52
	v_cvt_pk_bf16_f32 v48, v48, v49
	v_pk_mul_f32 v[50:51], v[2:3], v[50:51]
	v_add_u32_e32 v49, -1, v53
	v_fma_f32 v54, -v49, v53, v52
	v_cmp_ge_f32_e64 s[0:1], 0, v54
	v_add_u32_e32 v54, 1, v53
	s_nop 0
	v_cndmask_b32_e64 v49, v53, v49, s[0:1]
	v_fma_f32 v53, -v54, v53, v52
	v_cmp_lt_f32_e64 s[0:1], 0, v53
	s_nop 1
	v_cndmask_b32_e64 v49, v49, v54, s[0:1]
	v_mul_f32_e32 v53, 0x37800000, v49
	v_cndmask_b32_e32 v49, v49, v53, vcc
	v_cmp_class_f32_e32 vcc, v52, v197
	s_nop 1
	v_cndmask_b32_e32 v56, v49, v52, vcc
	v_div_scale_f32 v52, s[0:1], v56, v56, 1.0
	v_rcp_f32_e32 v53, v52
	v_cvt_pk_bf16_f32 v49, v50, v51
	global_store_dwordx2 v[66:67], v[48:49], off offset:1536 sc1
	v_fma_f32 v48, -v52, v53, 1.0
	v_fmac_f32_e32 v53, v48, v53
	v_div_scale_f32 v48, vcc, 1.0, v56, 1.0
	v_mul_f32_e32 v49, v48, v53
	v_fma_f32 v50, -v52, v49, v48
	v_fmac_f32_e32 v49, v50, v53
	v_fma_f32 v48, -v52, v49, v48
	v_div_fmas_f32 v57, v48, v53, v49
	v_pk_mul_f32 v[48:49], v[30:31], v[30:31]
	v_pk_mul_f32 v[50:51], v[28:29], v[28:29]
	s_nop 0
	v_pk_mov_b32 v[52:53], v[50:51], v[48:49] op_sel:[1,0]
	v_mov_b32_e32 v51, v49
	v_pk_add_f32 v[48:49], v[52:53], v[50:51]
	v_pk_mul_f32 v[50:51], v[26:27], v[26:27]
	v_pk_add_f32 v[48:49], v[48:49], v[48:49] op_sel_hi:[0,1]
	v_pk_mul_f32 v[52:53], v[24:25], v[24:25]
	v_mul_f32_e32 v48, v20, v20
	v_pk_mov_b32 v[54:55], v[52:53], v[50:51] op_sel:[1,0]
	v_mov_b32_e32 v53, v51
	v_pk_add_f32 v[50:51], v[54:55], v[52:53]
	v_pk_fma_f32 v[52:53], v[20:21], v[20:21], v[48:49] op_sel_hi:[1,1,0]
	v_mul_f32_e32 v48, v22, v22
	v_pk_add_f32 v[50:51], v[50:51], v[50:51] op_sel_hi:[0,1]
	v_pk_fma_f32 v[54:55], v[22:23], v[22:23], v[48:49] op_sel_hi:[1,1,0]
	v_mul_f32_e32 v52, v16, v16
	v_mul_f32_e32 v54, v17, v17
	v_mul_f32_e32 v50, v18, v18
	v_mul_f32_e32 v48, v19, v19
	v_pk_add_f32 v[52:53], v[52:53], v[54:55]
	v_pk_add_f32 v[48:49], v[50:51], v[48:49]
	v_lshl_add_u64 v[50:51], v[84:85], 0, v[94:95]
	v_pk_add_f32 v[48:49], v[52:53], v[48:49]
	s_nop 0
	v_add_f32_e32 v49, v48, v49
	ds_bpermute_b32 v52, v98, v49
	v_div_fixup_f32 v48, v57, v56, 1.0
	v_pk_mul_f32 v[44:45], v[44:45], v[48:49] op_sel_hi:[1,0]
	s_waitcnt lgkmcnt(0)
; __device__ __forceinline__ unsigned cvtpk(float lo, float hi) { f32x2_t v = {lo, hi}; bf16x2_t b = __builtin_convertvector(v, bf16x2_t); return __builtin_bit_cast(unsigned, b); }
; __device__ __forceinline__ void norm_phase(const float* x, const _Float16* xh, const float* g, bf16_t* h, int rows) {
;     ...
;     for (int m0 = gw * 4; m0 < rows; m0 += NGW * 4) {
;         f32x4 v[4][4];
;         if (xh) {
; #pragma unroll
;             for (int r = 0; r < 4; ++r) { const f16x4* xr = (const f16x4*)(xh + (size_t)(m0 + r) * DM) + lane;
; #pragma unroll
;                 for (int j = 0; j < 4; ++j) v[r][j] = __builtin_convertvector(xr[64 * j], f32x4); }
;         } else {
; #pragma unroll
;             for (int r = 0; r < 4; ++r) { const f32x4* xr = (const f32x4*)(x + (size_t)(m0 + r) * DM) + lane;
; #pragma unroll
;                 for (int j = 0; j < 4; ++j) v[r][j] = xr[64 * j]; }
;         }
; #pragma unroll
;         for (int r = 0; r < 4; ++r) { float s = 0.f;
; #pragma unroll
;             for (int j = 0; j < 4; ++j) s += (v[r][j].x * v[r][j].x + v[r][j].y * v[r][j].y) + (v[r][j].z * v[r][j].z + v[r][j].w * v[r][j].w);
;             const float rstd = 1.0f / sqrtf(wave_sum(s) * (1.0f / DM) + RMS_EPS);
;             u32x2* o8 = (u32x2*)(h + (size_t)(m0 + r) * DM) + lane;
; #pragma unroll
;             for (int j = 0; j < 4; ++j) { u32x2 w; w.x = cvtpk(v[r][j].x * rstd * gv[j].x, v[r][j].y * rstd * gv[j].y); w.y = cvtpk(v[r][j].z * rstd * gv[j].z, v[r][j].w * rstd * gv[j].w); o8[64 * j] = w; } }
	v_add_f32_e32 v49, v49, v52
	ds_bpermute_b32 v52, v99, v49
	v_pk_mul_f32 v[46:47], v[46:47], v[48:49] op_sel_hi:[1,0]
	v_pk_mul_f32 v[44:45], v[12:13], v[44:45]
	v_pk_mul_f32 v[46:47], v[14:15], v[46:47]
	v_cvt_pk_bf16_f32 v44, v44, v45
	v_cvt_pk_bf16_f32 v45, v46, v47
	s_waitcnt lgkmcnt(0)
	v_add_f32_e32 v46, v49, v52
	ds_bpermute_b32 v47, v100, v46
	global_store_dwordx2 v[50:51], v[44:45], off sc1
	v_pk_mul_f32 v[40:41], v[40:41], v[48:49] op_sel_hi:[1,0]
	v_pk_mul_f32 v[42:43], v[42:43], v[48:49] op_sel_hi:[1,0]
	v_pk_mul_f32 v[40:41], v[8:9], v[40:41]
	s_waitcnt lgkmcnt(0)
	v_add_f32_e32 v44, v46, v47
	ds_bpermute_b32 v45, v101, v44
	v_pk_mul_f32 v[42:43], v[10:11], v[42:43]
	v_cvt_pk_bf16_f32 v40, v40, v41
	v_cvt_pk_bf16_f32 v41, v42, v43
	global_store_dwordx2 v[50:51], v[40:41], off offset:512 sc1
	s_waitcnt lgkmcnt(0)
	v_add_f32_e32 v40, v44, v45
	ds_bpermute_b32 v41, v102, v40
	v_pk_mul_f32 v[36:37], v[36:37], v[48:49] op_sel_hi:[1,0]
	v_pk_mul_f32 v[38:39], v[38:39], v[48:49] op_sel_hi:[1,0]
	v_pk_mul_f32 v[36:37], v[4:5], v[36:37]
	v_pk_mul_f32 v[38:39], v[6:7], v[38:39]
	s_waitcnt lgkmcnt(0)
	v_add_f32_e32 v40, v40, v41
	ds_bpermute_b32 v41, v103, v40
	v_cvt_pk_bf16_f32 v36, v36, v37
	v_cvt_pk_bf16_f32 v37, v38, v39
	global_store_dwordx2 v[50:51], v[36:37], off offset:1024 sc1
	v_pk_mul_f32 v[32:33], v[32:33], v[48:49] op_sel_hi:[1,0]
	s_waitcnt lgkmcnt(0)
	v_add_f32_e32 v36, v40, v41
	v_fmamk_f32 v36, v36, 0x3a800000, v195
	v_mul_f32_e32 v37, 0x4f800000, v36
	v_cmp_gt_f32_e32 vcc, s33, v36
	v_pk_mul_f32 v[32:33], v[0:1], v[32:33]
	v_pk_mul_f32 v[34:35], v[34:35], v[48:49] op_sel_hi:[1,0]
	v_cndmask_b32_e32 v36, v36, v37, vcc
	v_sqrt_f32_e32 v37, v36
	v_cvt_pk_bf16_f32 v32, v32, v33
	v_pk_mul_f32 v[34:35], v[2:3], v[34:35]
	v_add_u32_e32 v33, -1, v37
	v_fma_f32 v38, -v33, v37, v36
	v_cmp_ge_f32_e64 s[0:1], 0, v38
	v_add_u32_e32 v38, 1, v37
	s_nop 0
	v_cndmask_b32_e64 v33, v37, v33, s[0:1]
	v_fma_f32 v37, -v38, v37, v36
	v_cmp_lt_f32_e64 s[0:1], 0, v37
	s_nop 1
	v_cndmask_b32_e64 v33, v33, v38, s[0:1]
	v_mul_f32_e32 v37, 0x37800000, v33
	v_cndmask_b32_e32 v33, v33, v37, vcc
	v_cmp_class_f32_e32 vcc, v36, v197
	s_nop 1
	v_cndmask_b32_e32 v36, v33, v36, vcc
	v_div_scale_f32 v37, s[0:1], v36, v36, 1.0
	v_rcp_f32_e32 v38, v37
	v_cvt_pk_bf16_f32 v33, v34, v35
	global_store_dwordx2 v[50:51], v[32:33], off offset:1536 sc1
	v_fma_f32 v32, -v37, v38, 1.0
	v_fmac_f32_e32 v38, v32, v38
	v_div_scale_f32 v32, vcc, 1.0, v36, 1.0
	v_mul_f32_e32 v33, v32, v38
	v_fma_f32 v34, -v37, v33, v32
	v_fmac_f32_e32 v33, v34, v38
	v_fma_f32 v32, -v37, v33, v32
	v_div_fmas_f32 v32, v32, v38, v33
	v_div_fixup_f32 v32, v32, v36, 1.0
	v_pk_mul_f32 v[28:29], v[28:29], v[32:33] op_sel_hi:[1,0]
	v_pk_mul_f32 v[30:31], v[30:31], v[32:33] op_sel_hi:[1,0]
	v_pk_mul_f32 v[24:25], v[24:25], v[32:33] op_sel_hi:[1,0]
	v_pk_mul_f32 v[26:27], v[26:27], v[32:33] op_sel_hi:[1,0]
	v_pk_mul_f32 v[20:21], v[20:21], v[32:33] op_sel_hi:[1,0]
	v_pk_mul_f32 v[22:23], v[22:23], v[32:33] op_sel_hi:[1,0]
	v_pk_mul_f32 v[16:17], v[16:17], v[32:33] op_sel_hi:[1,0]
	v_pk_mul_f32 v[18:19], v[18:19], v[32:33] op_sel_hi:[1,0]
	v_pk_mul_f32 v[28:29], v[12:13], v[28:29]
	v_pk_mul_f32 v[30:31], v[14:15], v[30:31]
	v_pk_mul_f32 v[24:25], v[8:9], v[24:25]
	v_pk_mul_f32 v[26:27], v[10:11], v[26:27]
	v_pk_mul_f32 v[20:21], v[4:5], v[20:21]
	v_pk_mul_f32 v[22:23], v[6:7], v[22:23]
	v_pk_mul_f32 v[16:17], v[0:1], v[16:17]
	v_pk_mul_f32 v[18:19], v[2:3], v[18:19]
	v_cmp_le_i32_e32 vcc, s62, v80
	v_lshl_add_u64 v[34:35], v[84:85], 0, v[92:93]
	v_cvt_pk_bf16_f32 v28, v28, v29
	v_cvt_pk_bf16_f32 v29, v30, v31
	v_cvt_pk_bf16_f32 v24, v24, v25
	v_cvt_pk_bf16_f32 v25, v26, v27
	v_cvt_pk_bf16_f32 v20, v20, v21
	v_cvt_pk_bf16_f32 v21, v22, v23
	v_cvt_pk_bf16_f32 v16, v16, v17
	v_cvt_pk_bf16_f32 v17, v18, v19
	s_or_b64 s[6:7], vcc, s[6:7]
	global_store_dwordx2 v[34:35], v[28:29], off sc1
	global_store_dwordx2 v[34:35], v[24:25], off offset:512 sc1
	global_store_dwordx2 v[34:35], v[20:21], off offset:1024 sc1
	global_store_dwordx2 v[34:35], v[16:17], off offset:1536 sc1
	s_andn2_b64 exec, exec, s[6:7]
	s_cbranch_execz .LBB0_69
